# GEMM: first k-step MFMAs take C=0, accumulator zero-init v_movs removed
# baseline (speedup 1.0000x reference)
; #define G_LOAD(KT) do { _Pragma("unroll") for (int i = 0; i < 4; ++i) { ra[i] = *(const u32x4*)(Ag + (size_t)i * 64 * lda + (KT) * 64); rb[i] = *(const u32x4*)(Bg + (size_t)i * 64 * K + (KT) * 64); } } while (0)
; #define G_STORE(BUF) do { u16* ad = As + (BUF) * 256 * 64 + sto; u16* bd = Bs + (BUF) * 256 * 64 + sto; _Pragma("unroll") for (int i = 0; i < 4; ++i) { *(u32x4*)(ad + i * 64 * 64) = ra[i]; *(u32x4*)(bd + i * 64 * 64) = rb[i]; } } while (0)
; template <int EPI>
; DI void gemm_phase(const u16* __restrict__ A, int lda, const u16* __restrict__ Bt, int K, int N, u16* outb, int ldo,
;                    const float* r0, const float* r1, float* outf, char* lds, int bid, int nb) {
;     ...
;   for (int it = 0; it < nIter; ++it) {
;     int tm, tn;
;     if (swz) { const int st = xcd + 8 * it, sm = st / nSN, sn = st - sm * nSN; tm = sm * GM + jb / GN; tn = sn * GN + (jb % GN); }
;     else { const int t = bid + it * nb; tm = t / nN; tn = t - tm * nN; }
;     const u16* Ag = A + (size_t)(tm * 256 + lrow) * lda + lch * 8;
;     const u16* Bg = Bt + (size_t)(tn * 256 + lrow) * K + lch * 8;
;     f32x4 acc[8][4];
; #pragma unroll
;     for (int i = 0; i < 8; ++i)
; #pragma unroll
;       for (int j = 0; j < 4; ++j) acc[i][j] = (f32x4){0.f, 0.f, 0.f, 0.f};
;     u32x4 ra[4], rb[4];
;     ...
;     G_LOAD(0);
;     G_STORE(0);
;     __syncthreads();
.LBB0_287:
	s_lshl_b32 s56, s56, 8
	v_or_b32_e32 v0, s56, v138
	s_lshl_b32 s57, s57, 8
	v_ashrrev_i32_e32 v1, 31, v0
	v_or_b32_e32 v2, s57, v138
	v_ashrrev_i32_e32 v3, 31, v2
	v_lshlrev_b64 v[64:65], 11, v[0:1]
	v_lshl_add_u64 v[0:1], v[130:131], 0, v[64:65]
	v_lshlrev_b64 v[2:3], 11, v[2:3]
	v_lshl_add_u64 v[134:135], v[128:129], 0, v[2:3]
	v_add_co_u32_e32 v2, vcc, s19, v0
	s_nop 1
	v_readfirstlane_b32 s98, v0
	v_readfirstlane_b32 s99, v1
	s_nop 1
	v_readfirstlane_b32 s100, v134
	v_readfirstlane_b32 s101, v135
	v_addc_co_u32_e32 v3, vcc, 0, v1, vcc
	v_add_co_u32_e32 v4, vcc, s19, v134
	s_mov_b32 s62, 0
	s_nop 0
	v_addc_co_u32_e32 v5, vcc, 0, v135, vcc
	v_add_co_u32_e32 v2, vcc, s20, v0
	s_mov_b64 s[12:13], 0
	s_nop 0
	v_addc_co_u32_e32 v3, vcc, 0, v1, vcc
	v_add_co_u32_e32 v4, vcc, s20, v134
	v_lshl_add_u64 v[136:137], v[132:133], 0, v[64:65]
	s_nop 0
	v_addc_co_u32_e32 v5, vcc, 0, v135, vcc
	v_add_co_u32_e32 v0, vcc, s21, v0
	v_addc_co_u32_e32 v1, vcc, 0, v1, vcc
	v_add_co_u32_e32 v2, vcc, s21, v134
	s_nop 1
	v_addc_co_u32_e32 v3, vcc, 0, v135, vcc
	v_mov_b32_e32 v0, 0
	v_and_b32_e32 v229, 63, v174
	v_lshrrev_b32_e32 v230, 3, v229
	v_mov_b32_e32 v233, 0x800
	v_mul_u32_u24_e32 v224, v230, v233
	v_bfe_u32 v231, v174, 4, 2
	v_bfe_u32 v232, v174, 6, 1
	v_lshl_or_b32 v232, v232, 2, v231
	v_and_b32_e32 v233, 7, v174
	v_xor_b32_e32 v232, v232, v233
	v_lshl_add_u32 v224, v232, 4, v224
	v_and_b32_e32 v229, 15, v174
	v_bfe_u32 v230, v174, 1, 3
	v_xor_b32_e32 v230, v230, v231
	v_lshlrev_b32_e32 v230, 4, v230
	v_lshl_or_b32 v230, v229, 7, v230
	v_lshrrev_b32_e32 v229, 8, v174
	v_lshl_or_b32 v225, v229, 14, v230
	v_bfe_u32 v229, v174, 6, 2
	v_lshl_or_b32 v227, v229, 13, v230
	v_or_b32_e32 v227, 0x10000, v227
	v_xor_b32_e32 v226, 64, v225
	v_xor_b32_e32 v228, 64, v227
	v_readfirstlane_b32 s97, v174
	s_lshl_b32 s97, s97, 4
	s_mov_b32 s28, 14
	s_add_u32 m0, s97, 0x0
	s_add_u32 s12, s98, 0x0
	s_addc_u32 s13, s99, 0
	global_load_lds_dwordx4 v224, s[12:13]
	s_add_u32 m0, s97, 0x10000
	s_add_u32 s12, s100, 0x0
	s_addc_u32 s13, s101, 0
	global_load_lds_dwordx4 v224, s[12:13]
	s_add_u32 m0, s97, 0x2000
	s_add_u32 s12, s98, 0x20000
	s_addc_u32 s13, s99, 0
	global_load_lds_dwordx4 v224, s[12:13]
	s_add_u32 m0, s97, 0x12000
	s_add_u32 s12, s100, 0x20000
	s_addc_u32 s13, s101, 0
	global_load_lds_dwordx4 v224, s[12:13]
	s_add_u32 m0, s97, 0x4000
	s_add_u32 s12, s98, 0x40000
	s_addc_u32 s13, s99, 0
	global_load_lds_dwordx4 v224, s[12:13]
	s_add_u32 m0, s97, 0x14000
	s_add_u32 s12, s100, 0x40000
	s_addc_u32 s13, s101, 0
	global_load_lds_dwordx4 v224, s[12:13]
	s_add_u32 m0, s97, 0x6000
	s_add_u32 s12, s98, 0x60000
	s_addc_u32 s13, s99, 0
	global_load_lds_dwordx4 v224, s[12:13]
	s_add_u32 m0, s97, 0x16000
	s_add_u32 s12, s100, 0x60000
	s_addc_u32 s13, s101, 0
	global_load_lds_dwordx4 v224, s[12:13]
	s_add_u32 m0, s97, 0x8000
	s_add_u32 s12, s98, 0x80
	s_addc_u32 s13, s99, 0
	global_load_lds_dwordx4 v224, s[12:13]
	s_add_u32 m0, s97, 0x18000
	s_add_u32 s12, s100, 0x80
	s_addc_u32 s13, s101, 0
	global_load_lds_dwordx4 v224, s[12:13]
	s_add_u32 m0, s97, 0xa000
	s_add_u32 s12, s98, 0x20080
	s_addc_u32 s13, s99, 0
	global_load_lds_dwordx4 v224, s[12:13]
	s_add_u32 m0, s97, 0x1a000
	s_add_u32 s12, s100, 0x20080
	s_addc_u32 s13, s101, 0
	global_load_lds_dwordx4 v224, s[12:13]
	s_add_u32 m0, s97, 0xc000
	s_add_u32 s12, s98, 0x40080
	s_addc_u32 s13, s99, 0
	global_load_lds_dwordx4 v224, s[12:13]
	s_add_u32 m0, s97, 0x1c000
	s_add_u32 s12, s100, 0x40080
	s_addc_u32 s13, s101, 0
	global_load_lds_dwordx4 v224, s[12:13]
	s_add_u32 m0, s97, 0xe000
	s_add_u32 s12, s98, 0x60080
	s_addc_u32 s13, s99, 0
	global_load_lds_dwordx4 v224, s[12:13]
	s_add_u32 m0, s97, 0x1e000
	s_add_u32 s12, s100, 0x60080
	s_addc_u32 s13, s101, 0
	global_load_lds_dwordx4 v224, s[12:13]
	s_add_u32 s98, s98, 0x100
	s_addc_u32 s99, s99, 0
	s_add_u32 s100, s100, 0x100
	s_addc_u32 s101, s101, 0
	s_waitcnt vmcnt(8)
	s_barrier
; #define G_LOAD(KT) do { _Pragma("unroll") for (int i = 0; i < 4; ++i) { ra[i] = *(const u32x4*)(Ag + (size_t)i * 64 * lda + (KT) * 64); rb[i] = *(const u32x4*)(Bg + (size_t)i * 64 * K + (KT) * 64); } } while (0)
; #define G_STORE(BUF) do { u16* ad = As + (BUF) * 256 * 64 + sto; u16* bd = Bs + (BUF) * 256 * 64 + sto; _Pragma("unroll") for (int i = 0; i < 4; ++i) { *(u32x4*)(ad + i * 64 * 64) = ra[i]; *(u32x4*)(bd + i * 64 * 64) = rb[i]; } } while (0)
; template <int EPI>
; DI void gemm_phase(const u16* __restrict__ A, int lda, const u16* __restrict__ Bt, int K, int N, u16* outb, int ldo,
;                    const float* r0, const float* r1, float* outf, char* lds, int bid, int nb) {
;     ...
;     G_LOAD(0);
;     G_STORE(0);
;     __syncthreads();
;     for (int kt = 0; kt < nk; ++kt) {
;       const int cur = kt & 1;
;       if (kt + 1 < nk) G_LOAD(kt + 1);
;       G_MMA(cur, fo0);
;       G_MMA(cur, fo1);
	ds_read_b128 v[152:155], v227 offset:0
	ds_read_b128 v[156:159], v227 offset:2048
	ds_read_b128 v[160:163], v227 offset:4096
	ds_read_b128 v[164:167], v227 offset:6144
	ds_read_b128 v[188:191], v225 offset:0
	ds_read_b128 v[192:195], v225 offset:2048
	ds_read_b128 v[196:199], v225 offset:4096
	ds_read_b128 v[200:203], v225 offset:6144
	ds_read_b128 v[204:207], v225 offset:8192
	ds_read_b128 v[208:211], v225 offset:10240
	ds_read_b128 v[212:215], v225 offset:12288
	ds_read_b128 v[216:219], v225 offset:14336
	v_xor_b32_e32 v225, 0x8000, v225
	v_xor_b32_e32 v227, 0x8000, v227
	s_waitcnt lgkmcnt(0)
	s_waitcnt lgkmcnt(4)
	v_mfma_f32_16x16x32_bf16 v[124:127], v[152:155], v[188:191], 0
	v_mfma_f32_16x16x32_bf16 v[120:123], v[156:159], v[188:191], 0
	v_mfma_f32_16x16x32_bf16 v[116:119], v[160:163], v[188:191], 0
	v_mfma_f32_16x16x32_bf16 v[112:115], v[164:167], v[188:191], 0
	ds_read_b128 v[188:191], v226 offset:0
	ds_read_b128 v[168:171], v228 offset:0
	v_mfma_f32_16x16x32_bf16 v[108:111], v[152:155], v[192:195], 0
	v_mfma_f32_16x16x32_bf16 v[104:107], v[156:159], v[192:195], 0
	v_mfma_f32_16x16x32_bf16 v[100:103], v[160:163], v[192:195], 0
	v_mfma_f32_16x16x32_bf16 v[96:99], v[164:167], v[192:195], 0
	ds_read_b128 v[192:195], v226 offset:2048
	ds_read_b128 v[176:179], v228 offset:2048
	v_mfma_f32_16x16x32_bf16 v[92:95], v[152:155], v[196:199], 0
	v_mfma_f32_16x16x32_bf16 v[88:91], v[156:159], v[196:199], 0
	v_mfma_f32_16x16x32_bf16 v[84:87], v[160:163], v[196:199], 0
	v_mfma_f32_16x16x32_bf16 v[80:83], v[164:167], v[196:199], 0
	ds_read_b128 v[196:199], v226 offset:4096
	ds_read_b128 v[180:183], v228 offset:4096
	v_mfma_f32_16x16x32_bf16 v[76:79], v[152:155], v[200:203], 0
	v_mfma_f32_16x16x32_bf16 v[72:75], v[156:159], v[200:203], 0
	v_mfma_f32_16x16x32_bf16 v[68:71], v[160:163], v[200:203], 0
	v_mfma_f32_16x16x32_bf16 v[64:67], v[164:167], v[200:203], 0
	ds_read_b128 v[200:203], v226 offset:6144
	ds_read_b128 v[184:187], v228 offset:6144
	s_waitcnt lgkmcnt(11)
	v_mfma_f32_16x16x32_bf16 v[60:63], v[152:155], v[204:207], 0
	v_mfma_f32_16x16x32_bf16 v[56:59], v[156:159], v[204:207], 0
	v_mfma_f32_16x16x32_bf16 v[52:55], v[160:163], v[204:207], 0
	v_mfma_f32_16x16x32_bf16 v[48:51], v[164:167], v[204:207], 0
	ds_read_b128 v[204:207], v226 offset:8192
	ds_read_b128 v[220:223], v226 offset:14336
	s_waitcnt lgkmcnt(11)
	v_mfma_f32_16x16x32_bf16 v[44:47], v[152:155], v[208:211], 0
	v_mfma_f32_16x16x32_bf16 v[40:43], v[156:159], v[208:211], 0
	v_mfma_f32_16x16x32_bf16 v[36:39], v[160:163], v[208:211], 0
	v_mfma_f32_16x16x32_bf16 v[32:35], v[164:167], v[208:211], 0
	ds_read_b128 v[208:211], v226 offset:10240
	s_waitcnt lgkmcnt(11)
	v_mfma_f32_16x16x32_bf16 v[28:31], v[152:155], v[212:215], 0
	v_mfma_f32_16x16x32_bf16 v[24:27], v[156:159], v[212:215], 0
	v_mfma_f32_16x16x32_bf16 v[20:23], v[160:163], v[212:215], 0
	v_mfma_f32_16x16x32_bf16 v[16:19], v[164:167], v[212:215], 0
	ds_read_b128 v[212:215], v226 offset:12288
	v_mfma_f32_16x16x32_bf16 v[12:15], v[152:155], v[216:219], 0
	v_mfma_f32_16x16x32_bf16 v[8:11], v[156:159], v[216:219], 0
	v_mfma_f32_16x16x32_bf16 v[4:7], v[160:163], v[216:219], 0
	v_mfma_f32_16x16x32_bf16 v[0:3], v[164:167], v[216:219], 0
	s_branch .Lgm0_mid0

; #define G_LOAD(KT) do { _Pragma("unroll") for (int i = 0; i < 4; ++i) { ra[i] = *(const u32x4*)(Ag + (size_t)i * 64 * lda + (KT) * 64); rb[i] = *(const u32x4*)(Bg + (size_t)i * 64 * K + (KT) * 64); } } while (0)
; #define G_STORE(BUF) do { u16* ad = As + (BUF) * 256 * 64 + sto; u16* bd = Bs + (BUF) * 256 * 64 + sto; _Pragma("unroll") for (int i = 0; i < 4; ++i) { *(u32x4*)(ad + i * 64 * 64) = ra[i]; *(u32x4*)(bd + i * 64 * 64) = rb[i]; } } while (0)
; template <int EPI>
; DI void gemm_phase(const u16* __restrict__ A, int lda, const u16* __restrict__ Bt, int K, int N, u16* outb, int ldo,
;                    const float* r0, const float* r1, float* outf, char* lds, int bid, int nb) {
;     ...
;     for (int kt = 0; kt < nk; ++kt) {
;       const int cur = kt & 1;
;       if (kt + 1 < nk) G_LOAD(kt + 1);
;       G_MMA(cur, fo0);
;       G_MMA(cur, fo1);
;       if (kt + 1 < nk) G_STORE(cur ^ 1);
;       __syncthreads();
.Lgm0_mid0:
	s_waitcnt vmcnt(0) lgkmcnt(0)
	s_barrier
	v_mfma_f32_16x16x32_bf16 v[124:127], v[168:171], v[188:191], v[124:127]
	v_mfma_f32_16x16x32_bf16 v[120:123], v[176:179], v[188:191], v[120:123]
	v_mfma_f32_16x16x32_bf16 v[116:119], v[180:183], v[188:191], v[116:119]
	v_mfma_f32_16x16x32_bf16 v[112:115], v[184:187], v[188:191], v[112:115]
	ds_read_b128 v[188:191], v225 offset:0
	ds_read_b128 v[152:155], v227 offset:0
	s_add_u32 m0, s97, 0x0
	s_add_u32 s12, s98, 0x0
	s_addc_u32 s13, s99, 0
	global_load_lds_dwordx4 v224, s[12:13]
	v_mfma_f32_16x16x32_bf16 v[108:111], v[168:171], v[192:195], v[108:111]
	v_mfma_f32_16x16x32_bf16 v[104:107], v[176:179], v[192:195], v[104:107]
	v_mfma_f32_16x16x32_bf16 v[100:103], v[180:183], v[192:195], v[100:103]
	v_mfma_f32_16x16x32_bf16 v[96:99], v[184:187], v[192:195], v[96:99]
	ds_read_b128 v[192:195], v225 offset:2048
	ds_read_b128 v[156:159], v227 offset:2048
	s_add_u32 m0, s97, 0x10000
	s_add_u32 s12, s100, 0x0
	s_addc_u32 s13, s101, 0
	global_load_lds_dwordx4 v224, s[12:13]
	v_mfma_f32_16x16x32_bf16 v[92:95], v[168:171], v[196:199], v[92:95]
	v_mfma_f32_16x16x32_bf16 v[88:91], v[176:179], v[196:199], v[88:91]
	v_mfma_f32_16x16x32_bf16 v[84:87], v[180:183], v[196:199], v[84:87]
	v_mfma_f32_16x16x32_bf16 v[80:83], v[184:187], v[196:199], v[80:83]
	ds_read_b128 v[196:199], v225 offset:4096
	ds_read_b128 v[160:163], v227 offset:4096
	s_add_u32 m0, s97, 0x2000
	s_add_u32 s12, s98, 0x20000
	s_addc_u32 s13, s99, 0
	global_load_lds_dwordx4 v224, s[12:13]
	v_mfma_f32_16x16x32_bf16 v[76:79], v[168:171], v[200:203], v[76:79]
	v_mfma_f32_16x16x32_bf16 v[72:75], v[176:179], v[200:203], v[72:75]
	v_mfma_f32_16x16x32_bf16 v[68:71], v[180:183], v[200:203], v[68:71]
	v_mfma_f32_16x16x32_bf16 v[64:67], v[184:187], v[200:203], v[64:67]
	ds_read_b128 v[200:203], v225 offset:6144
	ds_read_b128 v[164:167], v227 offset:6144
	s_add_u32 m0, s97, 0x12000
	s_add_u32 s12, s100, 0x20000
	s_addc_u32 s13, s101, 0
	global_load_lds_dwordx4 v224, s[12:13]
	v_mfma_f32_16x16x32_bf16 v[60:63], v[168:171], v[204:207], v[60:63]
	v_mfma_f32_16x16x32_bf16 v[56:59], v[176:179], v[204:207], v[56:59]
	v_mfma_f32_16x16x32_bf16 v[52:55], v[180:183], v[204:207], v[52:55]
	v_mfma_f32_16x16x32_bf16 v[48:51], v[184:187], v[204:207], v[48:51]
	ds_read_b128 v[204:207], v225 offset:8192
	ds_read_b128 v[216:219], v225 offset:14336
	s_add_u32 m0, s97, 0x4000
	s_add_u32 s12, s98, 0x40000
	s_addc_u32 s13, s99, 0
	global_load_lds_dwordx4 v224, s[12:13]
	v_mfma_f32_16x16x32_bf16 v[44:47], v[168:171], v[208:211], v[44:47]
	v_mfma_f32_16x16x32_bf16 v[40:43], v[176:179], v[208:211], v[40:43]
	v_mfma_f32_16x16x32_bf16 v[36:39], v[180:183], v[208:211], v[36:39]
	v_mfma_f32_16x16x32_bf16 v[32:35], v[184:187], v[208:211], v[32:35]
	ds_read_b128 v[208:211], v225 offset:10240
	s_add_u32 m0, s97, 0x14000
	s_add_u32 s12, s100, 0x40000
	s_addc_u32 s13, s101, 0
	global_load_lds_dwordx4 v224, s[12:13]
	v_mfma_f32_16x16x32_bf16 v[28:31], v[168:171], v[212:215], v[28:31]
	v_mfma_f32_16x16x32_bf16 v[24:27], v[176:179], v[212:215], v[24:27]
	v_mfma_f32_16x16x32_bf16 v[20:23], v[180:183], v[212:215], v[20:23]
	v_mfma_f32_16x16x32_bf16 v[16:19], v[184:187], v[212:215], v[16:19]
	ds_read_b128 v[212:215], v225 offset:12288
	s_add_u32 m0, s97, 0x6000
	s_add_u32 s12, s98, 0x60000
	s_addc_u32 s13, s99, 0
	global_load_lds_dwordx4 v224, s[12:13]
	v_mfma_f32_16x16x32_bf16 v[12:15], v[168:171], v[220:223], v[12:15]
	v_mfma_f32_16x16x32_bf16 v[8:11], v[176:179], v[220:223], v[8:11]
	v_mfma_f32_16x16x32_bf16 v[4:7], v[180:183], v[220:223], v[4:7]
	v_mfma_f32_16x16x32_bf16 v[0:3], v[184:187], v[220:223], v[0:3]
	s_add_u32 m0, s97, 0x16000
	s_add_u32 s12, s100, 0x60000
	s_addc_u32 s13, s101, 0
	global_load_lds_dwordx4 v224, s[12:13]
	v_xor_b32_e32 v225, 0x8000, v225
	v_xor_b32_e32 v227, 0x8000, v227
	v_xor_b32_e32 v226, 0x8000, v226
	v_xor_b32_e32 v228, 0x8000, v228
	s_xor_b32 s97, s97, 0x8000
	s_add_u32 s98, s98, 0x80
	s_addc_u32 s99, s99, 0
	s_add_u32 s100, s100, 0x80
	s_addc_u32 s101, s101, 0
	s_sub_u32 s28, s28, 1
	s_cmp_lg_u32 s28, 0
	s_cbranch_scc1 .Lgm0_loop
	s_waitcnt lgkmcnt(4)
	v_mfma_f32_16x16x32_bf16 v[124:127], v[152:155], v[188:191], v[124:127]
	v_mfma_f32_16x16x32_bf16 v[120:123], v[156:159], v[188:191], v[120:123]
	v_mfma_f32_16x16x32_bf16 v[116:119], v[160:163], v[188:191], v[116:119]
	v_mfma_f32_16x16x32_bf16 v[112:115], v[164:167], v[188:191], v[112:115]
	ds_read_b128 v[188:191], v226 offset:0
	ds_read_b128 v[168:171], v228 offset:0
	v_mfma_f32_16x16x32_bf16 v[108:111], v[152:155], v[192:195], v[108:111]
	v_mfma_f32_16x16x32_bf16 v[104:107], v[156:159], v[192:195], v[104:107]
	v_mfma_f32_16x16x32_bf16 v[100:103], v[160:163], v[192:195], v[100:103]
	v_mfma_f32_16x16x32_bf16 v[96:99], v[164:167], v[192:195], v[96:99]
	ds_read_b128 v[192:195], v226 offset:2048
	ds_read_b128 v[176:179], v228 offset:2048
	v_mfma_f32_16x16x32_bf16 v[92:95], v[152:155], v[196:199], v[92:95]
	v_mfma_f32_16x16x32_bf16 v[88:91], v[156:159], v[196:199], v[88:91]
	v_mfma_f32_16x16x32_bf16 v[84:87], v[160:163], v[196:199], v[84:87]
	v_mfma_f32_16x16x32_bf16 v[80:83], v[164:167], v[196:199], v[80:83]
	ds_read_b128 v[196:199], v226 offset:4096
	ds_read_b128 v[180:183], v228 offset:4096
	v_mfma_f32_16x16x32_bf16 v[76:79], v[152:155], v[200:203], v[76:79]
	v_mfma_f32_16x16x32_bf16 v[72:75], v[156:159], v[200:203], v[72:75]
	v_mfma_f32_16x16x32_bf16 v[68:71], v[160:163], v[200:203], v[68:71]
	v_mfma_f32_16x16x32_bf16 v[64:67], v[164:167], v[200:203], v[64:67]
	ds_read_b128 v[200:203], v226 offset:6144
	ds_read_b128 v[184:187], v228 offset:6144
	s_waitcnt lgkmcnt(11)
	v_mfma_f32_16x16x32_bf16 v[60:63], v[152:155], v[204:207], v[60:63]
	v_mfma_f32_16x16x32_bf16 v[56:59], v[156:159], v[204:207], v[56:59]
	v_mfma_f32_16x16x32_bf16 v[52:55], v[160:163], v[204:207], v[52:55]
	v_mfma_f32_16x16x32_bf16 v[48:51], v[164:167], v[204:207], v[48:51]
	ds_read_b128 v[204:207], v226 offset:8192
	ds_read_b128 v[220:223], v226 offset:14336
	s_waitcnt lgkmcnt(11)
	v_mfma_f32_16x16x32_bf16 v[44:47], v[152:155], v[208:211], v[44:47]
	v_mfma_f32_16x16x32_bf16 v[40:43], v[156:159], v[208:211], v[40:43]
	v_mfma_f32_16x16x32_bf16 v[36:39], v[160:163], v[208:211], v[36:39]
	v_mfma_f32_16x16x32_bf16 v[32:35], v[164:167], v[208:211], v[32:35]
	ds_read_b128 v[208:211], v226 offset:10240
	s_waitcnt lgkmcnt(11)
	v_mfma_f32_16x16x32_bf16 v[28:31], v[152:155], v[212:215], v[28:31]
	v_mfma_f32_16x16x32_bf16 v[24:27], v[156:159], v[212:215], v[24:27]
	v_mfma_f32_16x16x32_bf16 v[20:23], v[160:163], v[212:215], v[20:23]
	v_mfma_f32_16x16x32_bf16 v[16:19], v[164:167], v[212:215], v[16:19]
	ds_read_b128 v[212:215], v226 offset:12288
	v_mfma_f32_16x16x32_bf16 v[12:15], v[152:155], v[216:219], v[12:15]
	v_mfma_f32_16x16x32_bf16 v[8:11], v[156:159], v[216:219], v[8:11]
	v_mfma_f32_16x16x32_bf16 v[4:7], v[160:163], v[216:219], v[4:7]
	v_mfma_f32_16x16x32_bf16 v[0:3], v[164:167], v[216:219], v[0:3]
	s_waitcnt vmcnt(0) lgkmcnt(0)
	s_barrier
; #define G_LOAD(KT) do { _Pragma("unroll") for (int i = 0; i < 4; ++i) { ra[i] = *(const u32x4*)(Ag + (size_t)i * 64 * lda + (KT) * 64); rb[i] = *(const u32x4*)(Bg + (size_t)i * 64 * K + (KT) * 64); } } while (0)
; #define G_STORE(BUF) do { u16* ad = As + (BUF) * 256 * 64 + sto; u16* bd = Bs + (BUF) * 256 * 64 + sto; _Pragma("unroll") for (int i = 0; i < 4; ++i) { *(u32x4*)(ad + i * 64 * 64) = ra[i]; *(u32x4*)(bd + i * 64 * 64) = rb[i]; } } while (0)
; template <int EPI>
; DI void gemm_phase(const u16* __restrict__ A, int lda, const u16* __restrict__ Bt, int K, int N, u16* outb, int ldo,
;                    const float* r0, const float* r1, float* outf, char* lds, int bid, int nb) {
;     ...
;     for (int kt = 0; kt < nk; ++kt) {
;       const int cur = kt & 1;
;       if (kt + 1 < nk) G_LOAD(kt + 1);
;       G_MMA(cur, fo0);
;       G_MMA(cur, fo1);
;       if (kt + 1 < nk) G_STORE(cur ^ 1);
;       __syncthreads();
;     }
	v_mfma_f32_16x16x32_bf16 v[124:127], v[168:171], v[188:191], v[124:127]
	v_mfma_f32_16x16x32_bf16 v[120:123], v[176:179], v[188:191], v[120:123]
	v_mfma_f32_16x16x32_bf16 v[116:119], v[180:183], v[188:191], v[116:119]
	v_mfma_f32_16x16x32_bf16 v[112:115], v[184:187], v[188:191], v[112:115]
	ds_read_b128 v[188:191], v225 offset:0
	ds_read_b128 v[152:155], v227 offset:0
	v_mfma_f32_16x16x32_bf16 v[108:111], v[168:171], v[192:195], v[108:111]
	v_mfma_f32_16x16x32_bf16 v[104:107], v[176:179], v[192:195], v[104:107]
	v_mfma_f32_16x16x32_bf16 v[100:103], v[180:183], v[192:195], v[100:103]
	v_mfma_f32_16x16x32_bf16 v[96:99], v[184:187], v[192:195], v[96:99]
	ds_read_b128 v[192:195], v225 offset:2048
	ds_read_b128 v[156:159], v227 offset:2048
	v_mfma_f32_16x16x32_bf16 v[92:95], v[168:171], v[196:199], v[92:95]
	v_mfma_f32_16x16x32_bf16 v[88:91], v[176:179], v[196:199], v[88:91]
	v_mfma_f32_16x16x32_bf16 v[84:87], v[180:183], v[196:199], v[84:87]
	v_mfma_f32_16x16x32_bf16 v[80:83], v[184:187], v[196:199], v[80:83]
	ds_read_b128 v[196:199], v225 offset:4096
	ds_read_b128 v[160:163], v227 offset:4096
	v_mfma_f32_16x16x32_bf16 v[76:79], v[168:171], v[200:203], v[76:79]
	v_mfma_f32_16x16x32_bf16 v[72:75], v[176:179], v[200:203], v[72:75]
	v_mfma_f32_16x16x32_bf16 v[68:71], v[180:183], v[200:203], v[68:71]
	v_mfma_f32_16x16x32_bf16 v[64:67], v[184:187], v[200:203], v[64:67]
	ds_read_b128 v[200:203], v225 offset:6144
	ds_read_b128 v[164:167], v227 offset:6144
	v_mfma_f32_16x16x32_bf16 v[60:63], v[168:171], v[204:207], v[60:63]
	v_mfma_f32_16x16x32_bf16 v[56:59], v[176:179], v[204:207], v[56:59]
	v_mfma_f32_16x16x32_bf16 v[52:55], v[180:183], v[204:207], v[52:55]
	v_mfma_f32_16x16x32_bf16 v[48:51], v[184:187], v[204:207], v[48:51]
	ds_read_b128 v[204:207], v225 offset:8192
	ds_read_b128 v[216:219], v225 offset:14336
	v_mfma_f32_16x16x32_bf16 v[44:47], v[168:171], v[208:211], v[44:47]
	v_mfma_f32_16x16x32_bf16 v[40:43], v[176:179], v[208:211], v[40:43]
	v_mfma_f32_16x16x32_bf16 v[36:39], v[180:183], v[208:211], v[36:39]
	v_mfma_f32_16x16x32_bf16 v[32:35], v[184:187], v[208:211], v[32:35]
	ds_read_b128 v[208:211], v225 offset:10240
	v_mfma_f32_16x16x32_bf16 v[28:31], v[168:171], v[212:215], v[28:31]
	v_mfma_f32_16x16x32_bf16 v[24:27], v[176:179], v[212:215], v[24:27]
	v_mfma_f32_16x16x32_bf16 v[20:23], v[180:183], v[212:215], v[20:23]
	v_mfma_f32_16x16x32_bf16 v[16:19], v[184:187], v[212:215], v[16:19]
	ds_read_b128 v[212:215], v225 offset:12288
	v_mfma_f32_16x16x32_bf16 v[12:15], v[168:171], v[220:223], v[12:15]
	v_mfma_f32_16x16x32_bf16 v[8:11], v[176:179], v[220:223], v[8:11]
	v_mfma_f32_16x16x32_bf16 v[4:7], v[180:183], v[220:223], v[4:7]
	v_mfma_f32_16x16x32_bf16 v[0:3], v[184:187], v[220:223], v[0:3]
	v_xor_b32_e32 v226, 0x8000, v226
	v_xor_b32_e32 v228, 0x8000, v228
	s_waitcnt lgkmcnt(4)
	v_mfma_f32_16x16x32_bf16 v[124:127], v[152:155], v[188:191], v[124:127]
	v_mfma_f32_16x16x32_bf16 v[120:123], v[156:159], v[188:191], v[120:123]
	v_mfma_f32_16x16x32_bf16 v[116:119], v[160:163], v[188:191], v[116:119]
	v_mfma_f32_16x16x32_bf16 v[112:115], v[164:167], v[188:191], v[112:115]
	ds_read_b128 v[188:191], v226 offset:0
	ds_read_b128 v[168:171], v228 offset:0
	v_mfma_f32_16x16x32_bf16 v[108:111], v[152:155], v[192:195], v[108:111]
	v_mfma_f32_16x16x32_bf16 v[104:107], v[156:159], v[192:195], v[104:107]
	v_mfma_f32_16x16x32_bf16 v[100:103], v[160:163], v[192:195], v[100:103]
	v_mfma_f32_16x16x32_bf16 v[96:99], v[164:167], v[192:195], v[96:99]
	ds_read_b128 v[192:195], v226 offset:2048
	ds_read_b128 v[176:179], v228 offset:2048
	v_mfma_f32_16x16x32_bf16 v[92:95], v[152:155], v[196:199], v[92:95]
	v_mfma_f32_16x16x32_bf16 v[88:91], v[156:159], v[196:199], v[88:91]
	v_mfma_f32_16x16x32_bf16 v[84:87], v[160:163], v[196:199], v[84:87]
	v_mfma_f32_16x16x32_bf16 v[80:83], v[164:167], v[196:199], v[80:83]
	ds_read_b128 v[196:199], v226 offset:4096
	ds_read_b128 v[180:183], v228 offset:4096
	v_mfma_f32_16x16x32_bf16 v[76:79], v[152:155], v[200:203], v[76:79]
	v_mfma_f32_16x16x32_bf16 v[72:75], v[156:159], v[200:203], v[72:75]
	v_mfma_f32_16x16x32_bf16 v[68:71], v[160:163], v[200:203], v[68:71]
	v_mfma_f32_16x16x32_bf16 v[64:67], v[164:167], v[200:203], v[64:67]
	ds_read_b128 v[200:203], v226 offset:6144
	ds_read_b128 v[184:187], v228 offset:6144
	s_waitcnt lgkmcnt(11)
	v_mfma_f32_16x16x32_bf16 v[60:63], v[152:155], v[204:207], v[60:63]
	v_mfma_f32_16x16x32_bf16 v[56:59], v[156:159], v[204:207], v[56:59]
	v_mfma_f32_16x16x32_bf16 v[52:55], v[160:163], v[204:207], v[52:55]
	v_mfma_f32_16x16x32_bf16 v[48:51], v[164:167], v[204:207], v[48:51]
	ds_read_b128 v[204:207], v226 offset:8192
	ds_read_b128 v[220:223], v226 offset:14336
	s_waitcnt lgkmcnt(11)
	v_mfma_f32_16x16x32_bf16 v[44:47], v[152:155], v[208:211], v[44:47]
	v_mfma_f32_16x16x32_bf16 v[40:43], v[156:159], v[208:211], v[40:43]
	v_mfma_f32_16x16x32_bf16 v[36:39], v[160:163], v[208:211], v[36:39]
	v_mfma_f32_16x16x32_bf16 v[32:35], v[164:167], v[208:211], v[32:35]
	ds_read_b128 v[208:211], v226 offset:10240
	s_waitcnt lgkmcnt(11)
	v_mfma_f32_16x16x32_bf16 v[28:31], v[152:155], v[212:215], v[28:31]
	v_mfma_f32_16x16x32_bf16 v[24:27], v[156:159], v[212:215], v[24:27]
	v_mfma_f32_16x16x32_bf16 v[20:23], v[160:163], v[212:215], v[20:23]
	v_mfma_f32_16x16x32_bf16 v[16:19], v[164:167], v[212:215], v[16:19]
	ds_read_b128 v[212:215], v226 offset:12288
	v_mfma_f32_16x16x32_bf16 v[12:15], v[152:155], v[216:219], v[12:15]
	v_mfma_f32_16x16x32_bf16 v[8:11], v[156:159], v[216:219], v[8:11]
	v_mfma_f32_16x16x32_bf16 v[4:7], v[160:163], v[216:219], v[4:7]
	v_mfma_f32_16x16x32_bf16 v[0:3], v[164:167], v[216:219], v[0:3]
	s_waitcnt vmcnt(0) lgkmcnt(0)
	s_barrier
; DI u16 f2bf(float a) { return (u16)(pk2(a, 0.f) & 0xffffu); }
; template <int EPI>
; DI void gemm_phase(const u16* __restrict__ A, int lda, const u16* __restrict__ Bt, int K, int N, u16* outb, int ldo,
;                    const float* r0, const float* r1, float* outf, char* lds, int bid, int nb) {
;     ...
;     const int mrow = tm * 256 + wr * 128 + quad * 4;
;     if constexpr (EPI == EPI_BF16) {
;       const int col = tn * 256 + wc * 64 + l15;
; #pragma unroll
;       for (int i = 0; i < 8; ++i)
; #pragma unroll
;         for (int r = 0; r < 4; ++r) {
;           u16* o0 = outb + (size_t)(mrow + i * 16 + r) * ldo + col;
;           o0[0] = f2bf(acc[i][0][r]); o0[16] = f2bf(acc[i][1][r]); o0[32] = f2bf(acc[i][2][r]); o0[48] = f2bf(acc[i][3][r]);
;         }
	v_mfma_f32_16x16x32_bf16 v[124:127], v[168:171], v[188:191], v[124:127]
	v_mfma_f32_16x16x32_bf16 v[120:123], v[176:179], v[188:191], v[120:123]
	v_mfma_f32_16x16x32_bf16 v[116:119], v[180:183], v[188:191], v[116:119]
	v_mfma_f32_16x16x32_bf16 v[112:115], v[184:187], v[188:191], v[112:115]
	v_mfma_f32_16x16x32_bf16 v[108:111], v[168:171], v[192:195], v[108:111]
	v_mfma_f32_16x16x32_bf16 v[104:107], v[176:179], v[192:195], v[104:107]
	v_mfma_f32_16x16x32_bf16 v[100:103], v[180:183], v[192:195], v[100:103]
	v_mfma_f32_16x16x32_bf16 v[96:99], v[184:187], v[192:195], v[96:99]
	v_mfma_f32_16x16x32_bf16 v[92:95], v[168:171], v[196:199], v[92:95]
	v_mfma_f32_16x16x32_bf16 v[88:91], v[176:179], v[196:199], v[88:91]
	v_mfma_f32_16x16x32_bf16 v[84:87], v[180:183], v[196:199], v[84:87]
	v_mfma_f32_16x16x32_bf16 v[80:83], v[184:187], v[196:199], v[80:83]
	v_mfma_f32_16x16x32_bf16 v[76:79], v[168:171], v[200:203], v[76:79]
	v_mfma_f32_16x16x32_bf16 v[72:75], v[176:179], v[200:203], v[72:75]
	v_mfma_f32_16x16x32_bf16 v[68:71], v[180:183], v[200:203], v[68:71]
	v_mfma_f32_16x16x32_bf16 v[64:67], v[184:187], v[200:203], v[64:67]
	v_mfma_f32_16x16x32_bf16 v[60:63], v[168:171], v[204:207], v[60:63]
	v_mfma_f32_16x16x32_bf16 v[56:59], v[176:179], v[204:207], v[56:59]
	v_mfma_f32_16x16x32_bf16 v[52:55], v[180:183], v[204:207], v[52:55]
	v_mfma_f32_16x16x32_bf16 v[48:51], v[184:187], v[204:207], v[48:51]
	v_mfma_f32_16x16x32_bf16 v[44:47], v[168:171], v[208:211], v[44:47]
	v_mfma_f32_16x16x32_bf16 v[40:43], v[176:179], v[208:211], v[40:43]
	v_mfma_f32_16x16x32_bf16 v[36:39], v[180:183], v[208:211], v[36:39]
	v_mfma_f32_16x16x32_bf16 v[32:35], v[184:187], v[208:211], v[32:35]
	v_mfma_f32_16x16x32_bf16 v[28:31], v[168:171], v[212:215], v[28:31]
	v_mfma_f32_16x16x32_bf16 v[24:27], v[176:179], v[212:215], v[24:27]
	v_mfma_f32_16x16x32_bf16 v[20:23], v[180:183], v[212:215], v[20:23]
	v_mfma_f32_16x16x32_bf16 v[16:19], v[184:187], v[212:215], v[16:19]
	v_mfma_f32_16x16x32_bf16 v[12:15], v[168:171], v[220:223], v[12:15]
	v_mfma_f32_16x16x32_bf16 v[8:11], v[176:179], v[220:223], v[8:11]
	v_mfma_f32_16x16x32_bf16 v[4:7], v[180:183], v[220:223], v[4:7]
	v_mfma_f32_16x16x32_bf16 v[0:3], v[184:187], v[220:223], v[0:3]
	s_nop 7
	s_nop 3
	v_and_b32_e32 v225, 15, v174
	v_lshrrev_b32_e32 v226, 8, v174
	v_lshl_or_b32 v225, v226, 7, v225
	v_bfe_u32 v226, v174, 6, 2
	v_bfe_u32 v227, v174, 4, 2
	v_lshlrev_b32_e32 v227, 2, v227
	v_add_u32_e32 v225, s56, v225
	v_lshl_add_u32 v226, v226, 6, v227
	v_add_u32_e32 v226, s57, v226
	v_lshlrev_b32_e32 v226, 1, v226
	v_mov_b32_e32 v227, 0x1400
	v_mad_u32_u24 v224, v225, v227, v226
	v_cvt_pk_bf16_f32 v188, v124, v125
	v_cvt_pk_bf16_f32 v189, v126, v127
	global_store_dwordx2 v224, v[188:189], s[8:9] offset:0
	v_cvt_pk_bf16_f32 v190, v120, v121
	v_cvt_pk_bf16_f32 v191, v122, v123
	global_store_dwordx2 v224, v[190:191], s[8:9] offset:32
	v_cvt_pk_bf16_f32 v192, v116, v117
	v_cvt_pk_bf16_f32 v193, v118, v119
	global_store_dwordx2 v224, v[192:193], s[8:9] offset:64
	v_cvt_pk_bf16_f32 v194, v112, v113
	v_cvt_pk_bf16_f32 v195, v114, v115
	global_store_dwordx2 v224, v[194:195], s[8:9] offset:96
	v_add_u32_e32 v224, 0x14000, v224
	v_cvt_pk_bf16_f32 v196, v108, v109
	v_cvt_pk_bf16_f32 v197, v110, v111
	global_store_dwordx2 v224, v[196:197], s[8:9] offset:0
	v_cvt_pk_bf16_f32 v198, v104, v105
	v_cvt_pk_bf16_f32 v199, v106, v107
	global_store_dwordx2 v224, v[198:199], s[8:9] offset:32
	v_cvt_pk_bf16_f32 v200, v100, v101
	v_cvt_pk_bf16_f32 v201, v102, v103
	global_store_dwordx2 v224, v[200:201], s[8:9] offset:64
	v_cvt_pk_bf16_f32 v202, v96, v97
	v_cvt_pk_bf16_f32 v203, v98, v99
	global_store_dwordx2 v224, v[202:203], s[8:9] offset:96
	v_add_u32_e32 v224, 0x14000, v224
	v_cvt_pk_bf16_f32 v204, v92, v93
	v_cvt_pk_bf16_f32 v205, v94, v95
	global_store_dwordx2 v224, v[204:205], s[8:9] offset:0
	v_cvt_pk_bf16_f32 v206, v88, v89
	v_cvt_pk_bf16_f32 v207, v90, v91
	global_store_dwordx2 v224, v[206:207], s[8:9] offset:32
	v_cvt_pk_bf16_f32 v208, v84, v85
	v_cvt_pk_bf16_f32 v209, v86, v87
	global_store_dwordx2 v224, v[208:209], s[8:9] offset:64
	v_cvt_pk_bf16_f32 v210, v80, v81
	v_cvt_pk_bf16_f32 v211, v82, v83
	global_store_dwordx2 v224, v[210:211], s[8:9] offset:96
	v_add_u32_e32 v224, 0x14000, v224
	v_cvt_pk_bf16_f32 v212, v76, v77
	v_cvt_pk_bf16_f32 v213, v78, v79
	global_store_dwordx2 v224, v[212:213], s[8:9] offset:0
	v_cvt_pk_bf16_f32 v214, v72, v73
	v_cvt_pk_bf16_f32 v215, v74, v75
	global_store_dwordx2 v224, v[214:215], s[8:9] offset:32
	v_cvt_pk_bf16_f32 v216, v68, v69
	v_cvt_pk_bf16_f32 v217, v70, v71
	global_store_dwordx2 v224, v[216:217], s[8:9] offset:64
	v_cvt_pk_bf16_f32 v218, v64, v65
	v_cvt_pk_bf16_f32 v219, v66, v67
	global_store_dwordx2 v224, v[218:219], s[8:9] offset:96
	v_add_u32_e32 v224, 0x14000, v224
	v_cvt_pk_bf16_f32 v188, v60, v61
	v_cvt_pk_bf16_f32 v189, v62, v63
	global_store_dwordx2 v224, v[188:189], s[8:9] offset:0
	v_cvt_pk_bf16_f32 v190, v56, v57
	v_cvt_pk_bf16_f32 v191, v58, v59
	global_store_dwordx2 v224, v[190:191], s[8:9] offset:32
	v_cvt_pk_bf16_f32 v192, v52, v53
	v_cvt_pk_bf16_f32 v193, v54, v55
	global_store_dwordx2 v224, v[192:193], s[8:9] offset:64
	v_cvt_pk_bf16_f32 v194, v48, v49
	v_cvt_pk_bf16_f32 v195, v50, v51
	global_store_dwordx2 v224, v[194:195], s[8:9] offset:96
	v_add_u32_e32 v224, 0x14000, v224
	v_cvt_pk_bf16_f32 v196, v44, v45
	v_cvt_pk_bf16_f32 v197, v46, v47
	global_store_dwordx2 v224, v[196:197], s[8:9] offset:0
	v_cvt_pk_bf16_f32 v198, v40, v41
	v_cvt_pk_bf16_f32 v199, v42, v43
	global_store_dwordx2 v224, v[198:199], s[8:9] offset:32
	v_cvt_pk_bf16_f32 v200, v36, v37
	v_cvt_pk_bf16_f32 v201, v38, v39
	global_store_dwordx2 v224, v[200:201], s[8:9] offset:64
	v_cvt_pk_bf16_f32 v202, v32, v33
	v_cvt_pk_bf16_f32 v203, v34, v35
	global_store_dwordx2 v224, v[202:203], s[8:9] offset:96
	v_add_u32_e32 v224, 0x14000, v224
	v_cvt_pk_bf16_f32 v204, v28, v29
	v_cvt_pk_bf16_f32 v205, v30, v31
	global_store_dwordx2 v224, v[204:205], s[8:9] offset:0
	v_cvt_pk_bf16_f32 v206, v24, v25
	v_cvt_pk_bf16_f32 v207, v26, v27
	global_store_dwordx2 v224, v[206:207], s[8:9] offset:32
	v_cvt_pk_bf16_f32 v208, v20, v21
	v_cvt_pk_bf16_f32 v209, v22, v23
	global_store_dwordx2 v224, v[208:209], s[8:9] offset:64
	v_cvt_pk_bf16_f32 v210, v16, v17
	v_cvt_pk_bf16_f32 v211, v18, v19
	global_store_dwordx2 v224, v[210:211], s[8:9] offset:96
	v_add_u32_e32 v224, 0x14000, v224
	v_cvt_pk_bf16_f32 v212, v12, v13
	v_cvt_pk_bf16_f32 v213, v14, v15
	global_store_dwordx2 v224, v[212:213], s[8:9] offset:0
	v_cvt_pk_bf16_f32 v214, v8, v9
	v_cvt_pk_bf16_f32 v215, v10, v11
	global_store_dwordx2 v224, v[214:215], s[8:9] offset:32
	v_cvt_pk_bf16_f32 v216, v4, v5
	v_cvt_pk_bf16_f32 v217, v6, v7
	global_store_dwordx2 v224, v[216:217], s[8:9] offset:64
	v_cvt_pk_bf16_f32 v218, v0, v1
	v_cvt_pk_bf16_f32 v219, v2, v3
	global_store_dwordx2 v224, v[218:219], s[8:9] offset:96
	s_add_i32 s18, s18, 1
	s_cmp_eq_u32 s18, s14
	s_cbranch_scc0 .LBB0_283

; #define G_LOAD(KT) do { _Pragma("unroll") for (int i = 0; i < 4; ++i) { ra[i] = *(const u32x4*)(Ag + (size_t)i * 64 * lda + (KT) * 64); rb[i] = *(const u32x4*)(Bg + (size_t)i * 64 * K + (KT) * 64); } } while (0)
; #define G_STORE(BUF) do { u16* ad = As + (BUF) * 256 * 64 + sto; u16* bd = Bs + (BUF) * 256 * 64 + sto; _Pragma("unroll") for (int i = 0; i < 4; ++i) { *(u32x4*)(ad + i * 64 * 64) = ra[i]; *(u32x4*)(bd + i * 64 * 64) = rb[i]; } } while (0)
; template <int EPI>
; DI void gemm_phase(const u16* __restrict__ A, int lda, const u16* __restrict__ Bt, int K, int N, u16* outb, int ldo,
;                    const float* r0, const float* r1, float* outf, char* lds, int bid, int nb) {
;     ...
;   for (int it = 0; it < nIter; ++it) {
;     int tm, tn;
;     if (swz) { const int st = xcd + 8 * it, sm = st / nSN, sn = st - sm * nSN; tm = sm * GM + jb / GN; tn = sn * GN + (jb % GN); }
;     else { const int t = bid + it * nb; tm = t / nN; tn = t - tm * nN; }
;     const u16* Ag = A + (size_t)(tm * 256 + lrow) * lda + lch * 8;
;     const u16* Bg = Bt + (size_t)(tn * 256 + lrow) * K + lch * 8;
;     f32x4 acc[8][4];
; #pragma unroll
;     for (int i = 0; i < 8; ++i)
; #pragma unroll
;       for (int j = 0; j < 4; ++j) acc[i][j] = (f32x4){0.f, 0.f, 0.f, 0.f};
;     u32x4 ra[4], rb[4];
;     ...
;     G_LOAD(0);
;     G_STORE(0);
;     __syncthreads();
.LBB0_581:
	s_lshl_b32 s52, s51, 8
	v_or_b32_e32 v0, s52, v138
	v_ashrrev_i32_e32 v1, 31, v0
	s_lshl_b32 s53, s53, 8
	v_or_b32_e32 v2, s53, v138
	v_lshlrev_b64 v[62:63], 11, v[0:1]
	v_ashrrev_i32_e32 v3, 31, v2
	v_lshl_add_u64 v[0:1], v[128:129], 0, v[62:63]
	v_lshlrev_b64 v[64:65], 11, v[2:3]
	v_add_co_u32_e32 v4, vcc, s19, v0
	v_lshl_add_u64 v[2:3], v[130:131], 0, v[64:65]
	s_nop 0
	v_addc_co_u32_e32 v5, vcc, 0, v1, vcc
	v_add_co_u32_e32 v6, vcc, s19, v2
	s_nop 1
	v_readfirstlane_b32 s98, v0
	v_readfirstlane_b32 s99, v1
	s_nop 1
	v_readfirstlane_b32 s100, v2
	v_readfirstlane_b32 s101, v3
	v_addc_co_u32_e32 v7, vcc, 0, v3, vcc
	v_add_co_u32_e32 v4, vcc, s20, v0
	s_mov_b32 s54, 0
	s_nop 0
	v_addc_co_u32_e32 v5, vcc, 0, v1, vcc
	v_add_co_u32_e32 v6, vcc, s20, v2
	s_mov_b64 s[8:9], 0
	s_nop 0
	v_addc_co_u32_e32 v7, vcc, 0, v3, vcc
	v_add_co_u32_e32 v0, vcc, s21, v0
	v_addc_co_u32_e32 v1, vcc, 0, v1, vcc
	v_add_co_u32_e32 v2, vcc, s21, v2
	v_lshl_add_u64 v[134:135], v[132:133], 0, v[62:63]
	s_nop 0
	v_addc_co_u32_e32 v3, vcc, 0, v3, vcc
	v_mov_b32_e32 v0, 0
	v_lshl_add_u64 v[136:137], v[132:133], 0, v[64:65]
	v_and_b32_e32 v229, 63, v174
	v_lshrrev_b32_e32 v230, 3, v229
	v_mov_b32_e32 v233, 0x800
	v_mul_u32_u24_e32 v224, v230, v233
	v_bfe_u32 v231, v174, 4, 2
	v_bfe_u32 v232, v174, 6, 1
	v_lshl_or_b32 v232, v232, 2, v231
	v_and_b32_e32 v233, 7, v174
	v_xor_b32_e32 v232, v232, v233
	v_lshl_add_u32 v224, v232, 4, v224
	v_and_b32_e32 v229, 15, v174
	v_bfe_u32 v230, v174, 1, 3
	v_xor_b32_e32 v230, v230, v231
	v_lshlrev_b32_e32 v230, 4, v230
	v_lshl_or_b32 v230, v229, 7, v230
	v_lshrrev_b32_e32 v229, 8, v174
	v_lshl_or_b32 v225, v229, 14, v230
	v_bfe_u32 v229, v174, 6, 2
	v_lshl_or_b32 v227, v229, 13, v230
	v_or_b32_e32 v227, 0x10000, v227
	v_xor_b32_e32 v226, 64, v225
	v_xor_b32_e32 v228, 64, v227
	v_readfirstlane_b32 s97, v174
	s_lshl_b32 s97, s97, 4
	s_mov_b32 s28, 14
	s_add_u32 m0, s97, 0x0
	s_add_u32 s8, s98, 0x0
	s_addc_u32 s9, s99, 0
	global_load_lds_dwordx4 v224, s[8:9]
	s_add_u32 m0, s97, 0x10000
	s_add_u32 s8, s100, 0x0
	s_addc_u32 s9, s101, 0
	global_load_lds_dwordx4 v224, s[8:9]
	s_add_u32 m0, s97, 0x2000
	s_add_u32 s8, s98, 0x20000
	s_addc_u32 s9, s99, 0
	global_load_lds_dwordx4 v224, s[8:9]
	s_add_u32 m0, s97, 0x12000
	s_add_u32 s8, s100, 0x20000
	s_addc_u32 s9, s101, 0
	global_load_lds_dwordx4 v224, s[8:9]
	s_add_u32 m0, s97, 0x4000
	s_add_u32 s8, s98, 0x40000
	s_addc_u32 s9, s99, 0
	global_load_lds_dwordx4 v224, s[8:9]
	s_add_u32 m0, s97, 0x14000
	s_add_u32 s8, s100, 0x40000
	s_addc_u32 s9, s101, 0
	global_load_lds_dwordx4 v224, s[8:9]
	s_add_u32 m0, s97, 0x6000
	s_add_u32 s8, s98, 0x60000
	s_addc_u32 s9, s99, 0
	global_load_lds_dwordx4 v224, s[8:9]
	s_add_u32 m0, s97, 0x16000
	s_add_u32 s8, s100, 0x60000
	s_addc_u32 s9, s101, 0
	global_load_lds_dwordx4 v224, s[8:9]
	s_add_u32 m0, s97, 0x8000
	s_add_u32 s8, s98, 0x80
	s_addc_u32 s9, s99, 0
	global_load_lds_dwordx4 v224, s[8:9]
	s_add_u32 m0, s97, 0x18000
	s_add_u32 s8, s100, 0x80
	s_addc_u32 s9, s101, 0
	global_load_lds_dwordx4 v224, s[8:9]
	s_add_u32 m0, s97, 0xa000
	s_add_u32 s8, s98, 0x20080
	s_addc_u32 s9, s99, 0
	global_load_lds_dwordx4 v224, s[8:9]
	s_add_u32 m0, s97, 0x1a000
	s_add_u32 s8, s100, 0x20080
	s_addc_u32 s9, s101, 0
	global_load_lds_dwordx4 v224, s[8:9]
	s_add_u32 m0, s97, 0xc000
	s_add_u32 s8, s98, 0x40080
	s_addc_u32 s9, s99, 0
	global_load_lds_dwordx4 v224, s[8:9]
	s_add_u32 m0, s97, 0x1c000
	s_add_u32 s8, s100, 0x40080
	s_addc_u32 s9, s101, 0
	global_load_lds_dwordx4 v224, s[8:9]
	s_add_u32 m0, s97, 0xe000
	s_add_u32 s8, s98, 0x60080
	s_addc_u32 s9, s99, 0
	global_load_lds_dwordx4 v224, s[8:9]
	s_add_u32 m0, s97, 0x1e000
	s_add_u32 s8, s100, 0x60080
	s_addc_u32 s9, s101, 0
	global_load_lds_dwordx4 v224, s[8:9]
	s_add_u32 s98, s98, 0x100
	s_addc_u32 s99, s99, 0
	s_add_u32 s100, s100, 0x100
	s_addc_u32 s101, s101, 0
	s_waitcnt vmcnt(8)
	s_barrier
; #define G_LOAD(KT) do { _Pragma("unroll") for (int i = 0; i < 4; ++i) { ra[i] = *(const u32x4*)(Ag + (size_t)i * 64 * lda + (KT) * 64); rb[i] = *(const u32x4*)(Bg + (size_t)i * 64 * K + (KT) * 64); } } while (0)
; #define G_STORE(BUF) do { u16* ad = As + (BUF) * 256 * 64 + sto; u16* bd = Bs + (BUF) * 256 * 64 + sto; _Pragma("unroll") for (int i = 0; i < 4; ++i) { *(u32x4*)(ad + i * 64 * 64) = ra[i]; *(u32x4*)(bd + i * 64 * 64) = rb[i]; } } while (0)
; template <int EPI>
; DI void gemm_phase(const u16* __restrict__ A, int lda, const u16* __restrict__ Bt, int K, int N, u16* outb, int ldo,
;                    const float* r0, const float* r1, float* outf, char* lds, int bid, int nb) {
;     ...
;     G_LOAD(0);
;     G_STORE(0);
;     __syncthreads();
;     for (int kt = 0; kt < nk; ++kt) {
;       const int cur = kt & 1;
;       if (kt + 1 < nk) G_LOAD(kt + 1);
;       G_MMA(cur, fo0);
;       G_MMA(cur, fo1);
	ds_read_b128 v[152:155], v227 offset:0
	ds_read_b128 v[156:159], v227 offset:2048
	ds_read_b128 v[160:163], v227 offset:4096
	ds_read_b128 v[164:167], v227 offset:6144
	ds_read_b128 v[188:191], v225 offset:0
	ds_read_b128 v[192:195], v225 offset:2048
	ds_read_b128 v[196:199], v225 offset:4096
	ds_read_b128 v[200:203], v225 offset:6144
	ds_read_b128 v[204:207], v225 offset:8192
	ds_read_b128 v[208:211], v225 offset:10240
	ds_read_b128 v[212:215], v225 offset:12288
	ds_read_b128 v[216:219], v225 offset:14336
	v_xor_b32_e32 v225, 0x8000, v225
	v_xor_b32_e32 v227, 0x8000, v227
	s_waitcnt lgkmcnt(0)
	s_waitcnt lgkmcnt(4)
	v_mfma_f32_16x16x32_bf16 v[124:127], v[152:155], v[188:191], 0
	v_mfma_f32_16x16x32_bf16 v[120:123], v[156:159], v[188:191], 0
	v_mfma_f32_16x16x32_bf16 v[116:119], v[160:163], v[188:191], 0
	v_mfma_f32_16x16x32_bf16 v[112:115], v[164:167], v[188:191], 0
	ds_read_b128 v[188:191], v226 offset:0
	ds_read_b128 v[168:171], v228 offset:0
	v_mfma_f32_16x16x32_bf16 v[108:111], v[152:155], v[192:195], 0
	v_mfma_f32_16x16x32_bf16 v[104:107], v[156:159], v[192:195], 0
	v_mfma_f32_16x16x32_bf16 v[100:103], v[160:163], v[192:195], 0
	v_mfma_f32_16x16x32_bf16 v[96:99], v[164:167], v[192:195], 0
	ds_read_b128 v[192:195], v226 offset:2048
	ds_read_b128 v[176:179], v228 offset:2048
	v_mfma_f32_16x16x32_bf16 v[92:95], v[152:155], v[196:199], 0
	v_mfma_f32_16x16x32_bf16 v[88:91], v[156:159], v[196:199], 0
	v_mfma_f32_16x16x32_bf16 v[84:87], v[160:163], v[196:199], 0
	v_mfma_f32_16x16x32_bf16 v[80:83], v[164:167], v[196:199], 0
	ds_read_b128 v[196:199], v226 offset:4096
	ds_read_b128 v[180:183], v228 offset:4096
	v_mfma_f32_16x16x32_bf16 v[76:79], v[152:155], v[200:203], 0
	v_mfma_f32_16x16x32_bf16 v[72:75], v[156:159], v[200:203], 0
	v_mfma_f32_16x16x32_bf16 v[68:71], v[160:163], v[200:203], 0
	v_mfma_f32_16x16x32_bf16 v[64:67], v[164:167], v[200:203], 0
	ds_read_b128 v[200:203], v226 offset:6144
	ds_read_b128 v[184:187], v228 offset:6144
	s_waitcnt lgkmcnt(11)
	v_mfma_f32_16x16x32_bf16 v[60:63], v[152:155], v[204:207], 0
	v_mfma_f32_16x16x32_bf16 v[56:59], v[156:159], v[204:207], 0
	v_mfma_f32_16x16x32_bf16 v[52:55], v[160:163], v[204:207], 0
	v_mfma_f32_16x16x32_bf16 v[48:51], v[164:167], v[204:207], 0
	ds_read_b128 v[204:207], v226 offset:8192
	ds_read_b128 v[220:223], v226 offset:14336
	s_waitcnt lgkmcnt(11)
	v_mfma_f32_16x16x32_bf16 v[44:47], v[152:155], v[208:211], 0
	v_mfma_f32_16x16x32_bf16 v[40:43], v[156:159], v[208:211], 0
	v_mfma_f32_16x16x32_bf16 v[36:39], v[160:163], v[208:211], 0
	v_mfma_f32_16x16x32_bf16 v[32:35], v[164:167], v[208:211], 0
	ds_read_b128 v[208:211], v226 offset:10240
	s_waitcnt lgkmcnt(11)
	v_mfma_f32_16x16x32_bf16 v[28:31], v[152:155], v[212:215], 0
	v_mfma_f32_16x16x32_bf16 v[24:27], v[156:159], v[212:215], 0
	v_mfma_f32_16x16x32_bf16 v[20:23], v[160:163], v[212:215], 0
	v_mfma_f32_16x16x32_bf16 v[16:19], v[164:167], v[212:215], 0
	ds_read_b128 v[212:215], v226 offset:12288
	v_mfma_f32_16x16x32_bf16 v[12:15], v[152:155], v[216:219], 0
	v_mfma_f32_16x16x32_bf16 v[8:11], v[156:159], v[216:219], 0
	v_mfma_f32_16x16x32_bf16 v[4:7], v[160:163], v[216:219], 0
	v_mfma_f32_16x16x32_bf16 v[0:3], v[164:167], v[216:219], 0
	s_branch .Lgm1_mid0

; #define G_LOAD(KT) do { _Pragma("unroll") for (int i = 0; i < 4; ++i) { ra[i] = *(const u32x4*)(Ag + (size_t)i * 64 * lda + (KT) * 64); rb[i] = *(const u32x4*)(Bg + (size_t)i * 64 * K + (KT) * 64); } } while (0)
; #define G_STORE(BUF) do { u16* ad = As + (BUF) * 256 * 64 + sto; u16* bd = Bs + (BUF) * 256 * 64 + sto; _Pragma("unroll") for (int i = 0; i < 4; ++i) { *(u32x4*)(ad + i * 64 * 64) = ra[i]; *(u32x4*)(bd + i * 64 * 64) = rb[i]; } } while (0)
; template <int EPI>
; DI void gemm_phase(const u16* __restrict__ A, int lda, const u16* __restrict__ Bt, int K, int N, u16* outb, int ldo,
;                    const float* r0, const float* r1, float* outf, char* lds, int bid, int nb) {
;     ...
;     for (int kt = 0; kt < nk; ++kt) {
;       const int cur = kt & 1;
;       if (kt + 1 < nk) G_LOAD(kt + 1);
;       G_MMA(cur, fo0);
;       G_MMA(cur, fo1);
;       if (kt + 1 < nk) G_STORE(cur ^ 1);
;       __syncthreads();
.Lgm1_mid0:
	s_waitcnt vmcnt(0) lgkmcnt(0)
	s_barrier
	v_mfma_f32_16x16x32_bf16 v[124:127], v[168:171], v[188:191], v[124:127]
	v_mfma_f32_16x16x32_bf16 v[120:123], v[176:179], v[188:191], v[120:123]
	v_mfma_f32_16x16x32_bf16 v[116:119], v[180:183], v[188:191], v[116:119]
	v_mfma_f32_16x16x32_bf16 v[112:115], v[184:187], v[188:191], v[112:115]
	ds_read_b128 v[188:191], v225 offset:0
	ds_read_b128 v[152:155], v227 offset:0
	s_add_u32 m0, s97, 0x0
	s_add_u32 s8, s98, 0x0
	s_addc_u32 s9, s99, 0
	global_load_lds_dwordx4 v224, s[8:9]
	v_mfma_f32_16x16x32_bf16 v[108:111], v[168:171], v[192:195], v[108:111]
	v_mfma_f32_16x16x32_bf16 v[104:107], v[176:179], v[192:195], v[104:107]
	v_mfma_f32_16x16x32_bf16 v[100:103], v[180:183], v[192:195], v[100:103]
	v_mfma_f32_16x16x32_bf16 v[96:99], v[184:187], v[192:195], v[96:99]
	ds_read_b128 v[192:195], v225 offset:2048
	ds_read_b128 v[156:159], v227 offset:2048
	s_add_u32 m0, s97, 0x10000
	s_add_u32 s8, s100, 0x0
	s_addc_u32 s9, s101, 0
	global_load_lds_dwordx4 v224, s[8:9]
	v_mfma_f32_16x16x32_bf16 v[92:95], v[168:171], v[196:199], v[92:95]
	v_mfma_f32_16x16x32_bf16 v[88:91], v[176:179], v[196:199], v[88:91]
	v_mfma_f32_16x16x32_bf16 v[84:87], v[180:183], v[196:199], v[84:87]
	v_mfma_f32_16x16x32_bf16 v[80:83], v[184:187], v[196:199], v[80:83]
	ds_read_b128 v[196:199], v225 offset:4096
	ds_read_b128 v[160:163], v227 offset:4096
	s_add_u32 m0, s97, 0x2000
	s_add_u32 s8, s98, 0x20000
	s_addc_u32 s9, s99, 0
	global_load_lds_dwordx4 v224, s[8:9]
	v_mfma_f32_16x16x32_bf16 v[76:79], v[168:171], v[200:203], v[76:79]
	v_mfma_f32_16x16x32_bf16 v[72:75], v[176:179], v[200:203], v[72:75]
	v_mfma_f32_16x16x32_bf16 v[68:71], v[180:183], v[200:203], v[68:71]
	v_mfma_f32_16x16x32_bf16 v[64:67], v[184:187], v[200:203], v[64:67]
	ds_read_b128 v[200:203], v225 offset:6144
	ds_read_b128 v[164:167], v227 offset:6144
	s_add_u32 m0, s97, 0x12000
	s_add_u32 s8, s100, 0x20000
	s_addc_u32 s9, s101, 0
	global_load_lds_dwordx4 v224, s[8:9]
	v_mfma_f32_16x16x32_bf16 v[60:63], v[168:171], v[204:207], v[60:63]
	v_mfma_f32_16x16x32_bf16 v[56:59], v[176:179], v[204:207], v[56:59]
	v_mfma_f32_16x16x32_bf16 v[52:55], v[180:183], v[204:207], v[52:55]
	v_mfma_f32_16x16x32_bf16 v[48:51], v[184:187], v[204:207], v[48:51]
	ds_read_b128 v[204:207], v225 offset:8192
	ds_read_b128 v[216:219], v225 offset:14336
	s_add_u32 m0, s97, 0x4000
	s_add_u32 s8, s98, 0x40000
	s_addc_u32 s9, s99, 0
	global_load_lds_dwordx4 v224, s[8:9]
	v_mfma_f32_16x16x32_bf16 v[44:47], v[168:171], v[208:211], v[44:47]
	v_mfma_f32_16x16x32_bf16 v[40:43], v[176:179], v[208:211], v[40:43]
	v_mfma_f32_16x16x32_bf16 v[36:39], v[180:183], v[208:211], v[36:39]
	v_mfma_f32_16x16x32_bf16 v[32:35], v[184:187], v[208:211], v[32:35]
	ds_read_b128 v[208:211], v225 offset:10240
	s_add_u32 m0, s97, 0x14000
	s_add_u32 s8, s100, 0x40000
	s_addc_u32 s9, s101, 0
	global_load_lds_dwordx4 v224, s[8:9]
	v_mfma_f32_16x16x32_bf16 v[28:31], v[168:171], v[212:215], v[28:31]
	v_mfma_f32_16x16x32_bf16 v[24:27], v[176:179], v[212:215], v[24:27]
	v_mfma_f32_16x16x32_bf16 v[20:23], v[180:183], v[212:215], v[20:23]
	v_mfma_f32_16x16x32_bf16 v[16:19], v[184:187], v[212:215], v[16:19]
	ds_read_b128 v[212:215], v225 offset:12288
	s_add_u32 m0, s97, 0x6000
	s_add_u32 s8, s98, 0x60000
	s_addc_u32 s9, s99, 0
	global_load_lds_dwordx4 v224, s[8:9]
	v_mfma_f32_16x16x32_bf16 v[12:15], v[168:171], v[220:223], v[12:15]
	v_mfma_f32_16x16x32_bf16 v[8:11], v[176:179], v[220:223], v[8:11]
	v_mfma_f32_16x16x32_bf16 v[4:7], v[180:183], v[220:223], v[4:7]
	v_mfma_f32_16x16x32_bf16 v[0:3], v[184:187], v[220:223], v[0:3]
	s_add_u32 m0, s97, 0x16000
	s_add_u32 s8, s100, 0x60000
	s_addc_u32 s9, s101, 0
	global_load_lds_dwordx4 v224, s[8:9]
	v_xor_b32_e32 v225, 0x8000, v225
	v_xor_b32_e32 v227, 0x8000, v227
	v_xor_b32_e32 v226, 0x8000, v226
	v_xor_b32_e32 v228, 0x8000, v228
	s_xor_b32 s97, s97, 0x8000
	s_add_u32 s98, s98, 0x80
	s_addc_u32 s99, s99, 0
	s_add_u32 s100, s100, 0x80
	s_addc_u32 s101, s101, 0
	s_sub_u32 s28, s28, 1
	s_cmp_lg_u32 s28, 0
	s_cbranch_scc1 .Lgm1_loop
	s_waitcnt lgkmcnt(4)
	v_mfma_f32_16x16x32_bf16 v[124:127], v[152:155], v[188:191], v[124:127]
	v_mfma_f32_16x16x32_bf16 v[120:123], v[156:159], v[188:191], v[120:123]
	v_mfma_f32_16x16x32_bf16 v[116:119], v[160:163], v[188:191], v[116:119]
	v_mfma_f32_16x16x32_bf16 v[112:115], v[164:167], v[188:191], v[112:115]
	ds_read_b128 v[188:191], v226 offset:0
	ds_read_b128 v[168:171], v228 offset:0
	v_mfma_f32_16x16x32_bf16 v[108:111], v[152:155], v[192:195], v[108:111]
	v_mfma_f32_16x16x32_bf16 v[104:107], v[156:159], v[192:195], v[104:107]
	v_mfma_f32_16x16x32_bf16 v[100:103], v[160:163], v[192:195], v[100:103]
	v_mfma_f32_16x16x32_bf16 v[96:99], v[164:167], v[192:195], v[96:99]
	ds_read_b128 v[192:195], v226 offset:2048
	ds_read_b128 v[176:179], v228 offset:2048
	v_mfma_f32_16x16x32_bf16 v[92:95], v[152:155], v[196:199], v[92:95]
	v_mfma_f32_16x16x32_bf16 v[88:91], v[156:159], v[196:199], v[88:91]
	v_mfma_f32_16x16x32_bf16 v[84:87], v[160:163], v[196:199], v[84:87]
	v_mfma_f32_16x16x32_bf16 v[80:83], v[164:167], v[196:199], v[80:83]
	ds_read_b128 v[196:199], v226 offset:4096
	ds_read_b128 v[180:183], v228 offset:4096
	v_mfma_f32_16x16x32_bf16 v[76:79], v[152:155], v[200:203], v[76:79]
	v_mfma_f32_16x16x32_bf16 v[72:75], v[156:159], v[200:203], v[72:75]
	v_mfma_f32_16x16x32_bf16 v[68:71], v[160:163], v[200:203], v[68:71]
	v_mfma_f32_16x16x32_bf16 v[64:67], v[164:167], v[200:203], v[64:67]
	ds_read_b128 v[200:203], v226 offset:6144
	ds_read_b128 v[184:187], v228 offset:6144
	s_waitcnt lgkmcnt(11)
	v_mfma_f32_16x16x32_bf16 v[60:63], v[152:155], v[204:207], v[60:63]
	v_mfma_f32_16x16x32_bf16 v[56:59], v[156:159], v[204:207], v[56:59]
	v_mfma_f32_16x16x32_bf16 v[52:55], v[160:163], v[204:207], v[52:55]
	v_mfma_f32_16x16x32_bf16 v[48:51], v[164:167], v[204:207], v[48:51]
	ds_read_b128 v[204:207], v226 offset:8192
	ds_read_b128 v[220:223], v226 offset:14336
	s_waitcnt lgkmcnt(11)
	v_mfma_f32_16x16x32_bf16 v[44:47], v[152:155], v[208:211], v[44:47]
	v_mfma_f32_16x16x32_bf16 v[40:43], v[156:159], v[208:211], v[40:43]
	v_mfma_f32_16x16x32_bf16 v[36:39], v[160:163], v[208:211], v[36:39]
	v_mfma_f32_16x16x32_bf16 v[32:35], v[164:167], v[208:211], v[32:35]
	ds_read_b128 v[208:211], v226 offset:10240
	s_waitcnt lgkmcnt(11)
	v_mfma_f32_16x16x32_bf16 v[28:31], v[152:155], v[212:215], v[28:31]
	v_mfma_f32_16x16x32_bf16 v[24:27], v[156:159], v[212:215], v[24:27]
	v_mfma_f32_16x16x32_bf16 v[20:23], v[160:163], v[212:215], v[20:23]
	v_mfma_f32_16x16x32_bf16 v[16:19], v[164:167], v[212:215], v[16:19]
	ds_read_b128 v[212:215], v226 offset:12288
	v_mfma_f32_16x16x32_bf16 v[12:15], v[152:155], v[216:219], v[12:15]
	v_mfma_f32_16x16x32_bf16 v[8:11], v[156:159], v[216:219], v[8:11]
	v_mfma_f32_16x16x32_bf16 v[4:7], v[160:163], v[216:219], v[4:7]
	v_mfma_f32_16x16x32_bf16 v[0:3], v[164:167], v[216:219], v[0:3]
	s_waitcnt vmcnt(0) lgkmcnt(0)
	s_barrier
; #define G_LOAD(KT) do { _Pragma("unroll") for (int i = 0; i < 4; ++i) { ra[i] = *(const u32x4*)(Ag + (size_t)i * 64 * lda + (KT) * 64); rb[i] = *(const u32x4*)(Bg + (size_t)i * 64 * K + (KT) * 64); } } while (0)
; #define G_STORE(BUF) do { u16* ad = As + (BUF) * 256 * 64 + sto; u16* bd = Bs + (BUF) * 256 * 64 + sto; _Pragma("unroll") for (int i = 0; i < 4; ++i) { *(u32x4*)(ad + i * 64 * 64) = ra[i]; *(u32x4*)(bd + i * 64 * 64) = rb[i]; } } while (0)
; template <int EPI>
; DI void gemm_phase(const u16* __restrict__ A, int lda, const u16* __restrict__ Bt, int K, int N, u16* outb, int ldo,
;                    const float* r0, const float* r1, float* outf, char* lds, int bid, int nb) {
;     ...
;     for (int kt = 0; kt < nk; ++kt) {
;       const int cur = kt & 1;
;       if (kt + 1 < nk) G_LOAD(kt + 1);
;       G_MMA(cur, fo0);
;       G_MMA(cur, fo1);
;       if (kt + 1 < nk) G_STORE(cur ^ 1);
;       __syncthreads();
;     }
	v_mfma_f32_16x16x32_bf16 v[124:127], v[168:171], v[188:191], v[124:127]
	v_mfma_f32_16x16x32_bf16 v[120:123], v[176:179], v[188:191], v[120:123]
	v_mfma_f32_16x16x32_bf16 v[116:119], v[180:183], v[188:191], v[116:119]
	v_mfma_f32_16x16x32_bf16 v[112:115], v[184:187], v[188:191], v[112:115]
	ds_read_b128 v[188:191], v225 offset:0
	ds_read_b128 v[152:155], v227 offset:0
	v_mfma_f32_16x16x32_bf16 v[108:111], v[168:171], v[192:195], v[108:111]
	v_mfma_f32_16x16x32_bf16 v[104:107], v[176:179], v[192:195], v[104:107]
	v_mfma_f32_16x16x32_bf16 v[100:103], v[180:183], v[192:195], v[100:103]
	v_mfma_f32_16x16x32_bf16 v[96:99], v[184:187], v[192:195], v[96:99]
	ds_read_b128 v[192:195], v225 offset:2048
	ds_read_b128 v[156:159], v227 offset:2048
	v_mfma_f32_16x16x32_bf16 v[92:95], v[168:171], v[196:199], v[92:95]
	v_mfma_f32_16x16x32_bf16 v[88:91], v[176:179], v[196:199], v[88:91]
	v_mfma_f32_16x16x32_bf16 v[84:87], v[180:183], v[196:199], v[84:87]
	v_mfma_f32_16x16x32_bf16 v[80:83], v[184:187], v[196:199], v[80:83]
	ds_read_b128 v[196:199], v225 offset:4096
	ds_read_b128 v[160:163], v227 offset:4096
	v_mfma_f32_16x16x32_bf16 v[76:79], v[168:171], v[200:203], v[76:79]
	v_mfma_f32_16x16x32_bf16 v[72:75], v[176:179], v[200:203], v[72:75]
	v_mfma_f32_16x16x32_bf16 v[68:71], v[180:183], v[200:203], v[68:71]
	v_mfma_f32_16x16x32_bf16 v[64:67], v[184:187], v[200:203], v[64:67]
	ds_read_b128 v[200:203], v225 offset:6144
	ds_read_b128 v[164:167], v227 offset:6144
	v_mfma_f32_16x16x32_bf16 v[60:63], v[168:171], v[204:207], v[60:63]
	v_mfma_f32_16x16x32_bf16 v[56:59], v[176:179], v[204:207], v[56:59]
	v_mfma_f32_16x16x32_bf16 v[52:55], v[180:183], v[204:207], v[52:55]
	v_mfma_f32_16x16x32_bf16 v[48:51], v[184:187], v[204:207], v[48:51]
	ds_read_b128 v[204:207], v225 offset:8192
	ds_read_b128 v[216:219], v225 offset:14336
	v_mfma_f32_16x16x32_bf16 v[44:47], v[168:171], v[208:211], v[44:47]
	v_mfma_f32_16x16x32_bf16 v[40:43], v[176:179], v[208:211], v[40:43]
	v_mfma_f32_16x16x32_bf16 v[36:39], v[180:183], v[208:211], v[36:39]
	v_mfma_f32_16x16x32_bf16 v[32:35], v[184:187], v[208:211], v[32:35]
	ds_read_b128 v[208:211], v225 offset:10240
	v_mfma_f32_16x16x32_bf16 v[28:31], v[168:171], v[212:215], v[28:31]
	v_mfma_f32_16x16x32_bf16 v[24:27], v[176:179], v[212:215], v[24:27]
	v_mfma_f32_16x16x32_bf16 v[20:23], v[180:183], v[212:215], v[20:23]
	v_mfma_f32_16x16x32_bf16 v[16:19], v[184:187], v[212:215], v[16:19]
	ds_read_b128 v[212:215], v225 offset:12288
	v_mfma_f32_16x16x32_bf16 v[12:15], v[168:171], v[220:223], v[12:15]
	v_mfma_f32_16x16x32_bf16 v[8:11], v[176:179], v[220:223], v[8:11]
	v_mfma_f32_16x16x32_bf16 v[4:7], v[180:183], v[220:223], v[4:7]
	v_mfma_f32_16x16x32_bf16 v[0:3], v[184:187], v[220:223], v[0:3]
	v_xor_b32_e32 v226, 0x8000, v226
	v_xor_b32_e32 v228, 0x8000, v228
	s_waitcnt lgkmcnt(4)
	v_mfma_f32_16x16x32_bf16 v[124:127], v[152:155], v[188:191], v[124:127]
	v_mfma_f32_16x16x32_bf16 v[120:123], v[156:159], v[188:191], v[120:123]
	v_mfma_f32_16x16x32_bf16 v[116:119], v[160:163], v[188:191], v[116:119]
	v_mfma_f32_16x16x32_bf16 v[112:115], v[164:167], v[188:191], v[112:115]
	ds_read_b128 v[188:191], v226 offset:0
	ds_read_b128 v[168:171], v228 offset:0
	v_mfma_f32_16x16x32_bf16 v[108:111], v[152:155], v[192:195], v[108:111]
	v_mfma_f32_16x16x32_bf16 v[104:107], v[156:159], v[192:195], v[104:107]
	v_mfma_f32_16x16x32_bf16 v[100:103], v[160:163], v[192:195], v[100:103]
	v_mfma_f32_16x16x32_bf16 v[96:99], v[164:167], v[192:195], v[96:99]
	ds_read_b128 v[192:195], v226 offset:2048
	ds_read_b128 v[176:179], v228 offset:2048
	v_mfma_f32_16x16x32_bf16 v[92:95], v[152:155], v[196:199], v[92:95]
	v_mfma_f32_16x16x32_bf16 v[88:91], v[156:159], v[196:199], v[88:91]
	v_mfma_f32_16x16x32_bf16 v[84:87], v[160:163], v[196:199], v[84:87]
	v_mfma_f32_16x16x32_bf16 v[80:83], v[164:167], v[196:199], v[80:83]
	ds_read_b128 v[196:199], v226 offset:4096
	ds_read_b128 v[180:183], v228 offset:4096
	v_mfma_f32_16x16x32_bf16 v[76:79], v[152:155], v[200:203], v[76:79]
	v_mfma_f32_16x16x32_bf16 v[72:75], v[156:159], v[200:203], v[72:75]
	v_mfma_f32_16x16x32_bf16 v[68:71], v[160:163], v[200:203], v[68:71]
	v_mfma_f32_16x16x32_bf16 v[64:67], v[164:167], v[200:203], v[64:67]
	ds_read_b128 v[200:203], v226 offset:6144
	ds_read_b128 v[184:187], v228 offset:6144
	s_waitcnt lgkmcnt(11)
	v_mfma_f32_16x16x32_bf16 v[60:63], v[152:155], v[204:207], v[60:63]
	v_mfma_f32_16x16x32_bf16 v[56:59], v[156:159], v[204:207], v[56:59]
	v_mfma_f32_16x16x32_bf16 v[52:55], v[160:163], v[204:207], v[52:55]
	v_mfma_f32_16x16x32_bf16 v[48:51], v[164:167], v[204:207], v[48:51]
	ds_read_b128 v[204:207], v226 offset:8192
	ds_read_b128 v[220:223], v226 offset:14336
	s_waitcnt lgkmcnt(11)
	v_mfma_f32_16x16x32_bf16 v[44:47], v[152:155], v[208:211], v[44:47]
	v_mfma_f32_16x16x32_bf16 v[40:43], v[156:159], v[208:211], v[40:43]
	v_mfma_f32_16x16x32_bf16 v[36:39], v[160:163], v[208:211], v[36:39]
	v_mfma_f32_16x16x32_bf16 v[32:35], v[164:167], v[208:211], v[32:35]
	ds_read_b128 v[208:211], v226 offset:10240
	s_waitcnt lgkmcnt(11)
	v_mfma_f32_16x16x32_bf16 v[28:31], v[152:155], v[212:215], v[28:31]
	v_mfma_f32_16x16x32_bf16 v[24:27], v[156:159], v[212:215], v[24:27]
	v_mfma_f32_16x16x32_bf16 v[20:23], v[160:163], v[212:215], v[20:23]
	v_mfma_f32_16x16x32_bf16 v[16:19], v[164:167], v[212:215], v[16:19]
	ds_read_b128 v[212:215], v226 offset:12288
	v_mfma_f32_16x16x32_bf16 v[12:15], v[152:155], v[216:219], v[12:15]
	v_mfma_f32_16x16x32_bf16 v[8:11], v[156:159], v[216:219], v[8:11]
	v_mfma_f32_16x16x32_bf16 v[4:7], v[160:163], v[216:219], v[4:7]
	v_mfma_f32_16x16x32_bf16 v[0:3], v[164:167], v[216:219], v[0:3]
	s_waitcnt vmcnt(0) lgkmcnt(0)
	s_barrier
; template <int EPI>
; DI void gemm_phase(const u16* __restrict__ A, int lda, const u16* __restrict__ Bt, int K, int N, u16* outb, int ldo,
;                    const float* r0, const float* r1, float* outf, char* lds, int bid, int nb) {
;     ...
;     } else if constexpr (EPI == EPI_RESID) {
;       const int col = tn * 256 + wc * 64 + l15;
;       const float* rb_ = (tm * 256 < M_P) ? r0 : (r1 - (size_t)M_P * DM);
; #pragma unroll
;       for (int i = 0; i < 8; ++i)
; #pragma unroll
;         for (int r = 0; r < 4; ++r) {
;           const size_t i0 = (size_t)(mrow + i * 16 + r) * DM + col;
;           const float x0 = rb_[i0], x1 = rb_[i0 + 16], x2 = rb_[i0 + 32], x3 = rb_[i0 + 48];
;           outf[i0] = x0 + acc[i][0][r]; outf[i0 + 16] = x1 + acc[i][1][r]; outf[i0 + 32] = x2 + acc[i][2][r]; outf[i0 + 48] = x3 + acc[i][3][r];
;         }
	v_mfma_f32_16x16x32_bf16 v[124:127], v[168:171], v[188:191], v[124:127]
	v_mfma_f32_16x16x32_bf16 v[120:123], v[176:179], v[188:191], v[120:123]
	v_mfma_f32_16x16x32_bf16 v[116:119], v[180:183], v[188:191], v[116:119]
	v_mfma_f32_16x16x32_bf16 v[112:115], v[184:187], v[188:191], v[112:115]
	v_mfma_f32_16x16x32_bf16 v[108:111], v[168:171], v[192:195], v[108:111]
	v_mfma_f32_16x16x32_bf16 v[104:107], v[176:179], v[192:195], v[104:107]
	v_mfma_f32_16x16x32_bf16 v[100:103], v[180:183], v[192:195], v[100:103]
	v_mfma_f32_16x16x32_bf16 v[96:99], v[184:187], v[192:195], v[96:99]
	v_mfma_f32_16x16x32_bf16 v[92:95], v[168:171], v[196:199], v[92:95]
	v_mfma_f32_16x16x32_bf16 v[88:91], v[176:179], v[196:199], v[88:91]
	v_mfma_f32_16x16x32_bf16 v[84:87], v[180:183], v[196:199], v[84:87]
	v_mfma_f32_16x16x32_bf16 v[80:83], v[184:187], v[196:199], v[80:83]
	v_mfma_f32_16x16x32_bf16 v[76:79], v[168:171], v[200:203], v[76:79]
	v_mfma_f32_16x16x32_bf16 v[72:75], v[176:179], v[200:203], v[72:75]
	v_mfma_f32_16x16x32_bf16 v[68:71], v[180:183], v[200:203], v[68:71]
	v_mfma_f32_16x16x32_bf16 v[64:67], v[184:187], v[200:203], v[64:67]
	v_mfma_f32_16x16x32_bf16 v[60:63], v[168:171], v[204:207], v[60:63]
	v_mfma_f32_16x16x32_bf16 v[56:59], v[176:179], v[204:207], v[56:59]
	v_mfma_f32_16x16x32_bf16 v[52:55], v[180:183], v[204:207], v[52:55]
	v_mfma_f32_16x16x32_bf16 v[48:51], v[184:187], v[204:207], v[48:51]
	v_mfma_f32_16x16x32_bf16 v[44:47], v[168:171], v[208:211], v[44:47]
	v_mfma_f32_16x16x32_bf16 v[40:43], v[176:179], v[208:211], v[40:43]
	v_mfma_f32_16x16x32_bf16 v[36:39], v[180:183], v[208:211], v[36:39]
	v_mfma_f32_16x16x32_bf16 v[32:35], v[184:187], v[208:211], v[32:35]
	v_mfma_f32_16x16x32_bf16 v[28:31], v[168:171], v[212:215], v[28:31]
	v_mfma_f32_16x16x32_bf16 v[24:27], v[176:179], v[212:215], v[24:27]
	v_mfma_f32_16x16x32_bf16 v[20:23], v[180:183], v[212:215], v[20:23]
	v_mfma_f32_16x16x32_bf16 v[16:19], v[184:187], v[212:215], v[16:19]
	v_mfma_f32_16x16x32_bf16 v[12:15], v[168:171], v[220:223], v[12:15]
	v_mfma_f32_16x16x32_bf16 v[8:11], v[176:179], v[220:223], v[8:11]
	v_mfma_f32_16x16x32_bf16 v[4:7], v[180:183], v[220:223], v[4:7]
	v_mfma_f32_16x16x32_bf16 v[0:3], v[184:187], v[220:223], v[0:3]
	s_nop 7
	s_nop 3
	s_cmpk_lt_i32 s51, 0x80
	s_cselect_b32 s9, s37, s17
	s_cselect_b32 s8, s36, s16
	v_and_b32_e32 v225, 15, v174
	v_lshrrev_b32_e32 v226, 8, v174
	v_lshl_or_b32 v225, v226, 7, v225
	v_bfe_u32 v226, v174, 6, 2
	v_bfe_u32 v227, v174, 4, 2
	v_lshlrev_b32_e32 v227, 2, v227
	v_add_u32_e32 v225, s52, v225
	v_lshl_add_u32 v226, v226, 6, v227
	v_add_u32_e32 v226, s53, v226
	v_lshlrev_b32_e32 v226, 2, v226
	v_lshl_add_u32 v224, v225, 12, v226
	v_mov_b32_e32 v229, v224
	v_add_u32_e32 v224, 0x0, v229
	global_load_dwordx4 v[152:155], v224, s[8:9] offset:0
	global_load_dwordx4 v[156:159], v224, s[8:9] offset:64
	global_load_dwordx4 v[160:163], v224, s[8:9] offset:128
	global_load_dwordx4 v[164:167], v224, s[8:9] offset:192
	v_add_u32_e32 v228, 0x10000, v229
	global_load_dwordx4 v[168:171], v228, s[8:9] offset:0
	global_load_dwordx4 v[176:179], v228, s[8:9] offset:64
	global_load_dwordx4 v[180:183], v228, s[8:9] offset:128
	global_load_dwordx4 v[184:187], v228, s[8:9] offset:192
	s_waitcnt vmcnt(4)
	v_add_f32_e32 v152, v124, v152
	v_add_f32_e32 v153, v125, v153
	v_add_f32_e32 v154, v126, v154
	v_add_f32_e32 v155, v127, v155
	v_add_f32_e32 v156, v120, v156
	v_add_f32_e32 v157, v121, v157
	v_add_f32_e32 v158, v122, v158
	v_add_f32_e32 v159, v123, v159
	v_add_f32_e32 v160, v116, v160
	v_add_f32_e32 v161, v117, v161
	v_add_f32_e32 v162, v118, v162
	v_add_f32_e32 v163, v119, v163
	v_add_f32_e32 v164, v112, v164
	v_add_f32_e32 v165, v113, v165
	v_add_f32_e32 v166, v114, v166
	v_add_f32_e32 v167, v115, v167
	global_store_dwordx4 v224, v[152:155], s[22:23] offset:0
	global_store_dwordx4 v224, v[156:159], s[22:23] offset:64
	global_store_dwordx4 v224, v[160:163], s[22:23] offset:128
	global_store_dwordx4 v224, v[164:167], s[22:23] offset:192
	s_nop 1
	v_add_u32_e32 v224, 0x20000, v229
	global_load_dwordx4 v[152:155], v224, s[8:9] offset:0
	global_load_dwordx4 v[156:159], v224, s[8:9] offset:64
	global_load_dwordx4 v[160:163], v224, s[8:9] offset:128
	global_load_dwordx4 v[164:167], v224, s[8:9] offset:192
	s_waitcnt vmcnt(8)
	v_add_f32_e32 v168, v108, v168
	v_add_f32_e32 v169, v109, v169
	v_add_f32_e32 v170, v110, v170
	v_add_f32_e32 v171, v111, v171
	v_add_f32_e32 v176, v104, v176
	v_add_f32_e32 v177, v105, v177
	v_add_f32_e32 v178, v106, v178
	v_add_f32_e32 v179, v107, v179
	v_add_f32_e32 v180, v100, v180
	v_add_f32_e32 v181, v101, v181
	v_add_f32_e32 v182, v102, v182
	v_add_f32_e32 v183, v103, v183
	v_add_f32_e32 v184, v96, v184
	v_add_f32_e32 v185, v97, v185
	v_add_f32_e32 v186, v98, v186
	v_add_f32_e32 v187, v99, v187
	global_store_dwordx4 v228, v[168:171], s[22:23] offset:0
	global_store_dwordx4 v228, v[176:179], s[22:23] offset:64
	global_store_dwordx4 v228, v[180:183], s[22:23] offset:128
	global_store_dwordx4 v228, v[184:187], s[22:23] offset:192
	s_nop 1
	v_add_u32_e32 v228, 0x30000, v229
	global_load_dwordx4 v[168:171], v228, s[8:9] offset:0
	global_load_dwordx4 v[176:179], v228, s[8:9] offset:64
	global_load_dwordx4 v[180:183], v228, s[8:9] offset:128
	global_load_dwordx4 v[184:187], v228, s[8:9] offset:192
	s_waitcnt vmcnt(8)
; template <int EPI>
; DI void gemm_phase(const u16* __restrict__ A, int lda, const u16* __restrict__ Bt, int K, int N, u16* outb, int ldo,
;                    const float* r0, const float* r1, float* outf, char* lds, int bid, int nb) {
;     ...
;     } else if constexpr (EPI == EPI_RESID) {
;       const int col = tn * 256 + wc * 64 + l15;
;       const float* rb_ = (tm * 256 < M_P) ? r0 : (r1 - (size_t)M_P * DM);
; #pragma unroll
;       for (int i = 0; i < 8; ++i)
; #pragma unroll
;         for (int r = 0; r < 4; ++r) {
;           const size_t i0 = (size_t)(mrow + i * 16 + r) * DM + col;
;           const float x0 = rb_[i0], x1 = rb_[i0 + 16], x2 = rb_[i0 + 32], x3 = rb_[i0 + 48];
;           outf[i0] = x0 + acc[i][0][r]; outf[i0 + 16] = x1 + acc[i][1][r]; outf[i0 + 32] = x2 + acc[i][2][r]; outf[i0 + 48] = x3 + acc[i][3][r];
;         }
	v_add_f32_e32 v152, v92, v152
	v_add_f32_e32 v153, v93, v153
	v_add_f32_e32 v154, v94, v154
	v_add_f32_e32 v155, v95, v155
	v_add_f32_e32 v156, v88, v156
	v_add_f32_e32 v157, v89, v157
	v_add_f32_e32 v158, v90, v158
	v_add_f32_e32 v159, v91, v159
	v_add_f32_e32 v160, v84, v160
	v_add_f32_e32 v161, v85, v161
	v_add_f32_e32 v162, v86, v162
	v_add_f32_e32 v163, v87, v163
	v_add_f32_e32 v164, v80, v164
	v_add_f32_e32 v165, v81, v165
	v_add_f32_e32 v166, v82, v166
	v_add_f32_e32 v167, v83, v167
	global_store_dwordx4 v224, v[152:155], s[22:23] offset:0
	global_store_dwordx4 v224, v[156:159], s[22:23] offset:64
	global_store_dwordx4 v224, v[160:163], s[22:23] offset:128
	global_store_dwordx4 v224, v[164:167], s[22:23] offset:192
	s_nop 1
	v_add_u32_e32 v224, 0x40000, v229
	global_load_dwordx4 v[152:155], v224, s[8:9] offset:0
	global_load_dwordx4 v[156:159], v224, s[8:9] offset:64
	global_load_dwordx4 v[160:163], v224, s[8:9] offset:128
	global_load_dwordx4 v[164:167], v224, s[8:9] offset:192
	s_waitcnt vmcnt(8)
	v_add_f32_e32 v168, v76, v168
	v_add_f32_e32 v169, v77, v169
	v_add_f32_e32 v170, v78, v170
	v_add_f32_e32 v171, v79, v171
	v_add_f32_e32 v176, v72, v176
	v_add_f32_e32 v177, v73, v177
	v_add_f32_e32 v178, v74, v178
	v_add_f32_e32 v179, v75, v179
	v_add_f32_e32 v180, v68, v180
	v_add_f32_e32 v181, v69, v181
	v_add_f32_e32 v182, v70, v182
	v_add_f32_e32 v183, v71, v183
	v_add_f32_e32 v184, v64, v184
	v_add_f32_e32 v185, v65, v185
	v_add_f32_e32 v186, v66, v186
	v_add_f32_e32 v187, v67, v187
	global_store_dwordx4 v228, v[168:171], s[22:23] offset:0
	global_store_dwordx4 v228, v[176:179], s[22:23] offset:64
	global_store_dwordx4 v228, v[180:183], s[22:23] offset:128
	global_store_dwordx4 v228, v[184:187], s[22:23] offset:192
	s_nop 1
	v_add_u32_e32 v228, 0x50000, v229
	global_load_dwordx4 v[168:171], v228, s[8:9] offset:0
	global_load_dwordx4 v[176:179], v228, s[8:9] offset:64
	global_load_dwordx4 v[180:183], v228, s[8:9] offset:128
	global_load_dwordx4 v[184:187], v228, s[8:9] offset:192
	s_waitcnt vmcnt(8)
	v_add_f32_e32 v152, v60, v152
	v_add_f32_e32 v153, v61, v153
	v_add_f32_e32 v154, v62, v154
	v_add_f32_e32 v155, v63, v155
	v_add_f32_e32 v156, v56, v156
	v_add_f32_e32 v157, v57, v157
	v_add_f32_e32 v158, v58, v158
	v_add_f32_e32 v159, v59, v159
	v_add_f32_e32 v160, v52, v160
	v_add_f32_e32 v161, v53, v161
	v_add_f32_e32 v162, v54, v162
	v_add_f32_e32 v163, v55, v163
	v_add_f32_e32 v164, v48, v164
	v_add_f32_e32 v165, v49, v165
	v_add_f32_e32 v166, v50, v166
	v_add_f32_e32 v167, v51, v167
	global_store_dwordx4 v224, v[152:155], s[22:23] offset:0
	global_store_dwordx4 v224, v[156:159], s[22:23] offset:64
	global_store_dwordx4 v224, v[160:163], s[22:23] offset:128
	global_store_dwordx4 v224, v[164:167], s[22:23] offset:192
	s_nop 1
	v_add_u32_e32 v224, 0x60000, v229
	global_load_dwordx4 v[152:155], v224, s[8:9] offset:0
	global_load_dwordx4 v[156:159], v224, s[8:9] offset:64
	global_load_dwordx4 v[160:163], v224, s[8:9] offset:128
	global_load_dwordx4 v[164:167], v224, s[8:9] offset:192
	s_waitcnt vmcnt(8)
	v_add_f32_e32 v168, v44, v168
	v_add_f32_e32 v169, v45, v169
	v_add_f32_e32 v170, v46, v170
	v_add_f32_e32 v171, v47, v171
	v_add_f32_e32 v176, v40, v176
	v_add_f32_e32 v177, v41, v177
	v_add_f32_e32 v178, v42, v178
	v_add_f32_e32 v179, v43, v179
	v_add_f32_e32 v180, v36, v180
	v_add_f32_e32 v181, v37, v181
	v_add_f32_e32 v182, v38, v182
	v_add_f32_e32 v183, v39, v183
	v_add_f32_e32 v184, v32, v184
	v_add_f32_e32 v185, v33, v185
	v_add_f32_e32 v186, v34, v186
	v_add_f32_e32 v187, v35, v187
	global_store_dwordx4 v228, v[168:171], s[22:23] offset:0
	global_store_dwordx4 v228, v[176:179], s[22:23] offset:64
	global_store_dwordx4 v228, v[180:183], s[22:23] offset:128
	global_store_dwordx4 v228, v[184:187], s[22:23] offset:192
	s_nop 1
	v_add_u32_e32 v228, 0x70000, v229
	global_load_dwordx4 v[168:171], v228, s[8:9] offset:0
	global_load_dwordx4 v[176:179], v228, s[8:9] offset:64
	global_load_dwordx4 v[180:183], v228, s[8:9] offset:128
	global_load_dwordx4 v[184:187], v228, s[8:9] offset:192
	s_waitcnt vmcnt(8)
	v_add_f32_e32 v152, v28, v152
	v_add_f32_e32 v153, v29, v153
	v_add_f32_e32 v154, v30, v154
	v_add_f32_e32 v155, v31, v155
	v_add_f32_e32 v156, v24, v156
	v_add_f32_e32 v157, v25, v157
	v_add_f32_e32 v158, v26, v158
	v_add_f32_e32 v159, v27, v159
	v_add_f32_e32 v160, v20, v160
	v_add_f32_e32 v161, v21, v161
	v_add_f32_e32 v162, v22, v162
	v_add_f32_e32 v163, v23, v163
	v_add_f32_e32 v164, v16, v164
	v_add_f32_e32 v165, v17, v165
	v_add_f32_e32 v166, v18, v166
	v_add_f32_e32 v167, v19, v167
	global_store_dwordx4 v224, v[152:155], s[22:23] offset:0
	global_store_dwordx4 v224, v[156:159], s[22:23] offset:64
	global_store_dwordx4 v224, v[160:163], s[22:23] offset:128
	global_store_dwordx4 v224, v[164:167], s[22:23] offset:192
	s_waitcnt vmcnt(4)
	v_add_f32_e32 v168, v12, v168
	v_add_f32_e32 v169, v13, v169
	v_add_f32_e32 v170, v14, v170
	v_add_f32_e32 v171, v15, v171
	v_add_f32_e32 v176, v8, v176
	v_add_f32_e32 v177, v9, v177
	v_add_f32_e32 v178, v10, v178
	v_add_f32_e32 v179, v11, v179
	v_add_f32_e32 v180, v4, v180
	v_add_f32_e32 v181, v5, v181
	v_add_f32_e32 v182, v6, v182
	v_add_f32_e32 v183, v7, v183
	v_add_f32_e32 v184, v0, v184
	v_add_f32_e32 v185, v1, v185
	v_add_f32_e32 v186, v2, v186
	v_add_f32_e32 v187, v3, v187
	global_store_dwordx4 v228, v[168:171], s[22:23] offset:0
	global_store_dwordx4 v228, v[176:179], s[22:23] offset:64
	global_store_dwordx4 v228, v[180:183], s[22:23] offset:128
	global_store_dwordx4 v228, v[184:187], s[22:23] offset:192
	s_add_i32 s18, s18, 1
	s_cmp_eq_u32 s18, s3
	s_cbranch_scc0 .LBB0_577

; #define G_LOAD(KT) do { _Pragma("unroll") for (int i = 0; i < 4; ++i) { ra[i] = *(const u32x4*)(Ag + (size_t)i * 64 * lda + (KT) * 64); rb[i] = *(const u32x4*)(Bg + (size_t)i * 64 * K + (KT) * 64); } } while (0)
; #define G_STORE(BUF) do { u16* ad = As + (BUF) * 256 * 64 + sto; u16* bd = Bs + (BUF) * 256 * 64 + sto; _Pragma("unroll") for (int i = 0; i < 4; ++i) { *(u32x4*)(ad + i * 64 * 64) = ra[i]; *(u32x4*)(bd + i * 64 * 64) = rb[i]; } } while (0)
; template <int EPI>
; DI void gemm_phase(const u16* __restrict__ A, int lda, const u16* __restrict__ Bt, int K, int N, u16* outb, int ldo,
;                    const float* r0, const float* r1, float* outf, char* lds, int bid, int nb) {
;     ...
;   for (int it = 0; it < nIter; ++it) {
;     int tm, tn;
;     if (swz) { const int st = xcd + 8 * it, sm = st / nSN, sn = st - sm * nSN; tm = sm * GM + jb / GN; tn = sn * GN + (jb % GN); }
;     else { const int t = bid + it * nb; tm = t / nN; tn = t - tm * nN; }
;     const u16* Ag = A + (size_t)(tm * 256 + lrow) * lda + lch * 8;
;     const u16* Bg = Bt + (size_t)(tn * 256 + lrow) * K + lch * 8;
;     f32x4 acc[8][4];
; #pragma unroll
;     for (int i = 0; i < 8; ++i)
; #pragma unroll
;       for (int j = 0; j < 4; ++j) acc[i][j] = (f32x4){0.f, 0.f, 0.f, 0.f};
;     u32x4 ra[4], rb[4];
;     ...
;     G_LOAD(0);
;     G_STORE(0);
;     __syncthreads();
.LBB0_701:
	s_lshl_b32 s49, s49, 8
	v_or_b32_e32 v0, s49, v138
	v_ashrrev_i32_e32 v1, 31, v0
	v_lshlrev_b64 v[64:65], 11, v[0:1]
	v_lshl_or_b32 v0, s48, 8, v138
	v_ashrrev_i32_e32 v1, 31, v0
	v_lshlrev_b64 v[66:67], 11, v[0:1]
	v_lshl_add_u64 v[0:1], v[128:129], 0, v[64:65]
	v_add_co_u32_e32 v4, vcc, 0x20000, v0
	v_lshl_add_u64 v[2:3], v[130:131], 0, v[66:67]
	s_nop 0
	v_addc_co_u32_e32 v5, vcc, 0, v1, vcc
	v_add_co_u32_e32 v6, vcc, 0x20000, v2
	s_nop 1
	v_readfirstlane_b32 s98, v0
	v_readfirstlane_b32 s99, v1
	s_nop 1
	v_readfirstlane_b32 s100, v2
	v_readfirstlane_b32 s101, v3
	v_addc_co_u32_e32 v7, vcc, 0, v3, vcc
	v_add_co_u32_e32 v4, vcc, 0x40000, v0
	s_mov_b32 s50, 0
	s_nop 0
	v_addc_co_u32_e32 v5, vcc, 0, v1, vcc
	v_add_co_u32_e32 v6, vcc, 0x40000, v2
	s_mov_b64 s[14:15], 0
	s_nop 0
	v_addc_co_u32_e32 v7, vcc, 0, v3, vcc
	v_add_co_u32_e32 v0, vcc, 0x60000, v0
	v_addc_co_u32_e32 v1, vcc, 0, v1, vcc
	v_add_co_u32_e32 v2, vcc, 0x60000, v2
	v_lshl_add_u64 v[134:135], v[132:133], 0, v[66:67]
	s_nop 0
	v_addc_co_u32_e32 v3, vcc, 0, v3, vcc
	v_mov_b32_e32 v0, 0
	v_lshl_add_u64 v[136:137], v[132:133], 0, v[64:65]
	v_and_b32_e32 v229, 63, v174
	v_lshrrev_b32_e32 v230, 3, v229
	v_mov_b32_e32 v233, 0x800
	v_mul_u32_u24_e32 v224, v230, v233
	v_bfe_u32 v231, v174, 4, 2
	v_bfe_u32 v232, v174, 6, 1
	v_lshl_or_b32 v232, v232, 2, v231
	v_and_b32_e32 v233, 7, v174
	v_xor_b32_e32 v232, v232, v233
	v_lshl_add_u32 v224, v232, 4, v224
	v_and_b32_e32 v229, 15, v174
	v_bfe_u32 v230, v174, 1, 3
	v_xor_b32_e32 v230, v230, v231
	v_lshlrev_b32_e32 v230, 4, v230
	v_lshl_or_b32 v230, v229, 7, v230
	v_lshrrev_b32_e32 v229, 8, v174
	v_lshl_or_b32 v225, v229, 14, v230
	v_bfe_u32 v229, v174, 6, 2
	v_lshl_or_b32 v227, v229, 13, v230
	v_or_b32_e32 v227, 0x10000, v227
	v_xor_b32_e32 v226, 64, v225
	v_xor_b32_e32 v228, 64, v227
	v_readfirstlane_b32 s97, v174
	s_lshl_b32 s97, s97, 4
	s_mov_b32 s28, 14
	s_add_u32 m0, s97, 0x0
	s_add_u32 s14, s98, 0x0
	s_addc_u32 s15, s99, 0
	global_load_lds_dwordx4 v224, s[14:15]
	s_add_u32 m0, s97, 0x10000
	s_add_u32 s14, s100, 0x0
	s_addc_u32 s15, s101, 0
	global_load_lds_dwordx4 v224, s[14:15]
	s_add_u32 m0, s97, 0x2000
	s_add_u32 s14, s98, 0x20000
	s_addc_u32 s15, s99, 0
	global_load_lds_dwordx4 v224, s[14:15]
	s_add_u32 m0, s97, 0x12000
	s_add_u32 s14, s100, 0x20000
	s_addc_u32 s15, s101, 0
	global_load_lds_dwordx4 v224, s[14:15]
	s_add_u32 m0, s97, 0x4000
	s_add_u32 s14, s98, 0x40000
	s_addc_u32 s15, s99, 0
	global_load_lds_dwordx4 v224, s[14:15]
	s_add_u32 m0, s97, 0x14000
	s_add_u32 s14, s100, 0x40000
	s_addc_u32 s15, s101, 0
	global_load_lds_dwordx4 v224, s[14:15]
	s_add_u32 m0, s97, 0x6000
	s_add_u32 s14, s98, 0x60000
	s_addc_u32 s15, s99, 0
	global_load_lds_dwordx4 v224, s[14:15]
	s_add_u32 m0, s97, 0x16000
	s_add_u32 s14, s100, 0x60000
	s_addc_u32 s15, s101, 0
	global_load_lds_dwordx4 v224, s[14:15]
	s_add_u32 m0, s97, 0x8000
	s_add_u32 s14, s98, 0x80
	s_addc_u32 s15, s99, 0
	global_load_lds_dwordx4 v224, s[14:15]
	s_add_u32 m0, s97, 0x18000
	s_add_u32 s14, s100, 0x80
	s_addc_u32 s15, s101, 0
	global_load_lds_dwordx4 v224, s[14:15]
	s_add_u32 m0, s97, 0xa000
	s_add_u32 s14, s98, 0x20080
	s_addc_u32 s15, s99, 0
	global_load_lds_dwordx4 v224, s[14:15]
	s_add_u32 m0, s97, 0x1a000
	s_add_u32 s14, s100, 0x20080
	s_addc_u32 s15, s101, 0
	global_load_lds_dwordx4 v224, s[14:15]
	s_add_u32 m0, s97, 0xc000
	s_add_u32 s14, s98, 0x40080
	s_addc_u32 s15, s99, 0
	global_load_lds_dwordx4 v224, s[14:15]
	s_add_u32 m0, s97, 0x1c000
	s_add_u32 s14, s100, 0x40080
	s_addc_u32 s15, s101, 0
	global_load_lds_dwordx4 v224, s[14:15]
	s_add_u32 m0, s97, 0xe000
	s_add_u32 s14, s98, 0x60080
	s_addc_u32 s15, s99, 0
	global_load_lds_dwordx4 v224, s[14:15]
	s_add_u32 m0, s97, 0x1e000
	s_add_u32 s14, s100, 0x60080
	s_addc_u32 s15, s101, 0
	global_load_lds_dwordx4 v224, s[14:15]
	s_add_u32 s98, s98, 0x100
	s_addc_u32 s99, s99, 0
	s_add_u32 s100, s100, 0x100
	s_addc_u32 s101, s101, 0
	s_waitcnt vmcnt(8)
	s_barrier
; #define G_LOAD(KT) do { _Pragma("unroll") for (int i = 0; i < 4; ++i) { ra[i] = *(const u32x4*)(Ag + (size_t)i * 64 * lda + (KT) * 64); rb[i] = *(const u32x4*)(Bg + (size_t)i * 64 * K + (KT) * 64); } } while (0)
; #define G_STORE(BUF) do { u16* ad = As + (BUF) * 256 * 64 + sto; u16* bd = Bs + (BUF) * 256 * 64 + sto; _Pragma("unroll") for (int i = 0; i < 4; ++i) { *(u32x4*)(ad + i * 64 * 64) = ra[i]; *(u32x4*)(bd + i * 64 * 64) = rb[i]; } } while (0)
; template <int EPI>
; DI void gemm_phase(const u16* __restrict__ A, int lda, const u16* __restrict__ Bt, int K, int N, u16* outb, int ldo,
;                    const float* r0, const float* r1, float* outf, char* lds, int bid, int nb) {
;     ...
;     G_LOAD(0);
;     G_STORE(0);
;     __syncthreads();
;     for (int kt = 0; kt < nk; ++kt) {
;       const int cur = kt & 1;
;       if (kt + 1 < nk) G_LOAD(kt + 1);
;       G_MMA(cur, fo0);
;       G_MMA(cur, fo1);
	ds_read_b128 v[152:155], v227 offset:0
	ds_read_b128 v[156:159], v227 offset:2048
	ds_read_b128 v[160:163], v227 offset:4096
	ds_read_b128 v[164:167], v227 offset:6144
	ds_read_b128 v[188:191], v225 offset:0
	ds_read_b128 v[192:195], v225 offset:2048
	ds_read_b128 v[196:199], v225 offset:4096
	ds_read_b128 v[200:203], v225 offset:6144
	ds_read_b128 v[204:207], v225 offset:8192
	ds_read_b128 v[208:211], v225 offset:10240
	ds_read_b128 v[212:215], v225 offset:12288
	ds_read_b128 v[216:219], v225 offset:14336
	v_xor_b32_e32 v225, 0x8000, v225
	v_xor_b32_e32 v227, 0x8000, v227
	s_waitcnt lgkmcnt(0)
	s_waitcnt lgkmcnt(4)
	v_mfma_f32_16x16x32_bf16 v[124:127], v[152:155], v[188:191], 0
	v_mfma_f32_16x16x32_bf16 v[120:123], v[156:159], v[188:191], 0
	v_mfma_f32_16x16x32_bf16 v[116:119], v[160:163], v[188:191], 0
	v_mfma_f32_16x16x32_bf16 v[112:115], v[164:167], v[188:191], 0
	ds_read_b128 v[188:191], v226 offset:0
	ds_read_b128 v[168:171], v228 offset:0
	v_mfma_f32_16x16x32_bf16 v[108:111], v[152:155], v[192:195], 0
	v_mfma_f32_16x16x32_bf16 v[104:107], v[156:159], v[192:195], 0
	v_mfma_f32_16x16x32_bf16 v[100:103], v[160:163], v[192:195], 0
	v_mfma_f32_16x16x32_bf16 v[96:99], v[164:167], v[192:195], 0
	ds_read_b128 v[192:195], v226 offset:2048
	ds_read_b128 v[176:179], v228 offset:2048
	v_mfma_f32_16x16x32_bf16 v[92:95], v[152:155], v[196:199], 0
	v_mfma_f32_16x16x32_bf16 v[88:91], v[156:159], v[196:199], 0
	v_mfma_f32_16x16x32_bf16 v[84:87], v[160:163], v[196:199], 0
	v_mfma_f32_16x16x32_bf16 v[80:83], v[164:167], v[196:199], 0
	ds_read_b128 v[196:199], v226 offset:4096
	ds_read_b128 v[180:183], v228 offset:4096
	v_mfma_f32_16x16x32_bf16 v[76:79], v[152:155], v[200:203], 0
	v_mfma_f32_16x16x32_bf16 v[72:75], v[156:159], v[200:203], 0
	v_mfma_f32_16x16x32_bf16 v[68:71], v[160:163], v[200:203], 0
	v_mfma_f32_16x16x32_bf16 v[64:67], v[164:167], v[200:203], 0
	ds_read_b128 v[200:203], v226 offset:6144
	ds_read_b128 v[184:187], v228 offset:6144
	s_waitcnt lgkmcnt(11)
	v_mfma_f32_16x16x32_bf16 v[60:63], v[152:155], v[204:207], 0
	v_mfma_f32_16x16x32_bf16 v[56:59], v[156:159], v[204:207], 0
	v_mfma_f32_16x16x32_bf16 v[52:55], v[160:163], v[204:207], 0
	v_mfma_f32_16x16x32_bf16 v[48:51], v[164:167], v[204:207], 0
	ds_read_b128 v[204:207], v226 offset:8192
	ds_read_b128 v[220:223], v226 offset:14336
	s_waitcnt lgkmcnt(11)
	v_mfma_f32_16x16x32_bf16 v[44:47], v[152:155], v[208:211], 0
	v_mfma_f32_16x16x32_bf16 v[40:43], v[156:159], v[208:211], 0
	v_mfma_f32_16x16x32_bf16 v[36:39], v[160:163], v[208:211], 0
	v_mfma_f32_16x16x32_bf16 v[32:35], v[164:167], v[208:211], 0
	ds_read_b128 v[208:211], v226 offset:10240
	s_waitcnt lgkmcnt(11)
	v_mfma_f32_16x16x32_bf16 v[28:31], v[152:155], v[212:215], 0
	v_mfma_f32_16x16x32_bf16 v[24:27], v[156:159], v[212:215], 0
	v_mfma_f32_16x16x32_bf16 v[20:23], v[160:163], v[212:215], 0
	v_mfma_f32_16x16x32_bf16 v[16:19], v[164:167], v[212:215], 0
	ds_read_b128 v[212:215], v226 offset:12288
	v_mfma_f32_16x16x32_bf16 v[12:15], v[152:155], v[216:219], 0
	v_mfma_f32_16x16x32_bf16 v[8:11], v[156:159], v[216:219], 0
	v_mfma_f32_16x16x32_bf16 v[4:7], v[160:163], v[216:219], 0
	v_mfma_f32_16x16x32_bf16 v[0:3], v[164:167], v[216:219], 0
	s_branch .Lgm2_mid0

; #define G_LOAD(KT) do { _Pragma("unroll") for (int i = 0; i < 4; ++i) { ra[i] = *(const u32x4*)(Ag + (size_t)i * 64 * lda + (KT) * 64); rb[i] = *(const u32x4*)(Bg + (size_t)i * 64 * K + (KT) * 64); } } while (0)
; #define G_STORE(BUF) do { u16* ad = As + (BUF) * 256 * 64 + sto; u16* bd = Bs + (BUF) * 256 * 64 + sto; _Pragma("unroll") for (int i = 0; i < 4; ++i) { *(u32x4*)(ad + i * 64 * 64) = ra[i]; *(u32x4*)(bd + i * 64 * 64) = rb[i]; } } while (0)
; template <int EPI>
; DI void gemm_phase(const u16* __restrict__ A, int lda, const u16* __restrict__ Bt, int K, int N, u16* outb, int ldo,
;                    const float* r0, const float* r1, float* outf, char* lds, int bid, int nb) {
;     ...
;     for (int kt = 0; kt < nk; ++kt) {
;       const int cur = kt & 1;
;       if (kt + 1 < nk) G_LOAD(kt + 1);
;       G_MMA(cur, fo0);
;       G_MMA(cur, fo1);
;       if (kt + 1 < nk) G_STORE(cur ^ 1);
;       __syncthreads();
.Lgm2_mid0:
	s_waitcnt vmcnt(0) lgkmcnt(0)
	s_barrier
	v_mfma_f32_16x16x32_bf16 v[124:127], v[168:171], v[188:191], v[124:127]
	v_mfma_f32_16x16x32_bf16 v[120:123], v[176:179], v[188:191], v[120:123]
	v_mfma_f32_16x16x32_bf16 v[116:119], v[180:183], v[188:191], v[116:119]
	v_mfma_f32_16x16x32_bf16 v[112:115], v[184:187], v[188:191], v[112:115]
	ds_read_b128 v[188:191], v225 offset:0
	ds_read_b128 v[152:155], v227 offset:0
	s_add_u32 m0, s97, 0x0
	s_add_u32 s14, s98, 0x0
	s_addc_u32 s15, s99, 0
	global_load_lds_dwordx4 v224, s[14:15]
	v_mfma_f32_16x16x32_bf16 v[108:111], v[168:171], v[192:195], v[108:111]
	v_mfma_f32_16x16x32_bf16 v[104:107], v[176:179], v[192:195], v[104:107]
	v_mfma_f32_16x16x32_bf16 v[100:103], v[180:183], v[192:195], v[100:103]
	v_mfma_f32_16x16x32_bf16 v[96:99], v[184:187], v[192:195], v[96:99]
	ds_read_b128 v[192:195], v225 offset:2048
	ds_read_b128 v[156:159], v227 offset:2048
	s_add_u32 m0, s97, 0x10000
	s_add_u32 s14, s100, 0x0
	s_addc_u32 s15, s101, 0
	global_load_lds_dwordx4 v224, s[14:15]
	v_mfma_f32_16x16x32_bf16 v[92:95], v[168:171], v[196:199], v[92:95]
	v_mfma_f32_16x16x32_bf16 v[88:91], v[176:179], v[196:199], v[88:91]
	v_mfma_f32_16x16x32_bf16 v[84:87], v[180:183], v[196:199], v[84:87]
	v_mfma_f32_16x16x32_bf16 v[80:83], v[184:187], v[196:199], v[80:83]
	ds_read_b128 v[196:199], v225 offset:4096
	ds_read_b128 v[160:163], v227 offset:4096
	s_add_u32 m0, s97, 0x2000
	s_add_u32 s14, s98, 0x20000
	s_addc_u32 s15, s99, 0
	global_load_lds_dwordx4 v224, s[14:15]
	v_mfma_f32_16x16x32_bf16 v[76:79], v[168:171], v[200:203], v[76:79]
	v_mfma_f32_16x16x32_bf16 v[72:75], v[176:179], v[200:203], v[72:75]
	v_mfma_f32_16x16x32_bf16 v[68:71], v[180:183], v[200:203], v[68:71]
	v_mfma_f32_16x16x32_bf16 v[64:67], v[184:187], v[200:203], v[64:67]
	ds_read_b128 v[200:203], v225 offset:6144
	ds_read_b128 v[164:167], v227 offset:6144
	s_add_u32 m0, s97, 0x12000
	s_add_u32 s14, s100, 0x20000
	s_addc_u32 s15, s101, 0
	global_load_lds_dwordx4 v224, s[14:15]
	v_mfma_f32_16x16x32_bf16 v[60:63], v[168:171], v[204:207], v[60:63]
	v_mfma_f32_16x16x32_bf16 v[56:59], v[176:179], v[204:207], v[56:59]
	v_mfma_f32_16x16x32_bf16 v[52:55], v[180:183], v[204:207], v[52:55]
	v_mfma_f32_16x16x32_bf16 v[48:51], v[184:187], v[204:207], v[48:51]
	ds_read_b128 v[204:207], v225 offset:8192
	ds_read_b128 v[216:219], v225 offset:14336
	s_add_u32 m0, s97, 0x4000
	s_add_u32 s14, s98, 0x40000
	s_addc_u32 s15, s99, 0
	global_load_lds_dwordx4 v224, s[14:15]
	v_mfma_f32_16x16x32_bf16 v[44:47], v[168:171], v[208:211], v[44:47]
	v_mfma_f32_16x16x32_bf16 v[40:43], v[176:179], v[208:211], v[40:43]
	v_mfma_f32_16x16x32_bf16 v[36:39], v[180:183], v[208:211], v[36:39]
	v_mfma_f32_16x16x32_bf16 v[32:35], v[184:187], v[208:211], v[32:35]
	ds_read_b128 v[208:211], v225 offset:10240
	s_add_u32 m0, s97, 0x14000
	s_add_u32 s14, s100, 0x40000
	s_addc_u32 s15, s101, 0
	global_load_lds_dwordx4 v224, s[14:15]
	v_mfma_f32_16x16x32_bf16 v[28:31], v[168:171], v[212:215], v[28:31]
	v_mfma_f32_16x16x32_bf16 v[24:27], v[176:179], v[212:215], v[24:27]
	v_mfma_f32_16x16x32_bf16 v[20:23], v[180:183], v[212:215], v[20:23]
	v_mfma_f32_16x16x32_bf16 v[16:19], v[184:187], v[212:215], v[16:19]
	ds_read_b128 v[212:215], v225 offset:12288
	s_add_u32 m0, s97, 0x6000
	s_add_u32 s14, s98, 0x60000
	s_addc_u32 s15, s99, 0
	global_load_lds_dwordx4 v224, s[14:15]
	v_mfma_f32_16x16x32_bf16 v[12:15], v[168:171], v[220:223], v[12:15]
	v_mfma_f32_16x16x32_bf16 v[8:11], v[176:179], v[220:223], v[8:11]
	v_mfma_f32_16x16x32_bf16 v[4:7], v[180:183], v[220:223], v[4:7]
	v_mfma_f32_16x16x32_bf16 v[0:3], v[184:187], v[220:223], v[0:3]
	s_add_u32 m0, s97, 0x16000
	s_add_u32 s14, s100, 0x60000
	s_addc_u32 s15, s101, 0
	global_load_lds_dwordx4 v224, s[14:15]
	v_xor_b32_e32 v225, 0x8000, v225
	v_xor_b32_e32 v227, 0x8000, v227
	v_xor_b32_e32 v226, 0x8000, v226
	v_xor_b32_e32 v228, 0x8000, v228
	s_xor_b32 s97, s97, 0x8000
	s_add_u32 s98, s98, 0x80
	s_addc_u32 s99, s99, 0
	s_add_u32 s100, s100, 0x80
	s_addc_u32 s101, s101, 0
	s_sub_u32 s28, s28, 1
	s_cmp_lg_u32 s28, 0
	s_cbranch_scc1 .Lgm2_loop
	s_waitcnt lgkmcnt(4)
	v_mfma_f32_16x16x32_bf16 v[124:127], v[152:155], v[188:191], v[124:127]
	v_mfma_f32_16x16x32_bf16 v[120:123], v[156:159], v[188:191], v[120:123]
	v_mfma_f32_16x16x32_bf16 v[116:119], v[160:163], v[188:191], v[116:119]
	v_mfma_f32_16x16x32_bf16 v[112:115], v[164:167], v[188:191], v[112:115]
	ds_read_b128 v[188:191], v226 offset:0
	ds_read_b128 v[168:171], v228 offset:0
	v_mfma_f32_16x16x32_bf16 v[108:111], v[152:155], v[192:195], v[108:111]
	v_mfma_f32_16x16x32_bf16 v[104:107], v[156:159], v[192:195], v[104:107]
	v_mfma_f32_16x16x32_bf16 v[100:103], v[160:163], v[192:195], v[100:103]
	v_mfma_f32_16x16x32_bf16 v[96:99], v[164:167], v[192:195], v[96:99]
	ds_read_b128 v[192:195], v226 offset:2048
	ds_read_b128 v[176:179], v228 offset:2048
	v_mfma_f32_16x16x32_bf16 v[92:95], v[152:155], v[196:199], v[92:95]
	v_mfma_f32_16x16x32_bf16 v[88:91], v[156:159], v[196:199], v[88:91]
	v_mfma_f32_16x16x32_bf16 v[84:87], v[160:163], v[196:199], v[84:87]
	v_mfma_f32_16x16x32_bf16 v[80:83], v[164:167], v[196:199], v[80:83]
	ds_read_b128 v[196:199], v226 offset:4096
	ds_read_b128 v[180:183], v228 offset:4096
	v_mfma_f32_16x16x32_bf16 v[76:79], v[152:155], v[200:203], v[76:79]
	v_mfma_f32_16x16x32_bf16 v[72:75], v[156:159], v[200:203], v[72:75]
	v_mfma_f32_16x16x32_bf16 v[68:71], v[160:163], v[200:203], v[68:71]
	v_mfma_f32_16x16x32_bf16 v[64:67], v[164:167], v[200:203], v[64:67]
	ds_read_b128 v[200:203], v226 offset:6144
	ds_read_b128 v[184:187], v228 offset:6144
	s_waitcnt lgkmcnt(11)
	v_mfma_f32_16x16x32_bf16 v[60:63], v[152:155], v[204:207], v[60:63]
	v_mfma_f32_16x16x32_bf16 v[56:59], v[156:159], v[204:207], v[56:59]
	v_mfma_f32_16x16x32_bf16 v[52:55], v[160:163], v[204:207], v[52:55]
	v_mfma_f32_16x16x32_bf16 v[48:51], v[164:167], v[204:207], v[48:51]
	ds_read_b128 v[204:207], v226 offset:8192
	ds_read_b128 v[220:223], v226 offset:14336
	s_waitcnt lgkmcnt(11)
	v_mfma_f32_16x16x32_bf16 v[44:47], v[152:155], v[208:211], v[44:47]
	v_mfma_f32_16x16x32_bf16 v[40:43], v[156:159], v[208:211], v[40:43]
	v_mfma_f32_16x16x32_bf16 v[36:39], v[160:163], v[208:211], v[36:39]
	v_mfma_f32_16x16x32_bf16 v[32:35], v[164:167], v[208:211], v[32:35]
	ds_read_b128 v[208:211], v226 offset:10240
	s_waitcnt lgkmcnt(11)
	v_mfma_f32_16x16x32_bf16 v[28:31], v[152:155], v[212:215], v[28:31]
	v_mfma_f32_16x16x32_bf16 v[24:27], v[156:159], v[212:215], v[24:27]
	v_mfma_f32_16x16x32_bf16 v[20:23], v[160:163], v[212:215], v[20:23]
	v_mfma_f32_16x16x32_bf16 v[16:19], v[164:167], v[212:215], v[16:19]
	ds_read_b128 v[212:215], v226 offset:12288
	v_mfma_f32_16x16x32_bf16 v[12:15], v[152:155], v[216:219], v[12:15]
	v_mfma_f32_16x16x32_bf16 v[8:11], v[156:159], v[216:219], v[8:11]
	v_mfma_f32_16x16x32_bf16 v[4:7], v[160:163], v[216:219], v[4:7]
	v_mfma_f32_16x16x32_bf16 v[0:3], v[164:167], v[216:219], v[0:3]
	s_waitcnt vmcnt(0) lgkmcnt(0)
	s_barrier
; #define G_LOAD(KT) do { _Pragma("unroll") for (int i = 0; i < 4; ++i) { ra[i] = *(const u32x4*)(Ag + (size_t)i * 64 * lda + (KT) * 64); rb[i] = *(const u32x4*)(Bg + (size_t)i * 64 * K + (KT) * 64); } } while (0)
; #define G_STORE(BUF) do { u16* ad = As + (BUF) * 256 * 64 + sto; u16* bd = Bs + (BUF) * 256 * 64 + sto; _Pragma("unroll") for (int i = 0; i < 4; ++i) { *(u32x4*)(ad + i * 64 * 64) = ra[i]; *(u32x4*)(bd + i * 64 * 64) = rb[i]; } } while (0)
; template <int EPI>
; DI void gemm_phase(const u16* __restrict__ A, int lda, const u16* __restrict__ Bt, int K, int N, u16* outb, int ldo,
;                    const float* r0, const float* r1, float* outf, char* lds, int bid, int nb) {
;     ...
;     for (int kt = 0; kt < nk; ++kt) {
;       const int cur = kt & 1;
;       if (kt + 1 < nk) G_LOAD(kt + 1);
;       G_MMA(cur, fo0);
;       G_MMA(cur, fo1);
;       if (kt + 1 < nk) G_STORE(cur ^ 1);
;       __syncthreads();
;     }
	v_mfma_f32_16x16x32_bf16 v[124:127], v[168:171], v[188:191], v[124:127]
	v_mfma_f32_16x16x32_bf16 v[120:123], v[176:179], v[188:191], v[120:123]
	v_mfma_f32_16x16x32_bf16 v[116:119], v[180:183], v[188:191], v[116:119]
	v_mfma_f32_16x16x32_bf16 v[112:115], v[184:187], v[188:191], v[112:115]
	ds_read_b128 v[188:191], v225 offset:0
	ds_read_b128 v[152:155], v227 offset:0
	v_mfma_f32_16x16x32_bf16 v[108:111], v[168:171], v[192:195], v[108:111]
	v_mfma_f32_16x16x32_bf16 v[104:107], v[176:179], v[192:195], v[104:107]
	v_mfma_f32_16x16x32_bf16 v[100:103], v[180:183], v[192:195], v[100:103]
	v_mfma_f32_16x16x32_bf16 v[96:99], v[184:187], v[192:195], v[96:99]
	ds_read_b128 v[192:195], v225 offset:2048
	ds_read_b128 v[156:159], v227 offset:2048
	v_mfma_f32_16x16x32_bf16 v[92:95], v[168:171], v[196:199], v[92:95]
	v_mfma_f32_16x16x32_bf16 v[88:91], v[176:179], v[196:199], v[88:91]
	v_mfma_f32_16x16x32_bf16 v[84:87], v[180:183], v[196:199], v[84:87]
	v_mfma_f32_16x16x32_bf16 v[80:83], v[184:187], v[196:199], v[80:83]
	ds_read_b128 v[196:199], v225 offset:4096
	ds_read_b128 v[160:163], v227 offset:4096
	v_mfma_f32_16x16x32_bf16 v[76:79], v[168:171], v[200:203], v[76:79]
	v_mfma_f32_16x16x32_bf16 v[72:75], v[176:179], v[200:203], v[72:75]
	v_mfma_f32_16x16x32_bf16 v[68:71], v[180:183], v[200:203], v[68:71]
	v_mfma_f32_16x16x32_bf16 v[64:67], v[184:187], v[200:203], v[64:67]
	ds_read_b128 v[200:203], v225 offset:6144
	ds_read_b128 v[164:167], v227 offset:6144
	v_mfma_f32_16x16x32_bf16 v[60:63], v[168:171], v[204:207], v[60:63]
	v_mfma_f32_16x16x32_bf16 v[56:59], v[176:179], v[204:207], v[56:59]
	v_mfma_f32_16x16x32_bf16 v[52:55], v[180:183], v[204:207], v[52:55]
	v_mfma_f32_16x16x32_bf16 v[48:51], v[184:187], v[204:207], v[48:51]
	ds_read_b128 v[204:207], v225 offset:8192
	ds_read_b128 v[216:219], v225 offset:14336
	v_mfma_f32_16x16x32_bf16 v[44:47], v[168:171], v[208:211], v[44:47]
	v_mfma_f32_16x16x32_bf16 v[40:43], v[176:179], v[208:211], v[40:43]
	v_mfma_f32_16x16x32_bf16 v[36:39], v[180:183], v[208:211], v[36:39]
	v_mfma_f32_16x16x32_bf16 v[32:35], v[184:187], v[208:211], v[32:35]
	ds_read_b128 v[208:211], v225 offset:10240
	v_mfma_f32_16x16x32_bf16 v[28:31], v[168:171], v[212:215], v[28:31]
	v_mfma_f32_16x16x32_bf16 v[24:27], v[176:179], v[212:215], v[24:27]
	v_mfma_f32_16x16x32_bf16 v[20:23], v[180:183], v[212:215], v[20:23]
	v_mfma_f32_16x16x32_bf16 v[16:19], v[184:187], v[212:215], v[16:19]
	ds_read_b128 v[212:215], v225 offset:12288
	v_mfma_f32_16x16x32_bf16 v[12:15], v[168:171], v[220:223], v[12:15]
	v_mfma_f32_16x16x32_bf16 v[8:11], v[176:179], v[220:223], v[8:11]
	v_mfma_f32_16x16x32_bf16 v[4:7], v[180:183], v[220:223], v[4:7]
	v_mfma_f32_16x16x32_bf16 v[0:3], v[184:187], v[220:223], v[0:3]
	v_xor_b32_e32 v226, 0x8000, v226
	v_xor_b32_e32 v228, 0x8000, v228
	s_waitcnt lgkmcnt(4)
	v_mfma_f32_16x16x32_bf16 v[124:127], v[152:155], v[188:191], v[124:127]
	v_mfma_f32_16x16x32_bf16 v[120:123], v[156:159], v[188:191], v[120:123]
	v_mfma_f32_16x16x32_bf16 v[116:119], v[160:163], v[188:191], v[116:119]
	v_mfma_f32_16x16x32_bf16 v[112:115], v[164:167], v[188:191], v[112:115]
	ds_read_b128 v[188:191], v226 offset:0
	ds_read_b128 v[168:171], v228 offset:0
	v_mfma_f32_16x16x32_bf16 v[108:111], v[152:155], v[192:195], v[108:111]
	v_mfma_f32_16x16x32_bf16 v[104:107], v[156:159], v[192:195], v[104:107]
	v_mfma_f32_16x16x32_bf16 v[100:103], v[160:163], v[192:195], v[100:103]
	v_mfma_f32_16x16x32_bf16 v[96:99], v[164:167], v[192:195], v[96:99]
	ds_read_b128 v[192:195], v226 offset:2048
	ds_read_b128 v[176:179], v228 offset:2048
	v_mfma_f32_16x16x32_bf16 v[92:95], v[152:155], v[196:199], v[92:95]
	v_mfma_f32_16x16x32_bf16 v[88:91], v[156:159], v[196:199], v[88:91]
	v_mfma_f32_16x16x32_bf16 v[84:87], v[160:163], v[196:199], v[84:87]
	v_mfma_f32_16x16x32_bf16 v[80:83], v[164:167], v[196:199], v[80:83]
	ds_read_b128 v[196:199], v226 offset:4096
	ds_read_b128 v[180:183], v228 offset:4096
	v_mfma_f32_16x16x32_bf16 v[76:79], v[152:155], v[200:203], v[76:79]
	v_mfma_f32_16x16x32_bf16 v[72:75], v[156:159], v[200:203], v[72:75]
	v_mfma_f32_16x16x32_bf16 v[68:71], v[160:163], v[200:203], v[68:71]
	v_mfma_f32_16x16x32_bf16 v[64:67], v[164:167], v[200:203], v[64:67]
	ds_read_b128 v[200:203], v226 offset:6144
	ds_read_b128 v[184:187], v228 offset:6144
	s_waitcnt lgkmcnt(11)
	v_mfma_f32_16x16x32_bf16 v[60:63], v[152:155], v[204:207], v[60:63]
	v_mfma_f32_16x16x32_bf16 v[56:59], v[156:159], v[204:207], v[56:59]
	v_mfma_f32_16x16x32_bf16 v[52:55], v[160:163], v[204:207], v[52:55]
	v_mfma_f32_16x16x32_bf16 v[48:51], v[164:167], v[204:207], v[48:51]
	ds_read_b128 v[204:207], v226 offset:8192
	ds_read_b128 v[220:223], v226 offset:14336
	s_waitcnt lgkmcnt(11)
	v_mfma_f32_16x16x32_bf16 v[44:47], v[152:155], v[208:211], v[44:47]
	v_mfma_f32_16x16x32_bf16 v[40:43], v[156:159], v[208:211], v[40:43]
	v_mfma_f32_16x16x32_bf16 v[36:39], v[160:163], v[208:211], v[36:39]
	v_mfma_f32_16x16x32_bf16 v[32:35], v[164:167], v[208:211], v[32:35]
	ds_read_b128 v[208:211], v226 offset:10240
	s_waitcnt lgkmcnt(11)
	v_mfma_f32_16x16x32_bf16 v[28:31], v[152:155], v[212:215], v[28:31]
	v_mfma_f32_16x16x32_bf16 v[24:27], v[156:159], v[212:215], v[24:27]
	v_mfma_f32_16x16x32_bf16 v[20:23], v[160:163], v[212:215], v[20:23]
	v_mfma_f32_16x16x32_bf16 v[16:19], v[164:167], v[212:215], v[16:19]
	ds_read_b128 v[212:215], v226 offset:12288
	v_mfma_f32_16x16x32_bf16 v[12:15], v[152:155], v[216:219], v[12:15]
	v_mfma_f32_16x16x32_bf16 v[8:11], v[156:159], v[216:219], v[8:11]
	v_mfma_f32_16x16x32_bf16 v[4:7], v[160:163], v[216:219], v[4:7]
	v_mfma_f32_16x16x32_bf16 v[0:3], v[164:167], v[216:219], v[0:3]
	s_waitcnt vmcnt(0) lgkmcnt(0)
	s_barrier
; DI u16 f2bf(float a) { return (u16)(pk2(a, 0.f) & 0xffffu); }
; DI float sigmoidf_(float x) { return __builtin_amdgcn_rcpf(1.f + __builtin_amdgcn_exp2f(-1.4426950408889634f * x)); }
; template <int EPI>
; DI void gemm_phase(const u16* __restrict__ A, int lda, const u16* __restrict__ Bt, int K, int N, u16* outb, int ldo,
;                    const float* r0, const float* r1, float* outf, char* lds, int bid, int nb) {
;     ...
;     } else {
;       const int col = (tn * 4 + wc) * 32 + l15;
; #pragma unroll
;       for (int i = 0; i < 8; ++i)
; #pragma unroll
;         for (int r = 0; r < 4; ++r) {
;           const float g0 = acc[i][0][r], u0 = acc[i][2][r], g1 = acc[i][1][r], u1 = acc[i][3][r];
;           u16* o0 = outb + (size_t)(mrow + i * 16 + r) * ldo + col;
;           o0[0] = f2bf(g0 * sigmoidf_(g0) * u0); o0[16] = f2bf(g1 * sigmoidf_(g1) * u1);
;         }
	v_mfma_f32_16x16x32_bf16 v[124:127], v[168:171], v[188:191], v[124:127]
	v_mfma_f32_16x16x32_bf16 v[120:123], v[176:179], v[188:191], v[120:123]
	v_mfma_f32_16x16x32_bf16 v[116:119], v[180:183], v[188:191], v[116:119]
	v_mfma_f32_16x16x32_bf16 v[112:115], v[184:187], v[188:191], v[112:115]
	v_mfma_f32_16x16x32_bf16 v[108:111], v[168:171], v[192:195], v[108:111]
	v_mfma_f32_16x16x32_bf16 v[104:107], v[176:179], v[192:195], v[104:107]
	v_mfma_f32_16x16x32_bf16 v[100:103], v[180:183], v[192:195], v[100:103]
	v_mfma_f32_16x16x32_bf16 v[96:99], v[184:187], v[192:195], v[96:99]
	v_mfma_f32_16x16x32_bf16 v[92:95], v[168:171], v[196:199], v[92:95]
	v_mfma_f32_16x16x32_bf16 v[88:91], v[176:179], v[196:199], v[88:91]
	v_mfma_f32_16x16x32_bf16 v[84:87], v[180:183], v[196:199], v[84:87]
	v_mfma_f32_16x16x32_bf16 v[80:83], v[184:187], v[196:199], v[80:83]
	v_mfma_f32_16x16x32_bf16 v[76:79], v[168:171], v[200:203], v[76:79]
	v_mfma_f32_16x16x32_bf16 v[72:75], v[176:179], v[200:203], v[72:75]
	v_mfma_f32_16x16x32_bf16 v[68:71], v[180:183], v[200:203], v[68:71]
	v_mfma_f32_16x16x32_bf16 v[64:67], v[184:187], v[200:203], v[64:67]
	v_mfma_f32_16x16x32_bf16 v[60:63], v[168:171], v[204:207], v[60:63]
	v_mfma_f32_16x16x32_bf16 v[56:59], v[176:179], v[204:207], v[56:59]
	v_mfma_f32_16x16x32_bf16 v[52:55], v[180:183], v[204:207], v[52:55]
	v_mfma_f32_16x16x32_bf16 v[48:51], v[184:187], v[204:207], v[48:51]
	v_mfma_f32_16x16x32_bf16 v[44:47], v[168:171], v[208:211], v[44:47]
	v_mfma_f32_16x16x32_bf16 v[40:43], v[176:179], v[208:211], v[40:43]
	v_mfma_f32_16x16x32_bf16 v[36:39], v[180:183], v[208:211], v[36:39]
	v_mfma_f32_16x16x32_bf16 v[32:35], v[184:187], v[208:211], v[32:35]
	v_mfma_f32_16x16x32_bf16 v[28:31], v[168:171], v[212:215], v[28:31]
	v_mfma_f32_16x16x32_bf16 v[24:27], v[176:179], v[212:215], v[24:27]
	v_mfma_f32_16x16x32_bf16 v[20:23], v[180:183], v[212:215], v[20:23]
	v_mfma_f32_16x16x32_bf16 v[16:19], v[184:187], v[212:215], v[16:19]
	v_mfma_f32_16x16x32_bf16 v[12:15], v[168:171], v[220:223], v[12:15]
	v_mfma_f32_16x16x32_bf16 v[8:11], v[176:179], v[220:223], v[8:11]
	v_mfma_f32_16x16x32_bf16 v[4:7], v[180:183], v[220:223], v[4:7]
	v_mfma_f32_16x16x32_bf16 v[0:3], v[184:187], v[220:223], v[0:3]
	s_nop 7
	s_nop 3
	v_and_b32_e32 v225, 15, v174
	v_lshrrev_b32_e32 v226, 8, v174
	v_lshl_or_b32 v225, v226, 7, v225
	v_bfe_u32 v226, v174, 6, 2
	v_bfe_u32 v227, v174, 4, 2
	v_lshlrev_b32_e32 v227, 2, v227
	v_add_u32_e32 v225, s49, v225
	v_lshl_add_u32 v226, v226, 5, v227
	v_lshl_or_b32 v226, s48, 7, v226
	v_lshlrev_b32_e32 v226, 1, v226
	v_mov_b32_e32 v227, 0x1600
	v_mad_u32_u24 v224, v225, v227, v226
	v_mul_f32_e32 v188, 0xbfb8aa3b, v124
	v_mul_f32_e32 v189, 0xbfb8aa3b, v125
	v_mul_f32_e32 v190, 0xbfb8aa3b, v126
	v_mul_f32_e32 v191, 0xbfb8aa3b, v127
	v_exp_f32_e32 v188, v188
	v_exp_f32_e32 v189, v189
	v_exp_f32_e32 v190, v190
	v_exp_f32_e32 v191, v191
	v_add_f32_e32 v188, 1.0, v188
	v_add_f32_e32 v189, 1.0, v189
	v_add_f32_e32 v190, 1.0, v190
	v_add_f32_e32 v191, 1.0, v191
	v_rcp_f32_e32 v188, v188
	v_rcp_f32_e32 v189, v189
	v_rcp_f32_e32 v190, v190
	v_rcp_f32_e32 v191, v191
	v_mul_f32_e32 v188, v124, v188
	v_mul_f32_e32 v189, v125, v189
	v_mul_f32_e32 v190, v126, v190
	v_mul_f32_e32 v191, v127, v191
	v_mul_f32_e32 v188, v116, v188
	v_mul_f32_e32 v189, v117, v189
	v_mul_f32_e32 v190, v118, v190
	v_mul_f32_e32 v191, v119, v191
	v_cvt_pk_bf16_f32 v200, v188, v189
	v_cvt_pk_bf16_f32 v201, v190, v191
	global_store_dwordx2 v224, v[200:201], s[8:9] offset:0
	v_mul_f32_e32 v188, 0xbfb8aa3b, v120
	v_mul_f32_e32 v189, 0xbfb8aa3b, v121
	v_mul_f32_e32 v190, 0xbfb8aa3b, v122
	v_mul_f32_e32 v191, 0xbfb8aa3b, v123
	v_exp_f32_e32 v188, v188
	v_exp_f32_e32 v189, v189
	v_exp_f32_e32 v190, v190
	v_exp_f32_e32 v191, v191
	v_add_f32_e32 v188, 1.0, v188
	v_add_f32_e32 v189, 1.0, v189
	v_add_f32_e32 v190, 1.0, v190
	v_add_f32_e32 v191, 1.0, v191
	v_rcp_f32_e32 v188, v188
	v_rcp_f32_e32 v189, v189
	v_rcp_f32_e32 v190, v190
	v_rcp_f32_e32 v191, v191
	v_mul_f32_e32 v188, v120, v188
	v_mul_f32_e32 v189, v121, v189
	v_mul_f32_e32 v190, v122, v190
	v_mul_f32_e32 v191, v123, v191
	v_mul_f32_e32 v188, v112, v188
	v_mul_f32_e32 v189, v113, v189
	v_mul_f32_e32 v190, v114, v190
	v_mul_f32_e32 v191, v115, v191
	v_cvt_pk_bf16_f32 v202, v188, v189
	v_cvt_pk_bf16_f32 v203, v190, v191
	global_store_dwordx2 v224, v[202:203], s[8:9] offset:32
	v_add_u32_e32 v224, 0x16000, v224
	v_mul_f32_e32 v188, 0xbfb8aa3b, v108
	v_mul_f32_e32 v189, 0xbfb8aa3b, v109
	v_mul_f32_e32 v190, 0xbfb8aa3b, v110
	v_mul_f32_e32 v191, 0xbfb8aa3b, v111
	v_exp_f32_e32 v188, v188
	v_exp_f32_e32 v189, v189
	v_exp_f32_e32 v190, v190
	v_exp_f32_e32 v191, v191
	v_add_f32_e32 v188, 1.0, v188
	v_add_f32_e32 v189, 1.0, v189
	v_add_f32_e32 v190, 1.0, v190
	v_add_f32_e32 v191, 1.0, v191
	v_rcp_f32_e32 v188, v188
	v_rcp_f32_e32 v189, v189
	v_rcp_f32_e32 v190, v190
	v_rcp_f32_e32 v191, v191
	v_mul_f32_e32 v188, v108, v188
	v_mul_f32_e32 v189, v109, v189
	v_mul_f32_e32 v190, v110, v190
	v_mul_f32_e32 v191, v111, v191
	v_mul_f32_e32 v188, v100, v188
	v_mul_f32_e32 v189, v101, v189
	v_mul_f32_e32 v190, v102, v190
	v_mul_f32_e32 v191, v103, v191
	v_cvt_pk_bf16_f32 v204, v188, v189
	v_cvt_pk_bf16_f32 v205, v190, v191
	global_store_dwordx2 v224, v[204:205], s[8:9] offset:0
	v_mul_f32_e32 v188, 0xbfb8aa3b, v104
	v_mul_f32_e32 v189, 0xbfb8aa3b, v105
	v_mul_f32_e32 v190, 0xbfb8aa3b, v106
	v_mul_f32_e32 v191, 0xbfb8aa3b, v107
	v_exp_f32_e32 v188, v188
	v_exp_f32_e32 v189, v189
	v_exp_f32_e32 v190, v190
	v_exp_f32_e32 v191, v191
	v_add_f32_e32 v188, 1.0, v188
	v_add_f32_e32 v189, 1.0, v189
	v_add_f32_e32 v190, 1.0, v190
	v_add_f32_e32 v191, 1.0, v191
; DI u16 f2bf(float a) { return (u16)(pk2(a, 0.f) & 0xffffu); }
; DI float sigmoidf_(float x) { return __builtin_amdgcn_rcpf(1.f + __builtin_amdgcn_exp2f(-1.4426950408889634f * x)); }
; template <int EPI>
; DI void gemm_phase(const u16* __restrict__ A, int lda, const u16* __restrict__ Bt, int K, int N, u16* outb, int ldo,
;                    const float* r0, const float* r1, float* outf, char* lds, int bid, int nb) {
;     ...
;       const int col = (tn * 4 + wc) * 32 + l15;
; #pragma unroll
;       for (int i = 0; i < 8; ++i)
; #pragma unroll
;         for (int r = 0; r < 4; ++r) {
;           const float g0 = acc[i][0][r], u0 = acc[i][2][r], g1 = acc[i][1][r], u1 = acc[i][3][r];
;           u16* o0 = outb + (size_t)(mrow + i * 16 + r) * ldo + col;
;           o0[0] = f2bf(g0 * sigmoidf_(g0) * u0); o0[16] = f2bf(g1 * sigmoidf_(g1) * u1);
;         }
	v_rcp_f32_e32 v188, v188
	v_rcp_f32_e32 v189, v189
	v_rcp_f32_e32 v190, v190
	v_rcp_f32_e32 v191, v191
	v_mul_f32_e32 v188, v104, v188
	v_mul_f32_e32 v189, v105, v189
	v_mul_f32_e32 v190, v106, v190
	v_mul_f32_e32 v191, v107, v191
	v_mul_f32_e32 v188, v96, v188
	v_mul_f32_e32 v189, v97, v189
	v_mul_f32_e32 v190, v98, v190
	v_mul_f32_e32 v191, v99, v191
	v_cvt_pk_bf16_f32 v206, v188, v189
	v_cvt_pk_bf16_f32 v207, v190, v191
	global_store_dwordx2 v224, v[206:207], s[8:9] offset:32
	v_add_u32_e32 v224, 0x16000, v224
	v_mul_f32_e32 v188, 0xbfb8aa3b, v92
	v_mul_f32_e32 v189, 0xbfb8aa3b, v93
	v_mul_f32_e32 v190, 0xbfb8aa3b, v94
	v_mul_f32_e32 v191, 0xbfb8aa3b, v95
	v_exp_f32_e32 v188, v188
	v_exp_f32_e32 v189, v189
	v_exp_f32_e32 v190, v190
	v_exp_f32_e32 v191, v191
	v_add_f32_e32 v188, 1.0, v188
	v_add_f32_e32 v189, 1.0, v189
	v_add_f32_e32 v190, 1.0, v190
	v_add_f32_e32 v191, 1.0, v191
	v_rcp_f32_e32 v188, v188
	v_rcp_f32_e32 v189, v189
	v_rcp_f32_e32 v190, v190
	v_rcp_f32_e32 v191, v191
	v_mul_f32_e32 v188, v92, v188
	v_mul_f32_e32 v189, v93, v189
	v_mul_f32_e32 v190, v94, v190
	v_mul_f32_e32 v191, v95, v191
	v_mul_f32_e32 v188, v84, v188
	v_mul_f32_e32 v189, v85, v189
	v_mul_f32_e32 v190, v86, v190
	v_mul_f32_e32 v191, v87, v191
	v_cvt_pk_bf16_f32 v208, v188, v189
	v_cvt_pk_bf16_f32 v209, v190, v191
	global_store_dwordx2 v224, v[208:209], s[8:9] offset:0
	v_mul_f32_e32 v188, 0xbfb8aa3b, v88
	v_mul_f32_e32 v189, 0xbfb8aa3b, v89
	v_mul_f32_e32 v190, 0xbfb8aa3b, v90
	v_mul_f32_e32 v191, 0xbfb8aa3b, v91
	v_exp_f32_e32 v188, v188
	v_exp_f32_e32 v189, v189
	v_exp_f32_e32 v190, v190
	v_exp_f32_e32 v191, v191
	v_add_f32_e32 v188, 1.0, v188
	v_add_f32_e32 v189, 1.0, v189
	v_add_f32_e32 v190, 1.0, v190
	v_add_f32_e32 v191, 1.0, v191
	v_rcp_f32_e32 v188, v188
	v_rcp_f32_e32 v189, v189
	v_rcp_f32_e32 v190, v190
	v_rcp_f32_e32 v191, v191
	v_mul_f32_e32 v188, v88, v188
	v_mul_f32_e32 v189, v89, v189
	v_mul_f32_e32 v190, v90, v190
	v_mul_f32_e32 v191, v91, v191
	v_mul_f32_e32 v188, v80, v188
	v_mul_f32_e32 v189, v81, v189
	v_mul_f32_e32 v190, v82, v190
	v_mul_f32_e32 v191, v83, v191
	v_cvt_pk_bf16_f32 v210, v188, v189
	v_cvt_pk_bf16_f32 v211, v190, v191
	global_store_dwordx2 v224, v[210:211], s[8:9] offset:32
	v_add_u32_e32 v224, 0x16000, v224
	v_mul_f32_e32 v188, 0xbfb8aa3b, v76
	v_mul_f32_e32 v189, 0xbfb8aa3b, v77
	v_mul_f32_e32 v190, 0xbfb8aa3b, v78
	v_mul_f32_e32 v191, 0xbfb8aa3b, v79
	v_exp_f32_e32 v188, v188
	v_exp_f32_e32 v189, v189
	v_exp_f32_e32 v190, v190
	v_exp_f32_e32 v191, v191
	v_add_f32_e32 v188, 1.0, v188
	v_add_f32_e32 v189, 1.0, v189
	v_add_f32_e32 v190, 1.0, v190
	v_add_f32_e32 v191, 1.0, v191
	v_rcp_f32_e32 v188, v188
	v_rcp_f32_e32 v189, v189
	v_rcp_f32_e32 v190, v190
	v_rcp_f32_e32 v191, v191
	v_mul_f32_e32 v188, v76, v188
	v_mul_f32_e32 v189, v77, v189
	v_mul_f32_e32 v190, v78, v190
	v_mul_f32_e32 v191, v79, v191
	v_mul_f32_e32 v188, v68, v188
	v_mul_f32_e32 v189, v69, v189
	v_mul_f32_e32 v190, v70, v190
	v_mul_f32_e32 v191, v71, v191
	v_cvt_pk_bf16_f32 v212, v188, v189
	v_cvt_pk_bf16_f32 v213, v190, v191
	global_store_dwordx2 v224, v[212:213], s[8:9] offset:0
	v_mul_f32_e32 v188, 0xbfb8aa3b, v72
	v_mul_f32_e32 v189, 0xbfb8aa3b, v73
	v_mul_f32_e32 v190, 0xbfb8aa3b, v74
	v_mul_f32_e32 v191, 0xbfb8aa3b, v75
	v_exp_f32_e32 v188, v188
	v_exp_f32_e32 v189, v189
	v_exp_f32_e32 v190, v190
	v_exp_f32_e32 v191, v191
	v_add_f32_e32 v188, 1.0, v188
	v_add_f32_e32 v189, 1.0, v189
	v_add_f32_e32 v190, 1.0, v190
	v_add_f32_e32 v191, 1.0, v191
	v_rcp_f32_e32 v188, v188
	v_rcp_f32_e32 v189, v189
	v_rcp_f32_e32 v190, v190
	v_rcp_f32_e32 v191, v191
	v_mul_f32_e32 v188, v72, v188
	v_mul_f32_e32 v189, v73, v189
	v_mul_f32_e32 v190, v74, v190
	v_mul_f32_e32 v191, v75, v191
	v_mul_f32_e32 v188, v64, v188
	v_mul_f32_e32 v189, v65, v189
	v_mul_f32_e32 v190, v66, v190
	v_mul_f32_e32 v191, v67, v191
	v_cvt_pk_bf16_f32 v214, v188, v189
	v_cvt_pk_bf16_f32 v215, v190, v191
	global_store_dwordx2 v224, v[214:215], s[8:9] offset:32
	v_add_u32_e32 v224, 0x16000, v224
	v_mul_f32_e32 v188, 0xbfb8aa3b, v60
	v_mul_f32_e32 v189, 0xbfb8aa3b, v61
	v_mul_f32_e32 v190, 0xbfb8aa3b, v62
	v_mul_f32_e32 v191, 0xbfb8aa3b, v63
	v_exp_f32_e32 v188, v188
	v_exp_f32_e32 v189, v189
	v_exp_f32_e32 v190, v190
	v_exp_f32_e32 v191, v191
	v_add_f32_e32 v188, 1.0, v188
	v_add_f32_e32 v189, 1.0, v189
	v_add_f32_e32 v190, 1.0, v190
	v_add_f32_e32 v191, 1.0, v191
	v_rcp_f32_e32 v188, v188
	v_rcp_f32_e32 v189, v189
	v_rcp_f32_e32 v190, v190
	v_rcp_f32_e32 v191, v191
	v_mul_f32_e32 v188, v60, v188
	v_mul_f32_e32 v189, v61, v189
	v_mul_f32_e32 v190, v62, v190
	v_mul_f32_e32 v191, v63, v191
	v_mul_f32_e32 v188, v52, v188
	v_mul_f32_e32 v189, v53, v189
	v_mul_f32_e32 v190, v54, v190
	v_mul_f32_e32 v191, v55, v191
	v_cvt_pk_bf16_f32 v200, v188, v189
	v_cvt_pk_bf16_f32 v201, v190, v191
	global_store_dwordx2 v224, v[200:201], s[8:9] offset:0
	v_mul_f32_e32 v188, 0xbfb8aa3b, v56
	v_mul_f32_e32 v189, 0xbfb8aa3b, v57
	v_mul_f32_e32 v190, 0xbfb8aa3b, v58
	v_mul_f32_e32 v191, 0xbfb8aa3b, v59
	v_exp_f32_e32 v188, v188
	v_exp_f32_e32 v189, v189
	v_exp_f32_e32 v190, v190
	v_exp_f32_e32 v191, v191
	v_add_f32_e32 v188, 1.0, v188
	v_add_f32_e32 v189, 1.0, v189
	v_add_f32_e32 v190, 1.0, v190
	v_add_f32_e32 v191, 1.0, v191
	v_rcp_f32_e32 v188, v188
	v_rcp_f32_e32 v189, v189
	v_rcp_f32_e32 v190, v190
	v_rcp_f32_e32 v191, v191
	v_mul_f32_e32 v188, v56, v188
	v_mul_f32_e32 v189, v57, v189
	v_mul_f32_e32 v190, v58, v190
	v_mul_f32_e32 v191, v59, v191
	v_mul_f32_e32 v188, v48, v188
; DI u16 f2bf(float a) { return (u16)(pk2(a, 0.f) & 0xffffu); }
; DI float sigmoidf_(float x) { return __builtin_amdgcn_rcpf(1.f + __builtin_amdgcn_exp2f(-1.4426950408889634f * x)); }
; template <int EPI>
; DI void gemm_phase(const u16* __restrict__ A, int lda, const u16* __restrict__ Bt, int K, int N, u16* outb, int ldo,
;                    const float* r0, const float* r1, float* outf, char* lds, int bid, int nb) {
;     ...
;       const int col = (tn * 4 + wc) * 32 + l15;
; #pragma unroll
;       for (int i = 0; i < 8; ++i)
; #pragma unroll
;         for (int r = 0; r < 4; ++r) {
;           const float g0 = acc[i][0][r], u0 = acc[i][2][r], g1 = acc[i][1][r], u1 = acc[i][3][r];
;           u16* o0 = outb + (size_t)(mrow + i * 16 + r) * ldo + col;
;           o0[0] = f2bf(g0 * sigmoidf_(g0) * u0); o0[16] = f2bf(g1 * sigmoidf_(g1) * u1);
;         }
	v_mul_f32_e32 v189, v49, v189
	v_mul_f32_e32 v190, v50, v190
	v_mul_f32_e32 v191, v51, v191
	v_cvt_pk_bf16_f32 v202, v188, v189
	v_cvt_pk_bf16_f32 v203, v190, v191
	global_store_dwordx2 v224, v[202:203], s[8:9] offset:32
	v_add_u32_e32 v224, 0x16000, v224
	v_mul_f32_e32 v188, 0xbfb8aa3b, v44
	v_mul_f32_e32 v189, 0xbfb8aa3b, v45
	v_mul_f32_e32 v190, 0xbfb8aa3b, v46
	v_mul_f32_e32 v191, 0xbfb8aa3b, v47
	v_exp_f32_e32 v188, v188
	v_exp_f32_e32 v189, v189
	v_exp_f32_e32 v190, v190
	v_exp_f32_e32 v191, v191
	v_add_f32_e32 v188, 1.0, v188
	v_add_f32_e32 v189, 1.0, v189
	v_add_f32_e32 v190, 1.0, v190
	v_add_f32_e32 v191, 1.0, v191
	v_rcp_f32_e32 v188, v188
	v_rcp_f32_e32 v189, v189
	v_rcp_f32_e32 v190, v190
	v_rcp_f32_e32 v191, v191
	v_mul_f32_e32 v188, v44, v188
	v_mul_f32_e32 v189, v45, v189
	v_mul_f32_e32 v190, v46, v190
	v_mul_f32_e32 v191, v47, v191
	v_mul_f32_e32 v188, v36, v188
	v_mul_f32_e32 v189, v37, v189
	v_mul_f32_e32 v190, v38, v190
	v_mul_f32_e32 v191, v39, v191
	v_cvt_pk_bf16_f32 v204, v188, v189
	v_cvt_pk_bf16_f32 v205, v190, v191
	global_store_dwordx2 v224, v[204:205], s[8:9] offset:0
	v_mul_f32_e32 v188, 0xbfb8aa3b, v40
	v_mul_f32_e32 v189, 0xbfb8aa3b, v41
	v_mul_f32_e32 v190, 0xbfb8aa3b, v42
	v_mul_f32_e32 v191, 0xbfb8aa3b, v43
	v_exp_f32_e32 v188, v188
	v_exp_f32_e32 v189, v189
	v_exp_f32_e32 v190, v190
	v_exp_f32_e32 v191, v191
	v_add_f32_e32 v188, 1.0, v188
	v_add_f32_e32 v189, 1.0, v189
	v_add_f32_e32 v190, 1.0, v190
	v_add_f32_e32 v191, 1.0, v191
	v_rcp_f32_e32 v188, v188
	v_rcp_f32_e32 v189, v189
	v_rcp_f32_e32 v190, v190
	v_rcp_f32_e32 v191, v191
	v_mul_f32_e32 v188, v40, v188
	v_mul_f32_e32 v189, v41, v189
	v_mul_f32_e32 v190, v42, v190
	v_mul_f32_e32 v191, v43, v191
	v_mul_f32_e32 v188, v32, v188
	v_mul_f32_e32 v189, v33, v189
	v_mul_f32_e32 v190, v34, v190
	v_mul_f32_e32 v191, v35, v191
	v_cvt_pk_bf16_f32 v206, v188, v189
	v_cvt_pk_bf16_f32 v207, v190, v191
	global_store_dwordx2 v224, v[206:207], s[8:9] offset:32
	v_add_u32_e32 v224, 0x16000, v224
	v_mul_f32_e32 v188, 0xbfb8aa3b, v28
	v_mul_f32_e32 v189, 0xbfb8aa3b, v29
	v_mul_f32_e32 v190, 0xbfb8aa3b, v30
	v_mul_f32_e32 v191, 0xbfb8aa3b, v31
	v_exp_f32_e32 v188, v188
	v_exp_f32_e32 v189, v189
	v_exp_f32_e32 v190, v190
	v_exp_f32_e32 v191, v191
	v_add_f32_e32 v188, 1.0, v188
	v_add_f32_e32 v189, 1.0, v189
	v_add_f32_e32 v190, 1.0, v190
	v_add_f32_e32 v191, 1.0, v191
	v_rcp_f32_e32 v188, v188
	v_rcp_f32_e32 v189, v189
	v_rcp_f32_e32 v190, v190
	v_rcp_f32_e32 v191, v191
	v_mul_f32_e32 v188, v28, v188
	v_mul_f32_e32 v189, v29, v189
	v_mul_f32_e32 v190, v30, v190
	v_mul_f32_e32 v191, v31, v191
	v_mul_f32_e32 v188, v20, v188
	v_mul_f32_e32 v189, v21, v189
	v_mul_f32_e32 v190, v22, v190
	v_mul_f32_e32 v191, v23, v191
	v_cvt_pk_bf16_f32 v208, v188, v189
	v_cvt_pk_bf16_f32 v209, v190, v191
	global_store_dwordx2 v224, v[208:209], s[8:9] offset:0
	v_mul_f32_e32 v188, 0xbfb8aa3b, v24
	v_mul_f32_e32 v189, 0xbfb8aa3b, v25
	v_mul_f32_e32 v190, 0xbfb8aa3b, v26
	v_mul_f32_e32 v191, 0xbfb8aa3b, v27
	v_exp_f32_e32 v188, v188
	v_exp_f32_e32 v189, v189
	v_exp_f32_e32 v190, v190
	v_exp_f32_e32 v191, v191
	v_add_f32_e32 v188, 1.0, v188
	v_add_f32_e32 v189, 1.0, v189
	v_add_f32_e32 v190, 1.0, v190
	v_add_f32_e32 v191, 1.0, v191
	v_rcp_f32_e32 v188, v188
	v_rcp_f32_e32 v189, v189
	v_rcp_f32_e32 v190, v190
	v_rcp_f32_e32 v191, v191
	v_mul_f32_e32 v188, v24, v188
	v_mul_f32_e32 v189, v25, v189
	v_mul_f32_e32 v190, v26, v190
	v_mul_f32_e32 v191, v27, v191
	v_mul_f32_e32 v188, v16, v188
	v_mul_f32_e32 v189, v17, v189
	v_mul_f32_e32 v190, v18, v190
	v_mul_f32_e32 v191, v19, v191
	v_cvt_pk_bf16_f32 v210, v188, v189
	v_cvt_pk_bf16_f32 v211, v190, v191
	global_store_dwordx2 v224, v[210:211], s[8:9] offset:32
	v_add_u32_e32 v224, 0x16000, v224
	v_mul_f32_e32 v188, 0xbfb8aa3b, v12
	v_mul_f32_e32 v189, 0xbfb8aa3b, v13
	v_mul_f32_e32 v190, 0xbfb8aa3b, v14
	v_mul_f32_e32 v191, 0xbfb8aa3b, v15
	v_exp_f32_e32 v188, v188
	v_exp_f32_e32 v189, v189
	v_exp_f32_e32 v190, v190
	v_exp_f32_e32 v191, v191
	v_add_f32_e32 v188, 1.0, v188
	v_add_f32_e32 v189, 1.0, v189
	v_add_f32_e32 v190, 1.0, v190
	v_add_f32_e32 v191, 1.0, v191
	v_rcp_f32_e32 v188, v188
	v_rcp_f32_e32 v189, v189
	v_rcp_f32_e32 v190, v190
	v_rcp_f32_e32 v191, v191
	v_mul_f32_e32 v188, v12, v188
	v_mul_f32_e32 v189, v13, v189
	v_mul_f32_e32 v190, v14, v190
	v_mul_f32_e32 v191, v15, v191
	v_mul_f32_e32 v188, v4, v188
	v_mul_f32_e32 v189, v5, v189
	v_mul_f32_e32 v190, v6, v190
	v_mul_f32_e32 v191, v7, v191
	v_cvt_pk_bf16_f32 v212, v188, v189
	v_cvt_pk_bf16_f32 v213, v190, v191
	global_store_dwordx2 v224, v[212:213], s[8:9] offset:0
	v_mul_f32_e32 v188, 0xbfb8aa3b, v8
	v_mul_f32_e32 v189, 0xbfb8aa3b, v9
	v_mul_f32_e32 v190, 0xbfb8aa3b, v10
	v_mul_f32_e32 v191, 0xbfb8aa3b, v11
	v_exp_f32_e32 v188, v188
	v_exp_f32_e32 v189, v189
	v_exp_f32_e32 v190, v190
	v_exp_f32_e32 v191, v191
	v_add_f32_e32 v188, 1.0, v188
	v_add_f32_e32 v189, 1.0, v189
	v_add_f32_e32 v190, 1.0, v190
	v_add_f32_e32 v191, 1.0, v191
	v_rcp_f32_e32 v188, v188
	v_rcp_f32_e32 v189, v189
	v_rcp_f32_e32 v190, v190
	v_rcp_f32_e32 v191, v191
	v_mul_f32_e32 v188, v8, v188
	v_mul_f32_e32 v189, v9, v189
	v_mul_f32_e32 v190, v10, v190
	v_mul_f32_e32 v191, v11, v191
	v_mul_f32_e32 v188, v0, v188
	v_mul_f32_e32 v189, v1, v189
	v_mul_f32_e32 v190, v2, v190
	v_mul_f32_e32 v191, v3, v191
	v_cvt_pk_bf16_f32 v214, v188, v189
	v_cvt_pk_bf16_f32 v215, v190, v191
	global_store_dwordx2 v224, v[214:215], s[8:9] offset:32
	s_add_i32 s19, s19, 1
	s_cmp_eq_u32 s19, s3
	s_cbranch_scc0 .LBB0_697

; #define G_LOAD(KT) do { _Pragma("unroll") for (int i = 0; i < 4; ++i) { ra[i] = *(const u32x4*)(Ag + (size_t)i * 64 * lda + (KT) * 64); rb[i] = *(const u32x4*)(Bg + (size_t)i * 64 * K + (KT) * 64); } } while (0)
; #define G_STORE(BUF) do { u16* ad = As + (BUF) * 256 * 64 + sto; u16* bd = Bs + (BUF) * 256 * 64 + sto; _Pragma("unroll") for (int i = 0; i < 4; ++i) { *(u32x4*)(ad + i * 64 * 64) = ra[i]; *(u32x4*)(bd + i * 64 * 64) = rb[i]; } } while (0)
; template <int EPI>
; DI void gemm_phase(const u16* __restrict__ A, int lda, const u16* __restrict__ Bt, int K, int N, u16* outb, int ldo,
;                    const float* r0, const float* r1, float* outf, char* lds, int bid, int nb) {
;     ...
;     if (swz) { const int st = xcd + 8 * it, sm = st / nSN, sn = st - sm * nSN; tm = sm * GM + jb / GN; tn = sn * GN + (jb % GN); }
;     else { const int t = bid + it * nb; tm = t / nN; tn = t - tm * nN; }
;     const u16* Ag = A + (size_t)(tm * 256 + lrow) * lda + lch * 8;
;     const u16* Bg = Bt + (size_t)(tn * 256 + lrow) * K + lch * 8;
;     f32x4 acc[8][4];
; #pragma unroll
;     for (int i = 0; i < 8; ++i)
; #pragma unroll
;       for (int j = 0; j < 4; ++j) acc[i][j] = (f32x4){0.f, 0.f, 0.f, 0.f};
;     u32x4 ra[4], rb[4];
;     ...
;     G_LOAD(0);
;     G_STORE(0);
;     __syncthreads();
;     for (int kt = 0; kt < nk; ++kt) {
;       const int cur = kt & 1;
;       if (kt + 1 < nk) G_LOAD(kt + 1);
;       G_MMA(cur, fo0);
.LBB0_763:
	s_lshl_b32 s39, s39, 8
	v_or_b32_e32 v60, s39, v138
	s_lshl_b32 s46, s46, 8
	v_mad_i64_i32 v[0:1], s[8:9], v60, s17, v[128:129]
	v_or_b32_e32 v61, s46, v138
	v_add_co_u32_e32 v4, vcc, 0x58000, v0
	v_mad_i64_i32 v[2:3], s[8:9], v61, s17, v[130:131]
	s_nop 0
	v_addc_co_u32_e32 v5, vcc, 0, v1, vcc
	v_add_co_u32_e32 v6, vcc, 0x58000, v2
	s_nop 1
	v_readfirstlane_b32 s98, v0
	v_readfirstlane_b32 s99, v1
	s_nop 1
	v_readfirstlane_b32 s100, v2
	v_readfirstlane_b32 s101, v3
	v_addc_co_u32_e32 v7, vcc, 0, v3, vcc
	v_add_co_u32_e32 v4, vcc, 0xb0000, v0
	s_mov_b32 s47, 0
	s_nop 0
	v_addc_co_u32_e32 v5, vcc, 0, v1, vcc
	v_add_co_u32_e32 v6, vcc, 0xb0000, v2
	s_mov_b64 s[8:9], 0
	s_nop 0
	v_addc_co_u32_e32 v7, vcc, 0, v3, vcc
	v_add_co_u32_e32 v0, vcc, 0x108000, v0
	v_addc_co_u32_e32 v1, vcc, 0, v1, vcc
	v_add_co_u32_e32 v2, vcc, 0x108000, v2
	v_mad_i64_i32 v[134:135], s[28:29], v60, s17, v[132:133]
	s_nop 0
	v_addc_co_u32_e32 v3, vcc, 0, v3, vcc
	v_mov_b32_e32 v0, 0
	v_mad_i64_i32 v[136:137], s[28:29], v61, s17, v[132:133]
	v_and_b32_e32 v229, 63, v174
	v_lshrrev_b32_e32 v230, 3, v229
	v_mov_b32_e32 v233, 0x1600
	v_mul_u32_u24_e32 v224, v230, v233
	v_bfe_u32 v231, v174, 4, 2
	v_bfe_u32 v232, v174, 6, 1
	v_lshl_or_b32 v232, v232, 2, v231
	v_and_b32_e32 v233, 7, v174
	v_xor_b32_e32 v232, v232, v233
	v_lshl_add_u32 v224, v232, 4, v224
	v_and_b32_e32 v229, 15, v174
	v_bfe_u32 v230, v174, 1, 3
	v_xor_b32_e32 v230, v230, v231
	v_lshlrev_b32_e32 v230, 4, v230
	v_lshl_or_b32 v230, v229, 7, v230
	v_lshrrev_b32_e32 v229, 8, v174
	v_lshl_or_b32 v225, v229, 14, v230
	v_bfe_u32 v229, v174, 6, 2
	v_lshl_or_b32 v227, v229, 13, v230
	v_or_b32_e32 v227, 0x10000, v227
	v_xor_b32_e32 v226, 64, v225
	v_xor_b32_e32 v228, 64, v227
	v_readfirstlane_b32 s97, v174
	s_lshl_b32 s97, s97, 4
	s_mov_b32 s28, 42
	s_add_u32 m0, s97, 0x0
	s_add_u32 s8, s98, 0x0
	s_addc_u32 s9, s99, 0
	global_load_lds_dwordx4 v224, s[8:9]
	s_add_u32 m0, s97, 0x10000
	s_add_u32 s8, s100, 0x0
	s_addc_u32 s9, s101, 0
	global_load_lds_dwordx4 v224, s[8:9]
	s_add_u32 m0, s97, 0x2000
	s_add_u32 s8, s98, 0x58000
	s_addc_u32 s9, s99, 0
	global_load_lds_dwordx4 v224, s[8:9]
	s_add_u32 m0, s97, 0x12000
	s_add_u32 s8, s100, 0x58000
	s_addc_u32 s9, s101, 0
	global_load_lds_dwordx4 v224, s[8:9]
	s_add_u32 m0, s97, 0x4000
	s_add_u32 s8, s98, 0xb0000
	s_addc_u32 s9, s99, 0
	global_load_lds_dwordx4 v224, s[8:9]
	s_add_u32 m0, s97, 0x14000
	s_add_u32 s8, s100, 0xb0000
	s_addc_u32 s9, s101, 0
	global_load_lds_dwordx4 v224, s[8:9]
	s_add_u32 m0, s97, 0x6000
	s_add_u32 s8, s98, 0x108000
	s_addc_u32 s9, s99, 0
	global_load_lds_dwordx4 v224, s[8:9]
	s_add_u32 m0, s97, 0x16000
	s_add_u32 s8, s100, 0x108000
	s_addc_u32 s9, s101, 0
	global_load_lds_dwordx4 v224, s[8:9]
	s_add_u32 m0, s97, 0x8000
	s_add_u32 s8, s98, 0x80
	s_addc_u32 s9, s99, 0
	global_load_lds_dwordx4 v224, s[8:9]
	s_add_u32 m0, s97, 0x18000
	s_add_u32 s8, s100, 0x80
	s_addc_u32 s9, s101, 0
	global_load_lds_dwordx4 v224, s[8:9]
	s_add_u32 m0, s97, 0xa000
	s_add_u32 s8, s98, 0x58080
	s_addc_u32 s9, s99, 0
	global_load_lds_dwordx4 v224, s[8:9]
	s_add_u32 m0, s97, 0x1a000
	s_add_u32 s8, s100, 0x58080
	s_addc_u32 s9, s101, 0
	global_load_lds_dwordx4 v224, s[8:9]
	s_add_u32 m0, s97, 0xc000
	s_add_u32 s8, s98, 0xb0080
	s_addc_u32 s9, s99, 0
	global_load_lds_dwordx4 v224, s[8:9]
	s_add_u32 m0, s97, 0x1c000
	s_add_u32 s8, s100, 0xb0080
	s_addc_u32 s9, s101, 0
	global_load_lds_dwordx4 v224, s[8:9]
	s_add_u32 m0, s97, 0xe000
	s_add_u32 s8, s98, 0x108080
	s_addc_u32 s9, s99, 0
	global_load_lds_dwordx4 v224, s[8:9]
	s_add_u32 m0, s97, 0x1e000
	s_add_u32 s8, s100, 0x108080
	s_addc_u32 s9, s101, 0
	global_load_lds_dwordx4 v224, s[8:9]
	s_add_u32 s98, s98, 0x100
	s_addc_u32 s99, s99, 0
	s_add_u32 s100, s100, 0x100
	s_addc_u32 s101, s101, 0
	s_waitcnt vmcnt(8)
	s_barrier
	ds_read_b128 v[152:155], v227 offset:0
	ds_read_b128 v[156:159], v227 offset:2048
	ds_read_b128 v[160:163], v227 offset:4096
	ds_read_b128 v[164:167], v227 offset:6144
	ds_read_b128 v[188:191], v225 offset:0
	ds_read_b128 v[192:195], v225 offset:2048
	ds_read_b128 v[196:199], v225 offset:4096
	ds_read_b128 v[200:203], v225 offset:6144
	ds_read_b128 v[204:207], v225 offset:8192
	ds_read_b128 v[208:211], v225 offset:10240
	ds_read_b128 v[212:215], v225 offset:12288
	ds_read_b128 v[216:219], v225 offset:14336
	v_xor_b32_e32 v225, 0x8000, v225
	v_xor_b32_e32 v227, 0x8000, v227
	s_waitcnt lgkmcnt(0)
	s_waitcnt lgkmcnt(4)
	v_mfma_f32_16x16x32_bf16 v[124:127], v[152:155], v[188:191], 0
	v_mfma_f32_16x16x32_bf16 v[120:123], v[156:159], v[188:191], 0
	v_mfma_f32_16x16x32_bf16 v[116:119], v[160:163], v[188:191], 0
	v_mfma_f32_16x16x32_bf16 v[112:115], v[164:167], v[188:191], 0
	ds_read_b128 v[188:191], v226 offset:0
	ds_read_b128 v[168:171], v228 offset:0
	v_mfma_f32_16x16x32_bf16 v[108:111], v[152:155], v[192:195], 0
	v_mfma_f32_16x16x32_bf16 v[104:107], v[156:159], v[192:195], 0
	v_mfma_f32_16x16x32_bf16 v[100:103], v[160:163], v[192:195], 0
	v_mfma_f32_16x16x32_bf16 v[96:99], v[164:167], v[192:195], 0
	ds_read_b128 v[192:195], v226 offset:2048
	ds_read_b128 v[176:179], v228 offset:2048
	v_mfma_f32_16x16x32_bf16 v[92:95], v[152:155], v[196:199], 0
	v_mfma_f32_16x16x32_bf16 v[88:91], v[156:159], v[196:199], 0
	v_mfma_f32_16x16x32_bf16 v[84:87], v[160:163], v[196:199], 0
	v_mfma_f32_16x16x32_bf16 v[80:83], v[164:167], v[196:199], 0
	ds_read_b128 v[196:199], v226 offset:4096
	ds_read_b128 v[180:183], v228 offset:4096
	v_mfma_f32_16x16x32_bf16 v[76:79], v[152:155], v[200:203], 0
	v_mfma_f32_16x16x32_bf16 v[72:75], v[156:159], v[200:203], 0
	v_mfma_f32_16x16x32_bf16 v[68:71], v[160:163], v[200:203], 0
	v_mfma_f32_16x16x32_bf16 v[64:67], v[164:167], v[200:203], 0
	ds_read_b128 v[200:203], v226 offset:6144
	ds_read_b128 v[184:187], v228 offset:6144
	s_waitcnt lgkmcnt(11)
	v_mfma_f32_16x16x32_bf16 v[60:63], v[152:155], v[204:207], 0
	v_mfma_f32_16x16x32_bf16 v[56:59], v[156:159], v[204:207], 0
	v_mfma_f32_16x16x32_bf16 v[52:55], v[160:163], v[204:207], 0
	v_mfma_f32_16x16x32_bf16 v[48:51], v[164:167], v[204:207], 0
	ds_read_b128 v[204:207], v226 offset:8192
	ds_read_b128 v[220:223], v226 offset:14336
	s_waitcnt lgkmcnt(11)
	v_mfma_f32_16x16x32_bf16 v[44:47], v[152:155], v[208:211], 0
	v_mfma_f32_16x16x32_bf16 v[40:43], v[156:159], v[208:211], 0
	v_mfma_f32_16x16x32_bf16 v[36:39], v[160:163], v[208:211], 0
	v_mfma_f32_16x16x32_bf16 v[32:35], v[164:167], v[208:211], 0
	ds_read_b128 v[208:211], v226 offset:10240
	s_waitcnt lgkmcnt(11)
	v_mfma_f32_16x16x32_bf16 v[28:31], v[152:155], v[212:215], 0
	v_mfma_f32_16x16x32_bf16 v[24:27], v[156:159], v[212:215], 0
	v_mfma_f32_16x16x32_bf16 v[20:23], v[160:163], v[212:215], 0
	v_mfma_f32_16x16x32_bf16 v[16:19], v[164:167], v[212:215], 0
	ds_read_b128 v[212:215], v226 offset:12288
	v_mfma_f32_16x16x32_bf16 v[12:15], v[152:155], v[216:219], 0
	v_mfma_f32_16x16x32_bf16 v[8:11], v[156:159], v[216:219], 0
	v_mfma_f32_16x16x32_bf16 v[4:7], v[160:163], v[216:219], 0
	v_mfma_f32_16x16x32_bf16 v[0:3], v[164:167], v[216:219], 0
	s_branch .Lgm3_mid0

; #define G_LOAD(KT) do { _Pragma("unroll") for (int i = 0; i < 4; ++i) { ra[i] = *(const u32x4*)(Ag + (size_t)i * 64 * lda + (KT) * 64); rb[i] = *(const u32x4*)(Bg + (size_t)i * 64 * K + (KT) * 64); } } while (0)
; #define G_STORE(BUF) do { u16* ad = As + (BUF) * 256 * 64 + sto; u16* bd = Bs + (BUF) * 256 * 64 + sto; _Pragma("unroll") for (int i = 0; i < 4; ++i) { *(u32x4*)(ad + i * 64 * 64) = ra[i]; *(u32x4*)(bd + i * 64 * 64) = rb[i]; } } while (0)
; template <int EPI>
; DI void gemm_phase(const u16* __restrict__ A, int lda, const u16* __restrict__ Bt, int K, int N, u16* outb, int ldo,
;                    const float* r0, const float* r1, float* outf, char* lds, int bid, int nb) {
;     ...
;     for (int kt = 0; kt < nk; ++kt) {
;       const int cur = kt & 1;
;       if (kt + 1 < nk) G_LOAD(kt + 1);
;       G_MMA(cur, fo0);
;       G_MMA(cur, fo1);
;       if (kt + 1 < nk) G_STORE(cur ^ 1);
;       __syncthreads();
;     }
.Lgm3_mid0:
	s_waitcnt vmcnt(0) lgkmcnt(0)
	s_barrier
	v_mfma_f32_16x16x32_bf16 v[124:127], v[168:171], v[188:191], v[124:127]
	v_mfma_f32_16x16x32_bf16 v[120:123], v[176:179], v[188:191], v[120:123]
	v_mfma_f32_16x16x32_bf16 v[116:119], v[180:183], v[188:191], v[116:119]
	v_mfma_f32_16x16x32_bf16 v[112:115], v[184:187], v[188:191], v[112:115]
	ds_read_b128 v[188:191], v225 offset:0
	ds_read_b128 v[152:155], v227 offset:0
	s_add_u32 m0, s97, 0x0
	s_add_u32 s8, s98, 0x0
	s_addc_u32 s9, s99, 0
	global_load_lds_dwordx4 v224, s[8:9]
	v_mfma_f32_16x16x32_bf16 v[108:111], v[168:171], v[192:195], v[108:111]
	v_mfma_f32_16x16x32_bf16 v[104:107], v[176:179], v[192:195], v[104:107]
	v_mfma_f32_16x16x32_bf16 v[100:103], v[180:183], v[192:195], v[100:103]
	v_mfma_f32_16x16x32_bf16 v[96:99], v[184:187], v[192:195], v[96:99]
	ds_read_b128 v[192:195], v225 offset:2048
	ds_read_b128 v[156:159], v227 offset:2048
	s_add_u32 m0, s97, 0x10000
	s_add_u32 s8, s100, 0x0
	s_addc_u32 s9, s101, 0
	global_load_lds_dwordx4 v224, s[8:9]
	v_mfma_f32_16x16x32_bf16 v[92:95], v[168:171], v[196:199], v[92:95]
	v_mfma_f32_16x16x32_bf16 v[88:91], v[176:179], v[196:199], v[88:91]
	v_mfma_f32_16x16x32_bf16 v[84:87], v[180:183], v[196:199], v[84:87]
	v_mfma_f32_16x16x32_bf16 v[80:83], v[184:187], v[196:199], v[80:83]
	ds_read_b128 v[196:199], v225 offset:4096
	ds_read_b128 v[160:163], v227 offset:4096
	s_add_u32 m0, s97, 0x2000
	s_add_u32 s8, s98, 0x58000
	s_addc_u32 s9, s99, 0
	global_load_lds_dwordx4 v224, s[8:9]
	v_mfma_f32_16x16x32_bf16 v[76:79], v[168:171], v[200:203], v[76:79]
	v_mfma_f32_16x16x32_bf16 v[72:75], v[176:179], v[200:203], v[72:75]
	v_mfma_f32_16x16x32_bf16 v[68:71], v[180:183], v[200:203], v[68:71]
	v_mfma_f32_16x16x32_bf16 v[64:67], v[184:187], v[200:203], v[64:67]
	ds_read_b128 v[200:203], v225 offset:6144
	ds_read_b128 v[164:167], v227 offset:6144
	s_add_u32 m0, s97, 0x12000
	s_add_u32 s8, s100, 0x58000
	s_addc_u32 s9, s101, 0
	global_load_lds_dwordx4 v224, s[8:9]
	v_mfma_f32_16x16x32_bf16 v[60:63], v[168:171], v[204:207], v[60:63]
	v_mfma_f32_16x16x32_bf16 v[56:59], v[176:179], v[204:207], v[56:59]
	v_mfma_f32_16x16x32_bf16 v[52:55], v[180:183], v[204:207], v[52:55]
	v_mfma_f32_16x16x32_bf16 v[48:51], v[184:187], v[204:207], v[48:51]
	ds_read_b128 v[204:207], v225 offset:8192
	ds_read_b128 v[216:219], v225 offset:14336
	s_add_u32 m0, s97, 0x4000
	s_add_u32 s8, s98, 0xb0000
	s_addc_u32 s9, s99, 0
	global_load_lds_dwordx4 v224, s[8:9]
	v_mfma_f32_16x16x32_bf16 v[44:47], v[168:171], v[208:211], v[44:47]
	v_mfma_f32_16x16x32_bf16 v[40:43], v[176:179], v[208:211], v[40:43]
	v_mfma_f32_16x16x32_bf16 v[36:39], v[180:183], v[208:211], v[36:39]
	v_mfma_f32_16x16x32_bf16 v[32:35], v[184:187], v[208:211], v[32:35]
	ds_read_b128 v[208:211], v225 offset:10240
	s_add_u32 m0, s97, 0x14000
	s_add_u32 s8, s100, 0xb0000
	s_addc_u32 s9, s101, 0
	global_load_lds_dwordx4 v224, s[8:9]
	v_mfma_f32_16x16x32_bf16 v[28:31], v[168:171], v[212:215], v[28:31]
	v_mfma_f32_16x16x32_bf16 v[24:27], v[176:179], v[212:215], v[24:27]
	v_mfma_f32_16x16x32_bf16 v[20:23], v[180:183], v[212:215], v[20:23]
	v_mfma_f32_16x16x32_bf16 v[16:19], v[184:187], v[212:215], v[16:19]
	ds_read_b128 v[212:215], v225 offset:12288
	s_add_u32 m0, s97, 0x6000
	s_add_u32 s8, s98, 0x108000
	s_addc_u32 s9, s99, 0
	global_load_lds_dwordx4 v224, s[8:9]
	v_mfma_f32_16x16x32_bf16 v[12:15], v[168:171], v[220:223], v[12:15]
	v_mfma_f32_16x16x32_bf16 v[8:11], v[176:179], v[220:223], v[8:11]
	v_mfma_f32_16x16x32_bf16 v[4:7], v[180:183], v[220:223], v[4:7]
	v_mfma_f32_16x16x32_bf16 v[0:3], v[184:187], v[220:223], v[0:3]
	s_add_u32 m0, s97, 0x16000
	s_add_u32 s8, s100, 0x108000
	s_addc_u32 s9, s101, 0
	global_load_lds_dwordx4 v224, s[8:9]
	v_xor_b32_e32 v225, 0x8000, v225
	v_xor_b32_e32 v227, 0x8000, v227
	v_xor_b32_e32 v226, 0x8000, v226
	v_xor_b32_e32 v228, 0x8000, v228
	s_xor_b32 s97, s97, 0x8000
	s_add_u32 s98, s98, 0x80
	s_addc_u32 s99, s99, 0
	s_add_u32 s100, s100, 0x80
	s_addc_u32 s101, s101, 0
	s_sub_u32 s28, s28, 1
	s_cmp_lg_u32 s28, 0
	s_cbranch_scc1 .Lgm3_loop
	s_waitcnt lgkmcnt(4)
	v_mfma_f32_16x16x32_bf16 v[124:127], v[152:155], v[188:191], v[124:127]
	v_mfma_f32_16x16x32_bf16 v[120:123], v[156:159], v[188:191], v[120:123]
	v_mfma_f32_16x16x32_bf16 v[116:119], v[160:163], v[188:191], v[116:119]
	v_mfma_f32_16x16x32_bf16 v[112:115], v[164:167], v[188:191], v[112:115]
	ds_read_b128 v[188:191], v226 offset:0
	ds_read_b128 v[168:171], v228 offset:0
	v_mfma_f32_16x16x32_bf16 v[108:111], v[152:155], v[192:195], v[108:111]
	v_mfma_f32_16x16x32_bf16 v[104:107], v[156:159], v[192:195], v[104:107]
	v_mfma_f32_16x16x32_bf16 v[100:103], v[160:163], v[192:195], v[100:103]
	v_mfma_f32_16x16x32_bf16 v[96:99], v[164:167], v[192:195], v[96:99]
	ds_read_b128 v[192:195], v226 offset:2048
	ds_read_b128 v[176:179], v228 offset:2048
	v_mfma_f32_16x16x32_bf16 v[92:95], v[152:155], v[196:199], v[92:95]
	v_mfma_f32_16x16x32_bf16 v[88:91], v[156:159], v[196:199], v[88:91]
	v_mfma_f32_16x16x32_bf16 v[84:87], v[160:163], v[196:199], v[84:87]
	v_mfma_f32_16x16x32_bf16 v[80:83], v[164:167], v[196:199], v[80:83]
	ds_read_b128 v[196:199], v226 offset:4096
	ds_read_b128 v[180:183], v228 offset:4096
	v_mfma_f32_16x16x32_bf16 v[76:79], v[152:155], v[200:203], v[76:79]
	v_mfma_f32_16x16x32_bf16 v[72:75], v[156:159], v[200:203], v[72:75]
	v_mfma_f32_16x16x32_bf16 v[68:71], v[160:163], v[200:203], v[68:71]
	v_mfma_f32_16x16x32_bf16 v[64:67], v[164:167], v[200:203], v[64:67]
	ds_read_b128 v[200:203], v226 offset:6144
	ds_read_b128 v[184:187], v228 offset:6144
	s_waitcnt lgkmcnt(11)
	v_mfma_f32_16x16x32_bf16 v[60:63], v[152:155], v[204:207], v[60:63]
	v_mfma_f32_16x16x32_bf16 v[56:59], v[156:159], v[204:207], v[56:59]
	v_mfma_f32_16x16x32_bf16 v[52:55], v[160:163], v[204:207], v[52:55]
	v_mfma_f32_16x16x32_bf16 v[48:51], v[164:167], v[204:207], v[48:51]
	ds_read_b128 v[204:207], v226 offset:8192
	ds_read_b128 v[220:223], v226 offset:14336
	s_waitcnt lgkmcnt(11)
	v_mfma_f32_16x16x32_bf16 v[44:47], v[152:155], v[208:211], v[44:47]
	v_mfma_f32_16x16x32_bf16 v[40:43], v[156:159], v[208:211], v[40:43]
	v_mfma_f32_16x16x32_bf16 v[36:39], v[160:163], v[208:211], v[36:39]
	v_mfma_f32_16x16x32_bf16 v[32:35], v[164:167], v[208:211], v[32:35]
	ds_read_b128 v[208:211], v226 offset:10240
	s_waitcnt lgkmcnt(11)
	v_mfma_f32_16x16x32_bf16 v[28:31], v[152:155], v[212:215], v[28:31]
	v_mfma_f32_16x16x32_bf16 v[24:27], v[156:159], v[212:215], v[24:27]
	v_mfma_f32_16x16x32_bf16 v[20:23], v[160:163], v[212:215], v[20:23]
	v_mfma_f32_16x16x32_bf16 v[16:19], v[164:167], v[212:215], v[16:19]
	ds_read_b128 v[212:215], v226 offset:12288
	v_mfma_f32_16x16x32_bf16 v[12:15], v[152:155], v[216:219], v[12:15]
	v_mfma_f32_16x16x32_bf16 v[8:11], v[156:159], v[216:219], v[8:11]
	v_mfma_f32_16x16x32_bf16 v[4:7], v[160:163], v[216:219], v[4:7]
	v_mfma_f32_16x16x32_bf16 v[0:3], v[164:167], v[216:219], v[0:3]
	s_waitcnt vmcnt(0) lgkmcnt(0)
	s_barrier
; #define G_LOAD(KT) do { _Pragma("unroll") for (int i = 0; i < 4; ++i) { ra[i] = *(const u32x4*)(Ag + (size_t)i * 64 * lda + (KT) * 64); rb[i] = *(const u32x4*)(Bg + (size_t)i * 64 * K + (KT) * 64); } } while (0)
; #define G_STORE(BUF) do { u16* ad = As + (BUF) * 256 * 64 + sto; u16* bd = Bs + (BUF) * 256 * 64 + sto; _Pragma("unroll") for (int i = 0; i < 4; ++i) { *(u32x4*)(ad + i * 64 * 64) = ra[i]; *(u32x4*)(bd + i * 64 * 64) = rb[i]; } } while (0)
; template <int EPI>
; DI void gemm_phase(const u16* __restrict__ A, int lda, const u16* __restrict__ Bt, int K, int N, u16* outb, int ldo,
;                    const float* r0, const float* r1, float* outf, char* lds, int bid, int nb) {
;     ...
;     for (int kt = 0; kt < nk; ++kt) {
;       const int cur = kt & 1;
;       if (kt + 1 < nk) G_LOAD(kt + 1);
;       G_MMA(cur, fo0);
;       G_MMA(cur, fo1);
;       if (kt + 1 < nk) G_STORE(cur ^ 1);
;       __syncthreads();
;     }
	v_mfma_f32_16x16x32_bf16 v[124:127], v[168:171], v[188:191], v[124:127]
	v_mfma_f32_16x16x32_bf16 v[120:123], v[176:179], v[188:191], v[120:123]
	v_mfma_f32_16x16x32_bf16 v[116:119], v[180:183], v[188:191], v[116:119]
	v_mfma_f32_16x16x32_bf16 v[112:115], v[184:187], v[188:191], v[112:115]
	ds_read_b128 v[188:191], v225 offset:0
	ds_read_b128 v[152:155], v227 offset:0
	v_mfma_f32_16x16x32_bf16 v[108:111], v[168:171], v[192:195], v[108:111]
	v_mfma_f32_16x16x32_bf16 v[104:107], v[176:179], v[192:195], v[104:107]
	v_mfma_f32_16x16x32_bf16 v[100:103], v[180:183], v[192:195], v[100:103]
	v_mfma_f32_16x16x32_bf16 v[96:99], v[184:187], v[192:195], v[96:99]
	ds_read_b128 v[192:195], v225 offset:2048
	ds_read_b128 v[156:159], v227 offset:2048
	v_mfma_f32_16x16x32_bf16 v[92:95], v[168:171], v[196:199], v[92:95]
	v_mfma_f32_16x16x32_bf16 v[88:91], v[176:179], v[196:199], v[88:91]
	v_mfma_f32_16x16x32_bf16 v[84:87], v[180:183], v[196:199], v[84:87]
	v_mfma_f32_16x16x32_bf16 v[80:83], v[184:187], v[196:199], v[80:83]
	ds_read_b128 v[196:199], v225 offset:4096
	ds_read_b128 v[160:163], v227 offset:4096
	v_mfma_f32_16x16x32_bf16 v[76:79], v[168:171], v[200:203], v[76:79]
	v_mfma_f32_16x16x32_bf16 v[72:75], v[176:179], v[200:203], v[72:75]
	v_mfma_f32_16x16x32_bf16 v[68:71], v[180:183], v[200:203], v[68:71]
	v_mfma_f32_16x16x32_bf16 v[64:67], v[184:187], v[200:203], v[64:67]
	ds_read_b128 v[200:203], v225 offset:6144
	ds_read_b128 v[164:167], v227 offset:6144
	v_mfma_f32_16x16x32_bf16 v[60:63], v[168:171], v[204:207], v[60:63]
	v_mfma_f32_16x16x32_bf16 v[56:59], v[176:179], v[204:207], v[56:59]
	v_mfma_f32_16x16x32_bf16 v[52:55], v[180:183], v[204:207], v[52:55]
	v_mfma_f32_16x16x32_bf16 v[48:51], v[184:187], v[204:207], v[48:51]
	ds_read_b128 v[204:207], v225 offset:8192
	ds_read_b128 v[216:219], v225 offset:14336
	v_mfma_f32_16x16x32_bf16 v[44:47], v[168:171], v[208:211], v[44:47]
	v_mfma_f32_16x16x32_bf16 v[40:43], v[176:179], v[208:211], v[40:43]
	v_mfma_f32_16x16x32_bf16 v[36:39], v[180:183], v[208:211], v[36:39]
	v_mfma_f32_16x16x32_bf16 v[32:35], v[184:187], v[208:211], v[32:35]
	ds_read_b128 v[208:211], v225 offset:10240
	v_mfma_f32_16x16x32_bf16 v[28:31], v[168:171], v[212:215], v[28:31]
	v_mfma_f32_16x16x32_bf16 v[24:27], v[176:179], v[212:215], v[24:27]
	v_mfma_f32_16x16x32_bf16 v[20:23], v[180:183], v[212:215], v[20:23]
	v_mfma_f32_16x16x32_bf16 v[16:19], v[184:187], v[212:215], v[16:19]
	ds_read_b128 v[212:215], v225 offset:12288
	v_mfma_f32_16x16x32_bf16 v[12:15], v[168:171], v[220:223], v[12:15]
	v_mfma_f32_16x16x32_bf16 v[8:11], v[176:179], v[220:223], v[8:11]
	v_mfma_f32_16x16x32_bf16 v[4:7], v[180:183], v[220:223], v[4:7]
	v_mfma_f32_16x16x32_bf16 v[0:3], v[184:187], v[220:223], v[0:3]
	v_xor_b32_e32 v226, 0x8000, v226
	v_xor_b32_e32 v228, 0x8000, v228
	s_waitcnt lgkmcnt(4)
	v_mfma_f32_16x16x32_bf16 v[124:127], v[152:155], v[188:191], v[124:127]
	v_mfma_f32_16x16x32_bf16 v[120:123], v[156:159], v[188:191], v[120:123]
	v_mfma_f32_16x16x32_bf16 v[116:119], v[160:163], v[188:191], v[116:119]
	v_mfma_f32_16x16x32_bf16 v[112:115], v[164:167], v[188:191], v[112:115]
	ds_read_b128 v[188:191], v226 offset:0
	ds_read_b128 v[168:171], v228 offset:0
	v_mfma_f32_16x16x32_bf16 v[108:111], v[152:155], v[192:195], v[108:111]
	v_mfma_f32_16x16x32_bf16 v[104:107], v[156:159], v[192:195], v[104:107]
	v_mfma_f32_16x16x32_bf16 v[100:103], v[160:163], v[192:195], v[100:103]
	v_mfma_f32_16x16x32_bf16 v[96:99], v[164:167], v[192:195], v[96:99]
	ds_read_b128 v[192:195], v226 offset:2048
	ds_read_b128 v[176:179], v228 offset:2048
	v_mfma_f32_16x16x32_bf16 v[92:95], v[152:155], v[196:199], v[92:95]
	v_mfma_f32_16x16x32_bf16 v[88:91], v[156:159], v[196:199], v[88:91]
	v_mfma_f32_16x16x32_bf16 v[84:87], v[160:163], v[196:199], v[84:87]
	v_mfma_f32_16x16x32_bf16 v[80:83], v[164:167], v[196:199], v[80:83]
	ds_read_b128 v[196:199], v226 offset:4096
	ds_read_b128 v[180:183], v228 offset:4096
	v_mfma_f32_16x16x32_bf16 v[76:79], v[152:155], v[200:203], v[76:79]
	v_mfma_f32_16x16x32_bf16 v[72:75], v[156:159], v[200:203], v[72:75]
	v_mfma_f32_16x16x32_bf16 v[68:71], v[160:163], v[200:203], v[68:71]
	v_mfma_f32_16x16x32_bf16 v[64:67], v[164:167], v[200:203], v[64:67]
	ds_read_b128 v[200:203], v226 offset:6144
	ds_read_b128 v[184:187], v228 offset:6144
	s_waitcnt lgkmcnt(11)
	v_mfma_f32_16x16x32_bf16 v[60:63], v[152:155], v[204:207], v[60:63]
	v_mfma_f32_16x16x32_bf16 v[56:59], v[156:159], v[204:207], v[56:59]
	v_mfma_f32_16x16x32_bf16 v[52:55], v[160:163], v[204:207], v[52:55]
	v_mfma_f32_16x16x32_bf16 v[48:51], v[164:167], v[204:207], v[48:51]
	ds_read_b128 v[204:207], v226 offset:8192
	ds_read_b128 v[220:223], v226 offset:14336
	s_waitcnt lgkmcnt(11)
	v_mfma_f32_16x16x32_bf16 v[44:47], v[152:155], v[208:211], v[44:47]
	v_mfma_f32_16x16x32_bf16 v[40:43], v[156:159], v[208:211], v[40:43]
	v_mfma_f32_16x16x32_bf16 v[36:39], v[160:163], v[208:211], v[36:39]
	v_mfma_f32_16x16x32_bf16 v[32:35], v[164:167], v[208:211], v[32:35]
	ds_read_b128 v[208:211], v226 offset:10240
	s_waitcnt lgkmcnt(11)
	v_mfma_f32_16x16x32_bf16 v[28:31], v[152:155], v[212:215], v[28:31]
	v_mfma_f32_16x16x32_bf16 v[24:27], v[156:159], v[212:215], v[24:27]
	v_mfma_f32_16x16x32_bf16 v[20:23], v[160:163], v[212:215], v[20:23]
	v_mfma_f32_16x16x32_bf16 v[16:19], v[164:167], v[212:215], v[16:19]
	ds_read_b128 v[212:215], v226 offset:12288
	v_mfma_f32_16x16x32_bf16 v[12:15], v[152:155], v[216:219], v[12:15]
	v_mfma_f32_16x16x32_bf16 v[8:11], v[156:159], v[216:219], v[8:11]
	v_mfma_f32_16x16x32_bf16 v[4:7], v[160:163], v[216:219], v[4:7]
	v_mfma_f32_16x16x32_bf16 v[0:3], v[164:167], v[216:219], v[0:3]
	s_waitcnt vmcnt(0) lgkmcnt(0)
	s_barrier
; template <int EPI>
; DI void gemm_phase(const u16* __restrict__ A, int lda, const u16* __restrict__ Bt, int K, int N, u16* outb, int ldo,
;                    const float* r0, const float* r1, float* outf, char* lds, int bid, int nb) {
;     ...
;       const int col = tn * 256 + wc * 64 + l15;
;       const float* rb_ = (tm * 256 < M_P) ? r0 : (r1 - (size_t)M_P * DM);
; #pragma unroll
;       for (int i = 0; i < 8; ++i)
; #pragma unroll
;         for (int r = 0; r < 4; ++r) {
;           const size_t i0 = (size_t)(mrow + i * 16 + r) * DM + col;
;           const float x0 = rb_[i0], x1 = rb_[i0 + 16], x2 = rb_[i0 + 32], x3 = rb_[i0 + 48];
;           outf[i0] = x0 + acc[i][0][r]; outf[i0 + 16] = x1 + acc[i][1][r]; outf[i0 + 32] = x2 + acc[i][2][r]; outf[i0 + 48] = x3 + acc[i][3][r];
	v_mfma_f32_16x16x32_bf16 v[124:127], v[168:171], v[188:191], v[124:127]
	v_mfma_f32_16x16x32_bf16 v[120:123], v[176:179], v[188:191], v[120:123]
	v_mfma_f32_16x16x32_bf16 v[116:119], v[180:183], v[188:191], v[116:119]
	v_mfma_f32_16x16x32_bf16 v[112:115], v[184:187], v[188:191], v[112:115]
	v_mfma_f32_16x16x32_bf16 v[108:111], v[168:171], v[192:195], v[108:111]
	v_mfma_f32_16x16x32_bf16 v[104:107], v[176:179], v[192:195], v[104:107]
	v_mfma_f32_16x16x32_bf16 v[100:103], v[180:183], v[192:195], v[100:103]
	v_mfma_f32_16x16x32_bf16 v[96:99], v[184:187], v[192:195], v[96:99]
	v_mfma_f32_16x16x32_bf16 v[92:95], v[168:171], v[196:199], v[92:95]
	v_mfma_f32_16x16x32_bf16 v[88:91], v[176:179], v[196:199], v[88:91]
	v_mfma_f32_16x16x32_bf16 v[84:87], v[180:183], v[196:199], v[84:87]
	v_mfma_f32_16x16x32_bf16 v[80:83], v[184:187], v[196:199], v[80:83]
	v_mfma_f32_16x16x32_bf16 v[76:79], v[168:171], v[200:203], v[76:79]
	v_mfma_f32_16x16x32_bf16 v[72:75], v[176:179], v[200:203], v[72:75]
	v_mfma_f32_16x16x32_bf16 v[68:71], v[180:183], v[200:203], v[68:71]
	v_mfma_f32_16x16x32_bf16 v[64:67], v[184:187], v[200:203], v[64:67]
	v_mfma_f32_16x16x32_bf16 v[60:63], v[168:171], v[204:207], v[60:63]
	v_mfma_f32_16x16x32_bf16 v[56:59], v[176:179], v[204:207], v[56:59]
	v_mfma_f32_16x16x32_bf16 v[52:55], v[180:183], v[204:207], v[52:55]
	v_mfma_f32_16x16x32_bf16 v[48:51], v[184:187], v[204:207], v[48:51]
	v_mfma_f32_16x16x32_bf16 v[44:47], v[168:171], v[208:211], v[44:47]
	v_mfma_f32_16x16x32_bf16 v[40:43], v[176:179], v[208:211], v[40:43]
	v_mfma_f32_16x16x32_bf16 v[36:39], v[180:183], v[208:211], v[36:39]
	v_mfma_f32_16x16x32_bf16 v[32:35], v[184:187], v[208:211], v[32:35]
	v_mfma_f32_16x16x32_bf16 v[28:31], v[168:171], v[212:215], v[28:31]
	v_mfma_f32_16x16x32_bf16 v[24:27], v[176:179], v[212:215], v[24:27]
	v_mfma_f32_16x16x32_bf16 v[20:23], v[180:183], v[212:215], v[20:23]
	v_mfma_f32_16x16x32_bf16 v[16:19], v[184:187], v[212:215], v[16:19]
	v_mfma_f32_16x16x32_bf16 v[12:15], v[168:171], v[220:223], v[12:15]
	v_mfma_f32_16x16x32_bf16 v[8:11], v[176:179], v[220:223], v[8:11]
	v_mfma_f32_16x16x32_bf16 v[4:7], v[180:183], v[220:223], v[4:7]
	v_mfma_f32_16x16x32_bf16 v[0:3], v[184:187], v[220:223], v[0:3]
	s_nop 7
	s_nop 3
	v_and_b32_e32 v225, 15, v174
	v_lshrrev_b32_e32 v226, 8, v174
	v_lshl_or_b32 v225, v226, 7, v225
	v_bfe_u32 v226, v174, 6, 2
	v_bfe_u32 v227, v174, 4, 2
	v_lshlrev_b32_e32 v227, 2, v227
	v_add_u32_e32 v225, s39, v225
	v_lshl_add_u32 v226, v226, 6, v227
	v_add_u32_e32 v226, s46, v226
	v_lshlrev_b32_e32 v226, 2, v226
	v_lshl_add_u32 v224, v225, 12, v226
	v_mov_b32_e32 v229, v224
	v_add_u32_e32 v224, 0x0, v229
	global_load_dwordx4 v[152:155], v224, s[22:23] offset:0
	global_load_dwordx4 v[156:159], v224, s[22:23] offset:64
	global_load_dwordx4 v[160:163], v224, s[22:23] offset:128
	global_load_dwordx4 v[164:167], v224, s[22:23] offset:192
	v_add_u32_e32 v228, 0x10000, v229
	global_load_dwordx4 v[168:171], v228, s[22:23] offset:0
	global_load_dwordx4 v[176:179], v228, s[22:23] offset:64
	global_load_dwordx4 v[180:183], v228, s[22:23] offset:128
	global_load_dwordx4 v[184:187], v228, s[22:23] offset:192
	s_waitcnt vmcnt(4)
	v_add_f32_e32 v152, v124, v152
	v_add_f32_e32 v153, v125, v153
	v_add_f32_e32 v154, v126, v154
	v_add_f32_e32 v155, v127, v155
	v_add_f32_e32 v156, v120, v156
	v_add_f32_e32 v157, v121, v157
	v_add_f32_e32 v158, v122, v158
	v_add_f32_e32 v159, v123, v159
	v_add_f32_e32 v160, v116, v160
	v_add_f32_e32 v161, v117, v161
	v_add_f32_e32 v162, v118, v162
	v_add_f32_e32 v163, v119, v163
	v_add_f32_e32 v164, v112, v164
	v_add_f32_e32 v165, v113, v165
	v_add_f32_e32 v166, v114, v166
	v_add_f32_e32 v167, v115, v167
	global_store_dwordx4 v224, v[152:155], s[22:23] offset:0
	global_store_dwordx4 v224, v[156:159], s[22:23] offset:64
	global_store_dwordx4 v224, v[160:163], s[22:23] offset:128
	global_store_dwordx4 v224, v[164:167], s[22:23] offset:192
	s_nop 1
	v_add_u32_e32 v224, 0x20000, v229
	global_load_dwordx4 v[152:155], v224, s[22:23] offset:0
	global_load_dwordx4 v[156:159], v224, s[22:23] offset:64
	global_load_dwordx4 v[160:163], v224, s[22:23] offset:128
	global_load_dwordx4 v[164:167], v224, s[22:23] offset:192
	s_waitcnt vmcnt(8)
	v_add_f32_e32 v168, v108, v168
	v_add_f32_e32 v169, v109, v169
	v_add_f32_e32 v170, v110, v170
	v_add_f32_e32 v171, v111, v171
	v_add_f32_e32 v176, v104, v176
	v_add_f32_e32 v177, v105, v177
	v_add_f32_e32 v178, v106, v178
	v_add_f32_e32 v179, v107, v179
	v_add_f32_e32 v180, v100, v180
	v_add_f32_e32 v181, v101, v181
	v_add_f32_e32 v182, v102, v182
	v_add_f32_e32 v183, v103, v183
	v_add_f32_e32 v184, v96, v184
	v_add_f32_e32 v185, v97, v185
	v_add_f32_e32 v186, v98, v186
	v_add_f32_e32 v187, v99, v187
	global_store_dwordx4 v228, v[168:171], s[22:23] offset:0
	global_store_dwordx4 v228, v[176:179], s[22:23] offset:64
	global_store_dwordx4 v228, v[180:183], s[22:23] offset:128
	global_store_dwordx4 v228, v[184:187], s[22:23] offset:192
	s_nop 1
	v_add_u32_e32 v228, 0x30000, v229
	global_load_dwordx4 v[168:171], v228, s[22:23] offset:0
	global_load_dwordx4 v[176:179], v228, s[22:23] offset:64
	global_load_dwordx4 v[180:183], v228, s[22:23] offset:128
	global_load_dwordx4 v[184:187], v228, s[22:23] offset:192
	s_waitcnt vmcnt(8)
; template <int EPI>
; DI void gemm_phase(const u16* __restrict__ A, int lda, const u16* __restrict__ Bt, int K, int N, u16* outb, int ldo,
;                    const float* r0, const float* r1, float* outf, char* lds, int bid, int nb) {
;     ...
;       const int col = tn * 256 + wc * 64 + l15;
;       const float* rb_ = (tm * 256 < M_P) ? r0 : (r1 - (size_t)M_P * DM);
; #pragma unroll
;       for (int i = 0; i < 8; ++i)
; #pragma unroll
;         for (int r = 0; r < 4; ++r) {
;           const size_t i0 = (size_t)(mrow + i * 16 + r) * DM + col;
;           const float x0 = rb_[i0], x1 = rb_[i0 + 16], x2 = rb_[i0 + 32], x3 = rb_[i0 + 48];
;           outf[i0] = x0 + acc[i][0][r]; outf[i0 + 16] = x1 + acc[i][1][r]; outf[i0 + 32] = x2 + acc[i][2][r]; outf[i0 + 48] = x3 + acc[i][3][r];
	v_add_f32_e32 v152, v92, v152
	v_add_f32_e32 v153, v93, v153
	v_add_f32_e32 v154, v94, v154
	v_add_f32_e32 v155, v95, v155
	v_add_f32_e32 v156, v88, v156
	v_add_f32_e32 v157, v89, v157
	v_add_f32_e32 v158, v90, v158
	v_add_f32_e32 v159, v91, v159
	v_add_f32_e32 v160, v84, v160
	v_add_f32_e32 v161, v85, v161
	v_add_f32_e32 v162, v86, v162
	v_add_f32_e32 v163, v87, v163
	v_add_f32_e32 v164, v80, v164
	v_add_f32_e32 v165, v81, v165
	v_add_f32_e32 v166, v82, v166
	v_add_f32_e32 v167, v83, v167
	global_store_dwordx4 v224, v[152:155], s[22:23] offset:0
	global_store_dwordx4 v224, v[156:159], s[22:23] offset:64
	global_store_dwordx4 v224, v[160:163], s[22:23] offset:128
	global_store_dwordx4 v224, v[164:167], s[22:23] offset:192
	s_nop 1
	v_add_u32_e32 v224, 0x40000, v229
	global_load_dwordx4 v[152:155], v224, s[22:23] offset:0
	global_load_dwordx4 v[156:159], v224, s[22:23] offset:64
	global_load_dwordx4 v[160:163], v224, s[22:23] offset:128
	global_load_dwordx4 v[164:167], v224, s[22:23] offset:192
	s_waitcnt vmcnt(8)
	v_add_f32_e32 v168, v76, v168
	v_add_f32_e32 v169, v77, v169
	v_add_f32_e32 v170, v78, v170
	v_add_f32_e32 v171, v79, v171
	v_add_f32_e32 v176, v72, v176
	v_add_f32_e32 v177, v73, v177
	v_add_f32_e32 v178, v74, v178
	v_add_f32_e32 v179, v75, v179
	v_add_f32_e32 v180, v68, v180
	v_add_f32_e32 v181, v69, v181
	v_add_f32_e32 v182, v70, v182
	v_add_f32_e32 v183, v71, v183
	v_add_f32_e32 v184, v64, v184
	v_add_f32_e32 v185, v65, v185
	v_add_f32_e32 v186, v66, v186
	v_add_f32_e32 v187, v67, v187
	global_store_dwordx4 v228, v[168:171], s[22:23] offset:0
	global_store_dwordx4 v228, v[176:179], s[22:23] offset:64
	global_store_dwordx4 v228, v[180:183], s[22:23] offset:128
	global_store_dwordx4 v228, v[184:187], s[22:23] offset:192
	s_nop 1
	v_add_u32_e32 v228, 0x50000, v229
	global_load_dwordx4 v[168:171], v228, s[22:23] offset:0
	global_load_dwordx4 v[176:179], v228, s[22:23] offset:64
	global_load_dwordx4 v[180:183], v228, s[22:23] offset:128
	global_load_dwordx4 v[184:187], v228, s[22:23] offset:192
	s_waitcnt vmcnt(8)
	v_add_f32_e32 v152, v60, v152
	v_add_f32_e32 v153, v61, v153
	v_add_f32_e32 v154, v62, v154
	v_add_f32_e32 v155, v63, v155
	v_add_f32_e32 v156, v56, v156
	v_add_f32_e32 v157, v57, v157
	v_add_f32_e32 v158, v58, v158
	v_add_f32_e32 v159, v59, v159
	v_add_f32_e32 v160, v52, v160
	v_add_f32_e32 v161, v53, v161
	v_add_f32_e32 v162, v54, v162
	v_add_f32_e32 v163, v55, v163
	v_add_f32_e32 v164, v48, v164
	v_add_f32_e32 v165, v49, v165
	v_add_f32_e32 v166, v50, v166
	v_add_f32_e32 v167, v51, v167
	global_store_dwordx4 v224, v[152:155], s[22:23] offset:0
	global_store_dwordx4 v224, v[156:159], s[22:23] offset:64
	global_store_dwordx4 v224, v[160:163], s[22:23] offset:128
	global_store_dwordx4 v224, v[164:167], s[22:23] offset:192
	s_nop 1
	v_add_u32_e32 v224, 0x60000, v229
	global_load_dwordx4 v[152:155], v224, s[22:23] offset:0
	global_load_dwordx4 v[156:159], v224, s[22:23] offset:64
	global_load_dwordx4 v[160:163], v224, s[22:23] offset:128
	global_load_dwordx4 v[164:167], v224, s[22:23] offset:192
	s_waitcnt vmcnt(8)
	v_add_f32_e32 v168, v44, v168
	v_add_f32_e32 v169, v45, v169
	v_add_f32_e32 v170, v46, v170
	v_add_f32_e32 v171, v47, v171
	v_add_f32_e32 v176, v40, v176
	v_add_f32_e32 v177, v41, v177
	v_add_f32_e32 v178, v42, v178
	v_add_f32_e32 v179, v43, v179
	v_add_f32_e32 v180, v36, v180
	v_add_f32_e32 v181, v37, v181
	v_add_f32_e32 v182, v38, v182
	v_add_f32_e32 v183, v39, v183
	v_add_f32_e32 v184, v32, v184
	v_add_f32_e32 v185, v33, v185
	v_add_f32_e32 v186, v34, v186
	v_add_f32_e32 v187, v35, v187
	global_store_dwordx4 v228, v[168:171], s[22:23] offset:0
	global_store_dwordx4 v228, v[176:179], s[22:23] offset:64
	global_store_dwordx4 v228, v[180:183], s[22:23] offset:128
	global_store_dwordx4 v228, v[184:187], s[22:23] offset:192
	s_nop 1
	v_add_u32_e32 v228, 0x70000, v229
	global_load_dwordx4 v[168:171], v228, s[22:23] offset:0
	global_load_dwordx4 v[176:179], v228, s[22:23] offset:64
	global_load_dwordx4 v[180:183], v228, s[22:23] offset:128
	global_load_dwordx4 v[184:187], v228, s[22:23] offset:192
	s_waitcnt vmcnt(8)
	v_add_f32_e32 v152, v28, v152
	v_add_f32_e32 v153, v29, v153
	v_add_f32_e32 v154, v30, v154
	v_add_f32_e32 v155, v31, v155
	v_add_f32_e32 v156, v24, v156
	v_add_f32_e32 v157, v25, v157
	v_add_f32_e32 v158, v26, v158
	v_add_f32_e32 v159, v27, v159
	v_add_f32_e32 v160, v20, v160
	v_add_f32_e32 v161, v21, v161
	v_add_f32_e32 v162, v22, v162
	v_add_f32_e32 v163, v23, v163
	v_add_f32_e32 v164, v16, v164
	v_add_f32_e32 v165, v17, v165
	v_add_f32_e32 v166, v18, v166
	v_add_f32_e32 v167, v19, v167
	global_store_dwordx4 v224, v[152:155], s[22:23] offset:0
	global_store_dwordx4 v224, v[156:159], s[22:23] offset:64
	global_store_dwordx4 v224, v[160:163], s[22:23] offset:128
	global_store_dwordx4 v224, v[164:167], s[22:23] offset:192
	s_waitcnt vmcnt(4)
	v_add_f32_e32 v168, v12, v168
	v_add_f32_e32 v169, v13, v169
	v_add_f32_e32 v170, v14, v170
	v_add_f32_e32 v171, v15, v171
	v_add_f32_e32 v176, v8, v176
	v_add_f32_e32 v177, v9, v177
	v_add_f32_e32 v178, v10, v178
	v_add_f32_e32 v179, v11, v179
	v_add_f32_e32 v180, v4, v180
	v_add_f32_e32 v181, v5, v181
	v_add_f32_e32 v182, v6, v182
	v_add_f32_e32 v183, v7, v183
	v_add_f32_e32 v184, v0, v184
	v_add_f32_e32 v185, v1, v185
	v_add_f32_e32 v186, v2, v186
	v_add_f32_e32 v187, v3, v187
	global_store_dwordx4 v228, v[168:171], s[22:23] offset:0
	global_store_dwordx4 v228, v[176:179], s[22:23] offset:64
	global_store_dwordx4 v228, v[180:183], s[22:23] offset:128
	global_store_dwordx4 v228, v[184:187], s[22:23] offset:192
	s_add_i32 s16, s16, 1
	s_cmp_eq_u32 s16, s3
	s_cbranch_scc0 .LBB0_759

; #define G_LOAD(KT) do { _Pragma("unroll") for (int i = 0; i < 4; ++i) { ra[i] = *(const u32x4*)(Ag + (size_t)i * 64 * lda + (KT) * 64); rb[i] = *(const u32x4*)(Bg + (size_t)i * 64 * K + (KT) * 64); } } while (0)
; #define G_STORE(BUF) do { u16* ad = As + (BUF) * 256 * 64 + sto; u16* bd = Bs + (BUF) * 256 * 64 + sto; _Pragma("unroll") for (int i = 0; i < 4; ++i) { *(u32x4*)(ad + i * 64 * 64) = ra[i]; *(u32x4*)(bd + i * 64 * 64) = rb[i]; } } while (0)
; template <int EPI>
; DI void gemm_phase(const u16* __restrict__ A, int lda, const u16* __restrict__ Bt, int K, int N, u16* outb, int ldo,
;                    const float* r0, const float* r1, float* outf, char* lds, int bid, int nb) {
;     ...
;     if (swz) { const int st = xcd + 8 * it, sm = st / nSN, sn = st - sm * nSN; tm = sm * GM + jb / GN; tn = sn * GN + (jb % GN); }
;     else { const int t = bid + it * nb; tm = t / nN; tn = t - tm * nN; }
;     const u16* Ag = A + (size_t)(tm * 256 + lrow) * lda + lch * 8;
;     const u16* Bg = Bt + (size_t)(tn * 256 + lrow) * K + lch * 8;
;     f32x4 acc[8][4];
; #pragma unroll
;     for (int i = 0; i < 8; ++i)
; #pragma unroll
;       for (int j = 0; j < 4; ++j) acc[i][j] = (f32x4){0.f, 0.f, 0.f, 0.f};
;     u32x4 ra[4], rb[4];
;     ...
;     G_LOAD(0);
;     G_STORE(0);
;     __syncthreads();
;     for (int kt = 0; kt < nk; ++kt) {
;       const int cur = kt & 1;
;       if (kt + 1 < nk) G_LOAD(kt + 1);
;       G_MMA(cur, fo0);
.LBB0_883:
	s_lshl_b32 s48, s48, 8
	v_or_b32_e32 v0, s48, v138
	v_ashrrev_i32_e32 v1, 31, v0
	s_lshl_b32 s49, s49, 8
	v_or_b32_e32 v2, s49, v138
	v_lshlrev_b64 v[62:63], 11, v[0:1]
	v_ashrrev_i32_e32 v3, 31, v2
	v_lshl_add_u64 v[0:1], v[128:129], 0, v[62:63]
	v_lshlrev_b64 v[64:65], 11, v[2:3]
	v_add_co_u32_e32 v4, vcc, s19, v0
	v_lshl_add_u64 v[2:3], v[130:131], 0, v[64:65]
	s_nop 0
	v_addc_co_u32_e32 v5, vcc, 0, v1, vcc
	v_add_co_u32_e32 v6, vcc, s19, v2
	s_nop 1
	v_readfirstlane_b32 s98, v0
	v_readfirstlane_b32 s99, v1
	s_nop 1
	v_readfirstlane_b32 s100, v2
	v_readfirstlane_b32 s101, v3
	v_addc_co_u32_e32 v7, vcc, 0, v3, vcc
	v_add_co_u32_e32 v4, vcc, s20, v0
	s_mov_b32 s50, 0
	s_nop 0
	v_addc_co_u32_e32 v5, vcc, 0, v1, vcc
	v_add_co_u32_e32 v6, vcc, s20, v2
	s_mov_b64 s[14:15], 0
	s_nop 0
	v_addc_co_u32_e32 v7, vcc, 0, v3, vcc
	v_add_co_u32_e32 v0, vcc, s21, v0
	v_addc_co_u32_e32 v1, vcc, 0, v1, vcc
	v_add_co_u32_e32 v2, vcc, s21, v2
	v_lshl_add_u64 v[134:135], v[132:133], 0, v[62:63]
	s_nop 0
	v_addc_co_u32_e32 v3, vcc, 0, v3, vcc
	v_mov_b32_e32 v0, 0
	v_lshl_add_u64 v[136:137], v[132:133], 0, v[64:65]
	v_and_b32_e32 v229, 63, v174
	v_lshrrev_b32_e32 v230, 3, v229
	v_mov_b32_e32 v233, 0x800
	v_mul_u32_u24_e32 v224, v230, v233
	v_bfe_u32 v231, v174, 4, 2
	v_bfe_u32 v232, v174, 6, 1
	v_lshl_or_b32 v232, v232, 2, v231
	v_and_b32_e32 v233, 7, v174
	v_xor_b32_e32 v232, v232, v233
	v_lshl_add_u32 v224, v232, 4, v224
	v_and_b32_e32 v229, 15, v174
	v_bfe_u32 v230, v174, 1, 3
	v_xor_b32_e32 v230, v230, v231
	v_lshlrev_b32_e32 v230, 4, v230
	v_lshl_or_b32 v230, v229, 7, v230
	v_lshrrev_b32_e32 v229, 8, v174
	v_lshl_or_b32 v225, v229, 14, v230
	v_bfe_u32 v229, v174, 6, 2
	v_lshl_or_b32 v227, v229, 13, v230
	v_or_b32_e32 v227, 0x10000, v227
	v_xor_b32_e32 v226, 64, v225
	v_xor_b32_e32 v228, 64, v227
	v_readfirstlane_b32 s97, v174
	s_lshl_b32 s97, s97, 4
	s_mov_b32 s28, 14
	s_add_u32 m0, s97, 0x0
	s_add_u32 s14, s98, 0x0
	s_addc_u32 s15, s99, 0
	global_load_lds_dwordx4 v224, s[14:15]
	s_add_u32 m0, s97, 0x10000
	s_add_u32 s14, s100, 0x0
	s_addc_u32 s15, s101, 0
	global_load_lds_dwordx4 v224, s[14:15]
	s_add_u32 m0, s97, 0x2000
	s_add_u32 s14, s98, 0x20000
	s_addc_u32 s15, s99, 0
	global_load_lds_dwordx4 v224, s[14:15]
	s_add_u32 m0, s97, 0x12000
	s_add_u32 s14, s100, 0x20000
	s_addc_u32 s15, s101, 0
	global_load_lds_dwordx4 v224, s[14:15]
	s_add_u32 m0, s97, 0x4000
	s_add_u32 s14, s98, 0x40000
	s_addc_u32 s15, s99, 0
	global_load_lds_dwordx4 v224, s[14:15]
	s_add_u32 m0, s97, 0x14000
	s_add_u32 s14, s100, 0x40000
	s_addc_u32 s15, s101, 0
	global_load_lds_dwordx4 v224, s[14:15]
	s_add_u32 m0, s97, 0x6000
	s_add_u32 s14, s98, 0x60000
	s_addc_u32 s15, s99, 0
	global_load_lds_dwordx4 v224, s[14:15]
	s_add_u32 m0, s97, 0x16000
	s_add_u32 s14, s100, 0x60000
	s_addc_u32 s15, s101, 0
	global_load_lds_dwordx4 v224, s[14:15]
	s_add_u32 m0, s97, 0x8000
	s_add_u32 s14, s98, 0x80
	s_addc_u32 s15, s99, 0
	global_load_lds_dwordx4 v224, s[14:15]
	s_add_u32 m0, s97, 0x18000
	s_add_u32 s14, s100, 0x80
	s_addc_u32 s15, s101, 0
	global_load_lds_dwordx4 v224, s[14:15]
	s_add_u32 m0, s97, 0xa000
	s_add_u32 s14, s98, 0x20080
	s_addc_u32 s15, s99, 0
	global_load_lds_dwordx4 v224, s[14:15]
	s_add_u32 m0, s97, 0x1a000
	s_add_u32 s14, s100, 0x20080
	s_addc_u32 s15, s101, 0
	global_load_lds_dwordx4 v224, s[14:15]
	s_add_u32 m0, s97, 0xc000
	s_add_u32 s14, s98, 0x40080
	s_addc_u32 s15, s99, 0
	global_load_lds_dwordx4 v224, s[14:15]
	s_add_u32 m0, s97, 0x1c000
	s_add_u32 s14, s100, 0x40080
	s_addc_u32 s15, s101, 0
	global_load_lds_dwordx4 v224, s[14:15]
	s_add_u32 m0, s97, 0xe000
	s_add_u32 s14, s98, 0x60080
	s_addc_u32 s15, s99, 0
	global_load_lds_dwordx4 v224, s[14:15]
	s_add_u32 m0, s97, 0x1e000
	s_add_u32 s14, s100, 0x60080
	s_addc_u32 s15, s101, 0
	global_load_lds_dwordx4 v224, s[14:15]
	s_add_u32 s98, s98, 0x100
	s_addc_u32 s99, s99, 0
	s_add_u32 s100, s100, 0x100
	s_addc_u32 s101, s101, 0
	s_waitcnt vmcnt(8)
	s_barrier
; #define G_LOAD(KT) do { _Pragma("unroll") for (int i = 0; i < 4; ++i) { ra[i] = *(const u32x4*)(Ag + (size_t)i * 64 * lda + (KT) * 64); rb[i] = *(const u32x4*)(Bg + (size_t)i * 64 * K + (KT) * 64); } } while (0)
; template <int EPI>
; DI void gemm_phase(const u16* __restrict__ A, int lda, const u16* __restrict__ Bt, int K, int N, u16* outb, int ldo,
;                    const float* r0, const float* r1, float* outf, char* lds, int bid, int nb) {
;     ...
;     for (int kt = 0; kt < nk; ++kt) {
;       const int cur = kt & 1;
;       if (kt + 1 < nk) G_LOAD(kt + 1);
;       G_MMA(cur, fo0);
;       G_MMA(cur, fo1);
	ds_read_b128 v[152:155], v227 offset:0
	ds_read_b128 v[156:159], v227 offset:2048
	ds_read_b128 v[160:163], v227 offset:4096
	ds_read_b128 v[164:167], v227 offset:6144
	ds_read_b128 v[188:191], v225 offset:0
	ds_read_b128 v[192:195], v225 offset:2048
	ds_read_b128 v[196:199], v225 offset:4096
	ds_read_b128 v[200:203], v225 offset:6144
	ds_read_b128 v[204:207], v225 offset:8192
	ds_read_b128 v[208:211], v225 offset:10240
	ds_read_b128 v[212:215], v225 offset:12288
	ds_read_b128 v[216:219], v225 offset:14336
	v_xor_b32_e32 v225, 0x8000, v225
	v_xor_b32_e32 v227, 0x8000, v227
	s_waitcnt lgkmcnt(0)
	s_waitcnt lgkmcnt(4)
	v_mfma_f32_16x16x32_bf16 v[124:127], v[152:155], v[188:191], 0
	v_mfma_f32_16x16x32_bf16 v[120:123], v[156:159], v[188:191], 0
	v_mfma_f32_16x16x32_bf16 v[116:119], v[160:163], v[188:191], 0
	v_mfma_f32_16x16x32_bf16 v[112:115], v[164:167], v[188:191], 0
	ds_read_b128 v[188:191], v226 offset:0
	ds_read_b128 v[168:171], v228 offset:0
	v_mfma_f32_16x16x32_bf16 v[108:111], v[152:155], v[192:195], 0
	v_mfma_f32_16x16x32_bf16 v[104:107], v[156:159], v[192:195], 0
	v_mfma_f32_16x16x32_bf16 v[100:103], v[160:163], v[192:195], 0
	v_mfma_f32_16x16x32_bf16 v[96:99], v[164:167], v[192:195], 0
	ds_read_b128 v[192:195], v226 offset:2048
	ds_read_b128 v[176:179], v228 offset:2048
	v_mfma_f32_16x16x32_bf16 v[92:95], v[152:155], v[196:199], 0
	v_mfma_f32_16x16x32_bf16 v[88:91], v[156:159], v[196:199], 0
	v_mfma_f32_16x16x32_bf16 v[84:87], v[160:163], v[196:199], 0
	v_mfma_f32_16x16x32_bf16 v[80:83], v[164:167], v[196:199], 0
	ds_read_b128 v[196:199], v226 offset:4096
	ds_read_b128 v[180:183], v228 offset:4096
	v_mfma_f32_16x16x32_bf16 v[76:79], v[152:155], v[200:203], 0
	v_mfma_f32_16x16x32_bf16 v[72:75], v[156:159], v[200:203], 0
	v_mfma_f32_16x16x32_bf16 v[68:71], v[160:163], v[200:203], 0
	v_mfma_f32_16x16x32_bf16 v[64:67], v[164:167], v[200:203], 0
	ds_read_b128 v[200:203], v226 offset:6144
	ds_read_b128 v[184:187], v228 offset:6144
	s_waitcnt lgkmcnt(11)
	v_mfma_f32_16x16x32_bf16 v[60:63], v[152:155], v[204:207], 0
	v_mfma_f32_16x16x32_bf16 v[56:59], v[156:159], v[204:207], 0
	v_mfma_f32_16x16x32_bf16 v[52:55], v[160:163], v[204:207], 0
	v_mfma_f32_16x16x32_bf16 v[48:51], v[164:167], v[204:207], 0
	ds_read_b128 v[204:207], v226 offset:8192
	ds_read_b128 v[220:223], v226 offset:14336
	s_waitcnt lgkmcnt(11)
	v_mfma_f32_16x16x32_bf16 v[44:47], v[152:155], v[208:211], 0
	v_mfma_f32_16x16x32_bf16 v[40:43], v[156:159], v[208:211], 0
	v_mfma_f32_16x16x32_bf16 v[36:39], v[160:163], v[208:211], 0
	v_mfma_f32_16x16x32_bf16 v[32:35], v[164:167], v[208:211], 0
	ds_read_b128 v[208:211], v226 offset:10240
	s_waitcnt lgkmcnt(11)
	v_mfma_f32_16x16x32_bf16 v[28:31], v[152:155], v[212:215], 0
	v_mfma_f32_16x16x32_bf16 v[24:27], v[156:159], v[212:215], 0
	v_mfma_f32_16x16x32_bf16 v[20:23], v[160:163], v[212:215], 0
	v_mfma_f32_16x16x32_bf16 v[16:19], v[164:167], v[212:215], 0
	ds_read_b128 v[212:215], v226 offset:12288
	v_mfma_f32_16x16x32_bf16 v[12:15], v[152:155], v[216:219], 0
	v_mfma_f32_16x16x32_bf16 v[8:11], v[156:159], v[216:219], 0
	v_mfma_f32_16x16x32_bf16 v[4:7], v[160:163], v[216:219], 0
	v_mfma_f32_16x16x32_bf16 v[0:3], v[164:167], v[216:219], 0
	s_branch .Lgm4_mid0

; #define G_LOAD(KT) do { _Pragma("unroll") for (int i = 0; i < 4; ++i) { ra[i] = *(const u32x4*)(Ag + (size_t)i * 64 * lda + (KT) * 64); rb[i] = *(const u32x4*)(Bg + (size_t)i * 64 * K + (KT) * 64); } } while (0)
; #define G_STORE(BUF) do { u16* ad = As + (BUF) * 256 * 64 + sto; u16* bd = Bs + (BUF) * 256 * 64 + sto; _Pragma("unroll") for (int i = 0; i < 4; ++i) { *(u32x4*)(ad + i * 64 * 64) = ra[i]; *(u32x4*)(bd + i * 64 * 64) = rb[i]; } } while (0)
; template <int EPI>
; DI void gemm_phase(const u16* __restrict__ A, int lda, const u16* __restrict__ Bt, int K, int N, u16* outb, int ldo,
;                    const float* r0, const float* r1, float* outf, char* lds, int bid, int nb) {
;     ...
;     for (int kt = 0; kt < nk; ++kt) {
;       const int cur = kt & 1;
;       if (kt + 1 < nk) G_LOAD(kt + 1);
;       G_MMA(cur, fo0);
;       G_MMA(cur, fo1);
;       if (kt + 1 < nk) G_STORE(cur ^ 1);
;       __syncthreads();
;     }
.Lgm4_mid0:
	s_waitcnt vmcnt(0) lgkmcnt(0)
	s_barrier
	v_mfma_f32_16x16x32_bf16 v[124:127], v[168:171], v[188:191], v[124:127]
	v_mfma_f32_16x16x32_bf16 v[120:123], v[176:179], v[188:191], v[120:123]
	v_mfma_f32_16x16x32_bf16 v[116:119], v[180:183], v[188:191], v[116:119]
	v_mfma_f32_16x16x32_bf16 v[112:115], v[184:187], v[188:191], v[112:115]
	ds_read_b128 v[188:191], v225 offset:0
	ds_read_b128 v[152:155], v227 offset:0
	s_add_u32 m0, s97, 0x0
	s_add_u32 s14, s98, 0x0
	s_addc_u32 s15, s99, 0
	global_load_lds_dwordx4 v224, s[14:15]
	v_mfma_f32_16x16x32_bf16 v[108:111], v[168:171], v[192:195], v[108:111]
	v_mfma_f32_16x16x32_bf16 v[104:107], v[176:179], v[192:195], v[104:107]
	v_mfma_f32_16x16x32_bf16 v[100:103], v[180:183], v[192:195], v[100:103]
	v_mfma_f32_16x16x32_bf16 v[96:99], v[184:187], v[192:195], v[96:99]
	ds_read_b128 v[192:195], v225 offset:2048
	ds_read_b128 v[156:159], v227 offset:2048
	s_add_u32 m0, s97, 0x10000
	s_add_u32 s14, s100, 0x0
	s_addc_u32 s15, s101, 0
	global_load_lds_dwordx4 v224, s[14:15]
	v_mfma_f32_16x16x32_bf16 v[92:95], v[168:171], v[196:199], v[92:95]
	v_mfma_f32_16x16x32_bf16 v[88:91], v[176:179], v[196:199], v[88:91]
	v_mfma_f32_16x16x32_bf16 v[84:87], v[180:183], v[196:199], v[84:87]
	v_mfma_f32_16x16x32_bf16 v[80:83], v[184:187], v[196:199], v[80:83]
	ds_read_b128 v[196:199], v225 offset:4096
	ds_read_b128 v[160:163], v227 offset:4096
	s_add_u32 m0, s97, 0x2000
	s_add_u32 s14, s98, 0x20000
	s_addc_u32 s15, s99, 0
	global_load_lds_dwordx4 v224, s[14:15]
	v_mfma_f32_16x16x32_bf16 v[76:79], v[168:171], v[200:203], v[76:79]
	v_mfma_f32_16x16x32_bf16 v[72:75], v[176:179], v[200:203], v[72:75]
	v_mfma_f32_16x16x32_bf16 v[68:71], v[180:183], v[200:203], v[68:71]
	v_mfma_f32_16x16x32_bf16 v[64:67], v[184:187], v[200:203], v[64:67]
	ds_read_b128 v[200:203], v225 offset:6144
	ds_read_b128 v[164:167], v227 offset:6144
	s_add_u32 m0, s97, 0x12000
	s_add_u32 s14, s100, 0x20000
	s_addc_u32 s15, s101, 0
	global_load_lds_dwordx4 v224, s[14:15]
	v_mfma_f32_16x16x32_bf16 v[60:63], v[168:171], v[204:207], v[60:63]
	v_mfma_f32_16x16x32_bf16 v[56:59], v[176:179], v[204:207], v[56:59]
	v_mfma_f32_16x16x32_bf16 v[52:55], v[180:183], v[204:207], v[52:55]
	v_mfma_f32_16x16x32_bf16 v[48:51], v[184:187], v[204:207], v[48:51]
	ds_read_b128 v[204:207], v225 offset:8192
	ds_read_b128 v[216:219], v225 offset:14336
	s_add_u32 m0, s97, 0x4000
	s_add_u32 s14, s98, 0x40000
	s_addc_u32 s15, s99, 0
	global_load_lds_dwordx4 v224, s[14:15]
	v_mfma_f32_16x16x32_bf16 v[44:47], v[168:171], v[208:211], v[44:47]
	v_mfma_f32_16x16x32_bf16 v[40:43], v[176:179], v[208:211], v[40:43]
	v_mfma_f32_16x16x32_bf16 v[36:39], v[180:183], v[208:211], v[36:39]
	v_mfma_f32_16x16x32_bf16 v[32:35], v[184:187], v[208:211], v[32:35]
	ds_read_b128 v[208:211], v225 offset:10240
	s_add_u32 m0, s97, 0x14000
	s_add_u32 s14, s100, 0x40000
	s_addc_u32 s15, s101, 0
	global_load_lds_dwordx4 v224, s[14:15]
	v_mfma_f32_16x16x32_bf16 v[28:31], v[168:171], v[212:215], v[28:31]
	v_mfma_f32_16x16x32_bf16 v[24:27], v[176:179], v[212:215], v[24:27]
	v_mfma_f32_16x16x32_bf16 v[20:23], v[180:183], v[212:215], v[20:23]
	v_mfma_f32_16x16x32_bf16 v[16:19], v[184:187], v[212:215], v[16:19]
	ds_read_b128 v[212:215], v225 offset:12288
	s_add_u32 m0, s97, 0x6000
	s_add_u32 s14, s98, 0x60000
	s_addc_u32 s15, s99, 0
	global_load_lds_dwordx4 v224, s[14:15]
	v_mfma_f32_16x16x32_bf16 v[12:15], v[168:171], v[220:223], v[12:15]
	v_mfma_f32_16x16x32_bf16 v[8:11], v[176:179], v[220:223], v[8:11]
	v_mfma_f32_16x16x32_bf16 v[4:7], v[180:183], v[220:223], v[4:7]
	v_mfma_f32_16x16x32_bf16 v[0:3], v[184:187], v[220:223], v[0:3]
	s_add_u32 m0, s97, 0x16000
	s_add_u32 s14, s100, 0x60000
	s_addc_u32 s15, s101, 0
	global_load_lds_dwordx4 v224, s[14:15]
	v_xor_b32_e32 v225, 0x8000, v225
	v_xor_b32_e32 v227, 0x8000, v227
	v_xor_b32_e32 v226, 0x8000, v226
	v_xor_b32_e32 v228, 0x8000, v228
	s_xor_b32 s97, s97, 0x8000
	s_add_u32 s98, s98, 0x80
	s_addc_u32 s99, s99, 0
	s_add_u32 s100, s100, 0x80
	s_addc_u32 s101, s101, 0
	s_sub_u32 s28, s28, 1
	s_cmp_lg_u32 s28, 0
	s_cbranch_scc1 .Lgm4_loop
	s_waitcnt lgkmcnt(4)
	v_mfma_f32_16x16x32_bf16 v[124:127], v[152:155], v[188:191], v[124:127]
	v_mfma_f32_16x16x32_bf16 v[120:123], v[156:159], v[188:191], v[120:123]
	v_mfma_f32_16x16x32_bf16 v[116:119], v[160:163], v[188:191], v[116:119]
	v_mfma_f32_16x16x32_bf16 v[112:115], v[164:167], v[188:191], v[112:115]
	ds_read_b128 v[188:191], v226 offset:0
	ds_read_b128 v[168:171], v228 offset:0
	v_mfma_f32_16x16x32_bf16 v[108:111], v[152:155], v[192:195], v[108:111]
	v_mfma_f32_16x16x32_bf16 v[104:107], v[156:159], v[192:195], v[104:107]
	v_mfma_f32_16x16x32_bf16 v[100:103], v[160:163], v[192:195], v[100:103]
	v_mfma_f32_16x16x32_bf16 v[96:99], v[164:167], v[192:195], v[96:99]
	ds_read_b128 v[192:195], v226 offset:2048
	ds_read_b128 v[176:179], v228 offset:2048
	v_mfma_f32_16x16x32_bf16 v[92:95], v[152:155], v[196:199], v[92:95]
	v_mfma_f32_16x16x32_bf16 v[88:91], v[156:159], v[196:199], v[88:91]
	v_mfma_f32_16x16x32_bf16 v[84:87], v[160:163], v[196:199], v[84:87]
	v_mfma_f32_16x16x32_bf16 v[80:83], v[164:167], v[196:199], v[80:83]
	ds_read_b128 v[196:199], v226 offset:4096
	ds_read_b128 v[180:183], v228 offset:4096
	v_mfma_f32_16x16x32_bf16 v[76:79], v[152:155], v[200:203], v[76:79]
	v_mfma_f32_16x16x32_bf16 v[72:75], v[156:159], v[200:203], v[72:75]
	v_mfma_f32_16x16x32_bf16 v[68:71], v[160:163], v[200:203], v[68:71]
	v_mfma_f32_16x16x32_bf16 v[64:67], v[164:167], v[200:203], v[64:67]
	ds_read_b128 v[200:203], v226 offset:6144
	ds_read_b128 v[184:187], v228 offset:6144
	s_waitcnt lgkmcnt(11)
	v_mfma_f32_16x16x32_bf16 v[60:63], v[152:155], v[204:207], v[60:63]
	v_mfma_f32_16x16x32_bf16 v[56:59], v[156:159], v[204:207], v[56:59]
	v_mfma_f32_16x16x32_bf16 v[52:55], v[160:163], v[204:207], v[52:55]
	v_mfma_f32_16x16x32_bf16 v[48:51], v[164:167], v[204:207], v[48:51]
	ds_read_b128 v[204:207], v226 offset:8192
	ds_read_b128 v[220:223], v226 offset:14336
	s_waitcnt lgkmcnt(11)
	v_mfma_f32_16x16x32_bf16 v[44:47], v[152:155], v[208:211], v[44:47]
	v_mfma_f32_16x16x32_bf16 v[40:43], v[156:159], v[208:211], v[40:43]
	v_mfma_f32_16x16x32_bf16 v[36:39], v[160:163], v[208:211], v[36:39]
	v_mfma_f32_16x16x32_bf16 v[32:35], v[164:167], v[208:211], v[32:35]
	ds_read_b128 v[208:211], v226 offset:10240
	s_waitcnt lgkmcnt(11)
	v_mfma_f32_16x16x32_bf16 v[28:31], v[152:155], v[212:215], v[28:31]
	v_mfma_f32_16x16x32_bf16 v[24:27], v[156:159], v[212:215], v[24:27]
	v_mfma_f32_16x16x32_bf16 v[20:23], v[160:163], v[212:215], v[20:23]
	v_mfma_f32_16x16x32_bf16 v[16:19], v[164:167], v[212:215], v[16:19]
	ds_read_b128 v[212:215], v226 offset:12288
	v_mfma_f32_16x16x32_bf16 v[12:15], v[152:155], v[216:219], v[12:15]
	v_mfma_f32_16x16x32_bf16 v[8:11], v[156:159], v[216:219], v[8:11]
	v_mfma_f32_16x16x32_bf16 v[4:7], v[160:163], v[216:219], v[4:7]
	v_mfma_f32_16x16x32_bf16 v[0:3], v[164:167], v[216:219], v[0:3]
	s_waitcnt vmcnt(0) lgkmcnt(0)
	s_barrier
; #define G_LOAD(KT) do { _Pragma("unroll") for (int i = 0; i < 4; ++i) { ra[i] = *(const u32x4*)(Ag + (size_t)i * 64 * lda + (KT) * 64); rb[i] = *(const u32x4*)(Bg + (size_t)i * 64 * K + (KT) * 64); } } while (0)
; #define G_STORE(BUF) do { u16* ad = As + (BUF) * 256 * 64 + sto; u16* bd = Bs + (BUF) * 256 * 64 + sto; _Pragma("unroll") for (int i = 0; i < 4; ++i) { *(u32x4*)(ad + i * 64 * 64) = ra[i]; *(u32x4*)(bd + i * 64 * 64) = rb[i]; } } while (0)
; template <int EPI>
; DI void gemm_phase(const u16* __restrict__ A, int lda, const u16* __restrict__ Bt, int K, int N, u16* outb, int ldo,
;                    const float* r0, const float* r1, float* outf, char* lds, int bid, int nb) {
;     ...
;     for (int kt = 0; kt < nk; ++kt) {
;       const int cur = kt & 1;
;       if (kt + 1 < nk) G_LOAD(kt + 1);
;       G_MMA(cur, fo0);
;       G_MMA(cur, fo1);
;       if (kt + 1 < nk) G_STORE(cur ^ 1);
;       __syncthreads();
;     }
	v_mfma_f32_16x16x32_bf16 v[124:127], v[168:171], v[188:191], v[124:127]
	v_mfma_f32_16x16x32_bf16 v[120:123], v[176:179], v[188:191], v[120:123]
	v_mfma_f32_16x16x32_bf16 v[116:119], v[180:183], v[188:191], v[116:119]
	v_mfma_f32_16x16x32_bf16 v[112:115], v[184:187], v[188:191], v[112:115]
	ds_read_b128 v[188:191], v225 offset:0
	ds_read_b128 v[152:155], v227 offset:0
	v_mfma_f32_16x16x32_bf16 v[108:111], v[168:171], v[192:195], v[108:111]
	v_mfma_f32_16x16x32_bf16 v[104:107], v[176:179], v[192:195], v[104:107]
	v_mfma_f32_16x16x32_bf16 v[100:103], v[180:183], v[192:195], v[100:103]
	v_mfma_f32_16x16x32_bf16 v[96:99], v[184:187], v[192:195], v[96:99]
	ds_read_b128 v[192:195], v225 offset:2048
	ds_read_b128 v[156:159], v227 offset:2048
	v_mfma_f32_16x16x32_bf16 v[92:95], v[168:171], v[196:199], v[92:95]
	v_mfma_f32_16x16x32_bf16 v[88:91], v[176:179], v[196:199], v[88:91]
	v_mfma_f32_16x16x32_bf16 v[84:87], v[180:183], v[196:199], v[84:87]
	v_mfma_f32_16x16x32_bf16 v[80:83], v[184:187], v[196:199], v[80:83]
	ds_read_b128 v[196:199], v225 offset:4096
	ds_read_b128 v[160:163], v227 offset:4096
	v_mfma_f32_16x16x32_bf16 v[76:79], v[168:171], v[200:203], v[76:79]
	v_mfma_f32_16x16x32_bf16 v[72:75], v[176:179], v[200:203], v[72:75]
	v_mfma_f32_16x16x32_bf16 v[68:71], v[180:183], v[200:203], v[68:71]
	v_mfma_f32_16x16x32_bf16 v[64:67], v[184:187], v[200:203], v[64:67]
	ds_read_b128 v[200:203], v225 offset:6144
	ds_read_b128 v[164:167], v227 offset:6144
	v_mfma_f32_16x16x32_bf16 v[60:63], v[168:171], v[204:207], v[60:63]
	v_mfma_f32_16x16x32_bf16 v[56:59], v[176:179], v[204:207], v[56:59]
	v_mfma_f32_16x16x32_bf16 v[52:55], v[180:183], v[204:207], v[52:55]
	v_mfma_f32_16x16x32_bf16 v[48:51], v[184:187], v[204:207], v[48:51]
	ds_read_b128 v[204:207], v225 offset:8192
	ds_read_b128 v[216:219], v225 offset:14336
	v_mfma_f32_16x16x32_bf16 v[44:47], v[168:171], v[208:211], v[44:47]
	v_mfma_f32_16x16x32_bf16 v[40:43], v[176:179], v[208:211], v[40:43]
	v_mfma_f32_16x16x32_bf16 v[36:39], v[180:183], v[208:211], v[36:39]
	v_mfma_f32_16x16x32_bf16 v[32:35], v[184:187], v[208:211], v[32:35]
	ds_read_b128 v[208:211], v225 offset:10240
	v_mfma_f32_16x16x32_bf16 v[28:31], v[168:171], v[212:215], v[28:31]
	v_mfma_f32_16x16x32_bf16 v[24:27], v[176:179], v[212:215], v[24:27]
	v_mfma_f32_16x16x32_bf16 v[20:23], v[180:183], v[212:215], v[20:23]
	v_mfma_f32_16x16x32_bf16 v[16:19], v[184:187], v[212:215], v[16:19]
	ds_read_b128 v[212:215], v225 offset:12288
	v_mfma_f32_16x16x32_bf16 v[12:15], v[168:171], v[220:223], v[12:15]
	v_mfma_f32_16x16x32_bf16 v[8:11], v[176:179], v[220:223], v[8:11]
	v_mfma_f32_16x16x32_bf16 v[4:7], v[180:183], v[220:223], v[4:7]
	v_mfma_f32_16x16x32_bf16 v[0:3], v[184:187], v[220:223], v[0:3]
	v_xor_b32_e32 v226, 0x8000, v226
	v_xor_b32_e32 v228, 0x8000, v228
	s_waitcnt lgkmcnt(4)
	v_mfma_f32_16x16x32_bf16 v[124:127], v[152:155], v[188:191], v[124:127]
	v_mfma_f32_16x16x32_bf16 v[120:123], v[156:159], v[188:191], v[120:123]
	v_mfma_f32_16x16x32_bf16 v[116:119], v[160:163], v[188:191], v[116:119]
	v_mfma_f32_16x16x32_bf16 v[112:115], v[164:167], v[188:191], v[112:115]
	ds_read_b128 v[188:191], v226 offset:0
	ds_read_b128 v[168:171], v228 offset:0
	v_mfma_f32_16x16x32_bf16 v[108:111], v[152:155], v[192:195], v[108:111]
	v_mfma_f32_16x16x32_bf16 v[104:107], v[156:159], v[192:195], v[104:107]
	v_mfma_f32_16x16x32_bf16 v[100:103], v[160:163], v[192:195], v[100:103]
	v_mfma_f32_16x16x32_bf16 v[96:99], v[164:167], v[192:195], v[96:99]
	ds_read_b128 v[192:195], v226 offset:2048
	ds_read_b128 v[176:179], v228 offset:2048
	v_mfma_f32_16x16x32_bf16 v[92:95], v[152:155], v[196:199], v[92:95]
	v_mfma_f32_16x16x32_bf16 v[88:91], v[156:159], v[196:199], v[88:91]
	v_mfma_f32_16x16x32_bf16 v[84:87], v[160:163], v[196:199], v[84:87]
	v_mfma_f32_16x16x32_bf16 v[80:83], v[164:167], v[196:199], v[80:83]
	ds_read_b128 v[196:199], v226 offset:4096
	ds_read_b128 v[180:183], v228 offset:4096
	v_mfma_f32_16x16x32_bf16 v[76:79], v[152:155], v[200:203], v[76:79]
	v_mfma_f32_16x16x32_bf16 v[72:75], v[156:159], v[200:203], v[72:75]
	v_mfma_f32_16x16x32_bf16 v[68:71], v[160:163], v[200:203], v[68:71]
	v_mfma_f32_16x16x32_bf16 v[64:67], v[164:167], v[200:203], v[64:67]
	ds_read_b128 v[200:203], v226 offset:6144
	ds_read_b128 v[184:187], v228 offset:6144
	s_waitcnt lgkmcnt(11)
	v_mfma_f32_16x16x32_bf16 v[60:63], v[152:155], v[204:207], v[60:63]
	v_mfma_f32_16x16x32_bf16 v[56:59], v[156:159], v[204:207], v[56:59]
	v_mfma_f32_16x16x32_bf16 v[52:55], v[160:163], v[204:207], v[52:55]
	v_mfma_f32_16x16x32_bf16 v[48:51], v[164:167], v[204:207], v[48:51]
	ds_read_b128 v[204:207], v226 offset:8192
	ds_read_b128 v[220:223], v226 offset:14336
	s_waitcnt lgkmcnt(11)
	v_mfma_f32_16x16x32_bf16 v[44:47], v[152:155], v[208:211], v[44:47]
	v_mfma_f32_16x16x32_bf16 v[40:43], v[156:159], v[208:211], v[40:43]
	v_mfma_f32_16x16x32_bf16 v[36:39], v[160:163], v[208:211], v[36:39]
	v_mfma_f32_16x16x32_bf16 v[32:35], v[164:167], v[208:211], v[32:35]
	ds_read_b128 v[208:211], v226 offset:10240
	s_waitcnt lgkmcnt(11)
	v_mfma_f32_16x16x32_bf16 v[28:31], v[152:155], v[212:215], v[28:31]
	v_mfma_f32_16x16x32_bf16 v[24:27], v[156:159], v[212:215], v[24:27]
	v_mfma_f32_16x16x32_bf16 v[20:23], v[160:163], v[212:215], v[20:23]
	v_mfma_f32_16x16x32_bf16 v[16:19], v[164:167], v[212:215], v[16:19]
	ds_read_b128 v[212:215], v226 offset:12288
	v_mfma_f32_16x16x32_bf16 v[12:15], v[152:155], v[216:219], v[12:15]
	v_mfma_f32_16x16x32_bf16 v[8:11], v[156:159], v[216:219], v[8:11]
	v_mfma_f32_16x16x32_bf16 v[4:7], v[160:163], v[216:219], v[4:7]
	v_mfma_f32_16x16x32_bf16 v[0:3], v[164:167], v[216:219], v[0:3]
	s_waitcnt vmcnt(0) lgkmcnt(0)
	s_barrier
; DI u16 f2bf(float a) { return (u16)(pk2(a, 0.f) & 0xffffu); }
; template <int EPI>
; DI void gemm_phase(const u16* __restrict__ A, int lda, const u16* __restrict__ Bt, int K, int N, u16* outb, int ldo,
;                    const float* r0, const float* r1, float* outf, char* lds, int bid, int nb) {
;     ...
;     if constexpr (EPI == EPI_BF16) {
;       const int col = tn * 256 + wc * 64 + l15;
; #pragma unroll
;       for (int i = 0; i < 8; ++i)
; #pragma unroll
;         for (int r = 0; r < 4; ++r) {
;           u16* o0 = outb + (size_t)(mrow + i * 16 + r) * ldo + col;
;           o0[0] = f2bf(acc[i][0][r]); o0[16] = f2bf(acc[i][1][r]); o0[32] = f2bf(acc[i][2][r]); o0[48] = f2bf(acc[i][3][r]);
;         }
	v_mfma_f32_16x16x32_bf16 v[124:127], v[168:171], v[188:191], v[124:127]
	v_mfma_f32_16x16x32_bf16 v[120:123], v[176:179], v[188:191], v[120:123]
	v_mfma_f32_16x16x32_bf16 v[116:119], v[180:183], v[188:191], v[116:119]
	v_mfma_f32_16x16x32_bf16 v[112:115], v[184:187], v[188:191], v[112:115]
	v_mfma_f32_16x16x32_bf16 v[108:111], v[168:171], v[192:195], v[108:111]
	v_mfma_f32_16x16x32_bf16 v[104:107], v[176:179], v[192:195], v[104:107]
	v_mfma_f32_16x16x32_bf16 v[100:103], v[180:183], v[192:195], v[100:103]
	v_mfma_f32_16x16x32_bf16 v[96:99], v[184:187], v[192:195], v[96:99]
	v_mfma_f32_16x16x32_bf16 v[92:95], v[168:171], v[196:199], v[92:95]
	v_mfma_f32_16x16x32_bf16 v[88:91], v[176:179], v[196:199], v[88:91]
	v_mfma_f32_16x16x32_bf16 v[84:87], v[180:183], v[196:199], v[84:87]
	v_mfma_f32_16x16x32_bf16 v[80:83], v[184:187], v[196:199], v[80:83]
	v_mfma_f32_16x16x32_bf16 v[76:79], v[168:171], v[200:203], v[76:79]
	v_mfma_f32_16x16x32_bf16 v[72:75], v[176:179], v[200:203], v[72:75]
	v_mfma_f32_16x16x32_bf16 v[68:71], v[180:183], v[200:203], v[68:71]
	v_mfma_f32_16x16x32_bf16 v[64:67], v[184:187], v[200:203], v[64:67]
	v_mfma_f32_16x16x32_bf16 v[60:63], v[168:171], v[204:207], v[60:63]
	v_mfma_f32_16x16x32_bf16 v[56:59], v[176:179], v[204:207], v[56:59]
	v_mfma_f32_16x16x32_bf16 v[52:55], v[180:183], v[204:207], v[52:55]
	v_mfma_f32_16x16x32_bf16 v[48:51], v[184:187], v[204:207], v[48:51]
	v_mfma_f32_16x16x32_bf16 v[44:47], v[168:171], v[208:211], v[44:47]
	v_mfma_f32_16x16x32_bf16 v[40:43], v[176:179], v[208:211], v[40:43]
	v_mfma_f32_16x16x32_bf16 v[36:39], v[180:183], v[208:211], v[36:39]
	v_mfma_f32_16x16x32_bf16 v[32:35], v[184:187], v[208:211], v[32:35]
	v_mfma_f32_16x16x32_bf16 v[28:31], v[168:171], v[212:215], v[28:31]
	v_mfma_f32_16x16x32_bf16 v[24:27], v[176:179], v[212:215], v[24:27]
	v_mfma_f32_16x16x32_bf16 v[20:23], v[180:183], v[212:215], v[20:23]
	v_mfma_f32_16x16x32_bf16 v[16:19], v[184:187], v[212:215], v[16:19]
	v_mfma_f32_16x16x32_bf16 v[12:15], v[168:171], v[220:223], v[12:15]
	v_mfma_f32_16x16x32_bf16 v[8:11], v[176:179], v[220:223], v[8:11]
	v_mfma_f32_16x16x32_bf16 v[4:7], v[180:183], v[220:223], v[4:7]
	v_mfma_f32_16x16x32_bf16 v[0:3], v[184:187], v[220:223], v[0:3]
	s_nop 7
	s_nop 3
	v_and_b32_e32 v225, 15, v174
	v_lshrrev_b32_e32 v226, 8, v174
	v_lshl_or_b32 v225, v226, 7, v225
	v_bfe_u32 v226, v174, 6, 2
	v_bfe_u32 v227, v174, 4, 2
	v_lshlrev_b32_e32 v227, 2, v227
	v_add_u32_e32 v225, s48, v225
	v_lshl_add_u32 v226, v226, 6, v227
	v_add_u32_e32 v226, s49, v226
	v_lshlrev_b32_e32 v226, 1, v226
	v_mov_b32_e32 v227, 0x600
	v_mad_u32_u24 v224, v225, v227, v226
	v_cvt_pk_bf16_f32 v188, v124, v125
	v_cvt_pk_bf16_f32 v189, v126, v127
	global_store_dwordx2 v224, v[188:189], s[8:9] offset:0
	v_cvt_pk_bf16_f32 v190, v120, v121
	v_cvt_pk_bf16_f32 v191, v122, v123
	global_store_dwordx2 v224, v[190:191], s[8:9] offset:32
	v_cvt_pk_bf16_f32 v192, v116, v117
	v_cvt_pk_bf16_f32 v193, v118, v119
	global_store_dwordx2 v224, v[192:193], s[8:9] offset:64
	v_cvt_pk_bf16_f32 v194, v112, v113
	v_cvt_pk_bf16_f32 v195, v114, v115
	global_store_dwordx2 v224, v[194:195], s[8:9] offset:96
	v_add_u32_e32 v224, 0x6000, v224
	v_cvt_pk_bf16_f32 v196, v108, v109
	v_cvt_pk_bf16_f32 v197, v110, v111
	global_store_dwordx2 v224, v[196:197], s[8:9] offset:0
	v_cvt_pk_bf16_f32 v198, v104, v105
	v_cvt_pk_bf16_f32 v199, v106, v107
	global_store_dwordx2 v224, v[198:199], s[8:9] offset:32
	v_cvt_pk_bf16_f32 v200, v100, v101
	v_cvt_pk_bf16_f32 v201, v102, v103
	global_store_dwordx2 v224, v[200:201], s[8:9] offset:64
	v_cvt_pk_bf16_f32 v202, v96, v97
	v_cvt_pk_bf16_f32 v203, v98, v99
	global_store_dwordx2 v224, v[202:203], s[8:9] offset:96
	v_add_u32_e32 v224, 0x6000, v224
	v_cvt_pk_bf16_f32 v204, v92, v93
	v_cvt_pk_bf16_f32 v205, v94, v95
	global_store_dwordx2 v224, v[204:205], s[8:9] offset:0
	v_cvt_pk_bf16_f32 v206, v88, v89
	v_cvt_pk_bf16_f32 v207, v90, v91
	global_store_dwordx2 v224, v[206:207], s[8:9] offset:32
	v_cvt_pk_bf16_f32 v208, v84, v85
	v_cvt_pk_bf16_f32 v209, v86, v87
	global_store_dwordx2 v224, v[208:209], s[8:9] offset:64
	v_cvt_pk_bf16_f32 v210, v80, v81
	v_cvt_pk_bf16_f32 v211, v82, v83
	global_store_dwordx2 v224, v[210:211], s[8:9] offset:96
	v_add_u32_e32 v224, 0x6000, v224
	v_cvt_pk_bf16_f32 v212, v76, v77
	v_cvt_pk_bf16_f32 v213, v78, v79
	global_store_dwordx2 v224, v[212:213], s[8:9] offset:0
	v_cvt_pk_bf16_f32 v214, v72, v73
	v_cvt_pk_bf16_f32 v215, v74, v75
	global_store_dwordx2 v224, v[214:215], s[8:9] offset:32
	v_cvt_pk_bf16_f32 v216, v68, v69
	v_cvt_pk_bf16_f32 v217, v70, v71
	global_store_dwordx2 v224, v[216:217], s[8:9] offset:64
	v_cvt_pk_bf16_f32 v218, v64, v65
	v_cvt_pk_bf16_f32 v219, v66, v67
	global_store_dwordx2 v224, v[218:219], s[8:9] offset:96
	v_add_u32_e32 v224, 0x6000, v224
	v_cvt_pk_bf16_f32 v188, v60, v61
	v_cvt_pk_bf16_f32 v189, v62, v63
	global_store_dwordx2 v224, v[188:189], s[8:9] offset:0
	v_cvt_pk_bf16_f32 v190, v56, v57
	v_cvt_pk_bf16_f32 v191, v58, v59
	global_store_dwordx2 v224, v[190:191], s[8:9] offset:32
	v_cvt_pk_bf16_f32 v192, v52, v53
	v_cvt_pk_bf16_f32 v193, v54, v55
	global_store_dwordx2 v224, v[192:193], s[8:9] offset:64
	v_cvt_pk_bf16_f32 v194, v48, v49
	v_cvt_pk_bf16_f32 v195, v50, v51
	global_store_dwordx2 v224, v[194:195], s[8:9] offset:96
	v_add_u32_e32 v224, 0x6000, v224
	v_cvt_pk_bf16_f32 v196, v44, v45
	v_cvt_pk_bf16_f32 v197, v46, v47
	global_store_dwordx2 v224, v[196:197], s[8:9] offset:0
	v_cvt_pk_bf16_f32 v198, v40, v41
	v_cvt_pk_bf16_f32 v199, v42, v43
	global_store_dwordx2 v224, v[198:199], s[8:9] offset:32
	v_cvt_pk_bf16_f32 v200, v36, v37
	v_cvt_pk_bf16_f32 v201, v38, v39
	global_store_dwordx2 v224, v[200:201], s[8:9] offset:64
	v_cvt_pk_bf16_f32 v202, v32, v33
	v_cvt_pk_bf16_f32 v203, v34, v35
	global_store_dwordx2 v224, v[202:203], s[8:9] offset:96
	v_add_u32_e32 v224, 0x6000, v224
	v_cvt_pk_bf16_f32 v204, v28, v29
	v_cvt_pk_bf16_f32 v205, v30, v31
	global_store_dwordx2 v224, v[204:205], s[8:9] offset:0
	v_cvt_pk_bf16_f32 v206, v24, v25
	v_cvt_pk_bf16_f32 v207, v26, v27
	global_store_dwordx2 v224, v[206:207], s[8:9] offset:32
	v_cvt_pk_bf16_f32 v208, v20, v21
	v_cvt_pk_bf16_f32 v209, v22, v23
	global_store_dwordx2 v224, v[208:209], s[8:9] offset:64
	v_cvt_pk_bf16_f32 v210, v16, v17
	v_cvt_pk_bf16_f32 v211, v18, v19
	global_store_dwordx2 v224, v[210:211], s[8:9] offset:96
	v_add_u32_e32 v224, 0x6000, v224
	v_cvt_pk_bf16_f32 v212, v12, v13
	v_cvt_pk_bf16_f32 v213, v14, v15
	global_store_dwordx2 v224, v[212:213], s[8:9] offset:0
	v_cvt_pk_bf16_f32 v214, v8, v9
	v_cvt_pk_bf16_f32 v215, v10, v11
	global_store_dwordx2 v224, v[214:215], s[8:9] offset:32
	v_cvt_pk_bf16_f32 v216, v4, v5
	v_cvt_pk_bf16_f32 v217, v6, v7
	global_store_dwordx2 v224, v[216:217], s[8:9] offset:64
	v_cvt_pk_bf16_f32 v218, v0, v1
	v_cvt_pk_bf16_f32 v219, v2, v3
	global_store_dwordx2 v224, v[218:219], s[8:9] offset:96
	s_add_i32 s18, s18, 1
	s_cmp_eq_u32 s18, s3
	s_cbranch_scc0 .LBB0_879

; #define G_LOAD(KT) do { _Pragma("unroll") for (int i = 0; i < 4; ++i) { ra[i] = *(const u32x4*)(Ag + (size_t)i * 64 * lda + (KT) * 64); rb[i] = *(const u32x4*)(Bg + (size_t)i * 64 * K + (KT) * 64); } } while (0)
; #define G_STORE(BUF) do { u16* ad = As + (BUF) * 256 * 64 + sto; u16* bd = Bs + (BUF) * 256 * 64 + sto; _Pragma("unroll") for (int i = 0; i < 4; ++i) { *(u32x4*)(ad + i * 64 * 64) = ra[i]; *(u32x4*)(bd + i * 64 * 64) = rb[i]; } } while (0)
; template <int EPI>
; DI void gemm_phase(const u16* __restrict__ A, int lda, const u16* __restrict__ Bt, int K, int N, u16* outb, int ldo,
;                    const float* r0, const float* r1, float* outf, char* lds, int bid, int nb) {
;     ...
;     if (swz) { const int st = xcd + 8 * it, sm = st / nSN, sn = st - sm * nSN; tm = sm * GM + jb / GN; tn = sn * GN + (jb % GN); }
;     else { const int t = bid + it * nb; tm = t / nN; tn = t - tm * nN; }
;     const u16* Ag = A + (size_t)(tm * 256 + lrow) * lda + lch * 8;
;     const u16* Bg = Bt + (size_t)(tn * 256 + lrow) * K + lch * 8;
;     f32x4 acc[8][4];
; #pragma unroll
;     for (int i = 0; i < 8; ++i)
; #pragma unroll
;       for (int j = 0; j < 4; ++j) acc[i][j] = (f32x4){0.f, 0.f, 0.f, 0.f};
;     u32x4 ra[4], rb[4];
;     ...
;     G_LOAD(0);
;     G_STORE(0);
;     __syncthreads();
;     for (int kt = 0; kt < nk; ++kt) {
;       const int cur = kt & 1;
;       if (kt + 1 < nk) G_LOAD(kt + 1);
;       G_MMA(cur, fo0);
.LBB0_1181:
	s_lshl_b32 s39, s39, 8
	v_or_b32_e32 v0, s39, v138
	v_ashrrev_i32_e32 v1, 31, v0
	s_lshl_b32 s40, s40, 8
	v_or_b32_e32 v2, s40, v138
	v_lshlrev_b64 v[62:63], 11, v[0:1]
	v_ashrrev_i32_e32 v3, 31, v2
	v_lshl_add_u64 v[0:1], v[128:129], 0, v[62:63]
	v_lshlrev_b64 v[64:65], 11, v[2:3]
	v_add_co_u32_e32 v4, vcc, s15, v0
	v_lshl_add_u64 v[2:3], v[130:131], 0, v[64:65]
	s_nop 0
	v_addc_co_u32_e32 v5, vcc, 0, v1, vcc
	v_add_co_u32_e32 v6, vcc, s15, v2
	s_nop 1
	v_readfirstlane_b32 s98, v0
	v_readfirstlane_b32 s99, v1
	s_nop 1
	v_readfirstlane_b32 s100, v2
	v_readfirstlane_b32 s101, v3
	v_addc_co_u32_e32 v7, vcc, 0, v3, vcc
	v_add_co_u32_e32 v4, vcc, s16, v0
	s_mov_b32 s41, 0
	s_nop 0
	v_addc_co_u32_e32 v5, vcc, 0, v1, vcc
	v_add_co_u32_e32 v6, vcc, s16, v2
	s_mov_b64 s[8:9], 0
	s_nop 0
	v_addc_co_u32_e32 v7, vcc, 0, v3, vcc
	v_add_co_u32_e32 v0, vcc, s17, v0
	v_addc_co_u32_e32 v1, vcc, 0, v1, vcc
	v_add_co_u32_e32 v2, vcc, s17, v2
	v_lshl_add_u64 v[134:135], v[132:133], 0, v[62:63]
	s_nop 0
	v_addc_co_u32_e32 v3, vcc, 0, v3, vcc
	v_mov_b32_e32 v0, 0
	v_lshl_add_u64 v[136:137], v[132:133], 0, v[64:65]
	v_and_b32_e32 v229, 63, v174
	v_lshrrev_b32_e32 v230, 3, v229
	v_mov_b32_e32 v233, 0x800
	v_mul_u32_u24_e32 v224, v230, v233
	v_bfe_u32 v231, v174, 4, 2
	v_bfe_u32 v232, v174, 6, 1
	v_lshl_or_b32 v232, v232, 2, v231
	v_and_b32_e32 v233, 7, v174
	v_xor_b32_e32 v232, v232, v233
	v_lshl_add_u32 v224, v232, 4, v224
	v_and_b32_e32 v229, 15, v174
	v_bfe_u32 v230, v174, 1, 3
	v_xor_b32_e32 v230, v230, v231
	v_lshlrev_b32_e32 v230, 4, v230
	v_lshl_or_b32 v230, v229, 7, v230
	v_lshrrev_b32_e32 v229, 8, v174
	v_lshl_or_b32 v225, v229, 14, v230
	v_bfe_u32 v229, v174, 6, 2
	v_lshl_or_b32 v227, v229, 13, v230
	v_or_b32_e32 v227, 0x10000, v227
	v_xor_b32_e32 v226, 64, v225
	v_xor_b32_e32 v228, 64, v227
	v_readfirstlane_b32 s97, v174
	s_lshl_b32 s97, s97, 4
	s_mov_b32 s28, 14
	s_add_u32 m0, s97, 0x0
	s_add_u32 s8, s98, 0x0
	s_addc_u32 s9, s99, 0
	global_load_lds_dwordx4 v224, s[8:9]
	s_add_u32 m0, s97, 0x10000
	s_add_u32 s8, s100, 0x0
	s_addc_u32 s9, s101, 0
	global_load_lds_dwordx4 v224, s[8:9]
	s_add_u32 m0, s97, 0x2000
	s_add_u32 s8, s98, 0x20000
	s_addc_u32 s9, s99, 0
	global_load_lds_dwordx4 v224, s[8:9]
	s_add_u32 m0, s97, 0x12000
	s_add_u32 s8, s100, 0x20000
	s_addc_u32 s9, s101, 0
	global_load_lds_dwordx4 v224, s[8:9]
	s_add_u32 m0, s97, 0x4000
	s_add_u32 s8, s98, 0x40000
	s_addc_u32 s9, s99, 0
	global_load_lds_dwordx4 v224, s[8:9]
	s_add_u32 m0, s97, 0x14000
	s_add_u32 s8, s100, 0x40000
	s_addc_u32 s9, s101, 0
	global_load_lds_dwordx4 v224, s[8:9]
	s_add_u32 m0, s97, 0x6000
	s_add_u32 s8, s98, 0x60000
	s_addc_u32 s9, s99, 0
	global_load_lds_dwordx4 v224, s[8:9]
	s_add_u32 m0, s97, 0x16000
	s_add_u32 s8, s100, 0x60000
	s_addc_u32 s9, s101, 0
	global_load_lds_dwordx4 v224, s[8:9]
	s_add_u32 m0, s97, 0x8000
	s_add_u32 s8, s98, 0x80
	s_addc_u32 s9, s99, 0
	global_load_lds_dwordx4 v224, s[8:9]
	s_add_u32 m0, s97, 0x18000
	s_add_u32 s8, s100, 0x80
	s_addc_u32 s9, s101, 0
	global_load_lds_dwordx4 v224, s[8:9]
	s_add_u32 m0, s97, 0xa000
	s_add_u32 s8, s98, 0x20080
	s_addc_u32 s9, s99, 0
	global_load_lds_dwordx4 v224, s[8:9]
	s_add_u32 m0, s97, 0x1a000
	s_add_u32 s8, s100, 0x20080
	s_addc_u32 s9, s101, 0
	global_load_lds_dwordx4 v224, s[8:9]
	s_add_u32 m0, s97, 0xc000
	s_add_u32 s8, s98, 0x40080
	s_addc_u32 s9, s99, 0
	global_load_lds_dwordx4 v224, s[8:9]
	s_add_u32 m0, s97, 0x1c000
	s_add_u32 s8, s100, 0x40080
	s_addc_u32 s9, s101, 0
	global_load_lds_dwordx4 v224, s[8:9]
	s_add_u32 m0, s97, 0xe000
	s_add_u32 s8, s98, 0x60080
	s_addc_u32 s9, s99, 0
	global_load_lds_dwordx4 v224, s[8:9]
	s_add_u32 m0, s97, 0x1e000
	s_add_u32 s8, s100, 0x60080
	s_addc_u32 s9, s101, 0
	global_load_lds_dwordx4 v224, s[8:9]
	s_add_u32 s98, s98, 0x100
	s_addc_u32 s99, s99, 0
	s_add_u32 s100, s100, 0x100
	s_addc_u32 s101, s101, 0
	s_waitcnt vmcnt(8)
	s_barrier
; #define G_LOAD(KT) do { _Pragma("unroll") for (int i = 0; i < 4; ++i) { ra[i] = *(const u32x4*)(Ag + (size_t)i * 64 * lda + (KT) * 64); rb[i] = *(const u32x4*)(Bg + (size_t)i * 64 * K + (KT) * 64); } } while (0)
; template <int EPI>
; DI void gemm_phase(const u16* __restrict__ A, int lda, const u16* __restrict__ Bt, int K, int N, u16* outb, int ldo,
;                    const float* r0, const float* r1, float* outf, char* lds, int bid, int nb) {
;     ...
;     for (int kt = 0; kt < nk; ++kt) {
;       const int cur = kt & 1;
;       if (kt + 1 < nk) G_LOAD(kt + 1);
;       G_MMA(cur, fo0);
;       G_MMA(cur, fo1);
	ds_read_b128 v[152:155], v227 offset:0
	ds_read_b128 v[156:159], v227 offset:2048
	ds_read_b128 v[160:163], v227 offset:4096
	ds_read_b128 v[164:167], v227 offset:6144
	ds_read_b128 v[188:191], v225 offset:0
	ds_read_b128 v[192:195], v225 offset:2048
	ds_read_b128 v[196:199], v225 offset:4096
	ds_read_b128 v[200:203], v225 offset:6144
	ds_read_b128 v[204:207], v225 offset:8192
	ds_read_b128 v[208:211], v225 offset:10240
	ds_read_b128 v[212:215], v225 offset:12288
	ds_read_b128 v[216:219], v225 offset:14336
	v_xor_b32_e32 v225, 0x8000, v225
	v_xor_b32_e32 v227, 0x8000, v227
	s_waitcnt lgkmcnt(0)
	s_waitcnt lgkmcnt(4)
	v_mfma_f32_16x16x32_bf16 v[124:127], v[152:155], v[188:191], 0
	v_mfma_f32_16x16x32_bf16 v[120:123], v[156:159], v[188:191], 0
	v_mfma_f32_16x16x32_bf16 v[116:119], v[160:163], v[188:191], 0
	v_mfma_f32_16x16x32_bf16 v[112:115], v[164:167], v[188:191], 0
	ds_read_b128 v[188:191], v226 offset:0
	ds_read_b128 v[168:171], v228 offset:0
	v_mfma_f32_16x16x32_bf16 v[108:111], v[152:155], v[192:195], 0
	v_mfma_f32_16x16x32_bf16 v[104:107], v[156:159], v[192:195], 0
	v_mfma_f32_16x16x32_bf16 v[100:103], v[160:163], v[192:195], 0
	v_mfma_f32_16x16x32_bf16 v[96:99], v[164:167], v[192:195], 0
	ds_read_b128 v[192:195], v226 offset:2048
	ds_read_b128 v[176:179], v228 offset:2048
	v_mfma_f32_16x16x32_bf16 v[92:95], v[152:155], v[196:199], 0
	v_mfma_f32_16x16x32_bf16 v[88:91], v[156:159], v[196:199], 0
	v_mfma_f32_16x16x32_bf16 v[84:87], v[160:163], v[196:199], 0
	v_mfma_f32_16x16x32_bf16 v[80:83], v[164:167], v[196:199], 0
	ds_read_b128 v[196:199], v226 offset:4096
	ds_read_b128 v[180:183], v228 offset:4096
	v_mfma_f32_16x16x32_bf16 v[76:79], v[152:155], v[200:203], 0
	v_mfma_f32_16x16x32_bf16 v[72:75], v[156:159], v[200:203], 0
	v_mfma_f32_16x16x32_bf16 v[68:71], v[160:163], v[200:203], 0
	v_mfma_f32_16x16x32_bf16 v[64:67], v[164:167], v[200:203], 0
	ds_read_b128 v[200:203], v226 offset:6144
	ds_read_b128 v[184:187], v228 offset:6144
	s_waitcnt lgkmcnt(11)
	v_mfma_f32_16x16x32_bf16 v[60:63], v[152:155], v[204:207], 0
	v_mfma_f32_16x16x32_bf16 v[56:59], v[156:159], v[204:207], 0
	v_mfma_f32_16x16x32_bf16 v[52:55], v[160:163], v[204:207], 0
	v_mfma_f32_16x16x32_bf16 v[48:51], v[164:167], v[204:207], 0
	ds_read_b128 v[204:207], v226 offset:8192
	ds_read_b128 v[220:223], v226 offset:14336
	s_waitcnt lgkmcnt(11)
	v_mfma_f32_16x16x32_bf16 v[44:47], v[152:155], v[208:211], 0
	v_mfma_f32_16x16x32_bf16 v[40:43], v[156:159], v[208:211], 0
	v_mfma_f32_16x16x32_bf16 v[36:39], v[160:163], v[208:211], 0
	v_mfma_f32_16x16x32_bf16 v[32:35], v[164:167], v[208:211], 0
	ds_read_b128 v[208:211], v226 offset:10240
	s_waitcnt lgkmcnt(11)
	v_mfma_f32_16x16x32_bf16 v[28:31], v[152:155], v[212:215], 0
	v_mfma_f32_16x16x32_bf16 v[24:27], v[156:159], v[212:215], 0
	v_mfma_f32_16x16x32_bf16 v[20:23], v[160:163], v[212:215], 0
	v_mfma_f32_16x16x32_bf16 v[16:19], v[164:167], v[212:215], 0
	ds_read_b128 v[212:215], v226 offset:12288
	v_mfma_f32_16x16x32_bf16 v[12:15], v[152:155], v[216:219], 0
	v_mfma_f32_16x16x32_bf16 v[8:11], v[156:159], v[216:219], 0
	v_mfma_f32_16x16x32_bf16 v[4:7], v[160:163], v[216:219], 0
	v_mfma_f32_16x16x32_bf16 v[0:3], v[164:167], v[216:219], 0
	s_branch .Lgm5_mid0

; #define G_LOAD(KT) do { _Pragma("unroll") for (int i = 0; i < 4; ++i) { ra[i] = *(const u32x4*)(Ag + (size_t)i * 64 * lda + (KT) * 64); rb[i] = *(const u32x4*)(Bg + (size_t)i * 64 * K + (KT) * 64); } } while (0)
; #define G_STORE(BUF) do { u16* ad = As + (BUF) * 256 * 64 + sto; u16* bd = Bs + (BUF) * 256 * 64 + sto; _Pragma("unroll") for (int i = 0; i < 4; ++i) { *(u32x4*)(ad + i * 64 * 64) = ra[i]; *(u32x4*)(bd + i * 64 * 64) = rb[i]; } } while (0)
; template <int EPI>
; DI void gemm_phase(const u16* __restrict__ A, int lda, const u16* __restrict__ Bt, int K, int N, u16* outb, int ldo,
;                    const float* r0, const float* r1, float* outf, char* lds, int bid, int nb) {
;     ...
;     for (int kt = 0; kt < nk; ++kt) {
;       const int cur = kt & 1;
;       if (kt + 1 < nk) G_LOAD(kt + 1);
;       G_MMA(cur, fo0);
;       G_MMA(cur, fo1);
;       if (kt + 1 < nk) G_STORE(cur ^ 1);
;       __syncthreads();
;     }
.Lgm5_mid0:
	s_waitcnt vmcnt(0) lgkmcnt(0)
	s_barrier
	v_mfma_f32_16x16x32_bf16 v[124:127], v[168:171], v[188:191], v[124:127]
	v_mfma_f32_16x16x32_bf16 v[120:123], v[176:179], v[188:191], v[120:123]
	v_mfma_f32_16x16x32_bf16 v[116:119], v[180:183], v[188:191], v[116:119]
	v_mfma_f32_16x16x32_bf16 v[112:115], v[184:187], v[188:191], v[112:115]
	ds_read_b128 v[188:191], v225 offset:0
	ds_read_b128 v[152:155], v227 offset:0
	s_add_u32 m0, s97, 0x0
	s_add_u32 s8, s98, 0x0
	s_addc_u32 s9, s99, 0
	global_load_lds_dwordx4 v224, s[8:9]
	v_mfma_f32_16x16x32_bf16 v[108:111], v[168:171], v[192:195], v[108:111]
	v_mfma_f32_16x16x32_bf16 v[104:107], v[176:179], v[192:195], v[104:107]
	v_mfma_f32_16x16x32_bf16 v[100:103], v[180:183], v[192:195], v[100:103]
	v_mfma_f32_16x16x32_bf16 v[96:99], v[184:187], v[192:195], v[96:99]
	ds_read_b128 v[192:195], v225 offset:2048
	ds_read_b128 v[156:159], v227 offset:2048
	s_add_u32 m0, s97, 0x10000
	s_add_u32 s8, s100, 0x0
	s_addc_u32 s9, s101, 0
	global_load_lds_dwordx4 v224, s[8:9]
	v_mfma_f32_16x16x32_bf16 v[92:95], v[168:171], v[196:199], v[92:95]
	v_mfma_f32_16x16x32_bf16 v[88:91], v[176:179], v[196:199], v[88:91]
	v_mfma_f32_16x16x32_bf16 v[84:87], v[180:183], v[196:199], v[84:87]
	v_mfma_f32_16x16x32_bf16 v[80:83], v[184:187], v[196:199], v[80:83]
	ds_read_b128 v[196:199], v225 offset:4096
	ds_read_b128 v[160:163], v227 offset:4096
	s_add_u32 m0, s97, 0x2000
	s_add_u32 s8, s98, 0x20000
	s_addc_u32 s9, s99, 0
	global_load_lds_dwordx4 v224, s[8:9]
	v_mfma_f32_16x16x32_bf16 v[76:79], v[168:171], v[200:203], v[76:79]
	v_mfma_f32_16x16x32_bf16 v[72:75], v[176:179], v[200:203], v[72:75]
	v_mfma_f32_16x16x32_bf16 v[68:71], v[180:183], v[200:203], v[68:71]
	v_mfma_f32_16x16x32_bf16 v[64:67], v[184:187], v[200:203], v[64:67]
	ds_read_b128 v[200:203], v225 offset:6144
	ds_read_b128 v[164:167], v227 offset:6144
	s_add_u32 m0, s97, 0x12000
	s_add_u32 s8, s100, 0x20000
	s_addc_u32 s9, s101, 0
	global_load_lds_dwordx4 v224, s[8:9]
	v_mfma_f32_16x16x32_bf16 v[60:63], v[168:171], v[204:207], v[60:63]
	v_mfma_f32_16x16x32_bf16 v[56:59], v[176:179], v[204:207], v[56:59]
	v_mfma_f32_16x16x32_bf16 v[52:55], v[180:183], v[204:207], v[52:55]
	v_mfma_f32_16x16x32_bf16 v[48:51], v[184:187], v[204:207], v[48:51]
	ds_read_b128 v[204:207], v225 offset:8192
	ds_read_b128 v[216:219], v225 offset:14336
	s_add_u32 m0, s97, 0x4000
	s_add_u32 s8, s98, 0x40000
	s_addc_u32 s9, s99, 0
	global_load_lds_dwordx4 v224, s[8:9]
	v_mfma_f32_16x16x32_bf16 v[44:47], v[168:171], v[208:211], v[44:47]
	v_mfma_f32_16x16x32_bf16 v[40:43], v[176:179], v[208:211], v[40:43]
	v_mfma_f32_16x16x32_bf16 v[36:39], v[180:183], v[208:211], v[36:39]
	v_mfma_f32_16x16x32_bf16 v[32:35], v[184:187], v[208:211], v[32:35]
	ds_read_b128 v[208:211], v225 offset:10240
	s_add_u32 m0, s97, 0x14000
	s_add_u32 s8, s100, 0x40000
	s_addc_u32 s9, s101, 0
	global_load_lds_dwordx4 v224, s[8:9]
	v_mfma_f32_16x16x32_bf16 v[28:31], v[168:171], v[212:215], v[28:31]
	v_mfma_f32_16x16x32_bf16 v[24:27], v[176:179], v[212:215], v[24:27]
	v_mfma_f32_16x16x32_bf16 v[20:23], v[180:183], v[212:215], v[20:23]
	v_mfma_f32_16x16x32_bf16 v[16:19], v[184:187], v[212:215], v[16:19]
	ds_read_b128 v[212:215], v225 offset:12288
	s_add_u32 m0, s97, 0x6000
	s_add_u32 s8, s98, 0x60000
	s_addc_u32 s9, s99, 0
	global_load_lds_dwordx4 v224, s[8:9]
	v_mfma_f32_16x16x32_bf16 v[12:15], v[168:171], v[220:223], v[12:15]
	v_mfma_f32_16x16x32_bf16 v[8:11], v[176:179], v[220:223], v[8:11]
	v_mfma_f32_16x16x32_bf16 v[4:7], v[180:183], v[220:223], v[4:7]
	v_mfma_f32_16x16x32_bf16 v[0:3], v[184:187], v[220:223], v[0:3]
	s_add_u32 m0, s97, 0x16000
	s_add_u32 s8, s100, 0x60000
	s_addc_u32 s9, s101, 0
	global_load_lds_dwordx4 v224, s[8:9]
	v_xor_b32_e32 v225, 0x8000, v225
	v_xor_b32_e32 v227, 0x8000, v227
	v_xor_b32_e32 v226, 0x8000, v226
	v_xor_b32_e32 v228, 0x8000, v228
	s_xor_b32 s97, s97, 0x8000
	s_add_u32 s98, s98, 0x80
	s_addc_u32 s99, s99, 0
	s_add_u32 s100, s100, 0x80
	s_addc_u32 s101, s101, 0
	s_sub_u32 s28, s28, 1
	s_cmp_lg_u32 s28, 0
	s_cbranch_scc1 .Lgm5_loop
	s_waitcnt lgkmcnt(4)
	v_mfma_f32_16x16x32_bf16 v[124:127], v[152:155], v[188:191], v[124:127]
	v_mfma_f32_16x16x32_bf16 v[120:123], v[156:159], v[188:191], v[120:123]
	v_mfma_f32_16x16x32_bf16 v[116:119], v[160:163], v[188:191], v[116:119]
	v_mfma_f32_16x16x32_bf16 v[112:115], v[164:167], v[188:191], v[112:115]
	ds_read_b128 v[188:191], v226 offset:0
	ds_read_b128 v[168:171], v228 offset:0
	v_mfma_f32_16x16x32_bf16 v[108:111], v[152:155], v[192:195], v[108:111]
	v_mfma_f32_16x16x32_bf16 v[104:107], v[156:159], v[192:195], v[104:107]
	v_mfma_f32_16x16x32_bf16 v[100:103], v[160:163], v[192:195], v[100:103]
	v_mfma_f32_16x16x32_bf16 v[96:99], v[164:167], v[192:195], v[96:99]
	ds_read_b128 v[192:195], v226 offset:2048
	ds_read_b128 v[176:179], v228 offset:2048
	v_mfma_f32_16x16x32_bf16 v[92:95], v[152:155], v[196:199], v[92:95]
	v_mfma_f32_16x16x32_bf16 v[88:91], v[156:159], v[196:199], v[88:91]
	v_mfma_f32_16x16x32_bf16 v[84:87], v[160:163], v[196:199], v[84:87]
	v_mfma_f32_16x16x32_bf16 v[80:83], v[164:167], v[196:199], v[80:83]
	ds_read_b128 v[196:199], v226 offset:4096
	ds_read_b128 v[180:183], v228 offset:4096
	v_mfma_f32_16x16x32_bf16 v[76:79], v[152:155], v[200:203], v[76:79]
	v_mfma_f32_16x16x32_bf16 v[72:75], v[156:159], v[200:203], v[72:75]
	v_mfma_f32_16x16x32_bf16 v[68:71], v[160:163], v[200:203], v[68:71]
	v_mfma_f32_16x16x32_bf16 v[64:67], v[164:167], v[200:203], v[64:67]
	ds_read_b128 v[200:203], v226 offset:6144
	ds_read_b128 v[184:187], v228 offset:6144
	s_waitcnt lgkmcnt(11)
	v_mfma_f32_16x16x32_bf16 v[60:63], v[152:155], v[204:207], v[60:63]
	v_mfma_f32_16x16x32_bf16 v[56:59], v[156:159], v[204:207], v[56:59]
	v_mfma_f32_16x16x32_bf16 v[52:55], v[160:163], v[204:207], v[52:55]
	v_mfma_f32_16x16x32_bf16 v[48:51], v[164:167], v[204:207], v[48:51]
	ds_read_b128 v[204:207], v226 offset:8192
	ds_read_b128 v[220:223], v226 offset:14336
	s_waitcnt lgkmcnt(11)
	v_mfma_f32_16x16x32_bf16 v[44:47], v[152:155], v[208:211], v[44:47]
	v_mfma_f32_16x16x32_bf16 v[40:43], v[156:159], v[208:211], v[40:43]
	v_mfma_f32_16x16x32_bf16 v[36:39], v[160:163], v[208:211], v[36:39]
	v_mfma_f32_16x16x32_bf16 v[32:35], v[164:167], v[208:211], v[32:35]
	ds_read_b128 v[208:211], v226 offset:10240
	s_waitcnt lgkmcnt(11)
	v_mfma_f32_16x16x32_bf16 v[28:31], v[152:155], v[212:215], v[28:31]
	v_mfma_f32_16x16x32_bf16 v[24:27], v[156:159], v[212:215], v[24:27]
	v_mfma_f32_16x16x32_bf16 v[20:23], v[160:163], v[212:215], v[20:23]
	v_mfma_f32_16x16x32_bf16 v[16:19], v[164:167], v[212:215], v[16:19]
	ds_read_b128 v[212:215], v226 offset:12288
	v_mfma_f32_16x16x32_bf16 v[12:15], v[152:155], v[216:219], v[12:15]
	v_mfma_f32_16x16x32_bf16 v[8:11], v[156:159], v[216:219], v[8:11]
	v_mfma_f32_16x16x32_bf16 v[4:7], v[160:163], v[216:219], v[4:7]
	v_mfma_f32_16x16x32_bf16 v[0:3], v[164:167], v[216:219], v[0:3]
	s_waitcnt vmcnt(0) lgkmcnt(0)
	s_barrier
; #define G_LOAD(KT) do { _Pragma("unroll") for (int i = 0; i < 4; ++i) { ra[i] = *(const u32x4*)(Ag + (size_t)i * 64 * lda + (KT) * 64); rb[i] = *(const u32x4*)(Bg + (size_t)i * 64 * K + (KT) * 64); } } while (0)
; #define G_STORE(BUF) do { u16* ad = As + (BUF) * 256 * 64 + sto; u16* bd = Bs + (BUF) * 256 * 64 + sto; _Pragma("unroll") for (int i = 0; i < 4; ++i) { *(u32x4*)(ad + i * 64 * 64) = ra[i]; *(u32x4*)(bd + i * 64 * 64) = rb[i]; } } while (0)
; template <int EPI>
; DI void gemm_phase(const u16* __restrict__ A, int lda, const u16* __restrict__ Bt, int K, int N, u16* outb, int ldo,
;                    const float* r0, const float* r1, float* outf, char* lds, int bid, int nb) {
;     ...
;     for (int kt = 0; kt < nk; ++kt) {
;       const int cur = kt & 1;
;       if (kt + 1 < nk) G_LOAD(kt + 1);
;       G_MMA(cur, fo0);
;       G_MMA(cur, fo1);
;       if (kt + 1 < nk) G_STORE(cur ^ 1);
;       __syncthreads();
;     }
	v_mfma_f32_16x16x32_bf16 v[124:127], v[168:171], v[188:191], v[124:127]
	v_mfma_f32_16x16x32_bf16 v[120:123], v[176:179], v[188:191], v[120:123]
	v_mfma_f32_16x16x32_bf16 v[116:119], v[180:183], v[188:191], v[116:119]
	v_mfma_f32_16x16x32_bf16 v[112:115], v[184:187], v[188:191], v[112:115]
	ds_read_b128 v[188:191], v225 offset:0
	ds_read_b128 v[152:155], v227 offset:0
	v_mfma_f32_16x16x32_bf16 v[108:111], v[168:171], v[192:195], v[108:111]
	v_mfma_f32_16x16x32_bf16 v[104:107], v[176:179], v[192:195], v[104:107]
	v_mfma_f32_16x16x32_bf16 v[100:103], v[180:183], v[192:195], v[100:103]
	v_mfma_f32_16x16x32_bf16 v[96:99], v[184:187], v[192:195], v[96:99]
	ds_read_b128 v[192:195], v225 offset:2048
	ds_read_b128 v[156:159], v227 offset:2048
	v_mfma_f32_16x16x32_bf16 v[92:95], v[168:171], v[196:199], v[92:95]
	v_mfma_f32_16x16x32_bf16 v[88:91], v[176:179], v[196:199], v[88:91]
	v_mfma_f32_16x16x32_bf16 v[84:87], v[180:183], v[196:199], v[84:87]
	v_mfma_f32_16x16x32_bf16 v[80:83], v[184:187], v[196:199], v[80:83]
	ds_read_b128 v[196:199], v225 offset:4096
	ds_read_b128 v[160:163], v227 offset:4096
	v_mfma_f32_16x16x32_bf16 v[76:79], v[168:171], v[200:203], v[76:79]
	v_mfma_f32_16x16x32_bf16 v[72:75], v[176:179], v[200:203], v[72:75]
	v_mfma_f32_16x16x32_bf16 v[68:71], v[180:183], v[200:203], v[68:71]
	v_mfma_f32_16x16x32_bf16 v[64:67], v[184:187], v[200:203], v[64:67]
	ds_read_b128 v[200:203], v225 offset:6144
	ds_read_b128 v[164:167], v227 offset:6144
	v_mfma_f32_16x16x32_bf16 v[60:63], v[168:171], v[204:207], v[60:63]
	v_mfma_f32_16x16x32_bf16 v[56:59], v[176:179], v[204:207], v[56:59]
	v_mfma_f32_16x16x32_bf16 v[52:55], v[180:183], v[204:207], v[52:55]
	v_mfma_f32_16x16x32_bf16 v[48:51], v[184:187], v[204:207], v[48:51]
	ds_read_b128 v[204:207], v225 offset:8192
	ds_read_b128 v[216:219], v225 offset:14336
	v_mfma_f32_16x16x32_bf16 v[44:47], v[168:171], v[208:211], v[44:47]
	v_mfma_f32_16x16x32_bf16 v[40:43], v[176:179], v[208:211], v[40:43]
	v_mfma_f32_16x16x32_bf16 v[36:39], v[180:183], v[208:211], v[36:39]
	v_mfma_f32_16x16x32_bf16 v[32:35], v[184:187], v[208:211], v[32:35]
	ds_read_b128 v[208:211], v225 offset:10240
	v_mfma_f32_16x16x32_bf16 v[28:31], v[168:171], v[212:215], v[28:31]
	v_mfma_f32_16x16x32_bf16 v[24:27], v[176:179], v[212:215], v[24:27]
	v_mfma_f32_16x16x32_bf16 v[20:23], v[180:183], v[212:215], v[20:23]
	v_mfma_f32_16x16x32_bf16 v[16:19], v[184:187], v[212:215], v[16:19]
	ds_read_b128 v[212:215], v225 offset:12288
	v_mfma_f32_16x16x32_bf16 v[12:15], v[168:171], v[220:223], v[12:15]
	v_mfma_f32_16x16x32_bf16 v[8:11], v[176:179], v[220:223], v[8:11]
	v_mfma_f32_16x16x32_bf16 v[4:7], v[180:183], v[220:223], v[4:7]
	v_mfma_f32_16x16x32_bf16 v[0:3], v[184:187], v[220:223], v[0:3]
	v_xor_b32_e32 v226, 0x8000, v226
	v_xor_b32_e32 v228, 0x8000, v228
	s_waitcnt lgkmcnt(4)
	v_mfma_f32_16x16x32_bf16 v[124:127], v[152:155], v[188:191], v[124:127]
	v_mfma_f32_16x16x32_bf16 v[120:123], v[156:159], v[188:191], v[120:123]
	v_mfma_f32_16x16x32_bf16 v[116:119], v[160:163], v[188:191], v[116:119]
	v_mfma_f32_16x16x32_bf16 v[112:115], v[164:167], v[188:191], v[112:115]
	ds_read_b128 v[188:191], v226 offset:0
	ds_read_b128 v[168:171], v228 offset:0
	v_mfma_f32_16x16x32_bf16 v[108:111], v[152:155], v[192:195], v[108:111]
	v_mfma_f32_16x16x32_bf16 v[104:107], v[156:159], v[192:195], v[104:107]
	v_mfma_f32_16x16x32_bf16 v[100:103], v[160:163], v[192:195], v[100:103]
	v_mfma_f32_16x16x32_bf16 v[96:99], v[164:167], v[192:195], v[96:99]
	ds_read_b128 v[192:195], v226 offset:2048
	ds_read_b128 v[176:179], v228 offset:2048
	v_mfma_f32_16x16x32_bf16 v[92:95], v[152:155], v[196:199], v[92:95]
	v_mfma_f32_16x16x32_bf16 v[88:91], v[156:159], v[196:199], v[88:91]
	v_mfma_f32_16x16x32_bf16 v[84:87], v[160:163], v[196:199], v[84:87]
	v_mfma_f32_16x16x32_bf16 v[80:83], v[164:167], v[196:199], v[80:83]
	ds_read_b128 v[196:199], v226 offset:4096
	ds_read_b128 v[180:183], v228 offset:4096
	v_mfma_f32_16x16x32_bf16 v[76:79], v[152:155], v[200:203], v[76:79]
	v_mfma_f32_16x16x32_bf16 v[72:75], v[156:159], v[200:203], v[72:75]
	v_mfma_f32_16x16x32_bf16 v[68:71], v[160:163], v[200:203], v[68:71]
	v_mfma_f32_16x16x32_bf16 v[64:67], v[164:167], v[200:203], v[64:67]
	ds_read_b128 v[200:203], v226 offset:6144
	ds_read_b128 v[184:187], v228 offset:6144
	s_waitcnt lgkmcnt(11)
	v_mfma_f32_16x16x32_bf16 v[60:63], v[152:155], v[204:207], v[60:63]
	v_mfma_f32_16x16x32_bf16 v[56:59], v[156:159], v[204:207], v[56:59]
	v_mfma_f32_16x16x32_bf16 v[52:55], v[160:163], v[204:207], v[52:55]
	v_mfma_f32_16x16x32_bf16 v[48:51], v[164:167], v[204:207], v[48:51]
	ds_read_b128 v[204:207], v226 offset:8192
	ds_read_b128 v[220:223], v226 offset:14336
	s_waitcnt lgkmcnt(11)
	v_mfma_f32_16x16x32_bf16 v[44:47], v[152:155], v[208:211], v[44:47]
	v_mfma_f32_16x16x32_bf16 v[40:43], v[156:159], v[208:211], v[40:43]
	v_mfma_f32_16x16x32_bf16 v[36:39], v[160:163], v[208:211], v[36:39]
	v_mfma_f32_16x16x32_bf16 v[32:35], v[164:167], v[208:211], v[32:35]
	ds_read_b128 v[208:211], v226 offset:10240
	s_waitcnt lgkmcnt(11)
	v_mfma_f32_16x16x32_bf16 v[28:31], v[152:155], v[212:215], v[28:31]
	v_mfma_f32_16x16x32_bf16 v[24:27], v[156:159], v[212:215], v[24:27]
	v_mfma_f32_16x16x32_bf16 v[20:23], v[160:163], v[212:215], v[20:23]
	v_mfma_f32_16x16x32_bf16 v[16:19], v[164:167], v[212:215], v[16:19]
	ds_read_b128 v[212:215], v226 offset:12288
	v_mfma_f32_16x16x32_bf16 v[12:15], v[152:155], v[216:219], v[12:15]
	v_mfma_f32_16x16x32_bf16 v[8:11], v[156:159], v[216:219], v[8:11]
	v_mfma_f32_16x16x32_bf16 v[4:7], v[160:163], v[216:219], v[4:7]
	v_mfma_f32_16x16x32_bf16 v[0:3], v[164:167], v[216:219], v[0:3]
	s_waitcnt vmcnt(0) lgkmcnt(0)
	s_barrier
; template <int EPI>
; DI void gemm_phase(const u16* __restrict__ A, int lda, const u16* __restrict__ Bt, int K, int N, u16* outb, int ldo,
;                    const float* r0, const float* r1, float* outf, char* lds, int bid, int nb) {
;     ...
;       const int col = tn * 256 + wc * 64 + l15;
;       const float* rb_ = (tm * 256 < M_P) ? r0 : (r1 - (size_t)M_P * DM);
; #pragma unroll
;       for (int i = 0; i < 8; ++i)
; #pragma unroll
;         for (int r = 0; r < 4; ++r) {
;           const size_t i0 = (size_t)(mrow + i * 16 + r) * DM + col;
;           const float x0 = rb_[i0], x1 = rb_[i0 + 16], x2 = rb_[i0 + 32], x3 = rb_[i0 + 48];
;           outf[i0] = x0 + acc[i][0][r]; outf[i0 + 16] = x1 + acc[i][1][r]; outf[i0 + 32] = x2 + acc[i][2][r]; outf[i0 + 48] = x3 + acc[i][3][r];
	v_mfma_f32_16x16x32_bf16 v[124:127], v[168:171], v[188:191], v[124:127]
	v_mfma_f32_16x16x32_bf16 v[120:123], v[176:179], v[188:191], v[120:123]
	v_mfma_f32_16x16x32_bf16 v[116:119], v[180:183], v[188:191], v[116:119]
	v_mfma_f32_16x16x32_bf16 v[112:115], v[184:187], v[188:191], v[112:115]
	v_mfma_f32_16x16x32_bf16 v[108:111], v[168:171], v[192:195], v[108:111]
	v_mfma_f32_16x16x32_bf16 v[104:107], v[176:179], v[192:195], v[104:107]
	v_mfma_f32_16x16x32_bf16 v[100:103], v[180:183], v[192:195], v[100:103]
	v_mfma_f32_16x16x32_bf16 v[96:99], v[184:187], v[192:195], v[96:99]
	v_mfma_f32_16x16x32_bf16 v[92:95], v[168:171], v[196:199], v[92:95]
	v_mfma_f32_16x16x32_bf16 v[88:91], v[176:179], v[196:199], v[88:91]
	v_mfma_f32_16x16x32_bf16 v[84:87], v[180:183], v[196:199], v[84:87]
	v_mfma_f32_16x16x32_bf16 v[80:83], v[184:187], v[196:199], v[80:83]
	v_mfma_f32_16x16x32_bf16 v[76:79], v[168:171], v[200:203], v[76:79]
	v_mfma_f32_16x16x32_bf16 v[72:75], v[176:179], v[200:203], v[72:75]
	v_mfma_f32_16x16x32_bf16 v[68:71], v[180:183], v[200:203], v[68:71]
	v_mfma_f32_16x16x32_bf16 v[64:67], v[184:187], v[200:203], v[64:67]
	v_mfma_f32_16x16x32_bf16 v[60:63], v[168:171], v[204:207], v[60:63]
	v_mfma_f32_16x16x32_bf16 v[56:59], v[176:179], v[204:207], v[56:59]
	v_mfma_f32_16x16x32_bf16 v[52:55], v[180:183], v[204:207], v[52:55]
	v_mfma_f32_16x16x32_bf16 v[48:51], v[184:187], v[204:207], v[48:51]
	v_mfma_f32_16x16x32_bf16 v[44:47], v[168:171], v[208:211], v[44:47]
	v_mfma_f32_16x16x32_bf16 v[40:43], v[176:179], v[208:211], v[40:43]
	v_mfma_f32_16x16x32_bf16 v[36:39], v[180:183], v[208:211], v[36:39]
	v_mfma_f32_16x16x32_bf16 v[32:35], v[184:187], v[208:211], v[32:35]
	v_mfma_f32_16x16x32_bf16 v[28:31], v[168:171], v[212:215], v[28:31]
	v_mfma_f32_16x16x32_bf16 v[24:27], v[176:179], v[212:215], v[24:27]
	v_mfma_f32_16x16x32_bf16 v[20:23], v[180:183], v[212:215], v[20:23]
	v_mfma_f32_16x16x32_bf16 v[16:19], v[184:187], v[212:215], v[16:19]
	v_mfma_f32_16x16x32_bf16 v[12:15], v[168:171], v[220:223], v[12:15]
	v_mfma_f32_16x16x32_bf16 v[8:11], v[176:179], v[220:223], v[8:11]
	v_mfma_f32_16x16x32_bf16 v[4:7], v[180:183], v[220:223], v[4:7]
	v_mfma_f32_16x16x32_bf16 v[0:3], v[184:187], v[220:223], v[0:3]
	s_nop 7
	s_nop 3
	v_and_b32_e32 v225, 15, v174
	v_lshrrev_b32_e32 v226, 8, v174
	v_lshl_or_b32 v225, v226, 7, v225
	v_bfe_u32 v226, v174, 6, 2
	v_bfe_u32 v227, v174, 4, 2
	v_lshlrev_b32_e32 v227, 2, v227
	v_add_u32_e32 v225, s39, v225
	v_lshl_add_u32 v226, v226, 6, v227
	v_add_u32_e32 v226, s40, v226
	v_lshlrev_b32_e32 v226, 2, v226
	v_lshl_add_u32 v224, v225, 12, v226
	v_mov_b32_e32 v229, v224
	v_add_u32_e32 v224, 0x0, v229
	global_load_dwordx4 v[152:155], v224, s[22:23] offset:0
	global_load_dwordx4 v[156:159], v224, s[22:23] offset:64
	global_load_dwordx4 v[160:163], v224, s[22:23] offset:128
	global_load_dwordx4 v[164:167], v224, s[22:23] offset:192
	v_add_u32_e32 v228, 0x10000, v229
	global_load_dwordx4 v[168:171], v228, s[22:23] offset:0
	global_load_dwordx4 v[176:179], v228, s[22:23] offset:64
	global_load_dwordx4 v[180:183], v228, s[22:23] offset:128
	global_load_dwordx4 v[184:187], v228, s[22:23] offset:192
	s_waitcnt vmcnt(4)
	v_add_f32_e32 v152, v124, v152
	v_add_f32_e32 v153, v125, v153
	v_add_f32_e32 v154, v126, v154
	v_add_f32_e32 v155, v127, v155
	v_add_f32_e32 v156, v120, v156
	v_add_f32_e32 v157, v121, v157
	v_add_f32_e32 v158, v122, v158
	v_add_f32_e32 v159, v123, v159
	v_add_f32_e32 v160, v116, v160
	v_add_f32_e32 v161, v117, v161
	v_add_f32_e32 v162, v118, v162
	v_add_f32_e32 v163, v119, v163
	v_add_f32_e32 v164, v112, v164
	v_add_f32_e32 v165, v113, v165
	v_add_f32_e32 v166, v114, v166
	v_add_f32_e32 v167, v115, v167
	global_store_dwordx4 v224, v[152:155], s[22:23] offset:0
	global_store_dwordx4 v224, v[156:159], s[22:23] offset:64
	global_store_dwordx4 v224, v[160:163], s[22:23] offset:128
	global_store_dwordx4 v224, v[164:167], s[22:23] offset:192
	s_nop 1
	v_add_u32_e32 v224, 0x20000, v229
	global_load_dwordx4 v[152:155], v224, s[22:23] offset:0
	global_load_dwordx4 v[156:159], v224, s[22:23] offset:64
	global_load_dwordx4 v[160:163], v224, s[22:23] offset:128
	global_load_dwordx4 v[164:167], v224, s[22:23] offset:192
	s_waitcnt vmcnt(8)
	v_add_f32_e32 v168, v108, v168
	v_add_f32_e32 v169, v109, v169
	v_add_f32_e32 v170, v110, v170
	v_add_f32_e32 v171, v111, v171
	v_add_f32_e32 v176, v104, v176
	v_add_f32_e32 v177, v105, v177
	v_add_f32_e32 v178, v106, v178
	v_add_f32_e32 v179, v107, v179
	v_add_f32_e32 v180, v100, v180
	v_add_f32_e32 v181, v101, v181
	v_add_f32_e32 v182, v102, v182
	v_add_f32_e32 v183, v103, v183
	v_add_f32_e32 v184, v96, v184
	v_add_f32_e32 v185, v97, v185
	v_add_f32_e32 v186, v98, v186
	v_add_f32_e32 v187, v99, v187
	global_store_dwordx4 v228, v[168:171], s[22:23] offset:0
	global_store_dwordx4 v228, v[176:179], s[22:23] offset:64
	global_store_dwordx4 v228, v[180:183], s[22:23] offset:128
	global_store_dwordx4 v228, v[184:187], s[22:23] offset:192
	s_nop 1
	v_add_u32_e32 v228, 0x30000, v229
	global_load_dwordx4 v[168:171], v228, s[22:23] offset:0
	global_load_dwordx4 v[176:179], v228, s[22:23] offset:64
	global_load_dwordx4 v[180:183], v228, s[22:23] offset:128
	global_load_dwordx4 v[184:187], v228, s[22:23] offset:192
	s_waitcnt vmcnt(8)
; template <int EPI>
; DI void gemm_phase(const u16* __restrict__ A, int lda, const u16* __restrict__ Bt, int K, int N, u16* outb, int ldo,
;                    const float* r0, const float* r1, float* outf, char* lds, int bid, int nb) {
;     ...
;       const int col = tn * 256 + wc * 64 + l15;
;       const float* rb_ = (tm * 256 < M_P) ? r0 : (r1 - (size_t)M_P * DM);
; #pragma unroll
;       for (int i = 0; i < 8; ++i)
; #pragma unroll
;         for (int r = 0; r < 4; ++r) {
;           const size_t i0 = (size_t)(mrow + i * 16 + r) * DM + col;
;           const float x0 = rb_[i0], x1 = rb_[i0 + 16], x2 = rb_[i0 + 32], x3 = rb_[i0 + 48];
;           outf[i0] = x0 + acc[i][0][r]; outf[i0 + 16] = x1 + acc[i][1][r]; outf[i0 + 32] = x2 + acc[i][2][r]; outf[i0 + 48] = x3 + acc[i][3][r];
	v_add_f32_e32 v152, v92, v152
	v_add_f32_e32 v153, v93, v153
	v_add_f32_e32 v154, v94, v154
	v_add_f32_e32 v155, v95, v155
	v_add_f32_e32 v156, v88, v156
	v_add_f32_e32 v157, v89, v157
	v_add_f32_e32 v158, v90, v158
	v_add_f32_e32 v159, v91, v159
	v_add_f32_e32 v160, v84, v160
	v_add_f32_e32 v161, v85, v161
	v_add_f32_e32 v162, v86, v162
	v_add_f32_e32 v163, v87, v163
	v_add_f32_e32 v164, v80, v164
	v_add_f32_e32 v165, v81, v165
	v_add_f32_e32 v166, v82, v166
	v_add_f32_e32 v167, v83, v167
	global_store_dwordx4 v224, v[152:155], s[22:23] offset:0
	global_store_dwordx4 v224, v[156:159], s[22:23] offset:64
	global_store_dwordx4 v224, v[160:163], s[22:23] offset:128
	global_store_dwordx4 v224, v[164:167], s[22:23] offset:192
	s_nop 1
	v_add_u32_e32 v224, 0x40000, v229
	global_load_dwordx4 v[152:155], v224, s[22:23] offset:0
	global_load_dwordx4 v[156:159], v224, s[22:23] offset:64
	global_load_dwordx4 v[160:163], v224, s[22:23] offset:128
	global_load_dwordx4 v[164:167], v224, s[22:23] offset:192
	s_waitcnt vmcnt(8)
	v_add_f32_e32 v168, v76, v168
	v_add_f32_e32 v169, v77, v169
	v_add_f32_e32 v170, v78, v170
	v_add_f32_e32 v171, v79, v171
	v_add_f32_e32 v176, v72, v176
	v_add_f32_e32 v177, v73, v177
	v_add_f32_e32 v178, v74, v178
	v_add_f32_e32 v179, v75, v179
	v_add_f32_e32 v180, v68, v180
	v_add_f32_e32 v181, v69, v181
	v_add_f32_e32 v182, v70, v182
	v_add_f32_e32 v183, v71, v183
	v_add_f32_e32 v184, v64, v184
	v_add_f32_e32 v185, v65, v185
	v_add_f32_e32 v186, v66, v186
	v_add_f32_e32 v187, v67, v187
	global_store_dwordx4 v228, v[168:171], s[22:23] offset:0
	global_store_dwordx4 v228, v[176:179], s[22:23] offset:64
	global_store_dwordx4 v228, v[180:183], s[22:23] offset:128
	global_store_dwordx4 v228, v[184:187], s[22:23] offset:192
	s_nop 1
	v_add_u32_e32 v228, 0x50000, v229
	global_load_dwordx4 v[168:171], v228, s[22:23] offset:0
	global_load_dwordx4 v[176:179], v228, s[22:23] offset:64
	global_load_dwordx4 v[180:183], v228, s[22:23] offset:128
	global_load_dwordx4 v[184:187], v228, s[22:23] offset:192
	s_waitcnt vmcnt(8)
	v_add_f32_e32 v152, v60, v152
	v_add_f32_e32 v153, v61, v153
	v_add_f32_e32 v154, v62, v154
	v_add_f32_e32 v155, v63, v155
	v_add_f32_e32 v156, v56, v156
	v_add_f32_e32 v157, v57, v157
	v_add_f32_e32 v158, v58, v158
	v_add_f32_e32 v159, v59, v159
	v_add_f32_e32 v160, v52, v160
	v_add_f32_e32 v161, v53, v161
	v_add_f32_e32 v162, v54, v162
	v_add_f32_e32 v163, v55, v163
	v_add_f32_e32 v164, v48, v164
	v_add_f32_e32 v165, v49, v165
	v_add_f32_e32 v166, v50, v166
	v_add_f32_e32 v167, v51, v167
	global_store_dwordx4 v224, v[152:155], s[22:23] offset:0
	global_store_dwordx4 v224, v[156:159], s[22:23] offset:64
	global_store_dwordx4 v224, v[160:163], s[22:23] offset:128
	global_store_dwordx4 v224, v[164:167], s[22:23] offset:192
	s_nop 1
	v_add_u32_e32 v224, 0x60000, v229
	global_load_dwordx4 v[152:155], v224, s[22:23] offset:0
	global_load_dwordx4 v[156:159], v224, s[22:23] offset:64
	global_load_dwordx4 v[160:163], v224, s[22:23] offset:128
	global_load_dwordx4 v[164:167], v224, s[22:23] offset:192
	s_waitcnt vmcnt(8)
	v_add_f32_e32 v168, v44, v168
	v_add_f32_e32 v169, v45, v169
	v_add_f32_e32 v170, v46, v170
	v_add_f32_e32 v171, v47, v171
	v_add_f32_e32 v176, v40, v176
	v_add_f32_e32 v177, v41, v177
	v_add_f32_e32 v178, v42, v178
	v_add_f32_e32 v179, v43, v179
	v_add_f32_e32 v180, v36, v180
	v_add_f32_e32 v181, v37, v181
	v_add_f32_e32 v182, v38, v182
	v_add_f32_e32 v183, v39, v183
	v_add_f32_e32 v184, v32, v184
	v_add_f32_e32 v185, v33, v185
	v_add_f32_e32 v186, v34, v186
	v_add_f32_e32 v187, v35, v187
	global_store_dwordx4 v228, v[168:171], s[22:23] offset:0
	global_store_dwordx4 v228, v[176:179], s[22:23] offset:64
	global_store_dwordx4 v228, v[180:183], s[22:23] offset:128
	global_store_dwordx4 v228, v[184:187], s[22:23] offset:192
	s_nop 1
	v_add_u32_e32 v228, 0x70000, v229
	global_load_dwordx4 v[168:171], v228, s[22:23] offset:0
	global_load_dwordx4 v[176:179], v228, s[22:23] offset:64
	global_load_dwordx4 v[180:183], v228, s[22:23] offset:128
	global_load_dwordx4 v[184:187], v228, s[22:23] offset:192
	s_waitcnt vmcnt(8)
	v_add_f32_e32 v152, v28, v152
	v_add_f32_e32 v153, v29, v153
	v_add_f32_e32 v154, v30, v154
	v_add_f32_e32 v155, v31, v155
	v_add_f32_e32 v156, v24, v156
	v_add_f32_e32 v157, v25, v157
	v_add_f32_e32 v158, v26, v158
	v_add_f32_e32 v159, v27, v159
	v_add_f32_e32 v160, v20, v160
	v_add_f32_e32 v161, v21, v161
	v_add_f32_e32 v162, v22, v162
	v_add_f32_e32 v163, v23, v163
	v_add_f32_e32 v164, v16, v164
	v_add_f32_e32 v165, v17, v165
	v_add_f32_e32 v166, v18, v166
	v_add_f32_e32 v167, v19, v167
	global_store_dwordx4 v224, v[152:155], s[22:23] offset:0
	global_store_dwordx4 v224, v[156:159], s[22:23] offset:64
	global_store_dwordx4 v224, v[160:163], s[22:23] offset:128
	global_store_dwordx4 v224, v[164:167], s[22:23] offset:192
	s_waitcnt vmcnt(4)
	v_add_f32_e32 v168, v12, v168
	v_add_f32_e32 v169, v13, v169
	v_add_f32_e32 v170, v14, v170
	v_add_f32_e32 v171, v15, v171
	v_add_f32_e32 v176, v8, v176
	v_add_f32_e32 v177, v9, v177
	v_add_f32_e32 v178, v10, v178
	v_add_f32_e32 v179, v11, v179
	v_add_f32_e32 v180, v4, v180
	v_add_f32_e32 v181, v5, v181
	v_add_f32_e32 v182, v6, v182
	v_add_f32_e32 v183, v7, v183
	v_add_f32_e32 v184, v0, v184
	v_add_f32_e32 v185, v1, v185
	v_add_f32_e32 v186, v2, v186
	v_add_f32_e32 v187, v3, v187
	global_store_dwordx4 v228, v[168:171], s[22:23] offset:0
	global_store_dwordx4 v228, v[176:179], s[22:23] offset:64
	global_store_dwordx4 v228, v[180:183], s[22:23] offset:128
	global_store_dwordx4 v228, v[184:187], s[22:23] offset:192
	s_add_i32 s14, s14, 1
	s_cmp_eq_u32 s14, s3
	s_cbranch_scc0 .LBB0_1177

; #define G_LOAD(KT) do { _Pragma("unroll") for (int i = 0; i < 4; ++i) { ra[i] = *(const u32x4*)(Ag + (size_t)i * 64 * lda + (KT) * 64); rb[i] = *(const u32x4*)(Bg + (size_t)i * 64 * K + (KT) * 64); } } while (0)
; #define G_STORE(BUF) do { u16* ad = As + (BUF) * 256 * 64 + sto; u16* bd = Bs + (BUF) * 256 * 64 + sto; _Pragma("unroll") for (int i = 0; i < 4; ++i) { *(u32x4*)(ad + i * 64 * 64) = ra[i]; *(u32x4*)(bd + i * 64 * 64) = rb[i]; } } while (0)
; template <int EPI>
; DI void gemm_phase(const u16* __restrict__ A, int lda, const u16* __restrict__ Bt, int K, int N, u16* outb, int ldo,
;                    const float* r0, const float* r1, float* outf, char* lds, int bid, int nb) {
;     ...
;     if (swz) { const int st = xcd + 8 * it, sm = st / nSN, sn = st - sm * nSN; tm = sm * GM + jb / GN; tn = sn * GN + (jb % GN); }
;     else { const int t = bid + it * nb; tm = t / nN; tn = t - tm * nN; }
;     const u16* Ag = A + (size_t)(tm * 256 + lrow) * lda + lch * 8;
;     const u16* Bg = Bt + (size_t)(tn * 256 + lrow) * K + lch * 8;
;     f32x4 acc[8][4];
; #pragma unroll
;     for (int i = 0; i < 8; ++i)
; #pragma unroll
;       for (int j = 0; j < 4; ++j) acc[i][j] = (f32x4){0.f, 0.f, 0.f, 0.f};
;     u32x4 ra[4], rb[4];
;     ...
;     G_LOAD(0);
;     G_STORE(0);
;     __syncthreads();
;     for (int kt = 0; kt < nk; ++kt) {
;       const int cur = kt & 1;
;       if (kt + 1 < nk) G_LOAD(kt + 1);
;       G_MMA(cur, fo0);
.LBB0_1301:
	s_lshl_b32 s41, s41, 8
	v_or_b32_e32 v0, s41, v138
	v_ashrrev_i32_e32 v1, 31, v0
	v_lshlrev_b64 v[64:65], 11, v[0:1]
	v_lshl_or_b32 v0, s40, 8, v138
	v_ashrrev_i32_e32 v1, 31, v0
	v_lshlrev_b64 v[66:67], 11, v[0:1]
	v_lshl_add_u64 v[0:1], v[128:129], 0, v[64:65]
	v_add_co_u32_e32 v4, vcc, 0x20000, v0
	v_lshl_add_u64 v[2:3], v[130:131], 0, v[66:67]
	s_nop 0
	v_addc_co_u32_e32 v5, vcc, 0, v1, vcc
	v_add_co_u32_e32 v6, vcc, 0x20000, v2
	s_nop 1
	v_readfirstlane_b32 s98, v0
	v_readfirstlane_b32 s99, v1
	s_nop 1
	v_readfirstlane_b32 s100, v2
	v_readfirstlane_b32 s101, v3
	v_addc_co_u32_e32 v7, vcc, 0, v3, vcc
	v_add_co_u32_e32 v4, vcc, 0x40000, v0
	s_mov_b32 s42, 0
	s_nop 0
	v_addc_co_u32_e32 v5, vcc, 0, v1, vcc
	v_add_co_u32_e32 v6, vcc, 0x40000, v2
	s_mov_b64 s[10:11], 0
	s_nop 0
	v_addc_co_u32_e32 v7, vcc, 0, v3, vcc
	v_add_co_u32_e32 v0, vcc, 0x60000, v0
	v_addc_co_u32_e32 v1, vcc, 0, v1, vcc
	v_add_co_u32_e32 v2, vcc, 0x60000, v2
	v_lshl_add_u64 v[134:135], v[132:133], 0, v[66:67]
	s_nop 0
	v_addc_co_u32_e32 v3, vcc, 0, v3, vcc
	v_mov_b32_e32 v0, 0
	v_lshl_add_u64 v[136:137], v[132:133], 0, v[64:65]
	v_and_b32_e32 v229, 63, v174
	v_lshrrev_b32_e32 v230, 3, v229
	v_mov_b32_e32 v233, 0x800
	v_mul_u32_u24_e32 v224, v230, v233
	v_bfe_u32 v231, v174, 4, 2
	v_bfe_u32 v232, v174, 6, 1
	v_lshl_or_b32 v232, v232, 2, v231
	v_and_b32_e32 v233, 7, v174
	v_xor_b32_e32 v232, v232, v233
	v_lshl_add_u32 v224, v232, 4, v224
	v_and_b32_e32 v229, 15, v174
	v_bfe_u32 v230, v174, 1, 3
	v_xor_b32_e32 v230, v230, v231
	v_lshlrev_b32_e32 v230, 4, v230
	v_lshl_or_b32 v230, v229, 7, v230
	v_lshrrev_b32_e32 v229, 8, v174
	v_lshl_or_b32 v225, v229, 14, v230
	v_bfe_u32 v229, v174, 6, 2
	v_lshl_or_b32 v227, v229, 13, v230
	v_or_b32_e32 v227, 0x10000, v227
	v_xor_b32_e32 v226, 64, v225
	v_xor_b32_e32 v228, 64, v227
	v_readfirstlane_b32 s97, v174
	s_lshl_b32 s97, s97, 4
	s_mov_b32 s28, 14
	s_add_u32 m0, s97, 0x0
	s_add_u32 s10, s98, 0x0
	s_addc_u32 s11, s99, 0
	global_load_lds_dwordx4 v224, s[10:11]
	s_add_u32 m0, s97, 0x10000
	s_add_u32 s10, s100, 0x0
	s_addc_u32 s11, s101, 0
	global_load_lds_dwordx4 v224, s[10:11]
	s_add_u32 m0, s97, 0x2000
	s_add_u32 s10, s98, 0x20000
	s_addc_u32 s11, s99, 0
	global_load_lds_dwordx4 v224, s[10:11]
	s_add_u32 m0, s97, 0x12000
	s_add_u32 s10, s100, 0x20000
	s_addc_u32 s11, s101, 0
	global_load_lds_dwordx4 v224, s[10:11]
	s_add_u32 m0, s97, 0x4000
	s_add_u32 s10, s98, 0x40000
	s_addc_u32 s11, s99, 0
	global_load_lds_dwordx4 v224, s[10:11]
	s_add_u32 m0, s97, 0x14000
	s_add_u32 s10, s100, 0x40000
	s_addc_u32 s11, s101, 0
	global_load_lds_dwordx4 v224, s[10:11]
	s_add_u32 m0, s97, 0x6000
	s_add_u32 s10, s98, 0x60000
	s_addc_u32 s11, s99, 0
	global_load_lds_dwordx4 v224, s[10:11]
	s_add_u32 m0, s97, 0x16000
	s_add_u32 s10, s100, 0x60000
	s_addc_u32 s11, s101, 0
	global_load_lds_dwordx4 v224, s[10:11]
	s_add_u32 m0, s97, 0x8000
	s_add_u32 s10, s98, 0x80
	s_addc_u32 s11, s99, 0
	global_load_lds_dwordx4 v224, s[10:11]
	s_add_u32 m0, s97, 0x18000
	s_add_u32 s10, s100, 0x80
	s_addc_u32 s11, s101, 0
	global_load_lds_dwordx4 v224, s[10:11]
	s_add_u32 m0, s97, 0xa000
	s_add_u32 s10, s98, 0x20080
	s_addc_u32 s11, s99, 0
	global_load_lds_dwordx4 v224, s[10:11]
	s_add_u32 m0, s97, 0x1a000
	s_add_u32 s10, s100, 0x20080
	s_addc_u32 s11, s101, 0
	global_load_lds_dwordx4 v224, s[10:11]
	s_add_u32 m0, s97, 0xc000
	s_add_u32 s10, s98, 0x40080
	s_addc_u32 s11, s99, 0
	global_load_lds_dwordx4 v224, s[10:11]
	s_add_u32 m0, s97, 0x1c000
	s_add_u32 s10, s100, 0x40080
	s_addc_u32 s11, s101, 0
	global_load_lds_dwordx4 v224, s[10:11]
	s_add_u32 m0, s97, 0xe000
	s_add_u32 s10, s98, 0x60080
	s_addc_u32 s11, s99, 0
	global_load_lds_dwordx4 v224, s[10:11]
	s_add_u32 m0, s97, 0x1e000
	s_add_u32 s10, s100, 0x60080
	s_addc_u32 s11, s101, 0
	global_load_lds_dwordx4 v224, s[10:11]
	s_add_u32 s98, s98, 0x100
	s_addc_u32 s99, s99, 0
	s_add_u32 s100, s100, 0x100
	s_addc_u32 s101, s101, 0
	s_waitcnt vmcnt(8)
	s_barrier
; #define G_LOAD(KT) do { _Pragma("unroll") for (int i = 0; i < 4; ++i) { ra[i] = *(const u32x4*)(Ag + (size_t)i * 64 * lda + (KT) * 64); rb[i] = *(const u32x4*)(Bg + (size_t)i * 64 * K + (KT) * 64); } } while (0)
; template <int EPI>
; DI void gemm_phase(const u16* __restrict__ A, int lda, const u16* __restrict__ Bt, int K, int N, u16* outb, int ldo,
;                    const float* r0, const float* r1, float* outf, char* lds, int bid, int nb) {
;     ...
;     for (int kt = 0; kt < nk; ++kt) {
;       const int cur = kt & 1;
;       if (kt + 1 < nk) G_LOAD(kt + 1);
;       G_MMA(cur, fo0);
;       G_MMA(cur, fo1);
	ds_read_b128 v[152:155], v227 offset:0
	ds_read_b128 v[156:159], v227 offset:2048
	ds_read_b128 v[160:163], v227 offset:4096
	ds_read_b128 v[164:167], v227 offset:6144
	ds_read_b128 v[188:191], v225 offset:0
	ds_read_b128 v[192:195], v225 offset:2048
	ds_read_b128 v[196:199], v225 offset:4096
	ds_read_b128 v[200:203], v225 offset:6144
	ds_read_b128 v[204:207], v225 offset:8192
	ds_read_b128 v[208:211], v225 offset:10240
	ds_read_b128 v[212:215], v225 offset:12288
	ds_read_b128 v[216:219], v225 offset:14336
	v_xor_b32_e32 v225, 0x8000, v225
	v_xor_b32_e32 v227, 0x8000, v227
	s_waitcnt lgkmcnt(0)
	s_waitcnt lgkmcnt(4)
	v_mfma_f32_16x16x32_bf16 v[124:127], v[152:155], v[188:191], 0
	v_mfma_f32_16x16x32_bf16 v[120:123], v[156:159], v[188:191], 0
	v_mfma_f32_16x16x32_bf16 v[116:119], v[160:163], v[188:191], 0
	v_mfma_f32_16x16x32_bf16 v[112:115], v[164:167], v[188:191], 0
	ds_read_b128 v[188:191], v226 offset:0
	ds_read_b128 v[168:171], v228 offset:0
	v_mfma_f32_16x16x32_bf16 v[108:111], v[152:155], v[192:195], 0
	v_mfma_f32_16x16x32_bf16 v[104:107], v[156:159], v[192:195], 0
	v_mfma_f32_16x16x32_bf16 v[100:103], v[160:163], v[192:195], 0
	v_mfma_f32_16x16x32_bf16 v[96:99], v[164:167], v[192:195], 0
	ds_read_b128 v[192:195], v226 offset:2048
	ds_read_b128 v[176:179], v228 offset:2048
	v_mfma_f32_16x16x32_bf16 v[92:95], v[152:155], v[196:199], 0
	v_mfma_f32_16x16x32_bf16 v[88:91], v[156:159], v[196:199], 0
	v_mfma_f32_16x16x32_bf16 v[84:87], v[160:163], v[196:199], 0
	v_mfma_f32_16x16x32_bf16 v[80:83], v[164:167], v[196:199], 0
	ds_read_b128 v[196:199], v226 offset:4096
	ds_read_b128 v[180:183], v228 offset:4096
	v_mfma_f32_16x16x32_bf16 v[76:79], v[152:155], v[200:203], 0
	v_mfma_f32_16x16x32_bf16 v[72:75], v[156:159], v[200:203], 0
	v_mfma_f32_16x16x32_bf16 v[68:71], v[160:163], v[200:203], 0
	v_mfma_f32_16x16x32_bf16 v[64:67], v[164:167], v[200:203], 0
	ds_read_b128 v[200:203], v226 offset:6144
	ds_read_b128 v[184:187], v228 offset:6144
	s_waitcnt lgkmcnt(11)
	v_mfma_f32_16x16x32_bf16 v[60:63], v[152:155], v[204:207], 0
	v_mfma_f32_16x16x32_bf16 v[56:59], v[156:159], v[204:207], 0
	v_mfma_f32_16x16x32_bf16 v[52:55], v[160:163], v[204:207], 0
	v_mfma_f32_16x16x32_bf16 v[48:51], v[164:167], v[204:207], 0
	ds_read_b128 v[204:207], v226 offset:8192
	ds_read_b128 v[220:223], v226 offset:14336
	s_waitcnt lgkmcnt(11)
	v_mfma_f32_16x16x32_bf16 v[44:47], v[152:155], v[208:211], 0
	v_mfma_f32_16x16x32_bf16 v[40:43], v[156:159], v[208:211], 0
	v_mfma_f32_16x16x32_bf16 v[36:39], v[160:163], v[208:211], 0
	v_mfma_f32_16x16x32_bf16 v[32:35], v[164:167], v[208:211], 0
	ds_read_b128 v[208:211], v226 offset:10240
	s_waitcnt lgkmcnt(11)
	v_mfma_f32_16x16x32_bf16 v[28:31], v[152:155], v[212:215], 0
	v_mfma_f32_16x16x32_bf16 v[24:27], v[156:159], v[212:215], 0
	v_mfma_f32_16x16x32_bf16 v[20:23], v[160:163], v[212:215], 0
	v_mfma_f32_16x16x32_bf16 v[16:19], v[164:167], v[212:215], 0
	ds_read_b128 v[212:215], v226 offset:12288
	v_mfma_f32_16x16x32_bf16 v[12:15], v[152:155], v[216:219], 0
	v_mfma_f32_16x16x32_bf16 v[8:11], v[156:159], v[216:219], 0
	v_mfma_f32_16x16x32_bf16 v[4:7], v[160:163], v[216:219], 0
	v_mfma_f32_16x16x32_bf16 v[0:3], v[164:167], v[216:219], 0
	s_branch .Lgm6_mid0

; #define G_LOAD(KT) do { _Pragma("unroll") for (int i = 0; i < 4; ++i) { ra[i] = *(const u32x4*)(Ag + (size_t)i * 64 * lda + (KT) * 64); rb[i] = *(const u32x4*)(Bg + (size_t)i * 64 * K + (KT) * 64); } } while (0)
; #define G_STORE(BUF) do { u16* ad = As + (BUF) * 256 * 64 + sto; u16* bd = Bs + (BUF) * 256 * 64 + sto; _Pragma("unroll") for (int i = 0; i < 4; ++i) { *(u32x4*)(ad + i * 64 * 64) = ra[i]; *(u32x4*)(bd + i * 64 * 64) = rb[i]; } } while (0)
; template <int EPI>
; DI void gemm_phase(const u16* __restrict__ A, int lda, const u16* __restrict__ Bt, int K, int N, u16* outb, int ldo,
;                    const float* r0, const float* r1, float* outf, char* lds, int bid, int nb) {
;     ...
;     for (int kt = 0; kt < nk; ++kt) {
;       const int cur = kt & 1;
;       if (kt + 1 < nk) G_LOAD(kt + 1);
;       G_MMA(cur, fo0);
;       G_MMA(cur, fo1);
;       if (kt + 1 < nk) G_STORE(cur ^ 1);
;       __syncthreads();
;     }
.Lgm6_mid0:
	s_waitcnt vmcnt(0) lgkmcnt(0)
	s_barrier
	v_mfma_f32_16x16x32_bf16 v[124:127], v[168:171], v[188:191], v[124:127]
	v_mfma_f32_16x16x32_bf16 v[120:123], v[176:179], v[188:191], v[120:123]
	v_mfma_f32_16x16x32_bf16 v[116:119], v[180:183], v[188:191], v[116:119]
	v_mfma_f32_16x16x32_bf16 v[112:115], v[184:187], v[188:191], v[112:115]
	ds_read_b128 v[188:191], v225 offset:0
	ds_read_b128 v[152:155], v227 offset:0
	s_add_u32 m0, s97, 0x0
	s_add_u32 s10, s98, 0x0
	s_addc_u32 s11, s99, 0
	global_load_lds_dwordx4 v224, s[10:11]
	v_mfma_f32_16x16x32_bf16 v[108:111], v[168:171], v[192:195], v[108:111]
	v_mfma_f32_16x16x32_bf16 v[104:107], v[176:179], v[192:195], v[104:107]
	v_mfma_f32_16x16x32_bf16 v[100:103], v[180:183], v[192:195], v[100:103]
	v_mfma_f32_16x16x32_bf16 v[96:99], v[184:187], v[192:195], v[96:99]
	ds_read_b128 v[192:195], v225 offset:2048
	ds_read_b128 v[156:159], v227 offset:2048
	s_add_u32 m0, s97, 0x10000
	s_add_u32 s10, s100, 0x0
	s_addc_u32 s11, s101, 0
	global_load_lds_dwordx4 v224, s[10:11]
	v_mfma_f32_16x16x32_bf16 v[92:95], v[168:171], v[196:199], v[92:95]
	v_mfma_f32_16x16x32_bf16 v[88:91], v[176:179], v[196:199], v[88:91]
	v_mfma_f32_16x16x32_bf16 v[84:87], v[180:183], v[196:199], v[84:87]
	v_mfma_f32_16x16x32_bf16 v[80:83], v[184:187], v[196:199], v[80:83]
	ds_read_b128 v[196:199], v225 offset:4096
	ds_read_b128 v[160:163], v227 offset:4096
	s_add_u32 m0, s97, 0x2000
	s_add_u32 s10, s98, 0x20000
	s_addc_u32 s11, s99, 0
	global_load_lds_dwordx4 v224, s[10:11]
	v_mfma_f32_16x16x32_bf16 v[76:79], v[168:171], v[200:203], v[76:79]
	v_mfma_f32_16x16x32_bf16 v[72:75], v[176:179], v[200:203], v[72:75]
	v_mfma_f32_16x16x32_bf16 v[68:71], v[180:183], v[200:203], v[68:71]
	v_mfma_f32_16x16x32_bf16 v[64:67], v[184:187], v[200:203], v[64:67]
	ds_read_b128 v[200:203], v225 offset:6144
	ds_read_b128 v[164:167], v227 offset:6144
	s_add_u32 m0, s97, 0x12000
	s_add_u32 s10, s100, 0x20000
	s_addc_u32 s11, s101, 0
	global_load_lds_dwordx4 v224, s[10:11]
	v_mfma_f32_16x16x32_bf16 v[60:63], v[168:171], v[204:207], v[60:63]
	v_mfma_f32_16x16x32_bf16 v[56:59], v[176:179], v[204:207], v[56:59]
	v_mfma_f32_16x16x32_bf16 v[52:55], v[180:183], v[204:207], v[52:55]
	v_mfma_f32_16x16x32_bf16 v[48:51], v[184:187], v[204:207], v[48:51]
	ds_read_b128 v[204:207], v225 offset:8192
	ds_read_b128 v[216:219], v225 offset:14336
	s_add_u32 m0, s97, 0x4000
	s_add_u32 s10, s98, 0x40000
	s_addc_u32 s11, s99, 0
	global_load_lds_dwordx4 v224, s[10:11]
	v_mfma_f32_16x16x32_bf16 v[44:47], v[168:171], v[208:211], v[44:47]
	v_mfma_f32_16x16x32_bf16 v[40:43], v[176:179], v[208:211], v[40:43]
	v_mfma_f32_16x16x32_bf16 v[36:39], v[180:183], v[208:211], v[36:39]
	v_mfma_f32_16x16x32_bf16 v[32:35], v[184:187], v[208:211], v[32:35]
	ds_read_b128 v[208:211], v225 offset:10240
	s_add_u32 m0, s97, 0x14000
	s_add_u32 s10, s100, 0x40000
	s_addc_u32 s11, s101, 0
	global_load_lds_dwordx4 v224, s[10:11]
	v_mfma_f32_16x16x32_bf16 v[28:31], v[168:171], v[212:215], v[28:31]
	v_mfma_f32_16x16x32_bf16 v[24:27], v[176:179], v[212:215], v[24:27]
	v_mfma_f32_16x16x32_bf16 v[20:23], v[180:183], v[212:215], v[20:23]
	v_mfma_f32_16x16x32_bf16 v[16:19], v[184:187], v[212:215], v[16:19]
	ds_read_b128 v[212:215], v225 offset:12288
	s_add_u32 m0, s97, 0x6000
	s_add_u32 s10, s98, 0x60000
	s_addc_u32 s11, s99, 0
	global_load_lds_dwordx4 v224, s[10:11]
	v_mfma_f32_16x16x32_bf16 v[12:15], v[168:171], v[220:223], v[12:15]
	v_mfma_f32_16x16x32_bf16 v[8:11], v[176:179], v[220:223], v[8:11]
	v_mfma_f32_16x16x32_bf16 v[4:7], v[180:183], v[220:223], v[4:7]
	v_mfma_f32_16x16x32_bf16 v[0:3], v[184:187], v[220:223], v[0:3]
	s_add_u32 m0, s97, 0x16000
	s_add_u32 s10, s100, 0x60000
	s_addc_u32 s11, s101, 0
	global_load_lds_dwordx4 v224, s[10:11]
	v_xor_b32_e32 v225, 0x8000, v225
	v_xor_b32_e32 v227, 0x8000, v227
	v_xor_b32_e32 v226, 0x8000, v226
	v_xor_b32_e32 v228, 0x8000, v228
	s_xor_b32 s97, s97, 0x8000
	s_add_u32 s98, s98, 0x80
	s_addc_u32 s99, s99, 0
	s_add_u32 s100, s100, 0x80
	s_addc_u32 s101, s101, 0
	s_sub_u32 s28, s28, 1
	s_cmp_lg_u32 s28, 0
	s_cbranch_scc1 .Lgm6_loop
	s_waitcnt lgkmcnt(4)
	v_mfma_f32_16x16x32_bf16 v[124:127], v[152:155], v[188:191], v[124:127]
	v_mfma_f32_16x16x32_bf16 v[120:123], v[156:159], v[188:191], v[120:123]
	v_mfma_f32_16x16x32_bf16 v[116:119], v[160:163], v[188:191], v[116:119]
	v_mfma_f32_16x16x32_bf16 v[112:115], v[164:167], v[188:191], v[112:115]
	ds_read_b128 v[188:191], v226 offset:0
	ds_read_b128 v[168:171], v228 offset:0
	v_mfma_f32_16x16x32_bf16 v[108:111], v[152:155], v[192:195], v[108:111]
	v_mfma_f32_16x16x32_bf16 v[104:107], v[156:159], v[192:195], v[104:107]
	v_mfma_f32_16x16x32_bf16 v[100:103], v[160:163], v[192:195], v[100:103]
	v_mfma_f32_16x16x32_bf16 v[96:99], v[164:167], v[192:195], v[96:99]
	ds_read_b128 v[192:195], v226 offset:2048
	ds_read_b128 v[176:179], v228 offset:2048
	v_mfma_f32_16x16x32_bf16 v[92:95], v[152:155], v[196:199], v[92:95]
	v_mfma_f32_16x16x32_bf16 v[88:91], v[156:159], v[196:199], v[88:91]
	v_mfma_f32_16x16x32_bf16 v[84:87], v[160:163], v[196:199], v[84:87]
	v_mfma_f32_16x16x32_bf16 v[80:83], v[164:167], v[196:199], v[80:83]
	ds_read_b128 v[196:199], v226 offset:4096
	ds_read_b128 v[180:183], v228 offset:4096
	v_mfma_f32_16x16x32_bf16 v[76:79], v[152:155], v[200:203], v[76:79]
	v_mfma_f32_16x16x32_bf16 v[72:75], v[156:159], v[200:203], v[72:75]
	v_mfma_f32_16x16x32_bf16 v[68:71], v[160:163], v[200:203], v[68:71]
	v_mfma_f32_16x16x32_bf16 v[64:67], v[164:167], v[200:203], v[64:67]
	ds_read_b128 v[200:203], v226 offset:6144
	ds_read_b128 v[184:187], v228 offset:6144
	s_waitcnt lgkmcnt(11)
	v_mfma_f32_16x16x32_bf16 v[60:63], v[152:155], v[204:207], v[60:63]
	v_mfma_f32_16x16x32_bf16 v[56:59], v[156:159], v[204:207], v[56:59]
	v_mfma_f32_16x16x32_bf16 v[52:55], v[160:163], v[204:207], v[52:55]
	v_mfma_f32_16x16x32_bf16 v[48:51], v[164:167], v[204:207], v[48:51]
	ds_read_b128 v[204:207], v226 offset:8192
	ds_read_b128 v[220:223], v226 offset:14336
	s_waitcnt lgkmcnt(11)
	v_mfma_f32_16x16x32_bf16 v[44:47], v[152:155], v[208:211], v[44:47]
	v_mfma_f32_16x16x32_bf16 v[40:43], v[156:159], v[208:211], v[40:43]
	v_mfma_f32_16x16x32_bf16 v[36:39], v[160:163], v[208:211], v[36:39]
	v_mfma_f32_16x16x32_bf16 v[32:35], v[164:167], v[208:211], v[32:35]
	ds_read_b128 v[208:211], v226 offset:10240
	s_waitcnt lgkmcnt(11)
	v_mfma_f32_16x16x32_bf16 v[28:31], v[152:155], v[212:215], v[28:31]
	v_mfma_f32_16x16x32_bf16 v[24:27], v[156:159], v[212:215], v[24:27]
	v_mfma_f32_16x16x32_bf16 v[20:23], v[160:163], v[212:215], v[20:23]
	v_mfma_f32_16x16x32_bf16 v[16:19], v[164:167], v[212:215], v[16:19]
	ds_read_b128 v[212:215], v226 offset:12288
	v_mfma_f32_16x16x32_bf16 v[12:15], v[152:155], v[216:219], v[12:15]
	v_mfma_f32_16x16x32_bf16 v[8:11], v[156:159], v[216:219], v[8:11]
	v_mfma_f32_16x16x32_bf16 v[4:7], v[160:163], v[216:219], v[4:7]
	v_mfma_f32_16x16x32_bf16 v[0:3], v[164:167], v[216:219], v[0:3]
	s_waitcnt vmcnt(0) lgkmcnt(0)
	s_barrier
; #define G_LOAD(KT) do { _Pragma("unroll") for (int i = 0; i < 4; ++i) { ra[i] = *(const u32x4*)(Ag + (size_t)i * 64 * lda + (KT) * 64); rb[i] = *(const u32x4*)(Bg + (size_t)i * 64 * K + (KT) * 64); } } while (0)
; #define G_STORE(BUF) do { u16* ad = As + (BUF) * 256 * 64 + sto; u16* bd = Bs + (BUF) * 256 * 64 + sto; _Pragma("unroll") for (int i = 0; i < 4; ++i) { *(u32x4*)(ad + i * 64 * 64) = ra[i]; *(u32x4*)(bd + i * 64 * 64) = rb[i]; } } while (0)
; template <int EPI>
; DI void gemm_phase(const u16* __restrict__ A, int lda, const u16* __restrict__ Bt, int K, int N, u16* outb, int ldo,
;                    const float* r0, const float* r1, float* outf, char* lds, int bid, int nb) {
;     ...
;     for (int kt = 0; kt < nk; ++kt) {
;       const int cur = kt & 1;
;       if (kt + 1 < nk) G_LOAD(kt + 1);
;       G_MMA(cur, fo0);
;       G_MMA(cur, fo1);
;       if (kt + 1 < nk) G_STORE(cur ^ 1);
;       __syncthreads();
;     }
	v_mfma_f32_16x16x32_bf16 v[124:127], v[168:171], v[188:191], v[124:127]
	v_mfma_f32_16x16x32_bf16 v[120:123], v[176:179], v[188:191], v[120:123]
	v_mfma_f32_16x16x32_bf16 v[116:119], v[180:183], v[188:191], v[116:119]
	v_mfma_f32_16x16x32_bf16 v[112:115], v[184:187], v[188:191], v[112:115]
	ds_read_b128 v[188:191], v225 offset:0
	ds_read_b128 v[152:155], v227 offset:0
	v_mfma_f32_16x16x32_bf16 v[108:111], v[168:171], v[192:195], v[108:111]
	v_mfma_f32_16x16x32_bf16 v[104:107], v[176:179], v[192:195], v[104:107]
	v_mfma_f32_16x16x32_bf16 v[100:103], v[180:183], v[192:195], v[100:103]
	v_mfma_f32_16x16x32_bf16 v[96:99], v[184:187], v[192:195], v[96:99]
	ds_read_b128 v[192:195], v225 offset:2048
	ds_read_b128 v[156:159], v227 offset:2048
	v_mfma_f32_16x16x32_bf16 v[92:95], v[168:171], v[196:199], v[92:95]
	v_mfma_f32_16x16x32_bf16 v[88:91], v[176:179], v[196:199], v[88:91]
	v_mfma_f32_16x16x32_bf16 v[84:87], v[180:183], v[196:199], v[84:87]
	v_mfma_f32_16x16x32_bf16 v[80:83], v[184:187], v[196:199], v[80:83]
	ds_read_b128 v[196:199], v225 offset:4096
	ds_read_b128 v[160:163], v227 offset:4096
	v_mfma_f32_16x16x32_bf16 v[76:79], v[168:171], v[200:203], v[76:79]
	v_mfma_f32_16x16x32_bf16 v[72:75], v[176:179], v[200:203], v[72:75]
	v_mfma_f32_16x16x32_bf16 v[68:71], v[180:183], v[200:203], v[68:71]
	v_mfma_f32_16x16x32_bf16 v[64:67], v[184:187], v[200:203], v[64:67]
	ds_read_b128 v[200:203], v225 offset:6144
	ds_read_b128 v[164:167], v227 offset:6144
	v_mfma_f32_16x16x32_bf16 v[60:63], v[168:171], v[204:207], v[60:63]
	v_mfma_f32_16x16x32_bf16 v[56:59], v[176:179], v[204:207], v[56:59]
	v_mfma_f32_16x16x32_bf16 v[52:55], v[180:183], v[204:207], v[52:55]
	v_mfma_f32_16x16x32_bf16 v[48:51], v[184:187], v[204:207], v[48:51]
	ds_read_b128 v[204:207], v225 offset:8192
	ds_read_b128 v[216:219], v225 offset:14336
	v_mfma_f32_16x16x32_bf16 v[44:47], v[168:171], v[208:211], v[44:47]
	v_mfma_f32_16x16x32_bf16 v[40:43], v[176:179], v[208:211], v[40:43]
	v_mfma_f32_16x16x32_bf16 v[36:39], v[180:183], v[208:211], v[36:39]
	v_mfma_f32_16x16x32_bf16 v[32:35], v[184:187], v[208:211], v[32:35]
	ds_read_b128 v[208:211], v225 offset:10240
	v_mfma_f32_16x16x32_bf16 v[28:31], v[168:171], v[212:215], v[28:31]
	v_mfma_f32_16x16x32_bf16 v[24:27], v[176:179], v[212:215], v[24:27]
	v_mfma_f32_16x16x32_bf16 v[20:23], v[180:183], v[212:215], v[20:23]
	v_mfma_f32_16x16x32_bf16 v[16:19], v[184:187], v[212:215], v[16:19]
	ds_read_b128 v[212:215], v225 offset:12288
	v_mfma_f32_16x16x32_bf16 v[12:15], v[168:171], v[220:223], v[12:15]
	v_mfma_f32_16x16x32_bf16 v[8:11], v[176:179], v[220:223], v[8:11]
	v_mfma_f32_16x16x32_bf16 v[4:7], v[180:183], v[220:223], v[4:7]
	v_mfma_f32_16x16x32_bf16 v[0:3], v[184:187], v[220:223], v[0:3]
	v_xor_b32_e32 v226, 0x8000, v226
	v_xor_b32_e32 v228, 0x8000, v228
	s_waitcnt lgkmcnt(4)
	v_mfma_f32_16x16x32_bf16 v[124:127], v[152:155], v[188:191], v[124:127]
	v_mfma_f32_16x16x32_bf16 v[120:123], v[156:159], v[188:191], v[120:123]
	v_mfma_f32_16x16x32_bf16 v[116:119], v[160:163], v[188:191], v[116:119]
	v_mfma_f32_16x16x32_bf16 v[112:115], v[164:167], v[188:191], v[112:115]
	ds_read_b128 v[188:191], v226 offset:0
	ds_read_b128 v[168:171], v228 offset:0
	v_mfma_f32_16x16x32_bf16 v[108:111], v[152:155], v[192:195], v[108:111]
	v_mfma_f32_16x16x32_bf16 v[104:107], v[156:159], v[192:195], v[104:107]
	v_mfma_f32_16x16x32_bf16 v[100:103], v[160:163], v[192:195], v[100:103]
	v_mfma_f32_16x16x32_bf16 v[96:99], v[164:167], v[192:195], v[96:99]
	ds_read_b128 v[192:195], v226 offset:2048
	ds_read_b128 v[176:179], v228 offset:2048
	v_mfma_f32_16x16x32_bf16 v[92:95], v[152:155], v[196:199], v[92:95]
	v_mfma_f32_16x16x32_bf16 v[88:91], v[156:159], v[196:199], v[88:91]
	v_mfma_f32_16x16x32_bf16 v[84:87], v[160:163], v[196:199], v[84:87]
	v_mfma_f32_16x16x32_bf16 v[80:83], v[164:167], v[196:199], v[80:83]
	ds_read_b128 v[196:199], v226 offset:4096
	ds_read_b128 v[180:183], v228 offset:4096
	v_mfma_f32_16x16x32_bf16 v[76:79], v[152:155], v[200:203], v[76:79]
	v_mfma_f32_16x16x32_bf16 v[72:75], v[156:159], v[200:203], v[72:75]
	v_mfma_f32_16x16x32_bf16 v[68:71], v[160:163], v[200:203], v[68:71]
	v_mfma_f32_16x16x32_bf16 v[64:67], v[164:167], v[200:203], v[64:67]
	ds_read_b128 v[200:203], v226 offset:6144
	ds_read_b128 v[184:187], v228 offset:6144
	s_waitcnt lgkmcnt(11)
	v_mfma_f32_16x16x32_bf16 v[60:63], v[152:155], v[204:207], v[60:63]
	v_mfma_f32_16x16x32_bf16 v[56:59], v[156:159], v[204:207], v[56:59]
	v_mfma_f32_16x16x32_bf16 v[52:55], v[160:163], v[204:207], v[52:55]
	v_mfma_f32_16x16x32_bf16 v[48:51], v[164:167], v[204:207], v[48:51]
	ds_read_b128 v[204:207], v226 offset:8192
	ds_read_b128 v[220:223], v226 offset:14336
	s_waitcnt lgkmcnt(11)
	v_mfma_f32_16x16x32_bf16 v[44:47], v[152:155], v[208:211], v[44:47]
	v_mfma_f32_16x16x32_bf16 v[40:43], v[156:159], v[208:211], v[40:43]
	v_mfma_f32_16x16x32_bf16 v[36:39], v[160:163], v[208:211], v[36:39]
	v_mfma_f32_16x16x32_bf16 v[32:35], v[164:167], v[208:211], v[32:35]
	ds_read_b128 v[208:211], v226 offset:10240
	s_waitcnt lgkmcnt(11)
	v_mfma_f32_16x16x32_bf16 v[28:31], v[152:155], v[212:215], v[28:31]
	v_mfma_f32_16x16x32_bf16 v[24:27], v[156:159], v[212:215], v[24:27]
	v_mfma_f32_16x16x32_bf16 v[20:23], v[160:163], v[212:215], v[20:23]
	v_mfma_f32_16x16x32_bf16 v[16:19], v[164:167], v[212:215], v[16:19]
	ds_read_b128 v[212:215], v226 offset:12288
	v_mfma_f32_16x16x32_bf16 v[12:15], v[152:155], v[216:219], v[12:15]
	v_mfma_f32_16x16x32_bf16 v[8:11], v[156:159], v[216:219], v[8:11]
	v_mfma_f32_16x16x32_bf16 v[4:7], v[160:163], v[216:219], v[4:7]
	v_mfma_f32_16x16x32_bf16 v[0:3], v[164:167], v[216:219], v[0:3]
	s_waitcnt vmcnt(0) lgkmcnt(0)
	s_barrier
; DI u16 f2bf(float a) { return (u16)(pk2(a, 0.f) & 0xffffu); }
; DI float sigmoidf_(float x) { return __builtin_amdgcn_rcpf(1.f + __builtin_amdgcn_exp2f(-1.4426950408889634f * x)); }
; template <int EPI>
; DI void gemm_phase(const u16* __restrict__ A, int lda, const u16* __restrict__ Bt, int K, int N, u16* outb, int ldo,
;                    const float* r0, const float* r1, float* outf, char* lds, int bid, int nb) {
;     ...
;     } else {
;       const int col = (tn * 4 + wc) * 32 + l15;
; #pragma unroll
;       for (int i = 0; i < 8; ++i)
; #pragma unroll
;         for (int r = 0; r < 4; ++r) {
;           const float g0 = acc[i][0][r], u0 = acc[i][2][r], g1 = acc[i][1][r], u1 = acc[i][3][r];
;           u16* o0 = outb + (size_t)(mrow + i * 16 + r) * ldo + col;
;           o0[0] = f2bf(g0 * sigmoidf_(g0) * u0); o0[16] = f2bf(g1 * sigmoidf_(g1) * u1);
;         }
	v_mfma_f32_16x16x32_bf16 v[124:127], v[168:171], v[188:191], v[124:127]
	v_mfma_f32_16x16x32_bf16 v[120:123], v[176:179], v[188:191], v[120:123]
	v_mfma_f32_16x16x32_bf16 v[116:119], v[180:183], v[188:191], v[116:119]
	v_mfma_f32_16x16x32_bf16 v[112:115], v[184:187], v[188:191], v[112:115]
	v_mfma_f32_16x16x32_bf16 v[108:111], v[168:171], v[192:195], v[108:111]
	v_mfma_f32_16x16x32_bf16 v[104:107], v[176:179], v[192:195], v[104:107]
	v_mfma_f32_16x16x32_bf16 v[100:103], v[180:183], v[192:195], v[100:103]
	v_mfma_f32_16x16x32_bf16 v[96:99], v[184:187], v[192:195], v[96:99]
	v_mfma_f32_16x16x32_bf16 v[92:95], v[168:171], v[196:199], v[92:95]
	v_mfma_f32_16x16x32_bf16 v[88:91], v[176:179], v[196:199], v[88:91]
	v_mfma_f32_16x16x32_bf16 v[84:87], v[180:183], v[196:199], v[84:87]
	v_mfma_f32_16x16x32_bf16 v[80:83], v[184:187], v[196:199], v[80:83]
	v_mfma_f32_16x16x32_bf16 v[76:79], v[168:171], v[200:203], v[76:79]
	v_mfma_f32_16x16x32_bf16 v[72:75], v[176:179], v[200:203], v[72:75]
	v_mfma_f32_16x16x32_bf16 v[68:71], v[180:183], v[200:203], v[68:71]
	v_mfma_f32_16x16x32_bf16 v[64:67], v[184:187], v[200:203], v[64:67]
	v_mfma_f32_16x16x32_bf16 v[60:63], v[168:171], v[204:207], v[60:63]
	v_mfma_f32_16x16x32_bf16 v[56:59], v[176:179], v[204:207], v[56:59]
	v_mfma_f32_16x16x32_bf16 v[52:55], v[180:183], v[204:207], v[52:55]
	v_mfma_f32_16x16x32_bf16 v[48:51], v[184:187], v[204:207], v[48:51]
	v_mfma_f32_16x16x32_bf16 v[44:47], v[168:171], v[208:211], v[44:47]
	v_mfma_f32_16x16x32_bf16 v[40:43], v[176:179], v[208:211], v[40:43]
	v_mfma_f32_16x16x32_bf16 v[36:39], v[180:183], v[208:211], v[36:39]
	v_mfma_f32_16x16x32_bf16 v[32:35], v[184:187], v[208:211], v[32:35]
	v_mfma_f32_16x16x32_bf16 v[28:31], v[168:171], v[212:215], v[28:31]
	v_mfma_f32_16x16x32_bf16 v[24:27], v[176:179], v[212:215], v[24:27]
	v_mfma_f32_16x16x32_bf16 v[20:23], v[180:183], v[212:215], v[20:23]
	v_mfma_f32_16x16x32_bf16 v[16:19], v[184:187], v[212:215], v[16:19]
	v_mfma_f32_16x16x32_bf16 v[12:15], v[168:171], v[220:223], v[12:15]
	v_mfma_f32_16x16x32_bf16 v[8:11], v[176:179], v[220:223], v[8:11]
	v_mfma_f32_16x16x32_bf16 v[4:7], v[180:183], v[220:223], v[4:7]
	v_mfma_f32_16x16x32_bf16 v[0:3], v[184:187], v[220:223], v[0:3]
	s_nop 7
	s_nop 3
	v_and_b32_e32 v225, 15, v174
	v_lshrrev_b32_e32 v226, 8, v174
	v_lshl_or_b32 v225, v226, 7, v225
	v_bfe_u32 v226, v174, 6, 2
	v_bfe_u32 v227, v174, 4, 2
	v_lshlrev_b32_e32 v227, 2, v227
	v_add_u32_e32 v225, s41, v225
	v_lshl_add_u32 v226, v226, 5, v227
	v_lshl_or_b32 v226, s40, 7, v226
	v_lshlrev_b32_e32 v226, 1, v226
	v_mov_b32_e32 v227, 0x1600
	v_mad_u32_u24 v224, v225, v227, v226
	v_mul_f32_e32 v188, 0xbfb8aa3b, v124
	v_mul_f32_e32 v189, 0xbfb8aa3b, v125
	v_mul_f32_e32 v190, 0xbfb8aa3b, v126
	v_mul_f32_e32 v191, 0xbfb8aa3b, v127
	v_exp_f32_e32 v188, v188
	v_exp_f32_e32 v189, v189
	v_exp_f32_e32 v190, v190
	v_exp_f32_e32 v191, v191
	v_add_f32_e32 v188, 1.0, v188
	v_add_f32_e32 v189, 1.0, v189
	v_add_f32_e32 v190, 1.0, v190
	v_add_f32_e32 v191, 1.0, v191
	v_rcp_f32_e32 v188, v188
	v_rcp_f32_e32 v189, v189
	v_rcp_f32_e32 v190, v190
	v_rcp_f32_e32 v191, v191
	v_mul_f32_e32 v188, v124, v188
	v_mul_f32_e32 v189, v125, v189
	v_mul_f32_e32 v190, v126, v190
	v_mul_f32_e32 v191, v127, v191
	v_mul_f32_e32 v188, v116, v188
	v_mul_f32_e32 v189, v117, v189
	v_mul_f32_e32 v190, v118, v190
	v_mul_f32_e32 v191, v119, v191
	v_cvt_pk_bf16_f32 v200, v188, v189
	v_cvt_pk_bf16_f32 v201, v190, v191
	global_store_dwordx2 v224, v[200:201], s[8:9] offset:0
	v_mul_f32_e32 v188, 0xbfb8aa3b, v120
	v_mul_f32_e32 v189, 0xbfb8aa3b, v121
	v_mul_f32_e32 v190, 0xbfb8aa3b, v122
	v_mul_f32_e32 v191, 0xbfb8aa3b, v123
	v_exp_f32_e32 v188, v188
	v_exp_f32_e32 v189, v189
	v_exp_f32_e32 v190, v190
	v_exp_f32_e32 v191, v191
	v_add_f32_e32 v188, 1.0, v188
	v_add_f32_e32 v189, 1.0, v189
	v_add_f32_e32 v190, 1.0, v190
	v_add_f32_e32 v191, 1.0, v191
	v_rcp_f32_e32 v188, v188
	v_rcp_f32_e32 v189, v189
	v_rcp_f32_e32 v190, v190
	v_rcp_f32_e32 v191, v191
	v_mul_f32_e32 v188, v120, v188
	v_mul_f32_e32 v189, v121, v189
	v_mul_f32_e32 v190, v122, v190
	v_mul_f32_e32 v191, v123, v191
	v_mul_f32_e32 v188, v112, v188
	v_mul_f32_e32 v189, v113, v189
	v_mul_f32_e32 v190, v114, v190
	v_mul_f32_e32 v191, v115, v191
	v_cvt_pk_bf16_f32 v202, v188, v189
	v_cvt_pk_bf16_f32 v203, v190, v191
	global_store_dwordx2 v224, v[202:203], s[8:9] offset:32
	v_add_u32_e32 v224, 0x16000, v224
	v_mul_f32_e32 v188, 0xbfb8aa3b, v108
	v_mul_f32_e32 v189, 0xbfb8aa3b, v109
	v_mul_f32_e32 v190, 0xbfb8aa3b, v110
	v_mul_f32_e32 v191, 0xbfb8aa3b, v111
	v_exp_f32_e32 v188, v188
	v_exp_f32_e32 v189, v189
	v_exp_f32_e32 v190, v190
	v_exp_f32_e32 v191, v191
	v_add_f32_e32 v188, 1.0, v188
	v_add_f32_e32 v189, 1.0, v189
	v_add_f32_e32 v190, 1.0, v190
	v_add_f32_e32 v191, 1.0, v191
	v_rcp_f32_e32 v188, v188
	v_rcp_f32_e32 v189, v189
	v_rcp_f32_e32 v190, v190
	v_rcp_f32_e32 v191, v191
	v_mul_f32_e32 v188, v108, v188
	v_mul_f32_e32 v189, v109, v189
	v_mul_f32_e32 v190, v110, v190
	v_mul_f32_e32 v191, v111, v191
	v_mul_f32_e32 v188, v100, v188
	v_mul_f32_e32 v189, v101, v189
	v_mul_f32_e32 v190, v102, v190
	v_mul_f32_e32 v191, v103, v191
	v_cvt_pk_bf16_f32 v204, v188, v189
	v_cvt_pk_bf16_f32 v205, v190, v191
	global_store_dwordx2 v224, v[204:205], s[8:9] offset:0
	v_mul_f32_e32 v188, 0xbfb8aa3b, v104
	v_mul_f32_e32 v189, 0xbfb8aa3b, v105
	v_mul_f32_e32 v190, 0xbfb8aa3b, v106
	v_mul_f32_e32 v191, 0xbfb8aa3b, v107
	v_exp_f32_e32 v188, v188
	v_exp_f32_e32 v189, v189
	v_exp_f32_e32 v190, v190
	v_exp_f32_e32 v191, v191
	v_add_f32_e32 v188, 1.0, v188
	v_add_f32_e32 v189, 1.0, v189
	v_add_f32_e32 v190, 1.0, v190
	v_add_f32_e32 v191, 1.0, v191
; DI u16 f2bf(float a) { return (u16)(pk2(a, 0.f) & 0xffffu); }
; DI float sigmoidf_(float x) { return __builtin_amdgcn_rcpf(1.f + __builtin_amdgcn_exp2f(-1.4426950408889634f * x)); }
; template <int EPI>
; DI void gemm_phase(const u16* __restrict__ A, int lda, const u16* __restrict__ Bt, int K, int N, u16* outb, int ldo,
;                    const float* r0, const float* r1, float* outf, char* lds, int bid, int nb) {
;     ...
;     } else {
;       const int col = (tn * 4 + wc) * 32 + l15;
; #pragma unroll
;       for (int i = 0; i < 8; ++i)
; #pragma unroll
;         for (int r = 0; r < 4; ++r) {
;           const float g0 = acc[i][0][r], u0 = acc[i][2][r], g1 = acc[i][1][r], u1 = acc[i][3][r];
;           u16* o0 = outb + (size_t)(mrow + i * 16 + r) * ldo + col;
;           o0[0] = f2bf(g0 * sigmoidf_(g0) * u0); o0[16] = f2bf(g1 * sigmoidf_(g1) * u1);
;         }
	v_rcp_f32_e32 v188, v188
	v_rcp_f32_e32 v189, v189
	v_rcp_f32_e32 v190, v190
	v_rcp_f32_e32 v191, v191
	v_mul_f32_e32 v188, v104, v188
	v_mul_f32_e32 v189, v105, v189
	v_mul_f32_e32 v190, v106, v190
	v_mul_f32_e32 v191, v107, v191
	v_mul_f32_e32 v188, v96, v188
	v_mul_f32_e32 v189, v97, v189
	v_mul_f32_e32 v190, v98, v190
	v_mul_f32_e32 v191, v99, v191
	v_cvt_pk_bf16_f32 v206, v188, v189
	v_cvt_pk_bf16_f32 v207, v190, v191
	global_store_dwordx2 v224, v[206:207], s[8:9] offset:32
	v_add_u32_e32 v224, 0x16000, v224
	v_mul_f32_e32 v188, 0xbfb8aa3b, v92
	v_mul_f32_e32 v189, 0xbfb8aa3b, v93
	v_mul_f32_e32 v190, 0xbfb8aa3b, v94
	v_mul_f32_e32 v191, 0xbfb8aa3b, v95
	v_exp_f32_e32 v188, v188
	v_exp_f32_e32 v189, v189
	v_exp_f32_e32 v190, v190
	v_exp_f32_e32 v191, v191
	v_add_f32_e32 v188, 1.0, v188
	v_add_f32_e32 v189, 1.0, v189
	v_add_f32_e32 v190, 1.0, v190
	v_add_f32_e32 v191, 1.0, v191
	v_rcp_f32_e32 v188, v188
	v_rcp_f32_e32 v189, v189
	v_rcp_f32_e32 v190, v190
	v_rcp_f32_e32 v191, v191
	v_mul_f32_e32 v188, v92, v188
	v_mul_f32_e32 v189, v93, v189
	v_mul_f32_e32 v190, v94, v190
	v_mul_f32_e32 v191, v95, v191
	v_mul_f32_e32 v188, v84, v188
	v_mul_f32_e32 v189, v85, v189
	v_mul_f32_e32 v190, v86, v190
	v_mul_f32_e32 v191, v87, v191
	v_cvt_pk_bf16_f32 v208, v188, v189
	v_cvt_pk_bf16_f32 v209, v190, v191
	global_store_dwordx2 v224, v[208:209], s[8:9] offset:0
	v_mul_f32_e32 v188, 0xbfb8aa3b, v88
	v_mul_f32_e32 v189, 0xbfb8aa3b, v89
	v_mul_f32_e32 v190, 0xbfb8aa3b, v90
	v_mul_f32_e32 v191, 0xbfb8aa3b, v91
	v_exp_f32_e32 v188, v188
	v_exp_f32_e32 v189, v189
	v_exp_f32_e32 v190, v190
	v_exp_f32_e32 v191, v191
	v_add_f32_e32 v188, 1.0, v188
	v_add_f32_e32 v189, 1.0, v189
	v_add_f32_e32 v190, 1.0, v190
	v_add_f32_e32 v191, 1.0, v191
	v_rcp_f32_e32 v188, v188
	v_rcp_f32_e32 v189, v189
	v_rcp_f32_e32 v190, v190
	v_rcp_f32_e32 v191, v191
	v_mul_f32_e32 v188, v88, v188
	v_mul_f32_e32 v189, v89, v189
	v_mul_f32_e32 v190, v90, v190
	v_mul_f32_e32 v191, v91, v191
	v_mul_f32_e32 v188, v80, v188
	v_mul_f32_e32 v189, v81, v189
	v_mul_f32_e32 v190, v82, v190
	v_mul_f32_e32 v191, v83, v191
	v_cvt_pk_bf16_f32 v210, v188, v189
	v_cvt_pk_bf16_f32 v211, v190, v191
	global_store_dwordx2 v224, v[210:211], s[8:9] offset:32
	v_add_u32_e32 v224, 0x16000, v224
	v_mul_f32_e32 v188, 0xbfb8aa3b, v76
	v_mul_f32_e32 v189, 0xbfb8aa3b, v77
	v_mul_f32_e32 v190, 0xbfb8aa3b, v78
	v_mul_f32_e32 v191, 0xbfb8aa3b, v79
	v_exp_f32_e32 v188, v188
	v_exp_f32_e32 v189, v189
	v_exp_f32_e32 v190, v190
	v_exp_f32_e32 v191, v191
	v_add_f32_e32 v188, 1.0, v188
	v_add_f32_e32 v189, 1.0, v189
	v_add_f32_e32 v190, 1.0, v190
	v_add_f32_e32 v191, 1.0, v191
	v_rcp_f32_e32 v188, v188
	v_rcp_f32_e32 v189, v189
	v_rcp_f32_e32 v190, v190
	v_rcp_f32_e32 v191, v191
	v_mul_f32_e32 v188, v76, v188
	v_mul_f32_e32 v189, v77, v189
	v_mul_f32_e32 v190, v78, v190
	v_mul_f32_e32 v191, v79, v191
	v_mul_f32_e32 v188, v68, v188
	v_mul_f32_e32 v189, v69, v189
	v_mul_f32_e32 v190, v70, v190
	v_mul_f32_e32 v191, v71, v191
	v_cvt_pk_bf16_f32 v212, v188, v189
	v_cvt_pk_bf16_f32 v213, v190, v191
	global_store_dwordx2 v224, v[212:213], s[8:9] offset:0
	v_mul_f32_e32 v188, 0xbfb8aa3b, v72
	v_mul_f32_e32 v189, 0xbfb8aa3b, v73
	v_mul_f32_e32 v190, 0xbfb8aa3b, v74
	v_mul_f32_e32 v191, 0xbfb8aa3b, v75
	v_exp_f32_e32 v188, v188
	v_exp_f32_e32 v189, v189
	v_exp_f32_e32 v190, v190
	v_exp_f32_e32 v191, v191
	v_add_f32_e32 v188, 1.0, v188
	v_add_f32_e32 v189, 1.0, v189
	v_add_f32_e32 v190, 1.0, v190
	v_add_f32_e32 v191, 1.0, v191
	v_rcp_f32_e32 v188, v188
	v_rcp_f32_e32 v189, v189
	v_rcp_f32_e32 v190, v190
	v_rcp_f32_e32 v191, v191
	v_mul_f32_e32 v188, v72, v188
	v_mul_f32_e32 v189, v73, v189
	v_mul_f32_e32 v190, v74, v190
	v_mul_f32_e32 v191, v75, v191
	v_mul_f32_e32 v188, v64, v188
	v_mul_f32_e32 v189, v65, v189
	v_mul_f32_e32 v190, v66, v190
	v_mul_f32_e32 v191, v67, v191
	v_cvt_pk_bf16_f32 v214, v188, v189
	v_cvt_pk_bf16_f32 v215, v190, v191
	global_store_dwordx2 v224, v[214:215], s[8:9] offset:32
	v_add_u32_e32 v224, 0x16000, v224
	v_mul_f32_e32 v188, 0xbfb8aa3b, v60
	v_mul_f32_e32 v189, 0xbfb8aa3b, v61
	v_mul_f32_e32 v190, 0xbfb8aa3b, v62
	v_mul_f32_e32 v191, 0xbfb8aa3b, v63
	v_exp_f32_e32 v188, v188
	v_exp_f32_e32 v189, v189
	v_exp_f32_e32 v190, v190
	v_exp_f32_e32 v191, v191
	v_add_f32_e32 v188, 1.0, v188
	v_add_f32_e32 v189, 1.0, v189
	v_add_f32_e32 v190, 1.0, v190
	v_add_f32_e32 v191, 1.0, v191
	v_rcp_f32_e32 v188, v188
	v_rcp_f32_e32 v189, v189
	v_rcp_f32_e32 v190, v190
	v_rcp_f32_e32 v191, v191
	v_mul_f32_e32 v188, v60, v188
	v_mul_f32_e32 v189, v61, v189
	v_mul_f32_e32 v190, v62, v190
	v_mul_f32_e32 v191, v63, v191
	v_mul_f32_e32 v188, v52, v188
	v_mul_f32_e32 v189, v53, v189
	v_mul_f32_e32 v190, v54, v190
	v_mul_f32_e32 v191, v55, v191
	v_cvt_pk_bf16_f32 v200, v188, v189
	v_cvt_pk_bf16_f32 v201, v190, v191
	global_store_dwordx2 v224, v[200:201], s[8:9] offset:0
	v_mul_f32_e32 v188, 0xbfb8aa3b, v56
	v_mul_f32_e32 v189, 0xbfb8aa3b, v57
	v_mul_f32_e32 v190, 0xbfb8aa3b, v58
	v_mul_f32_e32 v191, 0xbfb8aa3b, v59
	v_exp_f32_e32 v188, v188
	v_exp_f32_e32 v189, v189
	v_exp_f32_e32 v190, v190
	v_exp_f32_e32 v191, v191
	v_add_f32_e32 v188, 1.0, v188
	v_add_f32_e32 v189, 1.0, v189
	v_add_f32_e32 v190, 1.0, v190
	v_add_f32_e32 v191, 1.0, v191
	v_rcp_f32_e32 v188, v188
	v_rcp_f32_e32 v189, v189
	v_rcp_f32_e32 v190, v190
	v_rcp_f32_e32 v191, v191
	v_mul_f32_e32 v188, v56, v188
	v_mul_f32_e32 v189, v57, v189
	v_mul_f32_e32 v190, v58, v190
	v_mul_f32_e32 v191, v59, v191
	v_mul_f32_e32 v188, v48, v188
; DI u16 f2bf(float a) { return (u16)(pk2(a, 0.f) & 0xffffu); }
; DI float sigmoidf_(float x) { return __builtin_amdgcn_rcpf(1.f + __builtin_amdgcn_exp2f(-1.4426950408889634f * x)); }
; template <int EPI>
; DI void gemm_phase(const u16* __restrict__ A, int lda, const u16* __restrict__ Bt, int K, int N, u16* outb, int ldo,
;                    const float* r0, const float* r1, float* outf, char* lds, int bid, int nb) {
;     ...
;     } else {
;       const int col = (tn * 4 + wc) * 32 + l15;
; #pragma unroll
;       for (int i = 0; i < 8; ++i)
; #pragma unroll
;         for (int r = 0; r < 4; ++r) {
;           const float g0 = acc[i][0][r], u0 = acc[i][2][r], g1 = acc[i][1][r], u1 = acc[i][3][r];
;           u16* o0 = outb + (size_t)(mrow + i * 16 + r) * ldo + col;
;           o0[0] = f2bf(g0 * sigmoidf_(g0) * u0); o0[16] = f2bf(g1 * sigmoidf_(g1) * u1);
;         }
	v_mul_f32_e32 v189, v49, v189
	v_mul_f32_e32 v190, v50, v190
	v_mul_f32_e32 v191, v51, v191
	v_cvt_pk_bf16_f32 v202, v188, v189
	v_cvt_pk_bf16_f32 v203, v190, v191
	global_store_dwordx2 v224, v[202:203], s[8:9] offset:32
	v_add_u32_e32 v224, 0x16000, v224
	v_mul_f32_e32 v188, 0xbfb8aa3b, v44
	v_mul_f32_e32 v189, 0xbfb8aa3b, v45
	v_mul_f32_e32 v190, 0xbfb8aa3b, v46
	v_mul_f32_e32 v191, 0xbfb8aa3b, v47
	v_exp_f32_e32 v188, v188
	v_exp_f32_e32 v189, v189
	v_exp_f32_e32 v190, v190
	v_exp_f32_e32 v191, v191
	v_add_f32_e32 v188, 1.0, v188
	v_add_f32_e32 v189, 1.0, v189
	v_add_f32_e32 v190, 1.0, v190
	v_add_f32_e32 v191, 1.0, v191
	v_rcp_f32_e32 v188, v188
	v_rcp_f32_e32 v189, v189
	v_rcp_f32_e32 v190, v190
	v_rcp_f32_e32 v191, v191
	v_mul_f32_e32 v188, v44, v188
	v_mul_f32_e32 v189, v45, v189
	v_mul_f32_e32 v190, v46, v190
	v_mul_f32_e32 v191, v47, v191
	v_mul_f32_e32 v188, v36, v188
	v_mul_f32_e32 v189, v37, v189
	v_mul_f32_e32 v190, v38, v190
	v_mul_f32_e32 v191, v39, v191
	v_cvt_pk_bf16_f32 v204, v188, v189
	v_cvt_pk_bf16_f32 v205, v190, v191
	global_store_dwordx2 v224, v[204:205], s[8:9] offset:0
	v_mul_f32_e32 v188, 0xbfb8aa3b, v40
	v_mul_f32_e32 v189, 0xbfb8aa3b, v41
	v_mul_f32_e32 v190, 0xbfb8aa3b, v42
	v_mul_f32_e32 v191, 0xbfb8aa3b, v43
	v_exp_f32_e32 v188, v188
	v_exp_f32_e32 v189, v189
	v_exp_f32_e32 v190, v190
	v_exp_f32_e32 v191, v191
	v_add_f32_e32 v188, 1.0, v188
	v_add_f32_e32 v189, 1.0, v189
	v_add_f32_e32 v190, 1.0, v190
	v_add_f32_e32 v191, 1.0, v191
	v_rcp_f32_e32 v188, v188
	v_rcp_f32_e32 v189, v189
	v_rcp_f32_e32 v190, v190
	v_rcp_f32_e32 v191, v191
	v_mul_f32_e32 v188, v40, v188
	v_mul_f32_e32 v189, v41, v189
	v_mul_f32_e32 v190, v42, v190
	v_mul_f32_e32 v191, v43, v191
	v_mul_f32_e32 v188, v32, v188
	v_mul_f32_e32 v189, v33, v189
	v_mul_f32_e32 v190, v34, v190
	v_mul_f32_e32 v191, v35, v191
	v_cvt_pk_bf16_f32 v206, v188, v189
	v_cvt_pk_bf16_f32 v207, v190, v191
	global_store_dwordx2 v224, v[206:207], s[8:9] offset:32
	v_add_u32_e32 v224, 0x16000, v224
	v_mul_f32_e32 v188, 0xbfb8aa3b, v28
	v_mul_f32_e32 v189, 0xbfb8aa3b, v29
	v_mul_f32_e32 v190, 0xbfb8aa3b, v30
	v_mul_f32_e32 v191, 0xbfb8aa3b, v31
	v_exp_f32_e32 v188, v188
	v_exp_f32_e32 v189, v189
	v_exp_f32_e32 v190, v190
	v_exp_f32_e32 v191, v191
	v_add_f32_e32 v188, 1.0, v188
	v_add_f32_e32 v189, 1.0, v189
	v_add_f32_e32 v190, 1.0, v190
	v_add_f32_e32 v191, 1.0, v191
	v_rcp_f32_e32 v188, v188
	v_rcp_f32_e32 v189, v189
	v_rcp_f32_e32 v190, v190
	v_rcp_f32_e32 v191, v191
	v_mul_f32_e32 v188, v28, v188
	v_mul_f32_e32 v189, v29, v189
	v_mul_f32_e32 v190, v30, v190
	v_mul_f32_e32 v191, v31, v191
	v_mul_f32_e32 v188, v20, v188
	v_mul_f32_e32 v189, v21, v189
	v_mul_f32_e32 v190, v22, v190
	v_mul_f32_e32 v191, v23, v191
	v_cvt_pk_bf16_f32 v208, v188, v189
	v_cvt_pk_bf16_f32 v209, v190, v191
	global_store_dwordx2 v224, v[208:209], s[8:9] offset:0
	v_mul_f32_e32 v188, 0xbfb8aa3b, v24
	v_mul_f32_e32 v189, 0xbfb8aa3b, v25
	v_mul_f32_e32 v190, 0xbfb8aa3b, v26
	v_mul_f32_e32 v191, 0xbfb8aa3b, v27
	v_exp_f32_e32 v188, v188
	v_exp_f32_e32 v189, v189
	v_exp_f32_e32 v190, v190
	v_exp_f32_e32 v191, v191
	v_add_f32_e32 v188, 1.0, v188
	v_add_f32_e32 v189, 1.0, v189
	v_add_f32_e32 v190, 1.0, v190
	v_add_f32_e32 v191, 1.0, v191
	v_rcp_f32_e32 v188, v188
	v_rcp_f32_e32 v189, v189
	v_rcp_f32_e32 v190, v190
	v_rcp_f32_e32 v191, v191
	v_mul_f32_e32 v188, v24, v188
	v_mul_f32_e32 v189, v25, v189
	v_mul_f32_e32 v190, v26, v190
	v_mul_f32_e32 v191, v27, v191
	v_mul_f32_e32 v188, v16, v188
	v_mul_f32_e32 v189, v17, v189
	v_mul_f32_e32 v190, v18, v190
	v_mul_f32_e32 v191, v19, v191
	v_cvt_pk_bf16_f32 v210, v188, v189
	v_cvt_pk_bf16_f32 v211, v190, v191
	global_store_dwordx2 v224, v[210:211], s[8:9] offset:32
	v_add_u32_e32 v224, 0x16000, v224
	v_mul_f32_e32 v188, 0xbfb8aa3b, v12
	v_mul_f32_e32 v189, 0xbfb8aa3b, v13
	v_mul_f32_e32 v190, 0xbfb8aa3b, v14
	v_mul_f32_e32 v191, 0xbfb8aa3b, v15
	v_exp_f32_e32 v188, v188
	v_exp_f32_e32 v189, v189
	v_exp_f32_e32 v190, v190
	v_exp_f32_e32 v191, v191
	v_add_f32_e32 v188, 1.0, v188
	v_add_f32_e32 v189, 1.0, v189
	v_add_f32_e32 v190, 1.0, v190
	v_add_f32_e32 v191, 1.0, v191
	v_rcp_f32_e32 v188, v188
	v_rcp_f32_e32 v189, v189
	v_rcp_f32_e32 v190, v190
	v_rcp_f32_e32 v191, v191
	v_mul_f32_e32 v188, v12, v188
	v_mul_f32_e32 v189, v13, v189
	v_mul_f32_e32 v190, v14, v190
	v_mul_f32_e32 v191, v15, v191
	v_mul_f32_e32 v188, v4, v188
	v_mul_f32_e32 v189, v5, v189
	v_mul_f32_e32 v190, v6, v190
	v_mul_f32_e32 v191, v7, v191
	v_cvt_pk_bf16_f32 v212, v188, v189
	v_cvt_pk_bf16_f32 v213, v190, v191
	global_store_dwordx2 v224, v[212:213], s[8:9] offset:0
	v_mul_f32_e32 v188, 0xbfb8aa3b, v8
	v_mul_f32_e32 v189, 0xbfb8aa3b, v9
	v_mul_f32_e32 v190, 0xbfb8aa3b, v10
	v_mul_f32_e32 v191, 0xbfb8aa3b, v11
	v_exp_f32_e32 v188, v188
	v_exp_f32_e32 v189, v189
	v_exp_f32_e32 v190, v190
	v_exp_f32_e32 v191, v191
	v_add_f32_e32 v188, 1.0, v188
	v_add_f32_e32 v189, 1.0, v189
	v_add_f32_e32 v190, 1.0, v190
	v_add_f32_e32 v191, 1.0, v191
	v_rcp_f32_e32 v188, v188
	v_rcp_f32_e32 v189, v189
	v_rcp_f32_e32 v190, v190
	v_rcp_f32_e32 v191, v191
	v_mul_f32_e32 v188, v8, v188
	v_mul_f32_e32 v189, v9, v189
	v_mul_f32_e32 v190, v10, v190
	v_mul_f32_e32 v191, v11, v191
	v_mul_f32_e32 v188, v0, v188
	v_mul_f32_e32 v189, v1, v189
	v_mul_f32_e32 v190, v2, v190
	v_mul_f32_e32 v191, v3, v191
	v_cvt_pk_bf16_f32 v214, v188, v189
	v_cvt_pk_bf16_f32 v215, v190, v191
	global_store_dwordx2 v224, v[214:215], s[8:9] offset:32
	s_add_i32 s17, s17, 1
	s_cmp_eq_u32 s17, s3
	s_cbranch_scc0 .LBB0_1297

; #define G_LOAD(KT) do { _Pragma("unroll") for (int i = 0; i < 4; ++i) { ra[i] = *(const u32x4*)(Ag + (size_t)i * 64 * lda + (KT) * 64); rb[i] = *(const u32x4*)(Bg + (size_t)i * 64 * K + (KT) * 64); } } while (0)
; #define G_STORE(BUF) do { u16* ad = As + (BUF) * 256 * 64 + sto; u16* bd = Bs + (BUF) * 256 * 64 + sto; _Pragma("unroll") for (int i = 0; i < 4; ++i) { *(u32x4*)(ad + i * 64 * 64) = ra[i]; *(u32x4*)(bd + i * 64 * 64) = rb[i]; } } while (0)
; template <int EPI>
; DI void gemm_phase(const u16* __restrict__ A, int lda, const u16* __restrict__ Bt, int K, int N, u16* outb, int ldo,
;                    const float* r0, const float* r1, float* outf, char* lds, int bid, int nb) {
;     ...
;   for (int it = 0; it < nIter; ++it) {
;     int tm, tn;
;     if (swz) { const int st = xcd + 8 * it, sm = st / nSN, sn = st - sm * nSN; tm = sm * GM + jb / GN; tn = sn * GN + (jb % GN); }
;     else { const int t = bid + it * nb; tm = t / nN; tn = t - tm * nN; }
;     const u16* Ag = A + (size_t)(tm * 256 + lrow) * lda + lch * 8;
;     const u16* Bg = Bt + (size_t)(tn * 256 + lrow) * K + lch * 8;
;     f32x4 acc[8][4];
; #pragma unroll
;     for (int i = 0; i < 8; ++i)
; #pragma unroll
;       for (int j = 0; j < 4; ++j) acc[i][j] = (f32x4){0.f, 0.f, 0.f, 0.f};
;     u32x4 ra[4], rb[4];
;     ...
;     G_LOAD(0);
;     G_STORE(0);
;     __syncthreads();
;     for (int kt = 0; kt < nk; ++kt) {
;       const int cur = kt & 1;
;       if (kt + 1 < nk) G_LOAD(kt + 1);
;       G_MMA(cur, fo0);
;       G_MMA(cur, fo1);
.LBB0_1363:
	s_lshl_b32 s37, s37, 8
	v_or_b32_e32 v60, s37, v138
	s_lshl_b32 s38, s38, 8
	v_mad_i64_i32 v[0:1], s[8:9], v60, s15, v[128:129]
	v_or_b32_e32 v61, s38, v138
	v_add_co_u32_e32 v4, vcc, 0x58000, v0
	v_mad_i64_i32 v[2:3], s[8:9], v61, s15, v[130:131]
	s_nop 0
	v_addc_co_u32_e32 v5, vcc, 0, v1, vcc
	v_add_co_u32_e32 v6, vcc, 0x58000, v2
	s_nop 1
	v_readfirstlane_b32 s98, v0
	v_readfirstlane_b32 s99, v1
	s_nop 1
	v_readfirstlane_b32 s100, v2
	v_readfirstlane_b32 s101, v3
	v_addc_co_u32_e32 v7, vcc, 0, v3, vcc
	v_add_co_u32_e32 v4, vcc, 0xb0000, v0
	s_mov_b32 s39, 0
	s_nop 0
	v_addc_co_u32_e32 v5, vcc, 0, v1, vcc
	v_add_co_u32_e32 v6, vcc, 0xb0000, v2
	s_mov_b64 s[8:9], 0
	s_nop 0
	v_addc_co_u32_e32 v7, vcc, 0, v3, vcc
	v_add_co_u32_e32 v0, vcc, 0x108000, v0
	v_addc_co_u32_e32 v1, vcc, 0, v1, vcc
	v_add_co_u32_e32 v2, vcc, 0x108000, v2
	v_mad_i64_i32 v[134:135], s[28:29], v60, s15, v[132:133]
	s_nop 0
	v_addc_co_u32_e32 v3, vcc, 0, v3, vcc
	v_mov_b32_e32 v0, 0
	v_mad_i64_i32 v[136:137], s[28:29], v61, s15, v[132:133]
	v_and_b32_e32 v229, 63, v174
	v_lshrrev_b32_e32 v230, 3, v229
	v_mov_b32_e32 v233, 0x1600
	v_mul_u32_u24_e32 v224, v230, v233
	v_bfe_u32 v231, v174, 4, 2
	v_bfe_u32 v232, v174, 6, 1
	v_lshl_or_b32 v232, v232, 2, v231
	v_and_b32_e32 v233, 7, v174
	v_xor_b32_e32 v232, v232, v233
	v_lshl_add_u32 v224, v232, 4, v224
	v_and_b32_e32 v229, 15, v174
	v_bfe_u32 v230, v174, 1, 3
	v_xor_b32_e32 v230, v230, v231
	v_lshlrev_b32_e32 v230, 4, v230
	v_lshl_or_b32 v230, v229, 7, v230
	v_lshrrev_b32_e32 v229, 8, v174
	v_lshl_or_b32 v225, v229, 14, v230
	v_bfe_u32 v229, v174, 6, 2
	v_lshl_or_b32 v227, v229, 13, v230
	v_or_b32_e32 v227, 0x10000, v227
	v_xor_b32_e32 v226, 64, v225
	v_xor_b32_e32 v228, 64, v227
	v_readfirstlane_b32 s97, v174
	s_lshl_b32 s97, s97, 4
	s_mov_b32 s28, 42
	s_add_u32 m0, s97, 0x0
	s_add_u32 s8, s98, 0x0
	s_addc_u32 s9, s99, 0
	global_load_lds_dwordx4 v224, s[8:9]
	s_add_u32 m0, s97, 0x10000
	s_add_u32 s8, s100, 0x0
	s_addc_u32 s9, s101, 0
	global_load_lds_dwordx4 v224, s[8:9]
	s_add_u32 m0, s97, 0x2000
	s_add_u32 s8, s98, 0x58000
	s_addc_u32 s9, s99, 0
	global_load_lds_dwordx4 v224, s[8:9]
	s_add_u32 m0, s97, 0x12000
	s_add_u32 s8, s100, 0x58000
	s_addc_u32 s9, s101, 0
	global_load_lds_dwordx4 v224, s[8:9]
	s_add_u32 m0, s97, 0x4000
	s_add_u32 s8, s98, 0xb0000
	s_addc_u32 s9, s99, 0
	global_load_lds_dwordx4 v224, s[8:9]
	s_add_u32 m0, s97, 0x14000
	s_add_u32 s8, s100, 0xb0000
	s_addc_u32 s9, s101, 0
	global_load_lds_dwordx4 v224, s[8:9]
	s_add_u32 m0, s97, 0x6000
	s_add_u32 s8, s98, 0x108000
	s_addc_u32 s9, s99, 0
	global_load_lds_dwordx4 v224, s[8:9]
	s_add_u32 m0, s97, 0x16000
	s_add_u32 s8, s100, 0x108000
	s_addc_u32 s9, s101, 0
	global_load_lds_dwordx4 v224, s[8:9]
	s_add_u32 m0, s97, 0x8000
	s_add_u32 s8, s98, 0x80
	s_addc_u32 s9, s99, 0
	global_load_lds_dwordx4 v224, s[8:9]
	s_add_u32 m0, s97, 0x18000
	s_add_u32 s8, s100, 0x80
	s_addc_u32 s9, s101, 0
	global_load_lds_dwordx4 v224, s[8:9]
	s_add_u32 m0, s97, 0xa000
	s_add_u32 s8, s98, 0x58080
	s_addc_u32 s9, s99, 0
	global_load_lds_dwordx4 v224, s[8:9]
	s_add_u32 m0, s97, 0x1a000
	s_add_u32 s8, s100, 0x58080
	s_addc_u32 s9, s101, 0
	global_load_lds_dwordx4 v224, s[8:9]
	s_add_u32 m0, s97, 0xc000
	s_add_u32 s8, s98, 0xb0080
	s_addc_u32 s9, s99, 0
	global_load_lds_dwordx4 v224, s[8:9]
	s_add_u32 m0, s97, 0x1c000
	s_add_u32 s8, s100, 0xb0080
	s_addc_u32 s9, s101, 0
	global_load_lds_dwordx4 v224, s[8:9]
	s_add_u32 m0, s97, 0xe000
	s_add_u32 s8, s98, 0x108080
	s_addc_u32 s9, s99, 0
	global_load_lds_dwordx4 v224, s[8:9]
	s_add_u32 m0, s97, 0x1e000
	s_add_u32 s8, s100, 0x108080
	s_addc_u32 s9, s101, 0
	global_load_lds_dwordx4 v224, s[8:9]
	s_add_u32 s98, s98, 0x100
	s_addc_u32 s99, s99, 0
	s_add_u32 s100, s100, 0x100
	s_addc_u32 s101, s101, 0
	s_waitcnt vmcnt(8)
	s_barrier
	ds_read_b128 v[152:155], v227 offset:0
	ds_read_b128 v[156:159], v227 offset:2048
	ds_read_b128 v[160:163], v227 offset:4096
	ds_read_b128 v[164:167], v227 offset:6144
	ds_read_b128 v[188:191], v225 offset:0
	ds_read_b128 v[192:195], v225 offset:2048
	ds_read_b128 v[196:199], v225 offset:4096
	ds_read_b128 v[200:203], v225 offset:6144
	ds_read_b128 v[204:207], v225 offset:8192
	ds_read_b128 v[208:211], v225 offset:10240
	ds_read_b128 v[212:215], v225 offset:12288
	ds_read_b128 v[216:219], v225 offset:14336
	v_xor_b32_e32 v225, 0x8000, v225
	v_xor_b32_e32 v227, 0x8000, v227
	s_waitcnt lgkmcnt(0)
	s_waitcnt lgkmcnt(4)
	v_mfma_f32_16x16x32_bf16 v[124:127], v[152:155], v[188:191], 0
	v_mfma_f32_16x16x32_bf16 v[120:123], v[156:159], v[188:191], 0
	v_mfma_f32_16x16x32_bf16 v[116:119], v[160:163], v[188:191], 0
	v_mfma_f32_16x16x32_bf16 v[112:115], v[164:167], v[188:191], 0
	ds_read_b128 v[188:191], v226 offset:0
	ds_read_b128 v[168:171], v228 offset:0
	v_mfma_f32_16x16x32_bf16 v[108:111], v[152:155], v[192:195], 0
	v_mfma_f32_16x16x32_bf16 v[104:107], v[156:159], v[192:195], 0
	v_mfma_f32_16x16x32_bf16 v[100:103], v[160:163], v[192:195], 0
	v_mfma_f32_16x16x32_bf16 v[96:99], v[164:167], v[192:195], 0
	ds_read_b128 v[192:195], v226 offset:2048
	ds_read_b128 v[176:179], v228 offset:2048
	v_mfma_f32_16x16x32_bf16 v[92:95], v[152:155], v[196:199], 0
	v_mfma_f32_16x16x32_bf16 v[88:91], v[156:159], v[196:199], 0
	v_mfma_f32_16x16x32_bf16 v[84:87], v[160:163], v[196:199], 0
	v_mfma_f32_16x16x32_bf16 v[80:83], v[164:167], v[196:199], 0
	ds_read_b128 v[196:199], v226 offset:4096
	ds_read_b128 v[180:183], v228 offset:4096
	v_mfma_f32_16x16x32_bf16 v[76:79], v[152:155], v[200:203], 0
	v_mfma_f32_16x16x32_bf16 v[72:75], v[156:159], v[200:203], 0
	v_mfma_f32_16x16x32_bf16 v[68:71], v[160:163], v[200:203], 0
	v_mfma_f32_16x16x32_bf16 v[64:67], v[164:167], v[200:203], 0
	ds_read_b128 v[200:203], v226 offset:6144
	ds_read_b128 v[184:187], v228 offset:6144
	s_waitcnt lgkmcnt(11)
	v_mfma_f32_16x16x32_bf16 v[60:63], v[152:155], v[204:207], 0
	v_mfma_f32_16x16x32_bf16 v[56:59], v[156:159], v[204:207], 0
	v_mfma_f32_16x16x32_bf16 v[52:55], v[160:163], v[204:207], 0
	v_mfma_f32_16x16x32_bf16 v[48:51], v[164:167], v[204:207], 0
	ds_read_b128 v[204:207], v226 offset:8192
	ds_read_b128 v[220:223], v226 offset:14336
	s_waitcnt lgkmcnt(11)
	v_mfma_f32_16x16x32_bf16 v[44:47], v[152:155], v[208:211], 0
	v_mfma_f32_16x16x32_bf16 v[40:43], v[156:159], v[208:211], 0
	v_mfma_f32_16x16x32_bf16 v[36:39], v[160:163], v[208:211], 0
	v_mfma_f32_16x16x32_bf16 v[32:35], v[164:167], v[208:211], 0
	ds_read_b128 v[208:211], v226 offset:10240
	s_waitcnt lgkmcnt(11)
	v_mfma_f32_16x16x32_bf16 v[28:31], v[152:155], v[212:215], 0
	v_mfma_f32_16x16x32_bf16 v[24:27], v[156:159], v[212:215], 0
	v_mfma_f32_16x16x32_bf16 v[20:23], v[160:163], v[212:215], 0
	v_mfma_f32_16x16x32_bf16 v[16:19], v[164:167], v[212:215], 0
	ds_read_b128 v[212:215], v226 offset:12288
	v_mfma_f32_16x16x32_bf16 v[12:15], v[152:155], v[216:219], 0
	v_mfma_f32_16x16x32_bf16 v[8:11], v[156:159], v[216:219], 0
	v_mfma_f32_16x16x32_bf16 v[4:7], v[160:163], v[216:219], 0
	v_mfma_f32_16x16x32_bf16 v[0:3], v[164:167], v[216:219], 0
	s_branch .Lgm7_mid0

; #define G_LOAD(KT) do { _Pragma("unroll") for (int i = 0; i < 4; ++i) { ra[i] = *(const u32x4*)(Ag + (size_t)i * 64 * lda + (KT) * 64); rb[i] = *(const u32x4*)(Bg + (size_t)i * 64 * K + (KT) * 64); } } while (0)
; #define G_STORE(BUF) do { u16* ad = As + (BUF) * 256 * 64 + sto; u16* bd = Bs + (BUF) * 256 * 64 + sto; _Pragma("unroll") for (int i = 0; i < 4; ++i) { *(u32x4*)(ad + i * 64 * 64) = ra[i]; *(u32x4*)(bd + i * 64 * 64) = rb[i]; } } while (0)
; template <int EPI>
; DI void gemm_phase(const u16* __restrict__ A, int lda, const u16* __restrict__ Bt, int K, int N, u16* outb, int ldo,
;                    const float* r0, const float* r1, float* outf, char* lds, int bid, int nb) {
;     ...
;     for (int kt = 0; kt < nk; ++kt) {
;       const int cur = kt & 1;
;       if (kt + 1 < nk) G_LOAD(kt + 1);
;       G_MMA(cur, fo0);
;       G_MMA(cur, fo1);
;       if (kt + 1 < nk) G_STORE(cur ^ 1);
;       __syncthreads();
;     }
.Lgm7_mid0:
	s_waitcnt vmcnt(0) lgkmcnt(0)
	s_barrier
	v_mfma_f32_16x16x32_bf16 v[124:127], v[168:171], v[188:191], v[124:127]
	v_mfma_f32_16x16x32_bf16 v[120:123], v[176:179], v[188:191], v[120:123]
	v_mfma_f32_16x16x32_bf16 v[116:119], v[180:183], v[188:191], v[116:119]
	v_mfma_f32_16x16x32_bf16 v[112:115], v[184:187], v[188:191], v[112:115]
	ds_read_b128 v[188:191], v225 offset:0
	ds_read_b128 v[152:155], v227 offset:0
	s_add_u32 m0, s97, 0x0
	s_add_u32 s8, s98, 0x0
	s_addc_u32 s9, s99, 0
	global_load_lds_dwordx4 v224, s[8:9]
	v_mfma_f32_16x16x32_bf16 v[108:111], v[168:171], v[192:195], v[108:111]
	v_mfma_f32_16x16x32_bf16 v[104:107], v[176:179], v[192:195], v[104:107]
	v_mfma_f32_16x16x32_bf16 v[100:103], v[180:183], v[192:195], v[100:103]
	v_mfma_f32_16x16x32_bf16 v[96:99], v[184:187], v[192:195], v[96:99]
	ds_read_b128 v[192:195], v225 offset:2048
	ds_read_b128 v[156:159], v227 offset:2048
	s_add_u32 m0, s97, 0x10000
	s_add_u32 s8, s100, 0x0
	s_addc_u32 s9, s101, 0
	global_load_lds_dwordx4 v224, s[8:9]
	v_mfma_f32_16x16x32_bf16 v[92:95], v[168:171], v[196:199], v[92:95]
	v_mfma_f32_16x16x32_bf16 v[88:91], v[176:179], v[196:199], v[88:91]
	v_mfma_f32_16x16x32_bf16 v[84:87], v[180:183], v[196:199], v[84:87]
	v_mfma_f32_16x16x32_bf16 v[80:83], v[184:187], v[196:199], v[80:83]
	ds_read_b128 v[196:199], v225 offset:4096
	ds_read_b128 v[160:163], v227 offset:4096
	s_add_u32 m0, s97, 0x2000
	s_add_u32 s8, s98, 0x58000
	s_addc_u32 s9, s99, 0
	global_load_lds_dwordx4 v224, s[8:9]
	v_mfma_f32_16x16x32_bf16 v[76:79], v[168:171], v[200:203], v[76:79]
	v_mfma_f32_16x16x32_bf16 v[72:75], v[176:179], v[200:203], v[72:75]
	v_mfma_f32_16x16x32_bf16 v[68:71], v[180:183], v[200:203], v[68:71]
	v_mfma_f32_16x16x32_bf16 v[64:67], v[184:187], v[200:203], v[64:67]
	ds_read_b128 v[200:203], v225 offset:6144
	ds_read_b128 v[164:167], v227 offset:6144
	s_add_u32 m0, s97, 0x12000
	s_add_u32 s8, s100, 0x58000
	s_addc_u32 s9, s101, 0
	global_load_lds_dwordx4 v224, s[8:9]
	v_mfma_f32_16x16x32_bf16 v[60:63], v[168:171], v[204:207], v[60:63]
	v_mfma_f32_16x16x32_bf16 v[56:59], v[176:179], v[204:207], v[56:59]
	v_mfma_f32_16x16x32_bf16 v[52:55], v[180:183], v[204:207], v[52:55]
	v_mfma_f32_16x16x32_bf16 v[48:51], v[184:187], v[204:207], v[48:51]
	ds_read_b128 v[204:207], v225 offset:8192
	ds_read_b128 v[216:219], v225 offset:14336
	s_add_u32 m0, s97, 0x4000
	s_add_u32 s8, s98, 0xb0000
	s_addc_u32 s9, s99, 0
	global_load_lds_dwordx4 v224, s[8:9]
	v_mfma_f32_16x16x32_bf16 v[44:47], v[168:171], v[208:211], v[44:47]
	v_mfma_f32_16x16x32_bf16 v[40:43], v[176:179], v[208:211], v[40:43]
	v_mfma_f32_16x16x32_bf16 v[36:39], v[180:183], v[208:211], v[36:39]
	v_mfma_f32_16x16x32_bf16 v[32:35], v[184:187], v[208:211], v[32:35]
	ds_read_b128 v[208:211], v225 offset:10240
	s_add_u32 m0, s97, 0x14000
	s_add_u32 s8, s100, 0xb0000
	s_addc_u32 s9, s101, 0
	global_load_lds_dwordx4 v224, s[8:9]
	v_mfma_f32_16x16x32_bf16 v[28:31], v[168:171], v[212:215], v[28:31]
	v_mfma_f32_16x16x32_bf16 v[24:27], v[176:179], v[212:215], v[24:27]
	v_mfma_f32_16x16x32_bf16 v[20:23], v[180:183], v[212:215], v[20:23]
	v_mfma_f32_16x16x32_bf16 v[16:19], v[184:187], v[212:215], v[16:19]
	ds_read_b128 v[212:215], v225 offset:12288
	s_add_u32 m0, s97, 0x6000
	s_add_u32 s8, s98, 0x108000
	s_addc_u32 s9, s99, 0
	global_load_lds_dwordx4 v224, s[8:9]
	v_mfma_f32_16x16x32_bf16 v[12:15], v[168:171], v[220:223], v[12:15]
	v_mfma_f32_16x16x32_bf16 v[8:11], v[176:179], v[220:223], v[8:11]
	v_mfma_f32_16x16x32_bf16 v[4:7], v[180:183], v[220:223], v[4:7]
	v_mfma_f32_16x16x32_bf16 v[0:3], v[184:187], v[220:223], v[0:3]
	s_add_u32 m0, s97, 0x16000
	s_add_u32 s8, s100, 0x108000
	s_addc_u32 s9, s101, 0
	global_load_lds_dwordx4 v224, s[8:9]
	v_xor_b32_e32 v225, 0x8000, v225
	v_xor_b32_e32 v227, 0x8000, v227
	v_xor_b32_e32 v226, 0x8000, v226
	v_xor_b32_e32 v228, 0x8000, v228
	s_xor_b32 s97, s97, 0x8000
	s_add_u32 s98, s98, 0x80
	s_addc_u32 s99, s99, 0
	s_add_u32 s100, s100, 0x80
	s_addc_u32 s101, s101, 0
	s_sub_u32 s28, s28, 1
	s_cmp_lg_u32 s28, 0
	s_cbranch_scc1 .Lgm7_loop
	s_waitcnt lgkmcnt(4)
	v_mfma_f32_16x16x32_bf16 v[124:127], v[152:155], v[188:191], v[124:127]
	v_mfma_f32_16x16x32_bf16 v[120:123], v[156:159], v[188:191], v[120:123]
	v_mfma_f32_16x16x32_bf16 v[116:119], v[160:163], v[188:191], v[116:119]
	v_mfma_f32_16x16x32_bf16 v[112:115], v[164:167], v[188:191], v[112:115]
	ds_read_b128 v[188:191], v226 offset:0
	ds_read_b128 v[168:171], v228 offset:0
	v_mfma_f32_16x16x32_bf16 v[108:111], v[152:155], v[192:195], v[108:111]
	v_mfma_f32_16x16x32_bf16 v[104:107], v[156:159], v[192:195], v[104:107]
	v_mfma_f32_16x16x32_bf16 v[100:103], v[160:163], v[192:195], v[100:103]
	v_mfma_f32_16x16x32_bf16 v[96:99], v[164:167], v[192:195], v[96:99]
	ds_read_b128 v[192:195], v226 offset:2048
	ds_read_b128 v[176:179], v228 offset:2048
	v_mfma_f32_16x16x32_bf16 v[92:95], v[152:155], v[196:199], v[92:95]
	v_mfma_f32_16x16x32_bf16 v[88:91], v[156:159], v[196:199], v[88:91]
	v_mfma_f32_16x16x32_bf16 v[84:87], v[160:163], v[196:199], v[84:87]
	v_mfma_f32_16x16x32_bf16 v[80:83], v[164:167], v[196:199], v[80:83]
	ds_read_b128 v[196:199], v226 offset:4096
	ds_read_b128 v[180:183], v228 offset:4096
	v_mfma_f32_16x16x32_bf16 v[76:79], v[152:155], v[200:203], v[76:79]
	v_mfma_f32_16x16x32_bf16 v[72:75], v[156:159], v[200:203], v[72:75]
	v_mfma_f32_16x16x32_bf16 v[68:71], v[160:163], v[200:203], v[68:71]
	v_mfma_f32_16x16x32_bf16 v[64:67], v[164:167], v[200:203], v[64:67]
	ds_read_b128 v[200:203], v226 offset:6144
	ds_read_b128 v[184:187], v228 offset:6144
	s_waitcnt lgkmcnt(11)
	v_mfma_f32_16x16x32_bf16 v[60:63], v[152:155], v[204:207], v[60:63]
	v_mfma_f32_16x16x32_bf16 v[56:59], v[156:159], v[204:207], v[56:59]
	v_mfma_f32_16x16x32_bf16 v[52:55], v[160:163], v[204:207], v[52:55]
	v_mfma_f32_16x16x32_bf16 v[48:51], v[164:167], v[204:207], v[48:51]
	ds_read_b128 v[204:207], v226 offset:8192
	ds_read_b128 v[220:223], v226 offset:14336
	s_waitcnt lgkmcnt(11)
	v_mfma_f32_16x16x32_bf16 v[44:47], v[152:155], v[208:211], v[44:47]
	v_mfma_f32_16x16x32_bf16 v[40:43], v[156:159], v[208:211], v[40:43]
	v_mfma_f32_16x16x32_bf16 v[36:39], v[160:163], v[208:211], v[36:39]
	v_mfma_f32_16x16x32_bf16 v[32:35], v[164:167], v[208:211], v[32:35]
	ds_read_b128 v[208:211], v226 offset:10240
	s_waitcnt lgkmcnt(11)
	v_mfma_f32_16x16x32_bf16 v[28:31], v[152:155], v[212:215], v[28:31]
	v_mfma_f32_16x16x32_bf16 v[24:27], v[156:159], v[212:215], v[24:27]
	v_mfma_f32_16x16x32_bf16 v[20:23], v[160:163], v[212:215], v[20:23]
	v_mfma_f32_16x16x32_bf16 v[16:19], v[164:167], v[212:215], v[16:19]
	ds_read_b128 v[212:215], v226 offset:12288
	v_mfma_f32_16x16x32_bf16 v[12:15], v[152:155], v[216:219], v[12:15]
	v_mfma_f32_16x16x32_bf16 v[8:11], v[156:159], v[216:219], v[8:11]
	v_mfma_f32_16x16x32_bf16 v[4:7], v[160:163], v[216:219], v[4:7]
	v_mfma_f32_16x16x32_bf16 v[0:3], v[164:167], v[216:219], v[0:3]
	s_waitcnt vmcnt(0) lgkmcnt(0)
	s_barrier
; #define G_LOAD(KT) do { _Pragma("unroll") for (int i = 0; i < 4; ++i) { ra[i] = *(const u32x4*)(Ag + (size_t)i * 64 * lda + (KT) * 64); rb[i] = *(const u32x4*)(Bg + (size_t)i * 64 * K + (KT) * 64); } } while (0)
; #define G_STORE(BUF) do { u16* ad = As + (BUF) * 256 * 64 + sto; u16* bd = Bs + (BUF) * 256 * 64 + sto; _Pragma("unroll") for (int i = 0; i < 4; ++i) { *(u32x4*)(ad + i * 64 * 64) = ra[i]; *(u32x4*)(bd + i * 64 * 64) = rb[i]; } } while (0)
; template <int EPI>
; DI void gemm_phase(const u16* __restrict__ A, int lda, const u16* __restrict__ Bt, int K, int N, u16* outb, int ldo,
;                    const float* r0, const float* r1, float* outf, char* lds, int bid, int nb) {
;     ...
;     for (int kt = 0; kt < nk; ++kt) {
;       const int cur = kt & 1;
;       if (kt + 1 < nk) G_LOAD(kt + 1);
;       G_MMA(cur, fo0);
;       G_MMA(cur, fo1);
;       if (kt + 1 < nk) G_STORE(cur ^ 1);
;       __syncthreads();
;     }
	v_mfma_f32_16x16x32_bf16 v[124:127], v[168:171], v[188:191], v[124:127]
	v_mfma_f32_16x16x32_bf16 v[120:123], v[176:179], v[188:191], v[120:123]
	v_mfma_f32_16x16x32_bf16 v[116:119], v[180:183], v[188:191], v[116:119]
	v_mfma_f32_16x16x32_bf16 v[112:115], v[184:187], v[188:191], v[112:115]
	ds_read_b128 v[188:191], v225 offset:0
	ds_read_b128 v[152:155], v227 offset:0
	v_mfma_f32_16x16x32_bf16 v[108:111], v[168:171], v[192:195], v[108:111]
	v_mfma_f32_16x16x32_bf16 v[104:107], v[176:179], v[192:195], v[104:107]
	v_mfma_f32_16x16x32_bf16 v[100:103], v[180:183], v[192:195], v[100:103]
	v_mfma_f32_16x16x32_bf16 v[96:99], v[184:187], v[192:195], v[96:99]
	ds_read_b128 v[192:195], v225 offset:2048
	ds_read_b128 v[156:159], v227 offset:2048
	v_mfma_f32_16x16x32_bf16 v[92:95], v[168:171], v[196:199], v[92:95]
	v_mfma_f32_16x16x32_bf16 v[88:91], v[176:179], v[196:199], v[88:91]
	v_mfma_f32_16x16x32_bf16 v[84:87], v[180:183], v[196:199], v[84:87]
	v_mfma_f32_16x16x32_bf16 v[80:83], v[184:187], v[196:199], v[80:83]
	ds_read_b128 v[196:199], v225 offset:4096
	ds_read_b128 v[160:163], v227 offset:4096
	v_mfma_f32_16x16x32_bf16 v[76:79], v[168:171], v[200:203], v[76:79]
	v_mfma_f32_16x16x32_bf16 v[72:75], v[176:179], v[200:203], v[72:75]
	v_mfma_f32_16x16x32_bf16 v[68:71], v[180:183], v[200:203], v[68:71]
	v_mfma_f32_16x16x32_bf16 v[64:67], v[184:187], v[200:203], v[64:67]
	ds_read_b128 v[200:203], v225 offset:6144
	ds_read_b128 v[164:167], v227 offset:6144
	v_mfma_f32_16x16x32_bf16 v[60:63], v[168:171], v[204:207], v[60:63]
	v_mfma_f32_16x16x32_bf16 v[56:59], v[176:179], v[204:207], v[56:59]
	v_mfma_f32_16x16x32_bf16 v[52:55], v[180:183], v[204:207], v[52:55]
	v_mfma_f32_16x16x32_bf16 v[48:51], v[184:187], v[204:207], v[48:51]
	ds_read_b128 v[204:207], v225 offset:8192
	ds_read_b128 v[216:219], v225 offset:14336
	v_mfma_f32_16x16x32_bf16 v[44:47], v[168:171], v[208:211], v[44:47]
	v_mfma_f32_16x16x32_bf16 v[40:43], v[176:179], v[208:211], v[40:43]
	v_mfma_f32_16x16x32_bf16 v[36:39], v[180:183], v[208:211], v[36:39]
	v_mfma_f32_16x16x32_bf16 v[32:35], v[184:187], v[208:211], v[32:35]
	ds_read_b128 v[208:211], v225 offset:10240
	v_mfma_f32_16x16x32_bf16 v[28:31], v[168:171], v[212:215], v[28:31]
	v_mfma_f32_16x16x32_bf16 v[24:27], v[176:179], v[212:215], v[24:27]
	v_mfma_f32_16x16x32_bf16 v[20:23], v[180:183], v[212:215], v[20:23]
	v_mfma_f32_16x16x32_bf16 v[16:19], v[184:187], v[212:215], v[16:19]
	ds_read_b128 v[212:215], v225 offset:12288
	v_mfma_f32_16x16x32_bf16 v[12:15], v[168:171], v[220:223], v[12:15]
	v_mfma_f32_16x16x32_bf16 v[8:11], v[176:179], v[220:223], v[8:11]
	v_mfma_f32_16x16x32_bf16 v[4:7], v[180:183], v[220:223], v[4:7]
	v_mfma_f32_16x16x32_bf16 v[0:3], v[184:187], v[220:223], v[0:3]
	v_xor_b32_e32 v226, 0x8000, v226
	v_xor_b32_e32 v228, 0x8000, v228
	s_waitcnt lgkmcnt(4)
	v_mfma_f32_16x16x32_bf16 v[124:127], v[152:155], v[188:191], v[124:127]
	v_mfma_f32_16x16x32_bf16 v[120:123], v[156:159], v[188:191], v[120:123]
	v_mfma_f32_16x16x32_bf16 v[116:119], v[160:163], v[188:191], v[116:119]
	v_mfma_f32_16x16x32_bf16 v[112:115], v[164:167], v[188:191], v[112:115]
	ds_read_b128 v[188:191], v226 offset:0
	ds_read_b128 v[168:171], v228 offset:0
	v_mfma_f32_16x16x32_bf16 v[108:111], v[152:155], v[192:195], v[108:111]
	v_mfma_f32_16x16x32_bf16 v[104:107], v[156:159], v[192:195], v[104:107]
	v_mfma_f32_16x16x32_bf16 v[100:103], v[160:163], v[192:195], v[100:103]
	v_mfma_f32_16x16x32_bf16 v[96:99], v[164:167], v[192:195], v[96:99]
	ds_read_b128 v[192:195], v226 offset:2048
	ds_read_b128 v[176:179], v228 offset:2048
	v_mfma_f32_16x16x32_bf16 v[92:95], v[152:155], v[196:199], v[92:95]
	v_mfma_f32_16x16x32_bf16 v[88:91], v[156:159], v[196:199], v[88:91]
	v_mfma_f32_16x16x32_bf16 v[84:87], v[160:163], v[196:199], v[84:87]
	v_mfma_f32_16x16x32_bf16 v[80:83], v[164:167], v[196:199], v[80:83]
	ds_read_b128 v[196:199], v226 offset:4096
	ds_read_b128 v[180:183], v228 offset:4096
	v_mfma_f32_16x16x32_bf16 v[76:79], v[152:155], v[200:203], v[76:79]
	v_mfma_f32_16x16x32_bf16 v[72:75], v[156:159], v[200:203], v[72:75]
	v_mfma_f32_16x16x32_bf16 v[68:71], v[160:163], v[200:203], v[68:71]
	v_mfma_f32_16x16x32_bf16 v[64:67], v[164:167], v[200:203], v[64:67]
	ds_read_b128 v[200:203], v226 offset:6144
	ds_read_b128 v[184:187], v228 offset:6144
	s_waitcnt lgkmcnt(11)
	v_mfma_f32_16x16x32_bf16 v[60:63], v[152:155], v[204:207], v[60:63]
	v_mfma_f32_16x16x32_bf16 v[56:59], v[156:159], v[204:207], v[56:59]
	v_mfma_f32_16x16x32_bf16 v[52:55], v[160:163], v[204:207], v[52:55]
	v_mfma_f32_16x16x32_bf16 v[48:51], v[164:167], v[204:207], v[48:51]
	ds_read_b128 v[204:207], v226 offset:8192
	ds_read_b128 v[220:223], v226 offset:14336
	s_waitcnt lgkmcnt(11)
	v_mfma_f32_16x16x32_bf16 v[44:47], v[152:155], v[208:211], v[44:47]
	v_mfma_f32_16x16x32_bf16 v[40:43], v[156:159], v[208:211], v[40:43]
	v_mfma_f32_16x16x32_bf16 v[36:39], v[160:163], v[208:211], v[36:39]
	v_mfma_f32_16x16x32_bf16 v[32:35], v[164:167], v[208:211], v[32:35]
	ds_read_b128 v[208:211], v226 offset:10240
	s_waitcnt lgkmcnt(11)
	v_mfma_f32_16x16x32_bf16 v[28:31], v[152:155], v[212:215], v[28:31]
	v_mfma_f32_16x16x32_bf16 v[24:27], v[156:159], v[212:215], v[24:27]
	v_mfma_f32_16x16x32_bf16 v[20:23], v[160:163], v[212:215], v[20:23]
	v_mfma_f32_16x16x32_bf16 v[16:19], v[164:167], v[212:215], v[16:19]
	ds_read_b128 v[212:215], v226 offset:12288
	v_mfma_f32_16x16x32_bf16 v[12:15], v[152:155], v[216:219], v[12:15]
	v_mfma_f32_16x16x32_bf16 v[8:11], v[156:159], v[216:219], v[8:11]
	v_mfma_f32_16x16x32_bf16 v[4:7], v[160:163], v[216:219], v[4:7]
	v_mfma_f32_16x16x32_bf16 v[0:3], v[164:167], v[216:219], v[0:3]
	s_waitcnt vmcnt(0) lgkmcnt(0)
	s_barrier
; template <int EPI>
; DI void gemm_phase(const u16* __restrict__ A, int lda, const u16* __restrict__ Bt, int K, int N, u16* outb, int ldo,
;                    const float* r0, const float* r1, float* outf, char* lds, int bid, int nb) {
;     ...
;     } else if constexpr (EPI == EPI_RESID) {
;       const int col = tn * 256 + wc * 64 + l15;
;       const float* rb_ = (tm * 256 < M_P) ? r0 : (r1 - (size_t)M_P * DM);
; #pragma unroll
;       for (int i = 0; i < 8; ++i)
; #pragma unroll
;         for (int r = 0; r < 4; ++r) {
;           const size_t i0 = (size_t)(mrow + i * 16 + r) * DM + col;
;           const float x0 = rb_[i0], x1 = rb_[i0 + 16], x2 = rb_[i0 + 32], x3 = rb_[i0 + 48];
;           outf[i0] = x0 + acc[i][0][r]; outf[i0 + 16] = x1 + acc[i][1][r]; outf[i0 + 32] = x2 + acc[i][2][r]; outf[i0 + 48] = x3 + acc[i][3][r];
;         }
	v_mfma_f32_16x16x32_bf16 v[124:127], v[168:171], v[188:191], v[124:127]
	v_mfma_f32_16x16x32_bf16 v[120:123], v[176:179], v[188:191], v[120:123]
	v_mfma_f32_16x16x32_bf16 v[116:119], v[180:183], v[188:191], v[116:119]
	v_mfma_f32_16x16x32_bf16 v[112:115], v[184:187], v[188:191], v[112:115]
	v_mfma_f32_16x16x32_bf16 v[108:111], v[168:171], v[192:195], v[108:111]
	v_mfma_f32_16x16x32_bf16 v[104:107], v[176:179], v[192:195], v[104:107]
	v_mfma_f32_16x16x32_bf16 v[100:103], v[180:183], v[192:195], v[100:103]
	v_mfma_f32_16x16x32_bf16 v[96:99], v[184:187], v[192:195], v[96:99]
	v_mfma_f32_16x16x32_bf16 v[92:95], v[168:171], v[196:199], v[92:95]
	v_mfma_f32_16x16x32_bf16 v[88:91], v[176:179], v[196:199], v[88:91]
	v_mfma_f32_16x16x32_bf16 v[84:87], v[180:183], v[196:199], v[84:87]
	v_mfma_f32_16x16x32_bf16 v[80:83], v[184:187], v[196:199], v[80:83]
	v_mfma_f32_16x16x32_bf16 v[76:79], v[168:171], v[200:203], v[76:79]
	v_mfma_f32_16x16x32_bf16 v[72:75], v[176:179], v[200:203], v[72:75]
	v_mfma_f32_16x16x32_bf16 v[68:71], v[180:183], v[200:203], v[68:71]
	v_mfma_f32_16x16x32_bf16 v[64:67], v[184:187], v[200:203], v[64:67]
	v_mfma_f32_16x16x32_bf16 v[60:63], v[168:171], v[204:207], v[60:63]
	v_mfma_f32_16x16x32_bf16 v[56:59], v[176:179], v[204:207], v[56:59]
	v_mfma_f32_16x16x32_bf16 v[52:55], v[180:183], v[204:207], v[52:55]
	v_mfma_f32_16x16x32_bf16 v[48:51], v[184:187], v[204:207], v[48:51]
	v_mfma_f32_16x16x32_bf16 v[44:47], v[168:171], v[208:211], v[44:47]
	v_mfma_f32_16x16x32_bf16 v[40:43], v[176:179], v[208:211], v[40:43]
	v_mfma_f32_16x16x32_bf16 v[36:39], v[180:183], v[208:211], v[36:39]
	v_mfma_f32_16x16x32_bf16 v[32:35], v[184:187], v[208:211], v[32:35]
	v_mfma_f32_16x16x32_bf16 v[28:31], v[168:171], v[212:215], v[28:31]
	v_mfma_f32_16x16x32_bf16 v[24:27], v[176:179], v[212:215], v[24:27]
	v_mfma_f32_16x16x32_bf16 v[20:23], v[180:183], v[212:215], v[20:23]
	v_mfma_f32_16x16x32_bf16 v[16:19], v[184:187], v[212:215], v[16:19]
	v_mfma_f32_16x16x32_bf16 v[12:15], v[168:171], v[220:223], v[12:15]
	v_mfma_f32_16x16x32_bf16 v[8:11], v[176:179], v[220:223], v[8:11]
	v_mfma_f32_16x16x32_bf16 v[4:7], v[180:183], v[220:223], v[4:7]
	v_mfma_f32_16x16x32_bf16 v[0:3], v[184:187], v[220:223], v[0:3]
	s_nop 7
	s_nop 3
	v_and_b32_e32 v225, 15, v174
	v_lshrrev_b32_e32 v226, 8, v174
	v_lshl_or_b32 v225, v226, 7, v225
	v_bfe_u32 v226, v174, 6, 2
	v_bfe_u32 v227, v174, 4, 2
	v_lshlrev_b32_e32 v227, 2, v227
	v_add_u32_e32 v225, s37, v225
	v_lshl_add_u32 v226, v226, 6, v227
	v_add_u32_e32 v226, s38, v226
	v_lshlrev_b32_e32 v226, 2, v226
	v_lshl_add_u32 v224, v225, 12, v226
	v_mov_b32_e32 v229, v224
	v_add_u32_e32 v224, 0x0, v229
	global_load_dwordx4 v[152:155], v224, s[22:23] offset:0
	global_load_dwordx4 v[156:159], v224, s[22:23] offset:64
	global_load_dwordx4 v[160:163], v224, s[22:23] offset:128
	global_load_dwordx4 v[164:167], v224, s[22:23] offset:192
	v_add_u32_e32 v228, 0x10000, v229
	global_load_dwordx4 v[168:171], v228, s[22:23] offset:0
	global_load_dwordx4 v[176:179], v228, s[22:23] offset:64
	global_load_dwordx4 v[180:183], v228, s[22:23] offset:128
	global_load_dwordx4 v[184:187], v228, s[22:23] offset:192
	s_waitcnt vmcnt(4)
	v_add_f32_e32 v152, v124, v152
	v_add_f32_e32 v153, v125, v153
	v_add_f32_e32 v154, v126, v154
	v_add_f32_e32 v155, v127, v155
	v_add_f32_e32 v156, v120, v156
	v_add_f32_e32 v157, v121, v157
	v_add_f32_e32 v158, v122, v158
	v_add_f32_e32 v159, v123, v159
	v_add_f32_e32 v160, v116, v160
	v_add_f32_e32 v161, v117, v161
	v_add_f32_e32 v162, v118, v162
	v_add_f32_e32 v163, v119, v163
	v_add_f32_e32 v164, v112, v164
	v_add_f32_e32 v165, v113, v165
	v_add_f32_e32 v166, v114, v166
	v_add_f32_e32 v167, v115, v167
	global_store_dwordx4 v224, v[152:155], s[22:23] offset:0
	global_store_dwordx4 v224, v[156:159], s[22:23] offset:64
	global_store_dwordx4 v224, v[160:163], s[22:23] offset:128
	global_store_dwordx4 v224, v[164:167], s[22:23] offset:192
	s_nop 1
	v_add_u32_e32 v224, 0x20000, v229
	global_load_dwordx4 v[152:155], v224, s[22:23] offset:0
	global_load_dwordx4 v[156:159], v224, s[22:23] offset:64
	global_load_dwordx4 v[160:163], v224, s[22:23] offset:128
	global_load_dwordx4 v[164:167], v224, s[22:23] offset:192
	s_waitcnt vmcnt(8)
	v_add_f32_e32 v168, v108, v168
	v_add_f32_e32 v169, v109, v169
	v_add_f32_e32 v170, v110, v170
	v_add_f32_e32 v171, v111, v171
	v_add_f32_e32 v176, v104, v176
	v_add_f32_e32 v177, v105, v177
	v_add_f32_e32 v178, v106, v178
	v_add_f32_e32 v179, v107, v179
	v_add_f32_e32 v180, v100, v180
	v_add_f32_e32 v181, v101, v181
	v_add_f32_e32 v182, v102, v182
	v_add_f32_e32 v183, v103, v183
	v_add_f32_e32 v184, v96, v184
	v_add_f32_e32 v185, v97, v185
	v_add_f32_e32 v186, v98, v186
	v_add_f32_e32 v187, v99, v187
	global_store_dwordx4 v228, v[168:171], s[22:23] offset:0
	global_store_dwordx4 v228, v[176:179], s[22:23] offset:64
	global_store_dwordx4 v228, v[180:183], s[22:23] offset:128
	global_store_dwordx4 v228, v[184:187], s[22:23] offset:192
	s_nop 1
	v_add_u32_e32 v228, 0x30000, v229
	global_load_dwordx4 v[168:171], v228, s[22:23] offset:0
	global_load_dwordx4 v[176:179], v228, s[22:23] offset:64
	global_load_dwordx4 v[180:183], v228, s[22:23] offset:128
	global_load_dwordx4 v[184:187], v228, s[22:23] offset:192
	s_waitcnt vmcnt(8)
; template <int EPI>
; DI void gemm_phase(const u16* __restrict__ A, int lda, const u16* __restrict__ Bt, int K, int N, u16* outb, int ldo,
;                    const float* r0, const float* r1, float* outf, char* lds, int bid, int nb) {
;     ...
;     } else if constexpr (EPI == EPI_RESID) {
;       const int col = tn * 256 + wc * 64 + l15;
;       const float* rb_ = (tm * 256 < M_P) ? r0 : (r1 - (size_t)M_P * DM);
; #pragma unroll
;       for (int i = 0; i < 8; ++i)
; #pragma unroll
;         for (int r = 0; r < 4; ++r) {
;           const size_t i0 = (size_t)(mrow + i * 16 + r) * DM + col;
;           const float x0 = rb_[i0], x1 = rb_[i0 + 16], x2 = rb_[i0 + 32], x3 = rb_[i0 + 48];
;           outf[i0] = x0 + acc[i][0][r]; outf[i0 + 16] = x1 + acc[i][1][r]; outf[i0 + 32] = x2 + acc[i][2][r]; outf[i0 + 48] = x3 + acc[i][3][r];
;         }
	v_add_f32_e32 v152, v92, v152
	v_add_f32_e32 v153, v93, v153
	v_add_f32_e32 v154, v94, v154
	v_add_f32_e32 v155, v95, v155
	v_add_f32_e32 v156, v88, v156
	v_add_f32_e32 v157, v89, v157
	v_add_f32_e32 v158, v90, v158
	v_add_f32_e32 v159, v91, v159
	v_add_f32_e32 v160, v84, v160
	v_add_f32_e32 v161, v85, v161
	v_add_f32_e32 v162, v86, v162
	v_add_f32_e32 v163, v87, v163
	v_add_f32_e32 v164, v80, v164
	v_add_f32_e32 v165, v81, v165
	v_add_f32_e32 v166, v82, v166
	v_add_f32_e32 v167, v83, v167
	global_store_dwordx4 v224, v[152:155], s[22:23] offset:0
	global_store_dwordx4 v224, v[156:159], s[22:23] offset:64
	global_store_dwordx4 v224, v[160:163], s[22:23] offset:128
	global_store_dwordx4 v224, v[164:167], s[22:23] offset:192
	s_nop 1
	v_add_u32_e32 v224, 0x40000, v229
	global_load_dwordx4 v[152:155], v224, s[22:23] offset:0
	global_load_dwordx4 v[156:159], v224, s[22:23] offset:64
	global_load_dwordx4 v[160:163], v224, s[22:23] offset:128
	global_load_dwordx4 v[164:167], v224, s[22:23] offset:192
	s_waitcnt vmcnt(8)
	v_add_f32_e32 v168, v76, v168
	v_add_f32_e32 v169, v77, v169
	v_add_f32_e32 v170, v78, v170
	v_add_f32_e32 v171, v79, v171
	v_add_f32_e32 v176, v72, v176
	v_add_f32_e32 v177, v73, v177
	v_add_f32_e32 v178, v74, v178
	v_add_f32_e32 v179, v75, v179
	v_add_f32_e32 v180, v68, v180
	v_add_f32_e32 v181, v69, v181
	v_add_f32_e32 v182, v70, v182
	v_add_f32_e32 v183, v71, v183
	v_add_f32_e32 v184, v64, v184
	v_add_f32_e32 v185, v65, v185
	v_add_f32_e32 v186, v66, v186
	v_add_f32_e32 v187, v67, v187
	global_store_dwordx4 v228, v[168:171], s[22:23] offset:0
	global_store_dwordx4 v228, v[176:179], s[22:23] offset:64
	global_store_dwordx4 v228, v[180:183], s[22:23] offset:128
	global_store_dwordx4 v228, v[184:187], s[22:23] offset:192
	s_nop 1
	v_add_u32_e32 v228, 0x50000, v229
	global_load_dwordx4 v[168:171], v228, s[22:23] offset:0
	global_load_dwordx4 v[176:179], v228, s[22:23] offset:64
	global_load_dwordx4 v[180:183], v228, s[22:23] offset:128
	global_load_dwordx4 v[184:187], v228, s[22:23] offset:192
	s_waitcnt vmcnt(8)
	v_add_f32_e32 v152, v60, v152
	v_add_f32_e32 v153, v61, v153
	v_add_f32_e32 v154, v62, v154
	v_add_f32_e32 v155, v63, v155
	v_add_f32_e32 v156, v56, v156
	v_add_f32_e32 v157, v57, v157
	v_add_f32_e32 v158, v58, v158
	v_add_f32_e32 v159, v59, v159
	v_add_f32_e32 v160, v52, v160
	v_add_f32_e32 v161, v53, v161
	v_add_f32_e32 v162, v54, v162
	v_add_f32_e32 v163, v55, v163
	v_add_f32_e32 v164, v48, v164
	v_add_f32_e32 v165, v49, v165
	v_add_f32_e32 v166, v50, v166
	v_add_f32_e32 v167, v51, v167
	global_store_dwordx4 v224, v[152:155], s[22:23] offset:0
	global_store_dwordx4 v224, v[156:159], s[22:23] offset:64
	global_store_dwordx4 v224, v[160:163], s[22:23] offset:128
	global_store_dwordx4 v224, v[164:167], s[22:23] offset:192
	s_nop 1
	v_add_u32_e32 v224, 0x60000, v229
	global_load_dwordx4 v[152:155], v224, s[22:23] offset:0
	global_load_dwordx4 v[156:159], v224, s[22:23] offset:64
	global_load_dwordx4 v[160:163], v224, s[22:23] offset:128
	global_load_dwordx4 v[164:167], v224, s[22:23] offset:192
	s_waitcnt vmcnt(8)
	v_add_f32_e32 v168, v44, v168
	v_add_f32_e32 v169, v45, v169
	v_add_f32_e32 v170, v46, v170
	v_add_f32_e32 v171, v47, v171
	v_add_f32_e32 v176, v40, v176
	v_add_f32_e32 v177, v41, v177
	v_add_f32_e32 v178, v42, v178
	v_add_f32_e32 v179, v43, v179
	v_add_f32_e32 v180, v36, v180
	v_add_f32_e32 v181, v37, v181
	v_add_f32_e32 v182, v38, v182
	v_add_f32_e32 v183, v39, v183
	v_add_f32_e32 v184, v32, v184
	v_add_f32_e32 v185, v33, v185
	v_add_f32_e32 v186, v34, v186
	v_add_f32_e32 v187, v35, v187
	global_store_dwordx4 v228, v[168:171], s[22:23] offset:0
	global_store_dwordx4 v228, v[176:179], s[22:23] offset:64
	global_store_dwordx4 v228, v[180:183], s[22:23] offset:128
	global_store_dwordx4 v228, v[184:187], s[22:23] offset:192
	s_nop 1
	v_add_u32_e32 v228, 0x70000, v229
	global_load_dwordx4 v[168:171], v228, s[22:23] offset:0
	global_load_dwordx4 v[176:179], v228, s[22:23] offset:64
	global_load_dwordx4 v[180:183], v228, s[22:23] offset:128
	global_load_dwordx4 v[184:187], v228, s[22:23] offset:192
	s_waitcnt vmcnt(8)
	v_add_f32_e32 v152, v28, v152
	v_add_f32_e32 v153, v29, v153
	v_add_f32_e32 v154, v30, v154
	v_add_f32_e32 v155, v31, v155
	v_add_f32_e32 v156, v24, v156
	v_add_f32_e32 v157, v25, v157
	v_add_f32_e32 v158, v26, v158
	v_add_f32_e32 v159, v27, v159
	v_add_f32_e32 v160, v20, v160
	v_add_f32_e32 v161, v21, v161
	v_add_f32_e32 v162, v22, v162
	v_add_f32_e32 v163, v23, v163
	v_add_f32_e32 v164, v16, v164
	v_add_f32_e32 v165, v17, v165
	v_add_f32_e32 v166, v18, v166
	v_add_f32_e32 v167, v19, v167
	global_store_dwordx4 v224, v[152:155], s[22:23] offset:0
	global_store_dwordx4 v224, v[156:159], s[22:23] offset:64
	global_store_dwordx4 v224, v[160:163], s[22:23] offset:128
	global_store_dwordx4 v224, v[164:167], s[22:23] offset:192
	s_waitcnt vmcnt(4)
	v_add_f32_e32 v168, v12, v168
	v_add_f32_e32 v169, v13, v169
	v_add_f32_e32 v170, v14, v170
	v_add_f32_e32 v171, v15, v171
	v_add_f32_e32 v176, v8, v176
	v_add_f32_e32 v177, v9, v177
	v_add_f32_e32 v178, v10, v178
	v_add_f32_e32 v179, v11, v179
	v_add_f32_e32 v180, v4, v180
	v_add_f32_e32 v181, v5, v181
	v_add_f32_e32 v182, v6, v182
	v_add_f32_e32 v183, v7, v183
	v_add_f32_e32 v184, v0, v184
	v_add_f32_e32 v185, v1, v185
	v_add_f32_e32 v186, v2, v186
	v_add_f32_e32 v187, v3, v187
	global_store_dwordx4 v228, v[168:171], s[22:23] offset:0
	global_store_dwordx4 v228, v[176:179], s[22:23] offset:64
	global_store_dwordx4 v228, v[180:183], s[22:23] offset:128
	global_store_dwordx4 v228, v[184:187], s[22:23] offset:192
	s_add_i32 s14, s14, 1
	s_cmp_eq_u32 s14, s3
	s_cbranch_scc0 .LBB0_1359
